# combined + GEMM load segments issue the LDS-DMA stages before the ds_read fragment loads (more lead time per staged half-tile)
# baseline (speedup 1.0000x reference)
; #define PG8_STAGE(bufoff, gbase, voff) do { _Pragma("unroll") for (int _i = 0; _i < 2; ++_i) \
;         __builtin_amdgcn_global_load_lds((const unsigned*)((const char*)(gbase) + (voff)[_i]), (LAS unsigned*)(lds + (bufoff) + ldsw + _i * 8192), 16, 0, 0); } while (0)
; #define PG8_LDA(dst, b, h) do { _Pragma("unroll") for (int m = 0; m < 4; ++m) _Pragma("unroll") for (int k = 0; k < 2; ++k) dst[m][k] = *(const LAS bf16x8*)(lds + PG8_SA(b, h) + aoff + m * 2048 + k * 1024); } while (0)
; #define PG8_LDB(dst, b, h) do { _Pragma("unroll") for (int n = 0; n < 2; ++n) _Pragma("unroll") for (int k = 0; k < 2; ++k) dst[n][k] = *(const LAS bf16x8*)(lds + PG8_SB(b, h) + boff + n * 2048 + k * 1024); } while (0)
; #define PG8_MMA(ai, bj, At, Bt) do { __builtin_amdgcn_s_setprio(1); _Pragma("unroll") for (int m = 0; m < 4; ++m) _Pragma("unroll") for (int n = 0; n < 2; ++n) _Pragma("unroll") for (int k = 0; k < 2; ++k) \
;         acc[ai][bj][m][n] = __builtin_amdgcn_mfma_f32_16x16x32_bf16(Bt[n][k], At[m][k], acc[ai][bj][m][n], 0, 0, 0); __builtin_amdgcn_s_setprio(0); } while (0)
; #define PG8_WAIT_V(n) asm volatile("s_waitcnt vmcnt(" #n ")" ::: "memory")
; #define PG8_WAIT_L(n) asm volatile("s_waitcnt lgkmcnt(" #n ")" ::: "memory")
; #define PG8_BAR __builtin_amdgcn_s_barrier()
; #define PG8_SCHED __builtin_amdgcn_sched_barrier(0)
; template <class Epi>
; __device__ __forceinline__ void gemm_phase(LAS unsigned char* lds, const Gemm g, int G, int c, const Epi& E) {
;     ...
;         for (int t = 0; t < nt; t += 2) {
;             const bool last = (t == nt - 2);
;             const char* a1 = cA + (size_t)(t + 1) * kstep;
;             const char* a2 = last ? nA : cA + (size_t)(t + 2) * kstep; const char* b2 = last ? nB : cB + (size_t)(t + 2) * kstep;
;             const char* a3 = a2 + kstep; const char* b3 = b2 + kstep;
;             PG8_LDB(B0, 0, 0); PG8_LDB(B1, 0, 1); PG8_SCHED; PG8_LDA(At, 0, 0); PG8_STAGE(PG8_SA(1, 1), a1 + hstepA, voffA);
;             PG8_WAIT_V(8); PG8_WAIT_L(0); PG8_BAR; PG8_MMA(0, 0, At, B0); PG8_MMA(0, 1, At, B1); PG8_BAR; PG8_SCHED;
;             PG8_LDA(At, 0, 1); PG8_STAGE(PG8_SB(0, 0), b2, voffB); PG8_STAGE(PG8_SB(0, 1), b2 + hstepB, voffB); PG8_STAGE(PG8_SA(0, 0), a2, voffA);
;             PG8_WAIT_V(8); PG8_WAIT_L(0); PG8_BAR; PG8_MMA(1, 0, At, B0); PG8_MMA(1, 1, At, B1); PG8_BAR; PG8_SCHED;
.LBB0_236:
	s_add_u32 s33, s4, 0xfffc0080
	s_addc_u32 s54, s5, -1
	s_cmp_eq_u32 s85, 12
	s_cselect_b32 s57, s47, s54
	s_cselect_b32 s56, s46, s33
	s_cselect_b32 s55, s7, s84
	s_cselect_b32 s54, s43, s45
	v_lshl_add_u64 v[218:219], s[4:5], 0, v[138:139]
	s_add_i32 m0, s11, 0xc000
	s_nop 0
	global_load_lds_dwordx4 v[218:219], off
	v_lshl_add_u64 v[218:219], s[4:5], 0, v[140:141]
	s_add_i32 m0, s11, 0xe000
	s_nop 0
	global_load_lds_dwordx4 v[218:219], off
	ds_read_b128 v[146:149], v152
	ds_read_b128 v[158:161], v152 offset:1024
	ds_read_b128 v[162:165], v152 offset:2048
	ds_read_b128 v[166:169], v152 offset:3072
	ds_read_b128 v[170:173], v153
	ds_read_b128 v[174:177], v153 offset:1024
	ds_read_b128 v[178:181], v153 offset:2048
	ds_read_b128 v[182:185], v153 offset:3072
	ds_read_b128 v[186:189], v154
	ds_read_b128 v[190:193], v154 offset:1024
	ds_read_b128 v[194:197], v154 offset:2048
	ds_read_b128 v[198:201], v154 offset:3072
	ds_read_b128 v[202:205], v154 offset:4096
	ds_read_b128 v[206:209], v154 offset:5120
	ds_read_b128 v[210:213], v154 offset:6144
	ds_read_b128 v[214:217], v154 offset:7168
	s_waitcnt vmcnt(8)
	s_waitcnt lgkmcnt(0)
	s_barrier
	s_setprio 0
	s_waitcnt lgkmcnt(0)
	v_mfma_f32_16x16x32_bf16 v[126:129], v[146:149], v[186:189], v[126:129]
	v_mfma_f32_16x16x32_bf16 v[122:125], v[162:165], v[186:189], v[122:125]
	v_mfma_f32_16x16x32_bf16 v[110:113], v[146:149], v[194:197], v[110:113]
	v_mfma_f32_16x16x32_bf16 v[106:109], v[162:165], v[194:197], v[106:109]
	v_mfma_f32_16x16x32_bf16 v[94:97], v[146:149], v[202:205], v[94:97]
	v_mfma_f32_16x16x32_bf16 v[90:93], v[162:165], v[202:205], v[90:93]
	v_mfma_f32_16x16x32_bf16 v[78:81], v[146:149], v[210:213], v[78:81]
	v_mfma_f32_16x16x32_bf16 v[74:77], v[162:165], v[210:213], v[74:77]
	v_mfma_f32_16x16x32_bf16 v[126:129], v[158:161], v[190:193], v[126:129]
	v_mfma_f32_16x16x32_bf16 v[122:125], v[166:169], v[190:193], v[122:125]
	v_mfma_f32_16x16x32_bf16 v[110:113], v[158:161], v[198:201], v[110:113]
	v_mfma_f32_16x16x32_bf16 v[106:109], v[166:169], v[198:201], v[106:109]
	v_mfma_f32_16x16x32_bf16 v[94:97], v[158:161], v[206:209], v[94:97]
	v_mfma_f32_16x16x32_bf16 v[90:93], v[166:169], v[206:209], v[90:93]
	v_mfma_f32_16x16x32_bf16 v[78:81], v[158:161], v[214:217], v[78:81]
	v_mfma_f32_16x16x32_bf16 v[74:77], v[166:169], v[214:217], v[74:77]
	s_setprio 2
	s_setprio 0
	v_mfma_f32_16x16x32_bf16 v[118:121], v[170:173], v[186:189], v[118:121]
	v_mfma_f32_16x16x32_bf16 v[114:117], v[178:181], v[186:189], v[114:117]
	v_mfma_f32_16x16x32_bf16 v[102:105], v[170:173], v[194:197], v[102:105]
	v_mfma_f32_16x16x32_bf16 v[98:101], v[178:181], v[194:197], v[98:101]
	v_mfma_f32_16x16x32_bf16 v[86:89], v[170:173], v[202:205], v[86:89]
	v_mfma_f32_16x16x32_bf16 v[82:85], v[178:181], v[202:205], v[82:85]
	v_mfma_f32_16x16x32_bf16 v[70:73], v[170:173], v[210:213], v[70:73]
	v_mfma_f32_16x16x32_bf16 v[66:69], v[178:181], v[210:213], v[66:69]
	v_mfma_f32_16x16x32_bf16 v[118:121], v[174:177], v[190:193], v[118:121]
	v_mfma_f32_16x16x32_bf16 v[114:117], v[182:185], v[190:193], v[114:117]
	v_mfma_f32_16x16x32_bf16 v[102:105], v[174:177], v[198:201], v[102:105]
	v_mfma_f32_16x16x32_bf16 v[98:101], v[182:185], v[198:201], v[98:101]
	v_mfma_f32_16x16x32_bf16 v[86:89], v[174:177], v[206:209], v[86:89]
	v_mfma_f32_16x16x32_bf16 v[82:85], v[182:185], v[206:209], v[82:85]
	v_mfma_f32_16x16x32_bf16 v[70:73], v[174:177], v[214:217], v[70:73]
	v_mfma_f32_16x16x32_bf16 v[66:69], v[182:185], v[214:217], v[66:69]
	s_setprio 2
	s_barrier
	s_add_i32 s33, s79, s60
	v_lshl_add_u64 v[218:219], s[54:55], 0, v[132:133]
	s_mov_b32 m0, s33
	s_nop 0
	global_load_lds_dwordx4 v[218:219], off
	s_add_i32 m0, s33, 0x2000
	s_add_u32 s62, s54, 0x40000
	v_lshl_add_u64 v[220:221], s[54:55], 0, v[136:137]
	s_addc_u32 s63, s55, 0
	s_add_i32 s33, s80, s60
	global_load_lds_dwordx4 v[220:221], off
	v_lshl_add_u64 v[222:223], s[62:63], 0, v[132:133]
	s_mov_b32 m0, s33
	v_lshl_add_u64 v[224:225], s[56:57], 0, v[134:135]
	global_load_lds_dwordx4 v[222:223], off
	v_lshl_add_u64 v[222:223], s[62:63], 0, v[136:137]
	s_add_i32 m0, s33, 0x2000
	s_nop 0
	global_load_lds_dwordx4 v[222:223], off
	v_lshl_add_u64 v[222:223], s[56:57], 0, v[130:131]
	s_mov_b32 m0, s11
	s_nop 0
	global_load_lds_dwordx4 v[222:223], off
	s_mov_b32 m0, s61
	s_nop 0
	global_load_lds_dwordx4 v[224:225], off
	ds_read_b128 v[186:189], v154 offset:16384
	ds_read_b128 v[190:193], v154 offset:17408
	ds_read_b128 v[194:197], v154 offset:18432
	ds_read_b128 v[198:201], v154 offset:19456
	ds_read_b128 v[202:205], v154 offset:20480
	ds_read_b128 v[206:209], v154 offset:21504
	ds_read_b128 v[210:213], v154 offset:22528
	ds_read_b128 v[214:217], v154 offset:23552
	s_waitcnt vmcnt(8)
	s_waitcnt lgkmcnt(0)
	s_barrier
; #define PG8_STAGE(bufoff, gbase, voff) do { _Pragma("unroll") for (int _i = 0; _i < 2; ++_i) \
;         __builtin_amdgcn_global_load_lds((const unsigned*)((const char*)(gbase) + (voff)[_i]), (LAS unsigned*)(lds + (bufoff) + ldsw + _i * 8192), 16, 0, 0); } while (0)
; #define PG8_LDA(dst, b, h) do { _Pragma("unroll") for (int m = 0; m < 4; ++m) _Pragma("unroll") for (int k = 0; k < 2; ++k) dst[m][k] = *(const LAS bf16x8*)(lds + PG8_SA(b, h) + aoff + m * 2048 + k * 1024); } while (0)
; #define PG8_LDB(dst, b, h) do { _Pragma("unroll") for (int n = 0; n < 2; ++n) _Pragma("unroll") for (int k = 0; k < 2; ++k) dst[n][k] = *(const LAS bf16x8*)(lds + PG8_SB(b, h) + boff + n * 2048 + k * 1024); } while (0)
; #define PG8_MMA(ai, bj, At, Bt) do { __builtin_amdgcn_s_setprio(1); _Pragma("unroll") for (int m = 0; m < 4; ++m) _Pragma("unroll") for (int n = 0; n < 2; ++n) _Pragma("unroll") for (int k = 0; k < 2; ++k) \
;         acc[ai][bj][m][n] = __builtin_amdgcn_mfma_f32_16x16x32_bf16(Bt[n][k], At[m][k], acc[ai][bj][m][n], 0, 0, 0); __builtin_amdgcn_s_setprio(0); } while (0)
; #define PG8_WAIT_V(n) asm volatile("s_waitcnt vmcnt(" #n ")" ::: "memory")
; #define PG8_WAIT_L(n) asm volatile("s_waitcnt lgkmcnt(" #n ")" ::: "memory")
; #define PG8_BAR __builtin_amdgcn_s_barrier()
; #define PG8_SCHED __builtin_amdgcn_sched_barrier(0)
; template <class Epi>
; __device__ __forceinline__ void gemm_phase(LAS unsigned char* lds, const Gemm g, int G, int c, const Epi& E) {
;     ...
;             PG8_WAIT_V(8); PG8_WAIT_L(0); PG8_BAR; PG8_MMA(1, 0, At, B0); PG8_MMA(1, 1, At, B1); PG8_BAR; PG8_SCHED;
;             PG8_LDB(B0, 1, 0); PG8_LDB(B1, 1, 1); PG8_SCHED; PG8_LDA(At, 1, 0); PG8_STAGE(PG8_SA(0, 1), a2 + hstepA, voffA);
;             PG8_WAIT_V(8); PG8_WAIT_L(0); PG8_BAR; PG8_MMA(0, 0, At, B0); PG8_MMA(0, 1, At, B1); PG8_BAR; PG8_SCHED;
	s_setprio 0
	s_waitcnt lgkmcnt(0)
	v_mfma_f32_16x16x32_bf16 v[62:65], v[146:149], v[186:189], v[62:65]
	v_mfma_f32_16x16x32_bf16 v[58:61], v[162:165], v[186:189], v[58:61]
	v_mfma_f32_16x16x32_bf16 v[46:49], v[146:149], v[194:197], v[46:49]
	v_mfma_f32_16x16x32_bf16 v[42:45], v[162:165], v[194:197], v[42:45]
	v_mfma_f32_16x16x32_bf16 v[30:33], v[146:149], v[202:205], v[30:33]
	v_mfma_f32_16x16x32_bf16 v[26:29], v[162:165], v[202:205], v[26:29]
	v_mfma_f32_16x16x32_bf16 v[14:17], v[146:149], v[210:213], v[14:17]
	v_mfma_f32_16x16x32_bf16 v[10:13], v[162:165], v[210:213], v[10:13]
	v_mfma_f32_16x16x32_bf16 v[62:65], v[158:161], v[190:193], v[62:65]
	v_mfma_f32_16x16x32_bf16 v[58:61], v[166:169], v[190:193], v[58:61]
	v_mfma_f32_16x16x32_bf16 v[46:49], v[158:161], v[198:201], v[46:49]
	v_mfma_f32_16x16x32_bf16 v[42:45], v[166:169], v[198:201], v[42:45]
	v_mfma_f32_16x16x32_bf16 v[30:33], v[158:161], v[206:209], v[30:33]
	v_mfma_f32_16x16x32_bf16 v[26:29], v[166:169], v[206:209], v[26:29]
	v_mfma_f32_16x16x32_bf16 v[14:17], v[158:161], v[214:217], v[14:17]
	v_mfma_f32_16x16x32_bf16 v[10:13], v[166:169], v[214:217], v[10:13]
	s_setprio 2
	s_setprio 0
	v_mfma_f32_16x16x32_bf16 v[54:57], v[170:173], v[186:189], v[54:57]
	v_mfma_f32_16x16x32_bf16 v[50:53], v[178:181], v[186:189], v[50:53]
	v_mfma_f32_16x16x32_bf16 v[38:41], v[170:173], v[194:197], v[38:41]
	v_mfma_f32_16x16x32_bf16 v[34:37], v[178:181], v[194:197], v[34:37]
	v_mfma_f32_16x16x32_bf16 v[22:25], v[170:173], v[202:205], v[22:25]
	v_mfma_f32_16x16x32_bf16 v[18:21], v[178:181], v[202:205], v[18:21]
	v_mfma_f32_16x16x32_bf16 v[6:9], v[170:173], v[210:213], v[6:9]
	v_mfma_f32_16x16x32_bf16 v[2:5], v[178:181], v[210:213], v[2:5]
	v_mfma_f32_16x16x32_bf16 v[54:57], v[174:177], v[190:193], v[54:57]
	v_mfma_f32_16x16x32_bf16 v[50:53], v[182:185], v[190:193], v[50:53]
	v_mfma_f32_16x16x32_bf16 v[38:41], v[174:177], v[198:201], v[38:41]
	v_mfma_f32_16x16x32_bf16 v[34:37], v[182:185], v[198:201], v[34:37]
	v_mfma_f32_16x16x32_bf16 v[22:25], v[174:177], v[206:209], v[22:25]
	v_mfma_f32_16x16x32_bf16 v[18:21], v[182:185], v[206:209], v[18:21]
	v_mfma_f32_16x16x32_bf16 v[6:9], v[174:177], v[214:217], v[6:9]
	v_mfma_f32_16x16x32_bf16 v[2:5], v[182:185], v[214:217], v[2:5]
	s_setprio 2
	s_barrier
	s_add_i32 s33, 0, 0x18000
	s_add_i32 s62, 0, 0x1c000
	s_add_u32 s56, s56, 0x40000
	s_addc_u32 s57, s57, 0
	s_mov_b32 m0, s66
	v_lshl_add_u64 v[226:227], s[56:57], 0, v[130:131]
	global_load_lds_dwordx4 v[226:227], off
	v_lshl_add_u64 v[226:227], s[56:57], 0, v[134:135]
	s_mov_b32 m0, s67
	s_nop 0
	global_load_lds_dwordx4 v[226:227], off
	v_add_u32_e32 v157, s33, v151
	ds_read_b128 v[146:149], v157
	ds_read_b128 v[158:161], v157 offset:1024
	ds_read_b128 v[162:165], v157 offset:2048
	ds_read_b128 v[166:169], v157 offset:3072
	v_add_u32_e32 v157, s62, v151
	ds_read_b128 v[170:173], v157
	ds_read_b128 v[174:177], v157 offset:1024
	ds_read_b128 v[178:181], v157 offset:2048
	ds_read_b128 v[182:185], v157 offset:3072
	ds_read_b128 v[186:189], v154 offset:32768
	ds_read_b128 v[190:193], v154 offset:33792
	ds_read_b128 v[194:197], v154 offset:34816
	ds_read_b128 v[198:201], v154 offset:35840
	ds_read_b128 v[202:205], v154 offset:36864
	ds_read_b128 v[206:209], v154 offset:37888
	ds_read_b128 v[210:213], v154 offset:38912
	ds_read_b128 v[214:217], v154 offset:39936
	s_waitcnt vmcnt(8)
	s_waitcnt lgkmcnt(0)
	s_barrier
	s_setprio 0
	s_waitcnt lgkmcnt(0)
	v_mfma_f32_16x16x32_bf16 v[126:129], v[146:149], v[186:189], v[126:129]
	v_mfma_f32_16x16x32_bf16 v[122:125], v[162:165], v[186:189], v[122:125]
	v_mfma_f32_16x16x32_bf16 v[110:113], v[146:149], v[194:197], v[110:113]
	v_mfma_f32_16x16x32_bf16 v[106:109], v[162:165], v[194:197], v[106:109]
	v_mfma_f32_16x16x32_bf16 v[94:97], v[146:149], v[202:205], v[94:97]
	v_mfma_f32_16x16x32_bf16 v[90:93], v[162:165], v[202:205], v[90:93]
	v_mfma_f32_16x16x32_bf16 v[78:81], v[146:149], v[210:213], v[78:81]
	v_mfma_f32_16x16x32_bf16 v[74:77], v[162:165], v[210:213], v[74:77]
	v_mfma_f32_16x16x32_bf16 v[126:129], v[158:161], v[190:193], v[126:129]
	v_mfma_f32_16x16x32_bf16 v[122:125], v[166:169], v[190:193], v[122:125]
	v_mfma_f32_16x16x32_bf16 v[110:113], v[158:161], v[198:201], v[110:113]
	v_mfma_f32_16x16x32_bf16 v[106:109], v[166:169], v[198:201], v[106:109]
	v_mfma_f32_16x16x32_bf16 v[94:97], v[158:161], v[206:209], v[94:97]
	v_mfma_f32_16x16x32_bf16 v[90:93], v[166:169], v[206:209], v[90:93]
	v_mfma_f32_16x16x32_bf16 v[78:81], v[158:161], v[214:217], v[78:81]
	v_mfma_f32_16x16x32_bf16 v[74:77], v[166:169], v[214:217], v[74:77]
	s_setprio 2
	s_setprio 0
	v_mfma_f32_16x16x32_bf16 v[118:121], v[170:173], v[186:189], v[118:121]
	v_mfma_f32_16x16x32_bf16 v[114:117], v[178:181], v[186:189], v[114:117]
	v_mfma_f32_16x16x32_bf16 v[102:105], v[170:173], v[194:197], v[102:105]
	v_mfma_f32_16x16x32_bf16 v[98:101], v[178:181], v[194:197], v[98:101]
	v_mfma_f32_16x16x32_bf16 v[86:89], v[170:173], v[202:205], v[86:89]
	v_mfma_f32_16x16x32_bf16 v[82:85], v[178:181], v[202:205], v[82:85]
	v_mfma_f32_16x16x32_bf16 v[70:73], v[170:173], v[210:213], v[70:73]
	v_mfma_f32_16x16x32_bf16 v[66:69], v[178:181], v[210:213], v[66:69]
	v_mfma_f32_16x16x32_bf16 v[118:121], v[174:177], v[190:193], v[118:121]
	v_mfma_f32_16x16x32_bf16 v[114:117], v[182:185], v[190:193], v[114:117]
	v_mfma_f32_16x16x32_bf16 v[102:105], v[174:177], v[198:201], v[102:105]
	v_mfma_f32_16x16x32_bf16 v[98:101], v[182:185], v[198:201], v[98:101]
	v_mfma_f32_16x16x32_bf16 v[86:89], v[174:177], v[206:209], v[86:89]
	v_mfma_f32_16x16x32_bf16 v[82:85], v[182:185], v[206:209], v[82:85]
	v_mfma_f32_16x16x32_bf16 v[70:73], v[174:177], v[214:217], v[70:73]
	v_mfma_f32_16x16x32_bf16 v[66:69], v[182:185], v[214:217], v[66:69]
	s_setprio 2
	s_barrier
; #define PG8_STAGE(bufoff, gbase, voff) do { _Pragma("unroll") for (int _i = 0; _i < 2; ++_i) \
;         __builtin_amdgcn_global_load_lds((const unsigned*)((const char*)(gbase) + (voff)[_i]), (LAS unsigned*)(lds + (bufoff) + ldsw + _i * 8192), 16, 0, 0); } while (0)
; #define PG8_LDA(dst, b, h) do { _Pragma("unroll") for (int m = 0; m < 4; ++m) _Pragma("unroll") for (int k = 0; k < 2; ++k) dst[m][k] = *(const LAS bf16x8*)(lds + PG8_SA(b, h) + aoff + m * 2048 + k * 1024); } while (0)
; #define PG8_MMA(ai, bj, At, Bt) do { __builtin_amdgcn_s_setprio(1); _Pragma("unroll") for (int m = 0; m < 4; ++m) _Pragma("unroll") for (int n = 0; n < 2; ++n) _Pragma("unroll") for (int k = 0; k < 2; ++k) \
;         acc[ai][bj][m][n] = __builtin_amdgcn_mfma_f32_16x16x32_bf16(Bt[n][k], At[m][k], acc[ai][bj][m][n], 0, 0, 0); __builtin_amdgcn_s_setprio(0); } while (0)
; #define PG8_WAIT_V(n) asm volatile("s_waitcnt vmcnt(" #n ")" ::: "memory")
; #define PG8_WAIT_L(n) asm volatile("s_waitcnt lgkmcnt(" #n ")" ::: "memory")
; #define PG8_BAR __builtin_amdgcn_s_barrier()
; #define PG8_SCHED __builtin_amdgcn_sched_barrier(0)
; template <class Epi>
; __device__ __forceinline__ void gemm_phase(LAS unsigned char* lds, const Gemm g, int G, int c, const Epi& E) {
;     ...
;             PG8_LDA(At, 1, 1); PG8_STAGE(PG8_SB(1, 0), b3, voffB); PG8_STAGE(PG8_SB(1, 1), b3 + hstepB, voffB); PG8_STAGE(PG8_SA(1, 0), a3, voffA);
;             PG8_WAIT_V(8); PG8_WAIT_L(0); PG8_BAR; PG8_MMA(1, 0, At, B0); PG8_MMA(1, 1, At, B1); PG8_BAR; PG8_SCHED;
;         }
	s_add_i32 s33, s33, s60
	v_lshl_add_u64 v[218:219], v[218:219], 0, s[20:21]
	s_mov_b32 m0, s33
	s_nop 0
	global_load_lds_dwordx4 v[218:219], off
	s_add_i32 m0, s33, 0x2000
	s_add_u32 s54, s54, 0x40080
	v_lshl_add_u64 v[218:219], v[220:221], 0, s[20:21]
	s_addc_u32 s55, s55, 0
	s_add_i32 s33, s62, s60
	global_load_lds_dwordx4 v[218:219], off
	v_lshl_add_u64 v[218:219], s[54:55], 0, v[132:133]
	s_mov_b32 m0, s33
	s_nop 0
	global_load_lds_dwordx4 v[218:219], off
	v_lshl_add_u64 v[218:219], s[54:55], 0, v[136:137]
	s_add_i32 m0, s33, 0x2000
	s_nop 0
	global_load_lds_dwordx4 v[218:219], off
	v_lshl_add_u64 v[218:219], v[222:223], 0, s[20:21]
	s_mov_b32 m0, s71
	s_nop 0
	global_load_lds_dwordx4 v[218:219], off
	v_lshl_add_u64 v[218:219], v[224:225], 0, s[20:21]
	s_mov_b32 m0, s72
	s_nop 0
	global_load_lds_dwordx4 v[218:219], off
	ds_read_b128 v[186:189], v154 offset:49152
	ds_read_b128 v[190:193], v154 offset:50176
	ds_read_b128 v[194:197], v154 offset:51200
	ds_read_b128 v[198:201], v154 offset:52224
	ds_read_b128 v[202:205], v154 offset:53248
	ds_read_b128 v[206:209], v154 offset:54272
	ds_read_b128 v[210:213], v154 offset:55296
	ds_read_b128 v[214:217], v154 offset:56320
	s_waitcnt vmcnt(8)
	s_waitcnt lgkmcnt(0)
	s_barrier
	s_setprio 0
	s_waitcnt lgkmcnt(0)
	v_mfma_f32_16x16x32_bf16 v[62:65], v[146:149], v[186:189], v[62:65]
	v_mfma_f32_16x16x32_bf16 v[58:61], v[162:165], v[186:189], v[58:61]
	v_mfma_f32_16x16x32_bf16 v[46:49], v[146:149], v[194:197], v[46:49]
	v_mfma_f32_16x16x32_bf16 v[42:45], v[162:165], v[194:197], v[42:45]
	v_mfma_f32_16x16x32_bf16 v[30:33], v[146:149], v[202:205], v[30:33]
	v_mfma_f32_16x16x32_bf16 v[26:29], v[162:165], v[202:205], v[26:29]
	v_mfma_f32_16x16x32_bf16 v[14:17], v[146:149], v[210:213], v[14:17]
	v_mfma_f32_16x16x32_bf16 v[10:13], v[162:165], v[210:213], v[10:13]
	v_mfma_f32_16x16x32_bf16 v[62:65], v[158:161], v[190:193], v[62:65]
	v_mfma_f32_16x16x32_bf16 v[58:61], v[166:169], v[190:193], v[58:61]
	v_mfma_f32_16x16x32_bf16 v[46:49], v[158:161], v[198:201], v[46:49]
	v_mfma_f32_16x16x32_bf16 v[42:45], v[166:169], v[198:201], v[42:45]
	v_mfma_f32_16x16x32_bf16 v[30:33], v[158:161], v[206:209], v[30:33]
	v_mfma_f32_16x16x32_bf16 v[26:29], v[166:169], v[206:209], v[26:29]
	v_mfma_f32_16x16x32_bf16 v[14:17], v[158:161], v[214:217], v[14:17]
	v_mfma_f32_16x16x32_bf16 v[10:13], v[166:169], v[214:217], v[10:13]
	s_setprio 2
	s_setprio 0
	v_mfma_f32_16x16x32_bf16 v[54:57], v[170:173], v[186:189], v[54:57]
	v_mfma_f32_16x16x32_bf16 v[50:53], v[178:181], v[186:189], v[50:53]
	v_mfma_f32_16x16x32_bf16 v[38:41], v[170:173], v[194:197], v[38:41]
	v_mfma_f32_16x16x32_bf16 v[34:37], v[178:181], v[194:197], v[34:37]
	v_mfma_f32_16x16x32_bf16 v[22:25], v[170:173], v[202:205], v[22:25]
	v_mfma_f32_16x16x32_bf16 v[18:21], v[178:181], v[202:205], v[18:21]
	v_mfma_f32_16x16x32_bf16 v[6:9], v[170:173], v[210:213], v[6:9]
	v_mfma_f32_16x16x32_bf16 v[2:5], v[178:181], v[210:213], v[2:5]
	v_mfma_f32_16x16x32_bf16 v[54:57], v[174:177], v[190:193], v[54:57]
	v_mfma_f32_16x16x32_bf16 v[50:53], v[182:185], v[190:193], v[50:53]
	v_mfma_f32_16x16x32_bf16 v[38:41], v[174:177], v[198:201], v[38:41]
	v_mfma_f32_16x16x32_bf16 v[34:37], v[182:185], v[198:201], v[34:37]
	v_mfma_f32_16x16x32_bf16 v[22:25], v[174:177], v[206:209], v[22:25]
	v_mfma_f32_16x16x32_bf16 v[18:21], v[182:185], v[206:209], v[18:21]
	v_mfma_f32_16x16x32_bf16 v[6:9], v[174:177], v[214:217], v[6:9]
	v_mfma_f32_16x16x32_bf16 v[2:5], v[182:185], v[214:217], v[2:5]
	s_setprio 2
	s_barrier
	s_add_i32 s85, s85, 2
	s_add_u32 s4, s4, 0x100
	s_addc_u32 s5, s5, 0
	s_add_u32 s45, s45, 0x100
	s_addc_u32 s84, s84, 0
	s_cmp_gt_u32 s85, 13
	s_cbranch_scc0 .LBB0_236
	s_and_b64 vcc, exec, s[22:23]
	s_cbranch_vccz .LBB0_239
	s_barrier

; #define PG8_STAGE(bufoff, gbase, voff) do { _Pragma("unroll") for (int _i = 0; _i < 2; ++_i) \
;         __builtin_amdgcn_global_load_lds((const unsigned*)((const char*)(gbase) + (voff)[_i]), (LAS unsigned*)(lds + (bufoff) + ldsw + _i * 8192), 16, 0, 0); } while (0)
; #define PG8_LDA(dst, b, h) do { _Pragma("unroll") for (int m = 0; m < 4; ++m) _Pragma("unroll") for (int k = 0; k < 2; ++k) dst[m][k] = *(const LAS bf16x8*)(lds + PG8_SA(b, h) + aoff + m * 2048 + k * 1024); } while (0)
; #define PG8_LDB(dst, b, h) do { _Pragma("unroll") for (int n = 0; n < 2; ++n) _Pragma("unroll") for (int k = 0; k < 2; ++k) dst[n][k] = *(const LAS bf16x8*)(lds + PG8_SB(b, h) + boff + n * 2048 + k * 1024); } while (0)
; #define PG8_MMA(ai, bj, At, Bt) do { __builtin_amdgcn_s_setprio(1); _Pragma("unroll") for (int m = 0; m < 4; ++m) _Pragma("unroll") for (int n = 0; n < 2; ++n) _Pragma("unroll") for (int k = 0; k < 2; ++k) \
;         acc[ai][bj][m][n] = __builtin_amdgcn_mfma_f32_16x16x32_bf16(Bt[n][k], At[m][k], acc[ai][bj][m][n], 0, 0, 0); __builtin_amdgcn_s_setprio(0); } while (0)
; #define PG8_WAIT_V(n) asm volatile("s_waitcnt vmcnt(" #n ")" ::: "memory")
; #define PG8_WAIT_L(n) asm volatile("s_waitcnt lgkmcnt(" #n ")" ::: "memory")
; #define PG8_BAR __builtin_amdgcn_s_barrier()
; #define PG8_SCHED __builtin_amdgcn_sched_barrier(0)
; template <class Epi>
; __device__ __forceinline__ void gemm_phase(LAS unsigned char* lds, const Gemm g, int G, int c, const Epi& E) {
;     ...
;             const char* a2 = last ? nA : cA + (size_t)(t + 2) * kstep; const char* b2 = last ? nB : cB + (size_t)(t + 2) * kstep;
;             const char* a3 = a2 + kstep; const char* b3 = b2 + kstep;
;             PG8_LDB(B0, 0, 0); PG8_LDB(B1, 0, 1); PG8_SCHED; PG8_LDA(At, 0, 0); PG8_STAGE(PG8_SA(1, 1), a1 + hstepA, voffA);
;             PG8_WAIT_V(8); PG8_WAIT_L(0); PG8_BAR; PG8_MMA(0, 0, At, B0); PG8_MMA(0, 1, At, B1); PG8_BAR; PG8_SCHED;
;             PG8_LDA(At, 0, 1); PG8_STAGE(PG8_SB(0, 0), b2, voffB); PG8_STAGE(PG8_SB(0, 1), b2 + hstepB, voffB); PG8_STAGE(PG8_SA(0, 0), a2, voffA);
;             PG8_WAIT_V(8); PG8_WAIT_L(0); PG8_BAR; PG8_MMA(1, 0, At, B0); PG8_MMA(1, 1, At, B1); PG8_BAR; PG8_SCHED;
.LBB0_368:
	s_add_u32 s33, s20, s13
	s_addc_u32 s42, s21, 0
	s_add_u32 s43, s33, 0x100
	s_addc_u32 s44, s42, 0
	s_and_b64 s[38:39], s[24:25], exec
	s_cselect_b32 s45, s5, s44
	s_cselect_b32 s44, s4, s43
	s_add_u32 s13, s18, s13
	s_addc_u32 s38, s19, 0
	s_add_u32 s13, s13, 0x100
	s_addc_u32 s38, s38, 0
	s_and_b64 s[24:25], s[24:25], exec
	s_cselect_b32 s47, s17, s38
	s_cselect_b32 s46, s16, s13
	s_add_u32 s54, s33, 0xb0080
	s_addc_u32 s55, s42, 0
	s_add_i32 s65, s81, s56
	s_add_i32 m0, s57, 0xc000
	s_add_i32 s74, s57, 0xe000
	v_lshl_add_u64 v[212:213], s[54:55], 0, v[136:137]
	global_load_lds_dwordx4 v[212:213], off
	v_lshl_add_u64 v[212:213], s[54:55], 0, v[132:133]
	s_mov_b32 m0, s74
	s_nop 0
	global_load_lds_dwordx4 v[212:213], off
	ds_read_b128 v[142:145], v148
	ds_read_b128 v[152:155], v148 offset:1024
	ds_read_b128 v[156:159], v148 offset:2048
	ds_read_b128 v[160:163], v148 offset:3072
	ds_read_b128 v[164:167], v149
	ds_read_b128 v[168:171], v149 offset:1024
	ds_read_b128 v[172:175], v149 offset:2048
	ds_read_b128 v[176:179], v149 offset:3072
	s_add_i32 s62, s65, 0x2000
	s_add_u32 s52, s46, 0xb0000
	s_addc_u32 s53, s47, 0
	s_add_i32 s64, s82, s56
	s_add_i32 s63, s64, 0x2000
	s_add_i32 s73, 0, 0x18000
	s_add_i32 s33, 0, 0x1c000
	s_add_u32 s42, s44, 0xb0000
	s_addc_u32 s43, s45, 0
	s_add_i32 s88, s73, s56
	s_add_i32 s38, s88, 0x2000
	s_add_u32 s24, s46, 0xb0080
	s_addc_u32 s25, s47, 0
	s_add_i32 s39, s33, s56
	s_add_i32 s13, s39, 0x2000
	ds_read_b128 v[180:183], v150
	ds_read_b128 v[184:187], v150 offset:1024
	ds_read_b128 v[188:191], v150 offset:2048
	ds_read_b128 v[192:195], v150 offset:3072
	ds_read_b128 v[196:199], v150 offset:4096
	ds_read_b128 v[200:203], v150 offset:5120
	ds_read_b128 v[204:207], v150 offset:6144
	ds_read_b128 v[208:211], v150 offset:7168
	s_waitcnt vmcnt(8)
	s_waitcnt lgkmcnt(0)
	s_barrier
	s_setprio 0
	s_waitcnt lgkmcnt(0)
	v_mfma_f32_16x16x32_bf16 v[126:129], v[142:145], v[180:183], v[126:129]
	v_mfma_f32_16x16x32_bf16 v[122:125], v[156:159], v[180:183], v[122:125]
	v_mfma_f32_16x16x32_bf16 v[118:121], v[142:145], v[188:191], v[118:121]
	v_mfma_f32_16x16x32_bf16 v[110:113], v[156:159], v[188:191], v[110:113]
	v_mfma_f32_16x16x32_bf16 v[102:105], v[142:145], v[196:199], v[102:105]
	v_mfma_f32_16x16x32_bf16 v[94:97], v[156:159], v[196:199], v[94:97]
	v_mfma_f32_16x16x32_bf16 v[86:89], v[142:145], v[204:207], v[86:89]
	v_mfma_f32_16x16x32_bf16 v[78:81], v[156:159], v[204:207], v[78:81]
	v_mfma_f32_16x16x32_bf16 v[126:129], v[152:155], v[184:187], v[126:129]
	v_mfma_f32_16x16x32_bf16 v[122:125], v[160:163], v[184:187], v[122:125]
	v_mfma_f32_16x16x32_bf16 v[118:121], v[152:155], v[192:195], v[118:121]
	v_mfma_f32_16x16x32_bf16 v[110:113], v[160:163], v[192:195], v[110:113]
	v_mfma_f32_16x16x32_bf16 v[102:105], v[152:155], v[200:203], v[102:105]
	v_mfma_f32_16x16x32_bf16 v[94:97], v[160:163], v[200:203], v[94:97]
	v_mfma_f32_16x16x32_bf16 v[86:89], v[152:155], v[208:211], v[86:89]
	v_mfma_f32_16x16x32_bf16 v[78:81], v[160:163], v[208:211], v[78:81]
	s_setprio 2
	s_setprio 0
	v_mfma_f32_16x16x32_bf16 v[114:117], v[164:167], v[180:183], v[114:117]
	v_mfma_f32_16x16x32_bf16 v[106:109], v[172:175], v[180:183], v[106:109]
	v_mfma_f32_16x16x32_bf16 v[98:101], v[164:167], v[188:191], v[98:101]
	v_mfma_f32_16x16x32_bf16 v[90:93], v[172:175], v[188:191], v[90:93]
	v_mfma_f32_16x16x32_bf16 v[82:85], v[164:167], v[196:199], v[82:85]
	v_mfma_f32_16x16x32_bf16 v[74:77], v[172:175], v[196:199], v[74:77]
	v_mfma_f32_16x16x32_bf16 v[70:73], v[164:167], v[204:207], v[70:73]
	v_mfma_f32_16x16x32_bf16 v[66:69], v[172:175], v[204:207], v[66:69]
	v_mfma_f32_16x16x32_bf16 v[114:117], v[168:171], v[184:187], v[114:117]
	v_mfma_f32_16x16x32_bf16 v[106:109], v[176:179], v[184:187], v[106:109]
	v_mfma_f32_16x16x32_bf16 v[98:101], v[168:171], v[192:195], v[98:101]
	v_mfma_f32_16x16x32_bf16 v[90:93], v[176:179], v[192:195], v[90:93]
	v_mfma_f32_16x16x32_bf16 v[82:85], v[168:171], v[200:203], v[82:85]
	v_mfma_f32_16x16x32_bf16 v[74:77], v[176:179], v[200:203], v[74:77]
	v_mfma_f32_16x16x32_bf16 v[70:73], v[168:171], v[208:211], v[70:73]
	v_mfma_f32_16x16x32_bf16 v[66:69], v[176:179], v[208:211], v[66:69]
	s_setprio 2
	s_barrier
	s_mov_b32 m0, s65
	v_lshl_add_u64 v[212:213], s[46:47], 0, v[134:135]
	global_load_lds_dwordx4 v[212:213], off
	v_lshl_add_u64 v[214:215], s[46:47], 0, v[130:131]
	s_mov_b32 m0, s62
	v_lshl_add_u64 v[216:217], s[52:53], 0, v[134:135]
	global_load_lds_dwordx4 v[214:215], off
	s_mov_b32 m0, s64
	v_lshl_add_u64 v[218:219], s[44:45], 0, v[132:133]
	global_load_lds_dwordx4 v[216:217], off
	v_lshl_add_u64 v[216:217], s[52:53], 0, v[130:131]
	s_mov_b32 m0, s63
	s_nop 0
	global_load_lds_dwordx4 v[216:217], off
	v_lshl_add_u64 v[216:217], s[44:45], 0, v[136:137]
	s_mov_b32 m0, s57
	s_nop 0
	global_load_lds_dwordx4 v[216:217], off
	s_mov_b32 m0, s58
	s_nop 0
	global_load_lds_dwordx4 v[218:219], off
	ds_read_b128 v[180:183], v150 offset:16384
	ds_read_b128 v[184:187], v150 offset:17408
	ds_read_b128 v[188:191], v150 offset:18432
	ds_read_b128 v[192:195], v150 offset:19456
	ds_read_b128 v[196:199], v150 offset:20480
	ds_read_b128 v[200:203], v150 offset:21504
	ds_read_b128 v[204:207], v150 offset:22528
	ds_read_b128 v[208:211], v150 offset:23552
	s_waitcnt vmcnt(8)
	s_waitcnt lgkmcnt(0)
	s_barrier
; #define PG8_STAGE(bufoff, gbase, voff) do { _Pragma("unroll") for (int _i = 0; _i < 2; ++_i) \
;         __builtin_amdgcn_global_load_lds((const unsigned*)((const char*)(gbase) + (voff)[_i]), (LAS unsigned*)(lds + (bufoff) + ldsw + _i * 8192), 16, 0, 0); } while (0)
; #define PG8_LDA(dst, b, h) do { _Pragma("unroll") for (int m = 0; m < 4; ++m) _Pragma("unroll") for (int k = 0; k < 2; ++k) dst[m][k] = *(const LAS bf16x8*)(lds + PG8_SA(b, h) + aoff + m * 2048 + k * 1024); } while (0)
; #define PG8_LDB(dst, b, h) do { _Pragma("unroll") for (int n = 0; n < 2; ++n) _Pragma("unroll") for (int k = 0; k < 2; ++k) dst[n][k] = *(const LAS bf16x8*)(lds + PG8_SB(b, h) + boff + n * 2048 + k * 1024); } while (0)
; #define PG8_MMA(ai, bj, At, Bt) do { __builtin_amdgcn_s_setprio(1); _Pragma("unroll") for (int m = 0; m < 4; ++m) _Pragma("unroll") for (int n = 0; n < 2; ++n) _Pragma("unroll") for (int k = 0; k < 2; ++k) \
;         acc[ai][bj][m][n] = __builtin_amdgcn_mfma_f32_16x16x32_bf16(Bt[n][k], At[m][k], acc[ai][bj][m][n], 0, 0, 0); __builtin_amdgcn_s_setprio(0); } while (0)
; #define PG8_WAIT_V(n) asm volatile("s_waitcnt vmcnt(" #n ")" ::: "memory")
; #define PG8_WAIT_L(n) asm volatile("s_waitcnt lgkmcnt(" #n ")" ::: "memory")
; #define PG8_BAR __builtin_amdgcn_s_barrier()
; #define PG8_SCHED __builtin_amdgcn_sched_barrier(0)
; template <class Epi>
; __device__ __forceinline__ void gemm_phase(LAS unsigned char* lds, const Gemm g, int G, int c, const Epi& E) {
;     ...
;             PG8_WAIT_V(8); PG8_WAIT_L(0); PG8_BAR; PG8_MMA(1, 0, At, B0); PG8_MMA(1, 1, At, B1); PG8_BAR; PG8_SCHED;
;             PG8_LDB(B0, 1, 0); PG8_LDB(B1, 1, 1); PG8_SCHED; PG8_LDA(At, 1, 0); PG8_STAGE(PG8_SA(0, 1), a2 + hstepA, voffA);
;             PG8_WAIT_V(8); PG8_WAIT_L(0); PG8_BAR; PG8_MMA(0, 0, At, B0); PG8_MMA(0, 1, At, B1); PG8_BAR; PG8_SCHED;
	s_setprio 0
	s_waitcnt lgkmcnt(0)
	v_mfma_f32_16x16x32_bf16 v[62:65], v[142:145], v[180:183], v[62:65]
	v_mfma_f32_16x16x32_bf16 v[58:61], v[156:159], v[180:183], v[58:61]
	v_mfma_f32_16x16x32_bf16 v[54:57], v[142:145], v[188:191], v[54:57]
	v_mfma_f32_16x16x32_bf16 v[46:49], v[156:159], v[188:191], v[46:49]
	v_mfma_f32_16x16x32_bf16 v[38:41], v[142:145], v[196:199], v[38:41]
	v_mfma_f32_16x16x32_bf16 v[30:33], v[156:159], v[196:199], v[30:33]
	v_mfma_f32_16x16x32_bf16 v[22:25], v[142:145], v[204:207], v[22:25]
	v_mfma_f32_16x16x32_bf16 v[14:17], v[156:159], v[204:207], v[14:17]
	v_mfma_f32_16x16x32_bf16 v[62:65], v[152:155], v[184:187], v[62:65]
	v_mfma_f32_16x16x32_bf16 v[58:61], v[160:163], v[184:187], v[58:61]
	v_mfma_f32_16x16x32_bf16 v[54:57], v[152:155], v[192:195], v[54:57]
	v_mfma_f32_16x16x32_bf16 v[46:49], v[160:163], v[192:195], v[46:49]
	v_mfma_f32_16x16x32_bf16 v[38:41], v[152:155], v[200:203], v[38:41]
	v_mfma_f32_16x16x32_bf16 v[30:33], v[160:163], v[200:203], v[30:33]
	v_mfma_f32_16x16x32_bf16 v[22:25], v[152:155], v[208:211], v[22:25]
	v_mfma_f32_16x16x32_bf16 v[14:17], v[160:163], v[208:211], v[14:17]
	s_setprio 2
	s_setprio 0
	v_mfma_f32_16x16x32_bf16 v[50:53], v[164:167], v[180:183], v[50:53]
	v_mfma_f32_16x16x32_bf16 v[42:45], v[172:175], v[180:183], v[42:45]
	v_mfma_f32_16x16x32_bf16 v[34:37], v[164:167], v[188:191], v[34:37]
	v_mfma_f32_16x16x32_bf16 v[26:29], v[172:175], v[188:191], v[26:29]
	v_mfma_f32_16x16x32_bf16 v[18:21], v[164:167], v[196:199], v[18:21]
	v_mfma_f32_16x16x32_bf16 v[10:13], v[172:175], v[196:199], v[10:13]
	v_mfma_f32_16x16x32_bf16 v[6:9], v[164:167], v[204:207], v[6:9]
	v_mfma_f32_16x16x32_bf16 v[2:5], v[172:175], v[204:207], v[2:5]
	v_mfma_f32_16x16x32_bf16 v[50:53], v[168:171], v[184:187], v[50:53]
	v_mfma_f32_16x16x32_bf16 v[42:45], v[176:179], v[184:187], v[42:45]
	v_mfma_f32_16x16x32_bf16 v[34:37], v[168:171], v[192:195], v[34:37]
	v_mfma_f32_16x16x32_bf16 v[26:29], v[176:179], v[192:195], v[26:29]
	v_mfma_f32_16x16x32_bf16 v[18:21], v[168:171], v[200:203], v[18:21]
	v_mfma_f32_16x16x32_bf16 v[10:13], v[176:179], v[200:203], v[10:13]
	v_mfma_f32_16x16x32_bf16 v[6:9], v[168:171], v[208:211], v[6:9]
	v_mfma_f32_16x16x32_bf16 v[2:5], v[176:179], v[208:211], v[2:5]
	s_setprio 2
	s_barrier
	s_mov_b32 m0, s59
	v_lshl_add_u64 v[220:221], s[42:43], 0, v[136:137]
	global_load_lds_dwordx4 v[220:221], off
	v_lshl_add_u64 v[220:221], s[42:43], 0, v[132:133]
	s_mov_b32 m0, s60
	s_nop 0
	global_load_lds_dwordx4 v[220:221], off
	v_add_u32_e32 v151, s73, v147
	ds_read_b128 v[142:145], v151
	ds_read_b128 v[152:155], v151 offset:1024
	ds_read_b128 v[156:159], v151 offset:2048
	ds_read_b128 v[160:163], v151 offset:3072
	v_add_u32_e32 v151, s33, v147
	ds_read_b128 v[164:167], v151
	ds_read_b128 v[168:171], v151 offset:1024
	ds_read_b128 v[172:175], v151 offset:2048
	ds_read_b128 v[176:179], v151 offset:3072
	ds_read_b128 v[180:183], v150 offset:32768
	ds_read_b128 v[184:187], v150 offset:33792
	ds_read_b128 v[188:191], v150 offset:34816
	ds_read_b128 v[192:195], v150 offset:35840
	ds_read_b128 v[196:199], v150 offset:36864
	ds_read_b128 v[200:203], v150 offset:37888
	ds_read_b128 v[204:207], v150 offset:38912
	ds_read_b128 v[208:211], v150 offset:39936
	s_waitcnt vmcnt(8)
	s_waitcnt lgkmcnt(0)
	s_barrier
	s_setprio 0
	s_waitcnt lgkmcnt(0)
	v_mfma_f32_16x16x32_bf16 v[126:129], v[142:145], v[180:183], v[126:129]
	v_mfma_f32_16x16x32_bf16 v[122:125], v[156:159], v[180:183], v[122:125]
	v_mfma_f32_16x16x32_bf16 v[118:121], v[142:145], v[188:191], v[118:121]
	v_mfma_f32_16x16x32_bf16 v[110:113], v[156:159], v[188:191], v[110:113]
	v_mfma_f32_16x16x32_bf16 v[102:105], v[142:145], v[196:199], v[102:105]
	v_mfma_f32_16x16x32_bf16 v[94:97], v[156:159], v[196:199], v[94:97]
	v_mfma_f32_16x16x32_bf16 v[86:89], v[142:145], v[204:207], v[86:89]
	v_mfma_f32_16x16x32_bf16 v[78:81], v[156:159], v[204:207], v[78:81]
	v_mfma_f32_16x16x32_bf16 v[126:129], v[152:155], v[184:187], v[126:129]
	v_mfma_f32_16x16x32_bf16 v[122:125], v[160:163], v[184:187], v[122:125]
	v_mfma_f32_16x16x32_bf16 v[118:121], v[152:155], v[192:195], v[118:121]
	v_mfma_f32_16x16x32_bf16 v[110:113], v[160:163], v[192:195], v[110:113]
	v_mfma_f32_16x16x32_bf16 v[102:105], v[152:155], v[200:203], v[102:105]
	v_mfma_f32_16x16x32_bf16 v[94:97], v[160:163], v[200:203], v[94:97]
	v_mfma_f32_16x16x32_bf16 v[86:89], v[152:155], v[208:211], v[86:89]
	v_mfma_f32_16x16x32_bf16 v[78:81], v[160:163], v[208:211], v[78:81]
	s_setprio 2
	s_setprio 0
	v_mfma_f32_16x16x32_bf16 v[114:117], v[164:167], v[180:183], v[114:117]
	v_mfma_f32_16x16x32_bf16 v[106:109], v[172:175], v[180:183], v[106:109]
	v_mfma_f32_16x16x32_bf16 v[98:101], v[164:167], v[188:191], v[98:101]
	v_mfma_f32_16x16x32_bf16 v[90:93], v[172:175], v[188:191], v[90:93]
	v_mfma_f32_16x16x32_bf16 v[82:85], v[164:167], v[196:199], v[82:85]
	v_mfma_f32_16x16x32_bf16 v[74:77], v[172:175], v[196:199], v[74:77]
	v_mfma_f32_16x16x32_bf16 v[70:73], v[164:167], v[204:207], v[70:73]
	v_mfma_f32_16x16x32_bf16 v[66:69], v[172:175], v[204:207], v[66:69]
	v_mfma_f32_16x16x32_bf16 v[114:117], v[168:171], v[184:187], v[114:117]
	v_mfma_f32_16x16x32_bf16 v[106:109], v[176:179], v[184:187], v[106:109]
	v_mfma_f32_16x16x32_bf16 v[98:101], v[168:171], v[192:195], v[98:101]
	v_mfma_f32_16x16x32_bf16 v[90:93], v[176:179], v[192:195], v[90:93]
	v_mfma_f32_16x16x32_bf16 v[82:85], v[168:171], v[200:203], v[82:85]
	v_mfma_f32_16x16x32_bf16 v[74:77], v[176:179], v[200:203], v[74:77]
	v_mfma_f32_16x16x32_bf16 v[70:73], v[168:171], v[208:211], v[70:73]
	v_mfma_f32_16x16x32_bf16 v[66:69], v[176:179], v[208:211], v[66:69]
	s_setprio 2
	s_barrier
; #define PG8_STAGE(bufoff, gbase, voff) do { _Pragma("unroll") for (int _i = 0; _i < 2; ++_i) \
;         __builtin_amdgcn_global_load_lds((const unsigned*)((const char*)(gbase) + (voff)[_i]), (LAS unsigned*)(lds + (bufoff) + ldsw + _i * 8192), 16, 0, 0); } while (0)
; #define PG8_LDA(dst, b, h) do { _Pragma("unroll") for (int m = 0; m < 4; ++m) _Pragma("unroll") for (int k = 0; k < 2; ++k) dst[m][k] = *(const LAS bf16x8*)(lds + PG8_SA(b, h) + aoff + m * 2048 + k * 1024); } while (0)
; #define PG8_MMA(ai, bj, At, Bt) do { __builtin_amdgcn_s_setprio(1); _Pragma("unroll") for (int m = 0; m < 4; ++m) _Pragma("unroll") for (int n = 0; n < 2; ++n) _Pragma("unroll") for (int k = 0; k < 2; ++k) \
;         acc[ai][bj][m][n] = __builtin_amdgcn_mfma_f32_16x16x32_bf16(Bt[n][k], At[m][k], acc[ai][bj][m][n], 0, 0, 0); __builtin_amdgcn_s_setprio(0); } while (0)
; #define PG8_WAIT_V(n) asm volatile("s_waitcnt vmcnt(" #n ")" ::: "memory")
; #define PG8_WAIT_L(n) asm volatile("s_waitcnt lgkmcnt(" #n ")" ::: "memory")
; #define PG8_BAR __builtin_amdgcn_s_barrier()
; #define PG8_SCHED __builtin_amdgcn_sched_barrier(0)
; template <class Epi>
; __device__ __forceinline__ void gemm_phase(LAS unsigned char* lds, const Gemm g, int G, int c, const Epi& E) {
;     ...
;             PG8_LDA(At, 1, 1); PG8_STAGE(PG8_SB(1, 0), b3, voffB); PG8_STAGE(PG8_SB(1, 1), b3 + hstepB, voffB); PG8_STAGE(PG8_SA(1, 0), a3, voffA);
;             PG8_WAIT_V(8); PG8_WAIT_L(0); PG8_BAR; PG8_MMA(1, 0, At, B0); PG8_MMA(1, 1, At, B1); PG8_BAR; PG8_SCHED;
;         }
;         if (wr == 0) PG8_BAR;
	s_mov_b32 m0, s88
	v_lshl_add_u64 v[212:213], v[212:213], 0, s[8:9]
	global_load_lds_dwordx4 v[212:213], off
	v_lshl_add_u64 v[212:213], v[214:215], 0, s[8:9]
	s_mov_b32 m0, s38
	s_nop 0
	global_load_lds_dwordx4 v[212:213], off
	v_lshl_add_u64 v[212:213], s[24:25], 0, v[134:135]
	s_mov_b32 m0, s39
	s_nop 0
	global_load_lds_dwordx4 v[212:213], off
	v_lshl_add_u64 v[212:213], s[24:25], 0, v[130:131]
	s_mov_b32 m0, s13
	s_nop 0
	global_load_lds_dwordx4 v[212:213], off
	v_lshl_add_u64 v[212:213], v[216:217], 0, s[8:9]
	s_mov_b32 m0, s79
	s_nop 0
	global_load_lds_dwordx4 v[212:213], off
	v_lshl_add_u64 v[212:213], v[218:219], 0, s[8:9]
	s_mov_b32 m0, s80
	s_nop 0
	global_load_lds_dwordx4 v[212:213], off
	ds_read_b128 v[180:183], v150 offset:49152
	ds_read_b128 v[184:187], v150 offset:50176
	ds_read_b128 v[188:191], v150 offset:51200
	ds_read_b128 v[192:195], v150 offset:52224
	ds_read_b128 v[196:199], v150 offset:53248
	ds_read_b128 v[200:203], v150 offset:54272
	ds_read_b128 v[204:207], v150 offset:55296
	ds_read_b128 v[208:211], v150 offset:56320
	s_waitcnt vmcnt(8)
	s_waitcnt lgkmcnt(0)
	s_barrier
	s_setprio 0
	s_waitcnt lgkmcnt(0)
	v_mfma_f32_16x16x32_bf16 v[62:65], v[142:145], v[180:183], v[62:65]
	v_mfma_f32_16x16x32_bf16 v[58:61], v[156:159], v[180:183], v[58:61]
	v_mfma_f32_16x16x32_bf16 v[54:57], v[142:145], v[188:191], v[54:57]
	v_mfma_f32_16x16x32_bf16 v[46:49], v[156:159], v[188:191], v[46:49]
	v_mfma_f32_16x16x32_bf16 v[38:41], v[142:145], v[196:199], v[38:41]
	v_mfma_f32_16x16x32_bf16 v[30:33], v[156:159], v[196:199], v[30:33]
	v_mfma_f32_16x16x32_bf16 v[22:25], v[142:145], v[204:207], v[22:25]
	v_mfma_f32_16x16x32_bf16 v[14:17], v[156:159], v[204:207], v[14:17]
	v_mfma_f32_16x16x32_bf16 v[62:65], v[152:155], v[184:187], v[62:65]
	v_mfma_f32_16x16x32_bf16 v[58:61], v[160:163], v[184:187], v[58:61]
	v_mfma_f32_16x16x32_bf16 v[54:57], v[152:155], v[192:195], v[54:57]
	v_mfma_f32_16x16x32_bf16 v[46:49], v[160:163], v[192:195], v[46:49]
	v_mfma_f32_16x16x32_bf16 v[38:41], v[152:155], v[200:203], v[38:41]
	v_mfma_f32_16x16x32_bf16 v[30:33], v[160:163], v[200:203], v[30:33]
	v_mfma_f32_16x16x32_bf16 v[22:25], v[152:155], v[208:211], v[22:25]
	v_mfma_f32_16x16x32_bf16 v[14:17], v[160:163], v[208:211], v[14:17]
	s_setprio 2
	s_setprio 0
	v_mfma_f32_16x16x32_bf16 v[50:53], v[164:167], v[180:183], v[50:53]
	v_mfma_f32_16x16x32_bf16 v[42:45], v[172:175], v[180:183], v[42:45]
	v_mfma_f32_16x16x32_bf16 v[34:37], v[164:167], v[188:191], v[34:37]
	v_mfma_f32_16x16x32_bf16 v[26:29], v[172:175], v[188:191], v[26:29]
	v_mfma_f32_16x16x32_bf16 v[18:21], v[164:167], v[196:199], v[18:21]
	v_mfma_f32_16x16x32_bf16 v[10:13], v[172:175], v[196:199], v[10:13]
	v_mfma_f32_16x16x32_bf16 v[6:9], v[164:167], v[204:207], v[6:9]
	v_mfma_f32_16x16x32_bf16 v[2:5], v[172:175], v[204:207], v[2:5]
	v_mfma_f32_16x16x32_bf16 v[50:53], v[168:171], v[184:187], v[50:53]
	v_mfma_f32_16x16x32_bf16 v[42:45], v[176:179], v[184:187], v[42:45]
	v_mfma_f32_16x16x32_bf16 v[34:37], v[168:171], v[192:195], v[34:37]
	v_mfma_f32_16x16x32_bf16 v[26:29], v[176:179], v[192:195], v[26:29]
	v_mfma_f32_16x16x32_bf16 v[18:21], v[168:171], v[200:203], v[18:21]
	v_mfma_f32_16x16x32_bf16 v[10:13], v[176:179], v[200:203], v[10:13]
	v_mfma_f32_16x16x32_bf16 v[6:9], v[168:171], v[208:211], v[6:9]
	v_mfma_f32_16x16x32_bf16 v[2:5], v[176:179], v[208:211], v[2:5]
	s_setprio 2
	s_barrier
	s_movk_i32 s13, 0x100
	s_andn2_b64 vcc, exec, s[22:23]
	s_mov_b64 s[24:25], -1
	s_mov_b64 s[22:23], 0
	s_cbranch_vccz .LBB0_368
	s_and_b64 vcc, exec, s[10:11]
	s_cbranch_vccz .LBB0_371
	s_barrier

; #define PG8_STAGE(bufoff, gbase, voff) do { _Pragma("unroll") for (int _i = 0; _i < 2; ++_i) \
;         __builtin_amdgcn_global_load_lds((const unsigned*)((const char*)(gbase) + (voff)[_i]), (LAS unsigned*)(lds + (bufoff) + ldsw + _i * 8192), 16, 0, 0); } while (0)
; #define PG8_LDA(dst, b, h) do { _Pragma("unroll") for (int m = 0; m < 4; ++m) _Pragma("unroll") for (int k = 0; k < 2; ++k) dst[m][k] = *(const LAS bf16x8*)(lds + PG8_SA(b, h) + aoff + m * 2048 + k * 1024); } while (0)
; #define PG8_LDB(dst, b, h) do { _Pragma("unroll") for (int n = 0; n < 2; ++n) _Pragma("unroll") for (int k = 0; k < 2; ++k) dst[n][k] = *(const LAS bf16x8*)(lds + PG8_SB(b, h) + boff + n * 2048 + k * 1024); } while (0)
; #define PG8_MMA(ai, bj, At, Bt) do { __builtin_amdgcn_s_setprio(1); _Pragma("unroll") for (int m = 0; m < 4; ++m) _Pragma("unroll") for (int n = 0; n < 2; ++n) _Pragma("unroll") for (int k = 0; k < 2; ++k) \
;         acc[ai][bj][m][n] = __builtin_amdgcn_mfma_f32_16x16x32_bf16(Bt[n][k], At[m][k], acc[ai][bj][m][n], 0, 0, 0); __builtin_amdgcn_s_setprio(0); } while (0)
; #define PG8_WAIT_V(n) asm volatile("s_waitcnt vmcnt(" #n ")" ::: "memory")
; #define PG8_WAIT_L(n) asm volatile("s_waitcnt lgkmcnt(" #n ")" ::: "memory")
; #define PG8_BAR __builtin_amdgcn_s_barrier()
; #define PG8_SCHED __builtin_amdgcn_sched_barrier(0)
; template <class Epi>
; __device__ __forceinline__ void gemm_phase(LAS unsigned char* lds, const Gemm g, int G, int c, const Epi& E) {
;     ...
;             const char* a2 = last ? nA : cA + (size_t)(t + 2) * kstep; const char* b2 = last ? nB : cB + (size_t)(t + 2) * kstep;
;             const char* a3 = a2 + kstep; const char* b3 = b2 + kstep;
;             PG8_LDB(B0, 0, 0); PG8_LDB(B1, 0, 1); PG8_SCHED; PG8_LDA(At, 0, 0); PG8_STAGE(PG8_SA(1, 1), a1 + hstepA, voffA);
;             PG8_WAIT_V(8); PG8_WAIT_L(0); PG8_BAR; PG8_MMA(0, 0, At, B0); PG8_MMA(0, 1, At, B1); PG8_BAR; PG8_SCHED;
;             PG8_LDA(At, 0, 1); PG8_STAGE(PG8_SB(0, 0), b2, voffB); PG8_STAGE(PG8_SB(0, 1), b2 + hstepB, voffB); PG8_STAGE(PG8_SA(0, 0), a2, voffA);
;             PG8_WAIT_V(8); PG8_WAIT_L(0); PG8_BAR; PG8_MMA(1, 0, At, B0); PG8_MMA(1, 1, At, B1); PG8_BAR; PG8_SCHED;
.LBB0_390:
	s_add_u32 s33, s8, s38
	s_addc_u32 s39, s9, 0
	s_add_u32 s56, s33, 0x100
	s_addc_u32 s57, s39, 0
	s_and_b64 s[54:55], s[10:11], exec
	s_cselect_b32 s57, s47, s57
	s_cselect_b32 s56, s46, s56
	s_add_u32 s38, s6, s38
	s_addc_u32 s54, s7, 0
	s_add_u32 s38, s38, 0x100
	s_addc_u32 s54, s54, 0
	s_and_b64 s[10:11], s[10:11], exec
	s_cselect_b32 s59, s53, s54
	s_cselect_b32 s58, s52, s38
	s_add_u32 s66, s33, 0xb0080
	s_addc_u32 s67, s39, 0
	s_add_i32 s65, s87, s14
	s_add_i32 m0, s78, 0xc000
	s_add_i32 s74, s78, 0xe000
	v_lshl_add_u64 v[214:215], s[66:67], 0, v[130:131]
	global_load_lds_dwordx4 v[214:215], off
	v_lshl_add_u64 v[214:215], s[66:67], 0, v[134:135]
	s_mov_b32 m0, s74
	s_nop 0
	global_load_lds_dwordx4 v[214:215], off
	ds_read_b128 v[142:145], v160
	ds_read_b128 v[146:149], v160 offset:1024
	ds_read_b128 v[150:153], v160 offset:2048
	ds_read_b128 v[154:157], v160 offset:3072
	ds_read_b128 v[166:169], v161
	ds_read_b128 v[170:173], v161 offset:1024
	ds_read_b128 v[174:177], v161 offset:2048
	ds_read_b128 v[178:181], v161 offset:3072
	s_add_i32 s62, s65, 0x2000
	s_add_u32 s60, s58, 0xb0000
	s_addc_u32 s61, s59, 0
	s_add_i32 s64, s88, s14
	s_add_i32 s63, s64, 0x2000
	s_add_i32 s73, 0, 0x18000
	s_add_i32 s33, 0, 0x1c000
	s_add_u32 s54, s56, 0xb0000
	s_addc_u32 s55, s57, 0
	s_add_i32 vcc_hi, s73, s14
	s_add_i32 s39, vcc_hi, 0x2000
	s_add_u32 s10, s58, 0xb0080
	s_addc_u32 s11, s59, 0
	s_add_i32 vcc_lo, s33, s14
	s_add_i32 s38, vcc_lo, 0x2000
	ds_read_b128 v[182:185], v162
	ds_read_b128 v[186:189], v162 offset:1024
	ds_read_b128 v[190:193], v162 offset:2048
	ds_read_b128 v[194:197], v162 offset:3072
	ds_read_b128 v[198:201], v162 offset:4096
	ds_read_b128 v[202:205], v162 offset:5120
	ds_read_b128 v[206:209], v162 offset:6144
	ds_read_b128 v[210:213], v162 offset:7168
	s_waitcnt vmcnt(8)
	s_waitcnt lgkmcnt(0)
	s_barrier
	s_setprio 0
	s_waitcnt lgkmcnt(0)
	v_mfma_f32_16x16x32_bf16 v[126:129], v[142:145], v[182:185], v[126:129]
	v_mfma_f32_16x16x32_bf16 v[122:125], v[150:153], v[182:185], v[122:125]
	v_mfma_f32_16x16x32_bf16 v[110:113], v[142:145], v[190:193], v[110:113]
	v_mfma_f32_16x16x32_bf16 v[106:109], v[150:153], v[190:193], v[106:109]
	v_mfma_f32_16x16x32_bf16 v[94:97], v[142:145], v[198:201], v[94:97]
	v_mfma_f32_16x16x32_bf16 v[90:93], v[150:153], v[198:201], v[90:93]
	v_mfma_f32_16x16x32_bf16 v[78:81], v[142:145], v[206:209], v[78:81]
	v_mfma_f32_16x16x32_bf16 v[74:77], v[150:153], v[206:209], v[74:77]
	v_mfma_f32_16x16x32_bf16 v[126:129], v[146:149], v[186:189], v[126:129]
	v_mfma_f32_16x16x32_bf16 v[122:125], v[154:157], v[186:189], v[122:125]
	v_mfma_f32_16x16x32_bf16 v[110:113], v[146:149], v[194:197], v[110:113]
	v_mfma_f32_16x16x32_bf16 v[106:109], v[154:157], v[194:197], v[106:109]
	v_mfma_f32_16x16x32_bf16 v[94:97], v[146:149], v[202:205], v[94:97]
	v_mfma_f32_16x16x32_bf16 v[90:93], v[154:157], v[202:205], v[90:93]
	v_mfma_f32_16x16x32_bf16 v[78:81], v[146:149], v[210:213], v[78:81]
	v_mfma_f32_16x16x32_bf16 v[74:77], v[154:157], v[210:213], v[74:77]
	s_setprio 2
	s_setprio 0
	v_mfma_f32_16x16x32_bf16 v[118:121], v[166:169], v[182:185], v[118:121]
	v_mfma_f32_16x16x32_bf16 v[114:117], v[174:177], v[182:185], v[114:117]
	v_mfma_f32_16x16x32_bf16 v[102:105], v[166:169], v[190:193], v[102:105]
	v_mfma_f32_16x16x32_bf16 v[98:101], v[174:177], v[190:193], v[98:101]
	v_mfma_f32_16x16x32_bf16 v[86:89], v[166:169], v[198:201], v[86:89]
	v_mfma_f32_16x16x32_bf16 v[82:85], v[174:177], v[198:201], v[82:85]
	v_mfma_f32_16x16x32_bf16 v[70:73], v[166:169], v[206:209], v[70:73]
	v_mfma_f32_16x16x32_bf16 v[66:69], v[174:177], v[206:209], v[66:69]
	v_mfma_f32_16x16x32_bf16 v[118:121], v[170:173], v[186:189], v[118:121]
	v_mfma_f32_16x16x32_bf16 v[114:117], v[178:181], v[186:189], v[114:117]
	v_mfma_f32_16x16x32_bf16 v[102:105], v[170:173], v[194:197], v[102:105]
	v_mfma_f32_16x16x32_bf16 v[98:101], v[178:181], v[194:197], v[98:101]
	v_mfma_f32_16x16x32_bf16 v[86:89], v[170:173], v[202:205], v[86:89]
	v_mfma_f32_16x16x32_bf16 v[82:85], v[178:181], v[202:205], v[82:85]
	v_mfma_f32_16x16x32_bf16 v[70:73], v[170:173], v[210:213], v[70:73]
	v_mfma_f32_16x16x32_bf16 v[66:69], v[178:181], v[210:213], v[66:69]
	s_setprio 2
	s_barrier
	s_mov_b32 m0, s65
	v_lshl_add_u64 v[214:215], s[58:59], 0, v[132:133]
	global_load_lds_dwordx4 v[214:215], off
	v_lshl_add_u64 v[216:217], s[58:59], 0, v[136:137]
	s_mov_b32 m0, s62
	v_lshl_add_u64 v[218:219], s[60:61], 0, v[132:133]
	global_load_lds_dwordx4 v[216:217], off
	s_mov_b32 m0, s64
	v_lshl_add_u64 v[220:221], s[56:57], 0, v[134:135]
	global_load_lds_dwordx4 v[218:219], off
	v_lshl_add_u64 v[218:219], s[60:61], 0, v[136:137]
	s_mov_b32 m0, s63
	s_nop 0
	global_load_lds_dwordx4 v[218:219], off
	v_lshl_add_u64 v[218:219], s[56:57], 0, v[130:131]
	s_mov_b32 m0, s78
	s_nop 0
	global_load_lds_dwordx4 v[218:219], off
	s_mov_b32 m0, s79
	s_nop 0
	global_load_lds_dwordx4 v[220:221], off
	ds_read_b128 v[182:185], v162 offset:16384
	ds_read_b128 v[186:189], v162 offset:17408
	ds_read_b128 v[190:193], v162 offset:18432
	ds_read_b128 v[194:197], v162 offset:19456
	ds_read_b128 v[198:201], v162 offset:20480
	ds_read_b128 v[202:205], v162 offset:21504
	ds_read_b128 v[206:209], v162 offset:22528
	ds_read_b128 v[210:213], v162 offset:23552
	s_waitcnt vmcnt(8)
	s_waitcnt lgkmcnt(0)
	s_barrier
; #define PG8_STAGE(bufoff, gbase, voff) do { _Pragma("unroll") for (int _i = 0; _i < 2; ++_i) \
;         __builtin_amdgcn_global_load_lds((const unsigned*)((const char*)(gbase) + (voff)[_i]), (LAS unsigned*)(lds + (bufoff) + ldsw + _i * 8192), 16, 0, 0); } while (0)
; #define PG8_LDA(dst, b, h) do { _Pragma("unroll") for (int m = 0; m < 4; ++m) _Pragma("unroll") for (int k = 0; k < 2; ++k) dst[m][k] = *(const LAS bf16x8*)(lds + PG8_SA(b, h) + aoff + m * 2048 + k * 1024); } while (0)
; #define PG8_LDB(dst, b, h) do { _Pragma("unroll") for (int n = 0; n < 2; ++n) _Pragma("unroll") for (int k = 0; k < 2; ++k) dst[n][k] = *(const LAS bf16x8*)(lds + PG8_SB(b, h) + boff + n * 2048 + k * 1024); } while (0)
; #define PG8_MMA(ai, bj, At, Bt) do { __builtin_amdgcn_s_setprio(1); _Pragma("unroll") for (int m = 0; m < 4; ++m) _Pragma("unroll") for (int n = 0; n < 2; ++n) _Pragma("unroll") for (int k = 0; k < 2; ++k) \
;         acc[ai][bj][m][n] = __builtin_amdgcn_mfma_f32_16x16x32_bf16(Bt[n][k], At[m][k], acc[ai][bj][m][n], 0, 0, 0); __builtin_amdgcn_s_setprio(0); } while (0)
; #define PG8_WAIT_V(n) asm volatile("s_waitcnt vmcnt(" #n ")" ::: "memory")
; #define PG8_WAIT_L(n) asm volatile("s_waitcnt lgkmcnt(" #n ")" ::: "memory")
; #define PG8_BAR __builtin_amdgcn_s_barrier()
; #define PG8_SCHED __builtin_amdgcn_sched_barrier(0)
; template <class Epi>
; __device__ __forceinline__ void gemm_phase(LAS unsigned char* lds, const Gemm g, int G, int c, const Epi& E) {
;     ...
;             PG8_WAIT_V(8); PG8_WAIT_L(0); PG8_BAR; PG8_MMA(1, 0, At, B0); PG8_MMA(1, 1, At, B1); PG8_BAR; PG8_SCHED;
;             PG8_LDB(B0, 1, 0); PG8_LDB(B1, 1, 1); PG8_SCHED; PG8_LDA(At, 1, 0); PG8_STAGE(PG8_SA(0, 1), a2 + hstepA, voffA);
;             PG8_WAIT_V(8); PG8_WAIT_L(0); PG8_BAR; PG8_MMA(0, 0, At, B0); PG8_MMA(0, 1, At, B1); PG8_BAR; PG8_SCHED;
	s_setprio 0
	s_waitcnt lgkmcnt(0)
	v_mfma_f32_16x16x32_bf16 v[62:65], v[142:145], v[182:185], v[62:65]
	v_mfma_f32_16x16x32_bf16 v[58:61], v[150:153], v[182:185], v[58:61]
	v_mfma_f32_16x16x32_bf16 v[46:49], v[142:145], v[190:193], v[46:49]
	v_mfma_f32_16x16x32_bf16 v[42:45], v[150:153], v[190:193], v[42:45]
	v_mfma_f32_16x16x32_bf16 v[30:33], v[142:145], v[198:201], v[30:33]
	v_mfma_f32_16x16x32_bf16 v[26:29], v[150:153], v[198:201], v[26:29]
	v_mfma_f32_16x16x32_bf16 v[14:17], v[142:145], v[206:209], v[14:17]
	v_mfma_f32_16x16x32_bf16 v[10:13], v[150:153], v[206:209], v[10:13]
	v_mfma_f32_16x16x32_bf16 v[62:65], v[146:149], v[186:189], v[62:65]
	v_mfma_f32_16x16x32_bf16 v[58:61], v[154:157], v[186:189], v[58:61]
	v_mfma_f32_16x16x32_bf16 v[46:49], v[146:149], v[194:197], v[46:49]
	v_mfma_f32_16x16x32_bf16 v[42:45], v[154:157], v[194:197], v[42:45]
	v_mfma_f32_16x16x32_bf16 v[30:33], v[146:149], v[202:205], v[30:33]
	v_mfma_f32_16x16x32_bf16 v[26:29], v[154:157], v[202:205], v[26:29]
	v_mfma_f32_16x16x32_bf16 v[14:17], v[146:149], v[210:213], v[14:17]
	v_mfma_f32_16x16x32_bf16 v[10:13], v[154:157], v[210:213], v[10:13]
	s_setprio 2
	s_setprio 0
	v_mfma_f32_16x16x32_bf16 v[54:57], v[166:169], v[182:185], v[54:57]
	v_mfma_f32_16x16x32_bf16 v[50:53], v[174:177], v[182:185], v[50:53]
	v_mfma_f32_16x16x32_bf16 v[38:41], v[166:169], v[190:193], v[38:41]
	v_mfma_f32_16x16x32_bf16 v[34:37], v[174:177], v[190:193], v[34:37]
	v_mfma_f32_16x16x32_bf16 v[22:25], v[166:169], v[198:201], v[22:25]
	v_mfma_f32_16x16x32_bf16 v[18:21], v[174:177], v[198:201], v[18:21]
	v_mfma_f32_16x16x32_bf16 v[6:9], v[166:169], v[206:209], v[6:9]
	v_mfma_f32_16x16x32_bf16 v[2:5], v[174:177], v[206:209], v[2:5]
	v_mfma_f32_16x16x32_bf16 v[54:57], v[170:173], v[186:189], v[54:57]
	v_mfma_f32_16x16x32_bf16 v[50:53], v[178:181], v[186:189], v[50:53]
	v_mfma_f32_16x16x32_bf16 v[38:41], v[170:173], v[194:197], v[38:41]
	v_mfma_f32_16x16x32_bf16 v[34:37], v[178:181], v[194:197], v[34:37]
	v_mfma_f32_16x16x32_bf16 v[22:25], v[170:173], v[202:205], v[22:25]
	v_mfma_f32_16x16x32_bf16 v[18:21], v[178:181], v[202:205], v[18:21]
	v_mfma_f32_16x16x32_bf16 v[6:9], v[170:173], v[210:213], v[6:9]
	v_mfma_f32_16x16x32_bf16 v[2:5], v[178:181], v[210:213], v[2:5]
	s_setprio 2
	s_barrier
	s_mov_b32 m0, s80
	v_lshl_add_u64 v[222:223], s[54:55], 0, v[130:131]
	global_load_lds_dwordx4 v[222:223], off
	v_lshl_add_u64 v[222:223], s[54:55], 0, v[134:135]
	s_mov_b32 m0, s81
	s_nop 0
	global_load_lds_dwordx4 v[222:223], off
	v_add_u32_e32 v154, s73, v159
	v_add_u32_e32 v178, s33, v159
	ds_read_b128 v[142:145], v154
	ds_read_b128 v[146:149], v154 offset:1024
	ds_read_b128 v[150:153], v154 offset:2048
	ds_read_b128 v[154:157], v154 offset:3072
	ds_read_b128 v[166:169], v178
	ds_read_b128 v[170:173], v178 offset:1024
	ds_read_b128 v[174:177], v178 offset:2048
	ds_read_b128 v[178:181], v178 offset:3072
	ds_read_b128 v[182:185], v162 offset:32768
	ds_read_b128 v[186:189], v162 offset:33792
	ds_read_b128 v[190:193], v162 offset:34816
	ds_read_b128 v[194:197], v162 offset:35840
	ds_read_b128 v[198:201], v162 offset:36864
	ds_read_b128 v[202:205], v162 offset:37888
	ds_read_b128 v[206:209], v162 offset:38912
	ds_read_b128 v[210:213], v162 offset:39936
	s_waitcnt vmcnt(8)
	s_waitcnt lgkmcnt(0)
	s_barrier
	s_setprio 0
	s_waitcnt lgkmcnt(0)
	v_mfma_f32_16x16x32_bf16 v[126:129], v[142:145], v[182:185], v[126:129]
	v_mfma_f32_16x16x32_bf16 v[122:125], v[150:153], v[182:185], v[122:125]
	v_mfma_f32_16x16x32_bf16 v[110:113], v[142:145], v[190:193], v[110:113]
	v_mfma_f32_16x16x32_bf16 v[106:109], v[150:153], v[190:193], v[106:109]
	v_mfma_f32_16x16x32_bf16 v[94:97], v[142:145], v[198:201], v[94:97]
	v_mfma_f32_16x16x32_bf16 v[90:93], v[150:153], v[198:201], v[90:93]
	v_mfma_f32_16x16x32_bf16 v[78:81], v[142:145], v[206:209], v[78:81]
	v_mfma_f32_16x16x32_bf16 v[74:77], v[150:153], v[206:209], v[74:77]
	v_mfma_f32_16x16x32_bf16 v[126:129], v[146:149], v[186:189], v[126:129]
	v_mfma_f32_16x16x32_bf16 v[122:125], v[154:157], v[186:189], v[122:125]
	v_mfma_f32_16x16x32_bf16 v[110:113], v[146:149], v[194:197], v[110:113]
	v_mfma_f32_16x16x32_bf16 v[106:109], v[154:157], v[194:197], v[106:109]
	v_mfma_f32_16x16x32_bf16 v[94:97], v[146:149], v[202:205], v[94:97]
	v_mfma_f32_16x16x32_bf16 v[90:93], v[154:157], v[202:205], v[90:93]
	v_mfma_f32_16x16x32_bf16 v[78:81], v[146:149], v[210:213], v[78:81]
	v_mfma_f32_16x16x32_bf16 v[74:77], v[154:157], v[210:213], v[74:77]
	s_setprio 2
	s_setprio 0
	v_mfma_f32_16x16x32_bf16 v[118:121], v[166:169], v[182:185], v[118:121]
	v_mfma_f32_16x16x32_bf16 v[114:117], v[174:177], v[182:185], v[114:117]
	v_mfma_f32_16x16x32_bf16 v[102:105], v[166:169], v[190:193], v[102:105]
	v_mfma_f32_16x16x32_bf16 v[98:101], v[174:177], v[190:193], v[98:101]
	v_mfma_f32_16x16x32_bf16 v[86:89], v[166:169], v[198:201], v[86:89]
	v_mfma_f32_16x16x32_bf16 v[82:85], v[174:177], v[198:201], v[82:85]
	v_mfma_f32_16x16x32_bf16 v[70:73], v[166:169], v[206:209], v[70:73]
	v_mfma_f32_16x16x32_bf16 v[66:69], v[174:177], v[206:209], v[66:69]
	v_mfma_f32_16x16x32_bf16 v[118:121], v[170:173], v[186:189], v[118:121]
	v_mfma_f32_16x16x32_bf16 v[114:117], v[178:181], v[186:189], v[114:117]
	v_mfma_f32_16x16x32_bf16 v[102:105], v[170:173], v[194:197], v[102:105]
	v_mfma_f32_16x16x32_bf16 v[98:101], v[178:181], v[194:197], v[98:101]
	v_mfma_f32_16x16x32_bf16 v[86:89], v[170:173], v[202:205], v[86:89]
	v_mfma_f32_16x16x32_bf16 v[82:85], v[178:181], v[202:205], v[82:85]
	v_mfma_f32_16x16x32_bf16 v[70:73], v[170:173], v[210:213], v[70:73]
	v_mfma_f32_16x16x32_bf16 v[66:69], v[178:181], v[210:213], v[66:69]
	s_setprio 2
	s_barrier
; #define PG8_STAGE(bufoff, gbase, voff) do { _Pragma("unroll") for (int _i = 0; _i < 2; ++_i) \
;         __builtin_amdgcn_global_load_lds((const unsigned*)((const char*)(gbase) + (voff)[_i]), (LAS unsigned*)(lds + (bufoff) + ldsw + _i * 8192), 16, 0, 0); } while (0)
; #define PG8_LDA(dst, b, h) do { _Pragma("unroll") for (int m = 0; m < 4; ++m) _Pragma("unroll") for (int k = 0; k < 2; ++k) dst[m][k] = *(const LAS bf16x8*)(lds + PG8_SA(b, h) + aoff + m * 2048 + k * 1024); } while (0)
; #define PG8_MMA(ai, bj, At, Bt) do { __builtin_amdgcn_s_setprio(1); _Pragma("unroll") for (int m = 0; m < 4; ++m) _Pragma("unroll") for (int n = 0; n < 2; ++n) _Pragma("unroll") for (int k = 0; k < 2; ++k) \
;         acc[ai][bj][m][n] = __builtin_amdgcn_mfma_f32_16x16x32_bf16(Bt[n][k], At[m][k], acc[ai][bj][m][n], 0, 0, 0); __builtin_amdgcn_s_setprio(0); } while (0)
; #define PG8_WAIT_V(n) asm volatile("s_waitcnt vmcnt(" #n ")" ::: "memory")
; #define PG8_WAIT_L(n) asm volatile("s_waitcnt lgkmcnt(" #n ")" ::: "memory")
; #define PG8_BAR __builtin_amdgcn_s_barrier()
; #define PG8_SCHED __builtin_amdgcn_sched_barrier(0)
; template <class Epi>
; __device__ __forceinline__ void gemm_phase(LAS unsigned char* lds, const Gemm g, int G, int c, const Epi& E) {
;     ...
;             PG8_LDA(At, 1, 1); PG8_STAGE(PG8_SB(1, 0), b3, voffB); PG8_STAGE(PG8_SB(1, 1), b3 + hstepB, voffB); PG8_STAGE(PG8_SA(1, 0), a3, voffA);
;             PG8_WAIT_V(8); PG8_WAIT_L(0); PG8_BAR; PG8_MMA(1, 0, At, B0); PG8_MMA(1, 1, At, B1); PG8_BAR; PG8_SCHED;
;         }
;         if (wr == 0) PG8_BAR;
	s_mov_b32 m0, vcc_hi
	v_lshl_add_u64 v[214:215], v[214:215], 0, s[24:25]
	global_load_lds_dwordx4 v[214:215], off
	v_lshl_add_u64 v[214:215], v[216:217], 0, s[24:25]
	s_mov_b32 m0, s39
	s_nop 0
	global_load_lds_dwordx4 v[214:215], off
	v_lshl_add_u64 v[214:215], s[10:11], 0, v[132:133]
	s_mov_b32 m0, vcc_lo
	s_nop 0
	global_load_lds_dwordx4 v[214:215], off
	v_lshl_add_u64 v[214:215], s[10:11], 0, v[136:137]
	s_mov_b32 m0, s38
	s_nop 0
	global_load_lds_dwordx4 v[214:215], off
	v_lshl_add_u64 v[214:215], v[218:219], 0, s[24:25]
	s_mov_b32 m0, s85
	s_nop 0
	global_load_lds_dwordx4 v[214:215], off
	v_lshl_add_u64 v[214:215], v[220:221], 0, s[24:25]
	s_mov_b32 m0, s86
	s_nop 0
	global_load_lds_dwordx4 v[214:215], off
	ds_read_b128 v[182:185], v162 offset:49152
	ds_read_b128 v[186:189], v162 offset:50176
	ds_read_b128 v[190:193], v162 offset:51200
	ds_read_b128 v[194:197], v162 offset:52224
	ds_read_b128 v[198:201], v162 offset:53248
	ds_read_b128 v[202:205], v162 offset:54272
	ds_read_b128 v[206:209], v162 offset:55296
	ds_read_b128 v[210:213], v162 offset:56320
	s_waitcnt vmcnt(8)
	s_waitcnt lgkmcnt(0)
	s_barrier
	s_setprio 0
	s_waitcnt lgkmcnt(0)
	v_mfma_f32_16x16x32_bf16 v[62:65], v[142:145], v[182:185], v[62:65]
	v_mfma_f32_16x16x32_bf16 v[58:61], v[150:153], v[182:185], v[58:61]
	v_mfma_f32_16x16x32_bf16 v[46:49], v[142:145], v[190:193], v[46:49]
	v_mfma_f32_16x16x32_bf16 v[42:45], v[150:153], v[190:193], v[42:45]
	v_mfma_f32_16x16x32_bf16 v[30:33], v[142:145], v[198:201], v[30:33]
	v_mfma_f32_16x16x32_bf16 v[26:29], v[150:153], v[198:201], v[26:29]
	v_mfma_f32_16x16x32_bf16 v[14:17], v[142:145], v[206:209], v[14:17]
	v_mfma_f32_16x16x32_bf16 v[10:13], v[150:153], v[206:209], v[10:13]
	v_mfma_f32_16x16x32_bf16 v[62:65], v[146:149], v[186:189], v[62:65]
	v_mfma_f32_16x16x32_bf16 v[58:61], v[154:157], v[186:189], v[58:61]
	v_mfma_f32_16x16x32_bf16 v[46:49], v[146:149], v[194:197], v[46:49]
	v_mfma_f32_16x16x32_bf16 v[42:45], v[154:157], v[194:197], v[42:45]
	v_mfma_f32_16x16x32_bf16 v[30:33], v[146:149], v[202:205], v[30:33]
	v_mfma_f32_16x16x32_bf16 v[26:29], v[154:157], v[202:205], v[26:29]
	v_mfma_f32_16x16x32_bf16 v[14:17], v[146:149], v[210:213], v[14:17]
	v_mfma_f32_16x16x32_bf16 v[10:13], v[154:157], v[210:213], v[10:13]
	s_setprio 2
	s_setprio 0
	v_mfma_f32_16x16x32_bf16 v[54:57], v[166:169], v[182:185], v[54:57]
	v_mfma_f32_16x16x32_bf16 v[50:53], v[174:177], v[182:185], v[50:53]
	v_mfma_f32_16x16x32_bf16 v[38:41], v[166:169], v[190:193], v[38:41]
	v_mfma_f32_16x16x32_bf16 v[34:37], v[174:177], v[190:193], v[34:37]
	v_mfma_f32_16x16x32_bf16 v[22:25], v[166:169], v[198:201], v[22:25]
	v_mfma_f32_16x16x32_bf16 v[18:21], v[174:177], v[198:201], v[18:21]
	v_mfma_f32_16x16x32_bf16 v[6:9], v[166:169], v[206:209], v[6:9]
	v_mfma_f32_16x16x32_bf16 v[2:5], v[174:177], v[206:209], v[2:5]
	v_mfma_f32_16x16x32_bf16 v[54:57], v[170:173], v[186:189], v[54:57]
	v_mfma_f32_16x16x32_bf16 v[50:53], v[178:181], v[186:189], v[50:53]
	v_mfma_f32_16x16x32_bf16 v[38:41], v[170:173], v[194:197], v[38:41]
	v_mfma_f32_16x16x32_bf16 v[34:37], v[178:181], v[194:197], v[34:37]
	v_mfma_f32_16x16x32_bf16 v[22:25], v[170:173], v[202:205], v[22:25]
	v_mfma_f32_16x16x32_bf16 v[18:21], v[178:181], v[202:205], v[18:21]
	v_mfma_f32_16x16x32_bf16 v[6:9], v[170:173], v[210:213], v[6:9]
	v_mfma_f32_16x16x32_bf16 v[2:5], v[178:181], v[210:213], v[2:5]
	s_setprio 2
	s_barrier
	s_movk_i32 s38, 0x100
	s_andn2_b64 vcc, exec, s[4:5]
	s_mov_b64 s[10:11], -1
	s_mov_b64 s[4:5], 0
	s_cbranch_vccz .LBB0_390
	s_and_b64 vcc, exec, s[44:45]
	s_cbranch_vccz .LBB0_393
	s_barrier

; #define PG8_STAGE(bufoff, gbase, voff) do { _Pragma("unroll") for (int _i = 0; _i < 2; ++_i) \
;         __builtin_amdgcn_global_load_lds((const unsigned*)((const char*)(gbase) + (voff)[_i]), (LAS unsigned*)(lds + (bufoff) + ldsw + _i * 8192), 16, 0, 0); } while (0)
; #define PG8_LDA(dst, b, h) do { _Pragma("unroll") for (int m = 0; m < 4; ++m) _Pragma("unroll") for (int k = 0; k < 2; ++k) dst[m][k] = *(const LAS bf16x8*)(lds + PG8_SA(b, h) + aoff + m * 2048 + k * 1024); } while (0)
; #define PG8_LDB(dst, b, h) do { _Pragma("unroll") for (int n = 0; n < 2; ++n) _Pragma("unroll") for (int k = 0; k < 2; ++k) dst[n][k] = *(const LAS bf16x8*)(lds + PG8_SB(b, h) + boff + n * 2048 + k * 1024); } while (0)
; #define PG8_MMA(ai, bj, At, Bt) do { __builtin_amdgcn_s_setprio(1); _Pragma("unroll") for (int m = 0; m < 4; ++m) _Pragma("unroll") for (int n = 0; n < 2; ++n) _Pragma("unroll") for (int k = 0; k < 2; ++k) \
;         acc[ai][bj][m][n] = __builtin_amdgcn_mfma_f32_16x16x32_bf16(Bt[n][k], At[m][k], acc[ai][bj][m][n], 0, 0, 0); __builtin_amdgcn_s_setprio(0); } while (0)
; #define PG8_WAIT_V(n) asm volatile("s_waitcnt vmcnt(" #n ")" ::: "memory")
; #define PG8_WAIT_L(n) asm volatile("s_waitcnt lgkmcnt(" #n ")" ::: "memory")
; #define PG8_BAR __builtin_amdgcn_s_barrier()
; #define PG8_SCHED __builtin_amdgcn_sched_barrier(0)
; template <class Epi>
; __device__ __forceinline__ void gemm_phase(LAS unsigned char* lds, const Gemm g, int G, int c, const Epi& E) {
;     ...
;             const char* a2 = last ? nA : cA + (size_t)(t + 2) * kstep; const char* b2 = last ? nB : cB + (size_t)(t + 2) * kstep;
;             const char* a3 = a2 + kstep; const char* b3 = b2 + kstep;
;             PG8_LDB(B0, 0, 0); PG8_LDB(B1, 0, 1); PG8_SCHED; PG8_LDA(At, 0, 0); PG8_STAGE(PG8_SA(1, 1), a1 + hstepA, voffA);
;             PG8_WAIT_V(8); PG8_WAIT_L(0); PG8_BAR; PG8_MMA(0, 0, At, B0); PG8_MMA(0, 1, At, B1); PG8_BAR; PG8_SCHED;
;             PG8_LDA(At, 0, 1); PG8_STAGE(PG8_SB(0, 0), b2, voffB); PG8_STAGE(PG8_SB(0, 1), b2 + hstepB, voffB); PG8_STAGE(PG8_SA(0, 0), a2, voffA);
;             PG8_WAIT_V(8); PG8_WAIT_L(0); PG8_BAR; PG8_MMA(1, 0, At, B0); PG8_MMA(1, 1, At, B1); PG8_BAR; PG8_SCHED;
.LBB0_476:
	s_add_u32 s33, s8, s38
	s_addc_u32 s39, s9, 0
	s_add_u32 s56, s33, 0x100
	s_addc_u32 s57, s39, 0
	s_and_b64 s[54:55], s[10:11], exec
	s_cselect_b32 s57, s47, s57
	s_cselect_b32 s56, s46, s56
	s_add_u32 s38, s6, s38
	s_addc_u32 s54, s7, 0
	s_add_u32 s38, s38, 0x100
	s_addc_u32 s54, s54, 0
	s_and_b64 s[10:11], s[10:11], exec
	s_cselect_b32 s59, s53, s54
	s_cselect_b32 s58, s52, s38
	s_add_u32 s66, s33, 0xb0080
	s_addc_u32 s67, s39, 0
	s_add_i32 s63, s95, s83
	s_add_i32 m0, s86, 0xc000
	s_add_i32 s64, s86, 0xe000
	v_lshl_add_u64 v[162:163], s[66:67], 0, v[138:139]
	global_load_lds_dwordx4 v[162:163], off
	v_lshl_add_u64 v[162:163], s[66:67], 0, v[142:143]
	s_mov_b32 m0, s64
	s_nop 0
	global_load_lds_dwordx4 v[162:163], off
	ds_read_b128 v[130:133], v166
	ds_read_b128 v[134:137], v166 offset:1024
	ds_read_b128 v[150:153], v166 offset:2048
	ds_read_b128 v[154:157], v166 offset:3072
	ds_read_b128 v[158:161], v167
	ds_read_b128 v[172:175], v167 offset:1024
	ds_read_b128 v[176:179], v167 offset:2048
	ds_read_b128 v[180:183], v167 offset:3072
	s_add_i32 s74, s63, 0x2000
	s_add_u32 s60, s58, 0xb0000
	s_addc_u32 s61, s59, 0
	s_add_i32 s75, s96, s83
	s_add_i32 s62, s75, 0x2000
	s_add_i32 vcc_hi, 0, 0x18000
	s_add_i32 vcc_lo, 0, 0x1c000
	s_add_u32 s54, s56, 0xb0000
	s_addc_u32 s55, s57, 0
	s_add_i32 s39, vcc_hi, s83
	s_add_i32 s73, s39, 0x2000
	s_add_u32 s10, s58, 0xb0080
	s_addc_u32 s11, s59, 0
	s_add_i32 s38, vcc_lo, s83
	s_add_i32 s33, s38, 0x2000
	ds_read_b128 v[184:187], v168
	ds_read_b128 v[188:191], v168 offset:1024
	ds_read_b128 v[192:195], v168 offset:2048
	ds_read_b128 v[196:199], v168 offset:3072
	ds_read_b128 v[200:203], v168 offset:4096
	ds_read_b128 v[204:207], v168 offset:5120
	ds_read_b128 v[208:211], v168 offset:6144
	ds_read_b128 v[212:215], v168 offset:7168
	s_waitcnt vmcnt(8)
	s_waitcnt lgkmcnt(0)
	s_barrier
	s_setprio 0
	s_waitcnt lgkmcnt(0)
	v_mfma_f32_16x16x32_bf16 v[126:129], v[130:133], v[184:187], v[126:129]
	v_mfma_f32_16x16x32_bf16 v[122:125], v[150:153], v[184:187], v[122:125]
	v_mfma_f32_16x16x32_bf16 v[110:113], v[130:133], v[192:195], v[110:113]
	v_mfma_f32_16x16x32_bf16 v[106:109], v[150:153], v[192:195], v[106:109]
	v_mfma_f32_16x16x32_bf16 v[94:97], v[130:133], v[200:203], v[94:97]
	v_mfma_f32_16x16x32_bf16 v[90:93], v[150:153], v[200:203], v[90:93]
	v_mfma_f32_16x16x32_bf16 v[78:81], v[130:133], v[208:211], v[78:81]
	v_mfma_f32_16x16x32_bf16 v[74:77], v[150:153], v[208:211], v[74:77]
	v_mfma_f32_16x16x32_bf16 v[126:129], v[134:137], v[188:191], v[126:129]
	v_mfma_f32_16x16x32_bf16 v[122:125], v[154:157], v[188:191], v[122:125]
	v_mfma_f32_16x16x32_bf16 v[110:113], v[134:137], v[196:199], v[110:113]
	v_mfma_f32_16x16x32_bf16 v[106:109], v[154:157], v[196:199], v[106:109]
	v_mfma_f32_16x16x32_bf16 v[94:97], v[134:137], v[204:207], v[94:97]
	v_mfma_f32_16x16x32_bf16 v[90:93], v[154:157], v[204:207], v[90:93]
	v_mfma_f32_16x16x32_bf16 v[78:81], v[134:137], v[212:215], v[78:81]
	v_mfma_f32_16x16x32_bf16 v[74:77], v[154:157], v[212:215], v[74:77]
	s_setprio 2
	s_setprio 0
	v_mfma_f32_16x16x32_bf16 v[118:121], v[158:161], v[184:187], v[118:121]
	v_mfma_f32_16x16x32_bf16 v[114:117], v[176:179], v[184:187], v[114:117]
	v_mfma_f32_16x16x32_bf16 v[102:105], v[158:161], v[192:195], v[102:105]
	v_mfma_f32_16x16x32_bf16 v[98:101], v[176:179], v[192:195], v[98:101]
	v_mfma_f32_16x16x32_bf16 v[86:89], v[158:161], v[200:203], v[86:89]
	v_mfma_f32_16x16x32_bf16 v[82:85], v[176:179], v[200:203], v[82:85]
	v_mfma_f32_16x16x32_bf16 v[70:73], v[158:161], v[208:211], v[70:73]
	v_mfma_f32_16x16x32_bf16 v[66:69], v[176:179], v[208:211], v[66:69]
	v_mfma_f32_16x16x32_bf16 v[118:121], v[172:175], v[188:191], v[118:121]
	v_mfma_f32_16x16x32_bf16 v[114:117], v[180:183], v[188:191], v[114:117]
	v_mfma_f32_16x16x32_bf16 v[102:105], v[172:175], v[196:199], v[102:105]
	v_mfma_f32_16x16x32_bf16 v[98:101], v[180:183], v[196:199], v[98:101]
	v_mfma_f32_16x16x32_bf16 v[86:89], v[172:175], v[204:207], v[86:89]
	v_mfma_f32_16x16x32_bf16 v[82:85], v[180:183], v[204:207], v[82:85]
	v_mfma_f32_16x16x32_bf16 v[70:73], v[172:175], v[212:215], v[70:73]
	v_mfma_f32_16x16x32_bf16 v[66:69], v[180:183], v[212:215], v[66:69]
	s_setprio 2
	s_barrier
	s_mov_b32 m0, s63
	v_lshl_add_u64 v[162:163], s[58:59], 0, v[140:141]
	global_load_lds_dwordx4 v[162:163], off
	v_lshl_add_u64 v[216:217], s[58:59], 0, v[144:145]
	s_mov_b32 m0, s74
	v_lshl_add_u64 v[218:219], s[60:61], 0, v[140:141]
	global_load_lds_dwordx4 v[216:217], off
	s_mov_b32 m0, s75
	v_lshl_add_u64 v[220:221], s[56:57], 0, v[142:143]
	global_load_lds_dwordx4 v[218:219], off
	v_lshl_add_u64 v[218:219], s[60:61], 0, v[144:145]
	s_mov_b32 m0, s62
	s_nop 0
	global_load_lds_dwordx4 v[218:219], off
	v_lshl_add_u64 v[218:219], s[56:57], 0, v[138:139]
	s_mov_b32 m0, s86
	s_nop 0
	global_load_lds_dwordx4 v[218:219], off
	s_mov_b32 m0, s87
	s_nop 0
	global_load_lds_dwordx4 v[220:221], off
	ds_read_b128 v[184:187], v168 offset:16384
	ds_read_b128 v[188:191], v168 offset:17408
	ds_read_b128 v[192:195], v168 offset:18432
	ds_read_b128 v[196:199], v168 offset:19456
	ds_read_b128 v[200:203], v168 offset:20480
	ds_read_b128 v[204:207], v168 offset:21504
	ds_read_b128 v[208:211], v168 offset:22528
	ds_read_b128 v[212:215], v168 offset:23552
	s_waitcnt vmcnt(8)
	s_waitcnt lgkmcnt(0)
	s_barrier
; #define PG8_STAGE(bufoff, gbase, voff) do { _Pragma("unroll") for (int _i = 0; _i < 2; ++_i) \
;         __builtin_amdgcn_global_load_lds((const unsigned*)((const char*)(gbase) + (voff)[_i]), (LAS unsigned*)(lds + (bufoff) + ldsw + _i * 8192), 16, 0, 0); } while (0)
; #define PG8_LDA(dst, b, h) do { _Pragma("unroll") for (int m = 0; m < 4; ++m) _Pragma("unroll") for (int k = 0; k < 2; ++k) dst[m][k] = *(const LAS bf16x8*)(lds + PG8_SA(b, h) + aoff + m * 2048 + k * 1024); } while (0)
; #define PG8_LDB(dst, b, h) do { _Pragma("unroll") for (int n = 0; n < 2; ++n) _Pragma("unroll") for (int k = 0; k < 2; ++k) dst[n][k] = *(const LAS bf16x8*)(lds + PG8_SB(b, h) + boff + n * 2048 + k * 1024); } while (0)
; #define PG8_MMA(ai, bj, At, Bt) do { __builtin_amdgcn_s_setprio(1); _Pragma("unroll") for (int m = 0; m < 4; ++m) _Pragma("unroll") for (int n = 0; n < 2; ++n) _Pragma("unroll") for (int k = 0; k < 2; ++k) \
;         acc[ai][bj][m][n] = __builtin_amdgcn_mfma_f32_16x16x32_bf16(Bt[n][k], At[m][k], acc[ai][bj][m][n], 0, 0, 0); __builtin_amdgcn_s_setprio(0); } while (0)
; #define PG8_WAIT_V(n) asm volatile("s_waitcnt vmcnt(" #n ")" ::: "memory")
; #define PG8_WAIT_L(n) asm volatile("s_waitcnt lgkmcnt(" #n ")" ::: "memory")
; #define PG8_BAR __builtin_amdgcn_s_barrier()
; #define PG8_SCHED __builtin_amdgcn_sched_barrier(0)
; template <class Epi>
; __device__ __forceinline__ void gemm_phase(LAS unsigned char* lds, const Gemm g, int G, int c, const Epi& E) {
;     ...
;             PG8_WAIT_V(8); PG8_WAIT_L(0); PG8_BAR; PG8_MMA(1, 0, At, B0); PG8_MMA(1, 1, At, B1); PG8_BAR; PG8_SCHED;
;             PG8_LDB(B0, 1, 0); PG8_LDB(B1, 1, 1); PG8_SCHED; PG8_LDA(At, 1, 0); PG8_STAGE(PG8_SA(0, 1), a2 + hstepA, voffA);
;             PG8_WAIT_V(8); PG8_WAIT_L(0); PG8_BAR; PG8_MMA(0, 0, At, B0); PG8_MMA(0, 1, At, B1); PG8_BAR; PG8_SCHED;
	s_setprio 0
	s_waitcnt lgkmcnt(0)
	v_mfma_f32_16x16x32_bf16 v[62:65], v[130:133], v[184:187], v[62:65]
	v_mfma_f32_16x16x32_bf16 v[58:61], v[150:153], v[184:187], v[58:61]
	v_mfma_f32_16x16x32_bf16 v[46:49], v[130:133], v[192:195], v[46:49]
	v_mfma_f32_16x16x32_bf16 v[42:45], v[150:153], v[192:195], v[42:45]
	v_mfma_f32_16x16x32_bf16 v[30:33], v[130:133], v[200:203], v[30:33]
	v_mfma_f32_16x16x32_bf16 v[26:29], v[150:153], v[200:203], v[26:29]
	v_mfma_f32_16x16x32_bf16 v[14:17], v[130:133], v[208:211], v[14:17]
	v_mfma_f32_16x16x32_bf16 v[10:13], v[150:153], v[208:211], v[10:13]
	v_mfma_f32_16x16x32_bf16 v[62:65], v[134:137], v[188:191], v[62:65]
	v_mfma_f32_16x16x32_bf16 v[58:61], v[154:157], v[188:191], v[58:61]
	v_mfma_f32_16x16x32_bf16 v[46:49], v[134:137], v[196:199], v[46:49]
	v_mfma_f32_16x16x32_bf16 v[42:45], v[154:157], v[196:199], v[42:45]
	v_mfma_f32_16x16x32_bf16 v[30:33], v[134:137], v[204:207], v[30:33]
	v_mfma_f32_16x16x32_bf16 v[26:29], v[154:157], v[204:207], v[26:29]
	v_mfma_f32_16x16x32_bf16 v[14:17], v[134:137], v[212:215], v[14:17]
	v_mfma_f32_16x16x32_bf16 v[10:13], v[154:157], v[212:215], v[10:13]
	s_setprio 2
	s_setprio 0
	v_mfma_f32_16x16x32_bf16 v[54:57], v[158:161], v[184:187], v[54:57]
	v_mfma_f32_16x16x32_bf16 v[50:53], v[176:179], v[184:187], v[50:53]
	v_mfma_f32_16x16x32_bf16 v[38:41], v[158:161], v[192:195], v[38:41]
	v_mfma_f32_16x16x32_bf16 v[34:37], v[176:179], v[192:195], v[34:37]
	v_mfma_f32_16x16x32_bf16 v[22:25], v[158:161], v[200:203], v[22:25]
	v_mfma_f32_16x16x32_bf16 v[18:21], v[176:179], v[200:203], v[18:21]
	v_mfma_f32_16x16x32_bf16 v[6:9], v[158:161], v[208:211], v[6:9]
	v_mfma_f32_16x16x32_bf16 v[2:5], v[176:179], v[208:211], v[2:5]
	v_mfma_f32_16x16x32_bf16 v[54:57], v[172:175], v[188:191], v[54:57]
	v_mfma_f32_16x16x32_bf16 v[50:53], v[180:183], v[188:191], v[50:53]
	v_mfma_f32_16x16x32_bf16 v[38:41], v[172:175], v[196:199], v[38:41]
	v_mfma_f32_16x16x32_bf16 v[34:37], v[180:183], v[196:199], v[34:37]
	v_mfma_f32_16x16x32_bf16 v[22:25], v[172:175], v[204:207], v[22:25]
	v_mfma_f32_16x16x32_bf16 v[18:21], v[180:183], v[204:207], v[18:21]
	v_mfma_f32_16x16x32_bf16 v[6:9], v[172:175], v[212:215], v[6:9]
	v_mfma_f32_16x16x32_bf16 v[2:5], v[180:183], v[212:215], v[2:5]
	s_setprio 2
	s_barrier
	s_mov_b32 m0, s88
	v_lshl_add_u64 v[222:223], s[54:55], 0, v[138:139]
	global_load_lds_dwordx4 v[222:223], off
	v_lshl_add_u64 v[222:223], s[54:55], 0, v[142:143]
	s_mov_b32 m0, s89
	s_nop 0
	global_load_lds_dwordx4 v[222:223], off
	v_add_u32_e32 v154, vcc_hi, v165
	v_add_u32_e32 v180, vcc_lo, v165
	ds_read_b128 v[130:133], v154
	ds_read_b128 v[134:137], v154 offset:1024
	ds_read_b128 v[150:153], v154 offset:2048
	ds_read_b128 v[154:157], v154 offset:3072
	ds_read_b128 v[158:161], v180
	ds_read_b128 v[172:175], v180 offset:1024
	ds_read_b128 v[176:179], v180 offset:2048
	ds_read_b128 v[180:183], v180 offset:3072
	ds_read_b128 v[184:187], v168 offset:32768
	ds_read_b128 v[188:191], v168 offset:33792
	ds_read_b128 v[192:195], v168 offset:34816
	ds_read_b128 v[196:199], v168 offset:35840
	ds_read_b128 v[200:203], v168 offset:36864
	ds_read_b128 v[204:207], v168 offset:37888
	ds_read_b128 v[208:211], v168 offset:38912
	ds_read_b128 v[212:215], v168 offset:39936
	s_waitcnt vmcnt(8)
	s_waitcnt lgkmcnt(0)
	s_barrier
	s_setprio 0
	s_waitcnt lgkmcnt(0)
	v_mfma_f32_16x16x32_bf16 v[126:129], v[130:133], v[184:187], v[126:129]
	v_mfma_f32_16x16x32_bf16 v[122:125], v[150:153], v[184:187], v[122:125]
	v_mfma_f32_16x16x32_bf16 v[110:113], v[130:133], v[192:195], v[110:113]
	v_mfma_f32_16x16x32_bf16 v[106:109], v[150:153], v[192:195], v[106:109]
	v_mfma_f32_16x16x32_bf16 v[94:97], v[130:133], v[200:203], v[94:97]
	v_mfma_f32_16x16x32_bf16 v[90:93], v[150:153], v[200:203], v[90:93]
	v_mfma_f32_16x16x32_bf16 v[78:81], v[130:133], v[208:211], v[78:81]
	v_mfma_f32_16x16x32_bf16 v[74:77], v[150:153], v[208:211], v[74:77]
	v_mfma_f32_16x16x32_bf16 v[126:129], v[134:137], v[188:191], v[126:129]
	v_mfma_f32_16x16x32_bf16 v[122:125], v[154:157], v[188:191], v[122:125]
	v_mfma_f32_16x16x32_bf16 v[110:113], v[134:137], v[196:199], v[110:113]
	v_mfma_f32_16x16x32_bf16 v[106:109], v[154:157], v[196:199], v[106:109]
	v_mfma_f32_16x16x32_bf16 v[94:97], v[134:137], v[204:207], v[94:97]
	v_mfma_f32_16x16x32_bf16 v[90:93], v[154:157], v[204:207], v[90:93]
	v_mfma_f32_16x16x32_bf16 v[78:81], v[134:137], v[212:215], v[78:81]
	v_mfma_f32_16x16x32_bf16 v[74:77], v[154:157], v[212:215], v[74:77]
	s_setprio 2
	s_setprio 0
	v_mfma_f32_16x16x32_bf16 v[118:121], v[158:161], v[184:187], v[118:121]
	v_mfma_f32_16x16x32_bf16 v[114:117], v[176:179], v[184:187], v[114:117]
	v_mfma_f32_16x16x32_bf16 v[102:105], v[158:161], v[192:195], v[102:105]
	v_mfma_f32_16x16x32_bf16 v[98:101], v[176:179], v[192:195], v[98:101]
	v_mfma_f32_16x16x32_bf16 v[86:89], v[158:161], v[200:203], v[86:89]
	v_mfma_f32_16x16x32_bf16 v[82:85], v[176:179], v[200:203], v[82:85]
	v_mfma_f32_16x16x32_bf16 v[70:73], v[158:161], v[208:211], v[70:73]
	v_mfma_f32_16x16x32_bf16 v[66:69], v[176:179], v[208:211], v[66:69]
	v_mfma_f32_16x16x32_bf16 v[118:121], v[172:175], v[188:191], v[118:121]
	v_mfma_f32_16x16x32_bf16 v[114:117], v[180:183], v[188:191], v[114:117]
	v_mfma_f32_16x16x32_bf16 v[102:105], v[172:175], v[196:199], v[102:105]
	v_mfma_f32_16x16x32_bf16 v[98:101], v[180:183], v[196:199], v[98:101]
	v_mfma_f32_16x16x32_bf16 v[86:89], v[172:175], v[204:207], v[86:89]
	v_mfma_f32_16x16x32_bf16 v[82:85], v[180:183], v[204:207], v[82:85]
	v_mfma_f32_16x16x32_bf16 v[70:73], v[172:175], v[212:215], v[70:73]
	v_mfma_f32_16x16x32_bf16 v[66:69], v[180:183], v[212:215], v[66:69]
	s_setprio 2
	s_barrier
; #define PG8_STAGE(bufoff, gbase, voff) do { _Pragma("unroll") for (int _i = 0; _i < 2; ++_i) \
;         __builtin_amdgcn_global_load_lds((const unsigned*)((const char*)(gbase) + (voff)[_i]), (LAS unsigned*)(lds + (bufoff) + ldsw + _i * 8192), 16, 0, 0); } while (0)
; #define PG8_LDA(dst, b, h) do { _Pragma("unroll") for (int m = 0; m < 4; ++m) _Pragma("unroll") for (int k = 0; k < 2; ++k) dst[m][k] = *(const LAS bf16x8*)(lds + PG8_SA(b, h) + aoff + m * 2048 + k * 1024); } while (0)
; #define PG8_MMA(ai, bj, At, Bt) do { __builtin_amdgcn_s_setprio(1); _Pragma("unroll") for (int m = 0; m < 4; ++m) _Pragma("unroll") for (int n = 0; n < 2; ++n) _Pragma("unroll") for (int k = 0; k < 2; ++k) \
;         acc[ai][bj][m][n] = __builtin_amdgcn_mfma_f32_16x16x32_bf16(Bt[n][k], At[m][k], acc[ai][bj][m][n], 0, 0, 0); __builtin_amdgcn_s_setprio(0); } while (0)
; #define PG8_WAIT_V(n) asm volatile("s_waitcnt vmcnt(" #n ")" ::: "memory")
; #define PG8_WAIT_L(n) asm volatile("s_waitcnt lgkmcnt(" #n ")" ::: "memory")
; #define PG8_BAR __builtin_amdgcn_s_barrier()
; #define PG8_SCHED __builtin_amdgcn_sched_barrier(0)
; template <class Epi>
; __device__ __forceinline__ void gemm_phase(LAS unsigned char* lds, const Gemm g, int G, int c, const Epi& E) {
;     ...
;             PG8_LDA(At, 1, 1); PG8_STAGE(PG8_SB(1, 0), b3, voffB); PG8_STAGE(PG8_SB(1, 1), b3 + hstepB, voffB); PG8_STAGE(PG8_SA(1, 0), a3, voffA);
;             PG8_WAIT_V(8); PG8_WAIT_L(0); PG8_BAR; PG8_MMA(1, 0, At, B0); PG8_MMA(1, 1, At, B1); PG8_BAR; PG8_SCHED;
;         }
;         if (wr == 0) PG8_BAR;
	s_mov_b32 m0, s39
	v_lshl_add_u64 v[162:163], v[162:163], 0, s[24:25]
	global_load_lds_dwordx4 v[162:163], off
	v_lshl_add_u64 v[162:163], v[216:217], 0, s[24:25]
	s_mov_b32 m0, s73
	s_nop 0
	global_load_lds_dwordx4 v[162:163], off
	v_lshl_add_u64 v[162:163], s[10:11], 0, v[140:141]
	s_mov_b32 m0, s38
	s_nop 0
	global_load_lds_dwordx4 v[162:163], off
	v_lshl_add_u64 v[162:163], s[10:11], 0, v[144:145]
	s_mov_b32 m0, s33
	s_nop 0
	global_load_lds_dwordx4 v[162:163], off
	v_lshl_add_u64 v[162:163], v[218:219], 0, s[24:25]
	s_mov_b32 m0, s93
	s_nop 0
	global_load_lds_dwordx4 v[162:163], off
	v_lshl_add_u64 v[162:163], v[220:221], 0, s[24:25]
	s_mov_b32 m0, s94
	s_nop 0
	global_load_lds_dwordx4 v[162:163], off
	ds_read_b128 v[184:187], v168 offset:49152
	ds_read_b128 v[188:191], v168 offset:50176
	ds_read_b128 v[192:195], v168 offset:51200
	ds_read_b128 v[196:199], v168 offset:52224
	ds_read_b128 v[200:203], v168 offset:53248
	ds_read_b128 v[204:207], v168 offset:54272
	ds_read_b128 v[208:211], v168 offset:55296
	ds_read_b128 v[212:215], v168 offset:56320
	s_waitcnt vmcnt(8)
	s_waitcnt lgkmcnt(0)
	s_barrier
	s_setprio 0
	s_waitcnt lgkmcnt(0)
	v_mfma_f32_16x16x32_bf16 v[62:65], v[130:133], v[184:187], v[62:65]
	v_mfma_f32_16x16x32_bf16 v[58:61], v[150:153], v[184:187], v[58:61]
	v_mfma_f32_16x16x32_bf16 v[46:49], v[130:133], v[192:195], v[46:49]
	v_mfma_f32_16x16x32_bf16 v[42:45], v[150:153], v[192:195], v[42:45]
	v_mfma_f32_16x16x32_bf16 v[30:33], v[130:133], v[200:203], v[30:33]
	v_mfma_f32_16x16x32_bf16 v[26:29], v[150:153], v[200:203], v[26:29]
	v_mfma_f32_16x16x32_bf16 v[14:17], v[130:133], v[208:211], v[14:17]
	v_mfma_f32_16x16x32_bf16 v[10:13], v[150:153], v[208:211], v[10:13]
	v_mfma_f32_16x16x32_bf16 v[62:65], v[134:137], v[188:191], v[62:65]
	v_mfma_f32_16x16x32_bf16 v[58:61], v[154:157], v[188:191], v[58:61]
	v_mfma_f32_16x16x32_bf16 v[46:49], v[134:137], v[196:199], v[46:49]
	v_mfma_f32_16x16x32_bf16 v[42:45], v[154:157], v[196:199], v[42:45]
	v_mfma_f32_16x16x32_bf16 v[30:33], v[134:137], v[204:207], v[30:33]
	v_mfma_f32_16x16x32_bf16 v[26:29], v[154:157], v[204:207], v[26:29]
	v_mfma_f32_16x16x32_bf16 v[14:17], v[134:137], v[212:215], v[14:17]
	v_mfma_f32_16x16x32_bf16 v[10:13], v[154:157], v[212:215], v[10:13]
	s_setprio 2
	s_setprio 0
	v_mfma_f32_16x16x32_bf16 v[54:57], v[158:161], v[184:187], v[54:57]
	v_mfma_f32_16x16x32_bf16 v[50:53], v[176:179], v[184:187], v[50:53]
	v_mfma_f32_16x16x32_bf16 v[38:41], v[158:161], v[192:195], v[38:41]
	v_mfma_f32_16x16x32_bf16 v[34:37], v[176:179], v[192:195], v[34:37]
	v_mfma_f32_16x16x32_bf16 v[22:25], v[158:161], v[200:203], v[22:25]
	v_mfma_f32_16x16x32_bf16 v[18:21], v[176:179], v[200:203], v[18:21]
	v_mfma_f32_16x16x32_bf16 v[6:9], v[158:161], v[208:211], v[6:9]
	v_mfma_f32_16x16x32_bf16 v[2:5], v[176:179], v[208:211], v[2:5]
	v_mfma_f32_16x16x32_bf16 v[54:57], v[172:175], v[188:191], v[54:57]
	v_mfma_f32_16x16x32_bf16 v[50:53], v[180:183], v[188:191], v[50:53]
	v_mfma_f32_16x16x32_bf16 v[38:41], v[172:175], v[196:199], v[38:41]
	v_mfma_f32_16x16x32_bf16 v[34:37], v[180:183], v[196:199], v[34:37]
	v_mfma_f32_16x16x32_bf16 v[22:25], v[172:175], v[204:207], v[22:25]
	v_mfma_f32_16x16x32_bf16 v[18:21], v[180:183], v[204:207], v[18:21]
	v_mfma_f32_16x16x32_bf16 v[6:9], v[172:175], v[212:215], v[6:9]
	v_mfma_f32_16x16x32_bf16 v[2:5], v[180:183], v[212:215], v[2:5]
	s_setprio 2
	s_barrier
	s_movk_i32 s38, 0x100
	s_andn2_b64 vcc, exec, s[4:5]
	s_mov_b64 s[10:11], -1
	s_mov_b64 s[4:5], 0
	s_cbranch_vccz .LBB0_476
	s_and_b64 vcc, exec, s[44:45]
	s_cbranch_vccz .LBB0_479
	s_barrier

; #define PG8_STAGE(bufoff, gbase, voff) do { _Pragma("unroll") for (int _i = 0; _i < 2; ++_i) \
;         __builtin_amdgcn_global_load_lds((const unsigned*)((const char*)(gbase) + (voff)[_i]), (LAS unsigned*)(lds + (bufoff) + ldsw + _i * 8192), 16, 0, 0); } while (0)
; #define PG8_LDA(dst, b, h) do { _Pragma("unroll") for (int m = 0; m < 4; ++m) _Pragma("unroll") for (int k = 0; k < 2; ++k) dst[m][k] = *(const LAS bf16x8*)(lds + PG8_SA(b, h) + aoff + m * 2048 + k * 1024); } while (0)
; #define PG8_LDB(dst, b, h) do { _Pragma("unroll") for (int n = 0; n < 2; ++n) _Pragma("unroll") for (int k = 0; k < 2; ++k) dst[n][k] = *(const LAS bf16x8*)(lds + PG8_SB(b, h) + boff + n * 2048 + k * 1024); } while (0)
; #define PG8_MMA(ai, bj, At, Bt) do { __builtin_amdgcn_s_setprio(1); _Pragma("unroll") for (int m = 0; m < 4; ++m) _Pragma("unroll") for (int n = 0; n < 2; ++n) _Pragma("unroll") for (int k = 0; k < 2; ++k) \
;         acc[ai][bj][m][n] = __builtin_amdgcn_mfma_f32_16x16x32_bf16(Bt[n][k], At[m][k], acc[ai][bj][m][n], 0, 0, 0); __builtin_amdgcn_s_setprio(0); } while (0)
; #define PG8_WAIT_V(n) asm volatile("s_waitcnt vmcnt(" #n ")" ::: "memory")
; #define PG8_WAIT_L(n) asm volatile("s_waitcnt lgkmcnt(" #n ")" ::: "memory")
; #define PG8_BAR __builtin_amdgcn_s_barrier()
; #define PG8_SCHED __builtin_amdgcn_sched_barrier(0)
; template <class Epi>
; __device__ __forceinline__ void gemm_phase(LAS unsigned char* lds, const Gemm g, int G, int c, const Epi& E) {
;     ...
;             const char* a2 = last ? nA : cA + (size_t)(t + 2) * kstep; const char* b2 = last ? nB : cB + (size_t)(t + 2) * kstep;
;             const char* a3 = a2 + kstep; const char* b3 = b2 + kstep;
;             PG8_LDB(B0, 0, 0); PG8_LDB(B1, 0, 1); PG8_SCHED; PG8_LDA(At, 0, 0); PG8_STAGE(PG8_SA(1, 1), a1 + hstepA, voffA);
;             PG8_WAIT_V(8); PG8_WAIT_L(0); PG8_BAR; PG8_MMA(0, 0, At, B0); PG8_MMA(0, 1, At, B1); PG8_BAR; PG8_SCHED;
;             PG8_LDA(At, 0, 1); PG8_STAGE(PG8_SB(0, 0), b2, voffB); PG8_STAGE(PG8_SB(0, 1), b2 + hstepB, voffB); PG8_STAGE(PG8_SA(0, 0), a2, voffA);
;             PG8_WAIT_V(8); PG8_WAIT_L(0); PG8_BAR; PG8_MMA(1, 0, At, B0); PG8_MMA(1, 1, At, B1); PG8_BAR; PG8_SCHED;
.LBB0_594:
	s_add_u32 s33, s8, s38
	s_addc_u32 s62, s9, 0
	s_add_u32 s39, s33, 0x100
	s_addc_u32 s58, s62, 0
	s_and_b64 s[56:57], s[54:55], exec
	s_cselect_b32 s59, s45, s58
	s_cselect_b32 s58, s44, s39
	s_add_u32 s38, s6, s38
	s_addc_u32 s39, s7, 0
	s_add_u32 s56, s38, 0x100
	s_addc_u32 s57, s39, 0
	s_and_b64 s[38:39], s[54:55], exec
	s_cselect_b32 s61, s47, s57
	s_cselect_b32 s60, s46, s56
	s_add_u32 s68, s33, 0xb0080
	s_addc_u32 s69, s62, 0
	s_add_i32 s63, s86, s23
	s_add_i32 m0, s72, 0xc000
	s_add_i32 s64, s72, 0xe000
	v_lshl_add_u64 v[162:163], s[68:69], 0, v[136:137]
	global_load_lds_dwordx4 v[162:163], off
	v_lshl_add_u64 v[162:163], s[68:69], 0, v[132:133]
	s_mov_b32 m0, s64
	s_nop 0
	global_load_lds_dwordx4 v[162:163], off
	ds_read_b128 v[142:145], v166
	ds_read_b128 v[146:149], v166 offset:1024
	ds_read_b128 v[150:153], v166 offset:2048
	ds_read_b128 v[154:157], v166 offset:3072
	ds_read_b128 v[158:161], v167
	ds_read_b128 v[170:173], v167 offset:1024
	ds_read_b128 v[174:177], v167 offset:2048
	ds_read_b128 v[178:181], v167 offset:3072
	s_add_i32 s74, s63, 0x2000
	s_add_u32 s66, s60, 0xb0000
	s_addc_u32 s67, s61, 0
	s_add_i32 s62, s87, s23
	s_add_i32 s75, s62, 0x2000
	s_add_i32 s97, 0, 0x18000
	s_add_i32 s33, 0, 0x1c000
	s_add_u32 s56, s58, 0xb0000
	s_addc_u32 s57, s59, 0
	s_add_i32 s96, s97, s23
	s_add_i32 s39, s96, 0x2000
	s_add_u32 s54, s60, 0xb0080
	s_addc_u32 s55, s61, 0
	s_add_i32 s95, s33, s23
	s_add_i32 s38, s95, 0x2000
	ds_read_b128 v[182:185], v168
	ds_read_b128 v[186:189], v168 offset:1024
	ds_read_b128 v[190:193], v168 offset:2048
	ds_read_b128 v[194:197], v168 offset:3072
	ds_read_b128 v[198:201], v168 offset:4096
	ds_read_b128 v[202:205], v168 offset:5120
	ds_read_b128 v[206:209], v168 offset:6144
	ds_read_b128 v[210:213], v168 offset:7168
	s_waitcnt vmcnt(8)
	s_waitcnt lgkmcnt(0)
	s_barrier
	s_setprio 0
	s_waitcnt lgkmcnt(0)
	v_mfma_f32_16x16x32_bf16 v[126:129], v[142:145], v[182:185], v[126:129]
	v_mfma_f32_16x16x32_bf16 v[122:125], v[150:153], v[182:185], v[122:125]
	v_mfma_f32_16x16x32_bf16 v[110:113], v[142:145], v[190:193], v[110:113]
	v_mfma_f32_16x16x32_bf16 v[106:109], v[150:153], v[190:193], v[106:109]
	v_mfma_f32_16x16x32_bf16 v[94:97], v[142:145], v[198:201], v[94:97]
	v_mfma_f32_16x16x32_bf16 v[90:93], v[150:153], v[198:201], v[90:93]
	v_mfma_f32_16x16x32_bf16 v[78:81], v[142:145], v[206:209], v[78:81]
	v_mfma_f32_16x16x32_bf16 v[74:77], v[150:153], v[206:209], v[74:77]
	v_mfma_f32_16x16x32_bf16 v[126:129], v[146:149], v[186:189], v[126:129]
	v_mfma_f32_16x16x32_bf16 v[122:125], v[154:157], v[186:189], v[122:125]
	v_mfma_f32_16x16x32_bf16 v[110:113], v[146:149], v[194:197], v[110:113]
	v_mfma_f32_16x16x32_bf16 v[106:109], v[154:157], v[194:197], v[106:109]
	v_mfma_f32_16x16x32_bf16 v[94:97], v[146:149], v[202:205], v[94:97]
	v_mfma_f32_16x16x32_bf16 v[90:93], v[154:157], v[202:205], v[90:93]
	v_mfma_f32_16x16x32_bf16 v[78:81], v[146:149], v[210:213], v[78:81]
	v_mfma_f32_16x16x32_bf16 v[74:77], v[154:157], v[210:213], v[74:77]
	s_setprio 2
	s_setprio 0
	v_mfma_f32_16x16x32_bf16 v[118:121], v[158:161], v[182:185], v[118:121]
	v_mfma_f32_16x16x32_bf16 v[114:117], v[174:177], v[182:185], v[114:117]
	v_mfma_f32_16x16x32_bf16 v[102:105], v[158:161], v[190:193], v[102:105]
	v_mfma_f32_16x16x32_bf16 v[98:101], v[174:177], v[190:193], v[98:101]
	v_mfma_f32_16x16x32_bf16 v[86:89], v[158:161], v[198:201], v[86:89]
	v_mfma_f32_16x16x32_bf16 v[82:85], v[174:177], v[198:201], v[82:85]
	v_mfma_f32_16x16x32_bf16 v[70:73], v[158:161], v[206:209], v[70:73]
	v_mfma_f32_16x16x32_bf16 v[66:69], v[174:177], v[206:209], v[66:69]
	v_mfma_f32_16x16x32_bf16 v[118:121], v[170:173], v[186:189], v[118:121]
	v_mfma_f32_16x16x32_bf16 v[114:117], v[178:181], v[186:189], v[114:117]
	v_mfma_f32_16x16x32_bf16 v[102:105], v[170:173], v[194:197], v[102:105]
	v_mfma_f32_16x16x32_bf16 v[98:101], v[178:181], v[194:197], v[98:101]
	v_mfma_f32_16x16x32_bf16 v[86:89], v[170:173], v[202:205], v[86:89]
	v_mfma_f32_16x16x32_bf16 v[82:85], v[178:181], v[202:205], v[82:85]
	v_mfma_f32_16x16x32_bf16 v[70:73], v[170:173], v[210:213], v[70:73]
	v_mfma_f32_16x16x32_bf16 v[66:69], v[178:181], v[210:213], v[66:69]
	s_setprio 2
	s_barrier
	s_mov_b32 m0, s63
	v_lshl_add_u64 v[162:163], s[60:61], 0, v[134:135]
	global_load_lds_dwordx4 v[162:163], off
	v_lshl_add_u64 v[214:215], s[60:61], 0, v[130:131]
	s_mov_b32 m0, s74
	v_lshl_add_u64 v[216:217], s[66:67], 0, v[134:135]
	global_load_lds_dwordx4 v[214:215], off
	s_mov_b32 m0, s62
	v_lshl_add_u64 v[218:219], s[58:59], 0, v[132:133]
	global_load_lds_dwordx4 v[216:217], off
	v_lshl_add_u64 v[216:217], s[66:67], 0, v[130:131]
	s_mov_b32 m0, s75
	s_nop 0
	global_load_lds_dwordx4 v[216:217], off
	v_lshl_add_u64 v[216:217], s[58:59], 0, v[136:137]
	s_mov_b32 m0, s72
	s_nop 0
	global_load_lds_dwordx4 v[216:217], off
	s_mov_b32 m0, s73
	s_nop 0
	global_load_lds_dwordx4 v[218:219], off
	ds_read_b128 v[182:185], v168 offset:16384
	ds_read_b128 v[186:189], v168 offset:17408
	ds_read_b128 v[190:193], v168 offset:18432
	ds_read_b128 v[194:197], v168 offset:19456
	ds_read_b128 v[198:201], v168 offset:20480
	ds_read_b128 v[202:205], v168 offset:21504
	ds_read_b128 v[206:209], v168 offset:22528
	ds_read_b128 v[210:213], v168 offset:23552
	s_waitcnt vmcnt(8)
	s_waitcnt lgkmcnt(0)
	s_barrier
; #define PG8_STAGE(bufoff, gbase, voff) do { _Pragma("unroll") for (int _i = 0; _i < 2; ++_i) \
;         __builtin_amdgcn_global_load_lds((const unsigned*)((const char*)(gbase) + (voff)[_i]), (LAS unsigned*)(lds + (bufoff) + ldsw + _i * 8192), 16, 0, 0); } while (0)
; #define PG8_LDA(dst, b, h) do { _Pragma("unroll") for (int m = 0; m < 4; ++m) _Pragma("unroll") for (int k = 0; k < 2; ++k) dst[m][k] = *(const LAS bf16x8*)(lds + PG8_SA(b, h) + aoff + m * 2048 + k * 1024); } while (0)
; #define PG8_LDB(dst, b, h) do { _Pragma("unroll") for (int n = 0; n < 2; ++n) _Pragma("unroll") for (int k = 0; k < 2; ++k) dst[n][k] = *(const LAS bf16x8*)(lds + PG8_SB(b, h) + boff + n * 2048 + k * 1024); } while (0)
; #define PG8_MMA(ai, bj, At, Bt) do { __builtin_amdgcn_s_setprio(1); _Pragma("unroll") for (int m = 0; m < 4; ++m) _Pragma("unroll") for (int n = 0; n < 2; ++n) _Pragma("unroll") for (int k = 0; k < 2; ++k) \
;         acc[ai][bj][m][n] = __builtin_amdgcn_mfma_f32_16x16x32_bf16(Bt[n][k], At[m][k], acc[ai][bj][m][n], 0, 0, 0); __builtin_amdgcn_s_setprio(0); } while (0)
; #define PG8_WAIT_V(n) asm volatile("s_waitcnt vmcnt(" #n ")" ::: "memory")
; #define PG8_WAIT_L(n) asm volatile("s_waitcnt lgkmcnt(" #n ")" ::: "memory")
; #define PG8_BAR __builtin_amdgcn_s_barrier()
; #define PG8_SCHED __builtin_amdgcn_sched_barrier(0)
; template <class Epi>
; __device__ __forceinline__ void gemm_phase(LAS unsigned char* lds, const Gemm g, int G, int c, const Epi& E) {
;     ...
;             PG8_WAIT_V(8); PG8_WAIT_L(0); PG8_BAR; PG8_MMA(1, 0, At, B0); PG8_MMA(1, 1, At, B1); PG8_BAR; PG8_SCHED;
;             PG8_LDB(B0, 1, 0); PG8_LDB(B1, 1, 1); PG8_SCHED; PG8_LDA(At, 1, 0); PG8_STAGE(PG8_SA(0, 1), a2 + hstepA, voffA);
;             PG8_WAIT_V(8); PG8_WAIT_L(0); PG8_BAR; PG8_MMA(0, 0, At, B0); PG8_MMA(0, 1, At, B1); PG8_BAR; PG8_SCHED;
	s_setprio 0
	s_waitcnt lgkmcnt(0)
	v_mfma_f32_16x16x32_bf16 v[62:65], v[142:145], v[182:185], v[62:65]
	v_mfma_f32_16x16x32_bf16 v[58:61], v[150:153], v[182:185], v[58:61]
	v_mfma_f32_16x16x32_bf16 v[46:49], v[142:145], v[190:193], v[46:49]
	v_mfma_f32_16x16x32_bf16 v[42:45], v[150:153], v[190:193], v[42:45]
	v_mfma_f32_16x16x32_bf16 v[30:33], v[142:145], v[198:201], v[30:33]
	v_mfma_f32_16x16x32_bf16 v[26:29], v[150:153], v[198:201], v[26:29]
	v_mfma_f32_16x16x32_bf16 v[14:17], v[142:145], v[206:209], v[14:17]
	v_mfma_f32_16x16x32_bf16 v[10:13], v[150:153], v[206:209], v[10:13]
	v_mfma_f32_16x16x32_bf16 v[62:65], v[146:149], v[186:189], v[62:65]
	v_mfma_f32_16x16x32_bf16 v[58:61], v[154:157], v[186:189], v[58:61]
	v_mfma_f32_16x16x32_bf16 v[46:49], v[146:149], v[194:197], v[46:49]
	v_mfma_f32_16x16x32_bf16 v[42:45], v[154:157], v[194:197], v[42:45]
	v_mfma_f32_16x16x32_bf16 v[30:33], v[146:149], v[202:205], v[30:33]
	v_mfma_f32_16x16x32_bf16 v[26:29], v[154:157], v[202:205], v[26:29]
	v_mfma_f32_16x16x32_bf16 v[14:17], v[146:149], v[210:213], v[14:17]
	v_mfma_f32_16x16x32_bf16 v[10:13], v[154:157], v[210:213], v[10:13]
	s_setprio 2
	s_setprio 0
	v_mfma_f32_16x16x32_bf16 v[54:57], v[158:161], v[182:185], v[54:57]
	v_mfma_f32_16x16x32_bf16 v[50:53], v[174:177], v[182:185], v[50:53]
	v_mfma_f32_16x16x32_bf16 v[38:41], v[158:161], v[190:193], v[38:41]
	v_mfma_f32_16x16x32_bf16 v[34:37], v[174:177], v[190:193], v[34:37]
	v_mfma_f32_16x16x32_bf16 v[22:25], v[158:161], v[198:201], v[22:25]
	v_mfma_f32_16x16x32_bf16 v[18:21], v[174:177], v[198:201], v[18:21]
	v_mfma_f32_16x16x32_bf16 v[6:9], v[158:161], v[206:209], v[6:9]
	v_mfma_f32_16x16x32_bf16 v[2:5], v[174:177], v[206:209], v[2:5]
	v_mfma_f32_16x16x32_bf16 v[54:57], v[170:173], v[186:189], v[54:57]
	v_mfma_f32_16x16x32_bf16 v[50:53], v[178:181], v[186:189], v[50:53]
	v_mfma_f32_16x16x32_bf16 v[38:41], v[170:173], v[194:197], v[38:41]
	v_mfma_f32_16x16x32_bf16 v[34:37], v[178:181], v[194:197], v[34:37]
	v_mfma_f32_16x16x32_bf16 v[22:25], v[170:173], v[202:205], v[22:25]
	v_mfma_f32_16x16x32_bf16 v[18:21], v[178:181], v[202:205], v[18:21]
	v_mfma_f32_16x16x32_bf16 v[6:9], v[170:173], v[210:213], v[6:9]
	v_mfma_f32_16x16x32_bf16 v[2:5], v[178:181], v[210:213], v[2:5]
	s_setprio 2
	s_barrier
	s_mov_b32 m0, s78
	v_lshl_add_u64 v[220:221], s[56:57], 0, v[136:137]
	global_load_lds_dwordx4 v[220:221], off
	v_lshl_add_u64 v[220:221], s[56:57], 0, v[132:133]
	s_mov_b32 m0, s81
	s_nop 0
	global_load_lds_dwordx4 v[220:221], off
	v_add_u32_e32 v154, s97, v165
	v_add_u32_e32 v178, s33, v165
	ds_read_b128 v[142:145], v154
	ds_read_b128 v[146:149], v154 offset:1024
	ds_read_b128 v[150:153], v154 offset:2048
	ds_read_b128 v[154:157], v154 offset:3072
	ds_read_b128 v[158:161], v178
	ds_read_b128 v[170:173], v178 offset:1024
	ds_read_b128 v[174:177], v178 offset:2048
	ds_read_b128 v[178:181], v178 offset:3072
	ds_read_b128 v[182:185], v168 offset:32768
	ds_read_b128 v[186:189], v168 offset:33792
	ds_read_b128 v[190:193], v168 offset:34816
	ds_read_b128 v[194:197], v168 offset:35840
	ds_read_b128 v[198:201], v168 offset:36864
	ds_read_b128 v[202:205], v168 offset:37888
	ds_read_b128 v[206:209], v168 offset:38912
	ds_read_b128 v[210:213], v168 offset:39936
	s_waitcnt vmcnt(8)
	s_waitcnt lgkmcnt(0)
	s_barrier
	s_setprio 0
	s_waitcnt lgkmcnt(0)
	v_mfma_f32_16x16x32_bf16 v[126:129], v[142:145], v[182:185], v[126:129]
	v_mfma_f32_16x16x32_bf16 v[122:125], v[150:153], v[182:185], v[122:125]
	v_mfma_f32_16x16x32_bf16 v[110:113], v[142:145], v[190:193], v[110:113]
	v_mfma_f32_16x16x32_bf16 v[106:109], v[150:153], v[190:193], v[106:109]
	v_mfma_f32_16x16x32_bf16 v[94:97], v[142:145], v[198:201], v[94:97]
	v_mfma_f32_16x16x32_bf16 v[90:93], v[150:153], v[198:201], v[90:93]
	v_mfma_f32_16x16x32_bf16 v[78:81], v[142:145], v[206:209], v[78:81]
	v_mfma_f32_16x16x32_bf16 v[74:77], v[150:153], v[206:209], v[74:77]
	v_mfma_f32_16x16x32_bf16 v[126:129], v[146:149], v[186:189], v[126:129]
	v_mfma_f32_16x16x32_bf16 v[122:125], v[154:157], v[186:189], v[122:125]
	v_mfma_f32_16x16x32_bf16 v[110:113], v[146:149], v[194:197], v[110:113]
	v_mfma_f32_16x16x32_bf16 v[106:109], v[154:157], v[194:197], v[106:109]
	v_mfma_f32_16x16x32_bf16 v[94:97], v[146:149], v[202:205], v[94:97]
	v_mfma_f32_16x16x32_bf16 v[90:93], v[154:157], v[202:205], v[90:93]
	v_mfma_f32_16x16x32_bf16 v[78:81], v[146:149], v[210:213], v[78:81]
	v_mfma_f32_16x16x32_bf16 v[74:77], v[154:157], v[210:213], v[74:77]
	s_setprio 2
	s_setprio 0
	v_mfma_f32_16x16x32_bf16 v[118:121], v[158:161], v[182:185], v[118:121]
	v_mfma_f32_16x16x32_bf16 v[114:117], v[174:177], v[182:185], v[114:117]
	v_mfma_f32_16x16x32_bf16 v[102:105], v[158:161], v[190:193], v[102:105]
	v_mfma_f32_16x16x32_bf16 v[98:101], v[174:177], v[190:193], v[98:101]
	v_mfma_f32_16x16x32_bf16 v[86:89], v[158:161], v[198:201], v[86:89]
	v_mfma_f32_16x16x32_bf16 v[82:85], v[174:177], v[198:201], v[82:85]
	v_mfma_f32_16x16x32_bf16 v[70:73], v[158:161], v[206:209], v[70:73]
	v_mfma_f32_16x16x32_bf16 v[66:69], v[174:177], v[206:209], v[66:69]
	v_mfma_f32_16x16x32_bf16 v[118:121], v[170:173], v[186:189], v[118:121]
	v_mfma_f32_16x16x32_bf16 v[114:117], v[178:181], v[186:189], v[114:117]
	v_mfma_f32_16x16x32_bf16 v[102:105], v[170:173], v[194:197], v[102:105]
	v_mfma_f32_16x16x32_bf16 v[98:101], v[178:181], v[194:197], v[98:101]
	v_mfma_f32_16x16x32_bf16 v[86:89], v[170:173], v[202:205], v[86:89]
	v_mfma_f32_16x16x32_bf16 v[82:85], v[178:181], v[202:205], v[82:85]
	v_mfma_f32_16x16x32_bf16 v[70:73], v[170:173], v[210:213], v[70:73]
	v_mfma_f32_16x16x32_bf16 v[66:69], v[178:181], v[210:213], v[66:69]
	s_setprio 2
	s_barrier
; #define PG8_STAGE(bufoff, gbase, voff) do { _Pragma("unroll") for (int _i = 0; _i < 2; ++_i) \
;         __builtin_amdgcn_global_load_lds((const unsigned*)((const char*)(gbase) + (voff)[_i]), (LAS unsigned*)(lds + (bufoff) + ldsw + _i * 8192), 16, 0, 0); } while (0)
; #define PG8_LDA(dst, b, h) do { _Pragma("unroll") for (int m = 0; m < 4; ++m) _Pragma("unroll") for (int k = 0; k < 2; ++k) dst[m][k] = *(const LAS bf16x8*)(lds + PG8_SA(b, h) + aoff + m * 2048 + k * 1024); } while (0)
; #define PG8_MMA(ai, bj, At, Bt) do { __builtin_amdgcn_s_setprio(1); _Pragma("unroll") for (int m = 0; m < 4; ++m) _Pragma("unroll") for (int n = 0; n < 2; ++n) _Pragma("unroll") for (int k = 0; k < 2; ++k) \
;         acc[ai][bj][m][n] = __builtin_amdgcn_mfma_f32_16x16x32_bf16(Bt[n][k], At[m][k], acc[ai][bj][m][n], 0, 0, 0); __builtin_amdgcn_s_setprio(0); } while (0)
; #define PG8_WAIT_V(n) asm volatile("s_waitcnt vmcnt(" #n ")" ::: "memory")
; #define PG8_WAIT_L(n) asm volatile("s_waitcnt lgkmcnt(" #n ")" ::: "memory")
; #define PG8_BAR __builtin_amdgcn_s_barrier()
; #define PG8_SCHED __builtin_amdgcn_sched_barrier(0)
; template <class Epi>
; __device__ __forceinline__ void gemm_phase(LAS unsigned char* lds, const Gemm g, int G, int c, const Epi& E) {
;     ...
;             PG8_LDA(At, 1, 1); PG8_STAGE(PG8_SB(1, 0), b3, voffB); PG8_STAGE(PG8_SB(1, 1), b3 + hstepB, voffB); PG8_STAGE(PG8_SA(1, 0), a3, voffA);
;             PG8_WAIT_V(8); PG8_WAIT_L(0); PG8_BAR; PG8_MMA(1, 0, At, B0); PG8_MMA(1, 1, At, B1); PG8_BAR; PG8_SCHED;
;         }
;         if (wr == 0) PG8_BAR;
	s_mov_b32 m0, s96
	v_lshl_add_u64 v[162:163], v[162:163], 0, s[18:19]
	global_load_lds_dwordx4 v[162:163], off
	v_lshl_add_u64 v[162:163], v[214:215], 0, s[18:19]
	s_mov_b32 m0, s39
	s_nop 0
	global_load_lds_dwordx4 v[162:163], off
	v_lshl_add_u64 v[162:163], s[54:55], 0, v[134:135]
	s_mov_b32 m0, s95
	s_nop 0
	global_load_lds_dwordx4 v[162:163], off
	v_lshl_add_u64 v[162:163], s[54:55], 0, v[130:131]
	s_mov_b32 m0, s38
	s_nop 0
	global_load_lds_dwordx4 v[162:163], off
	v_lshl_add_u64 v[162:163], v[216:217], 0, s[18:19]
	s_mov_b32 m0, s84
	s_nop 0
	global_load_lds_dwordx4 v[162:163], off
	v_lshl_add_u64 v[162:163], v[218:219], 0, s[18:19]
	s_mov_b32 m0, s85
	s_nop 0
	global_load_lds_dwordx4 v[162:163], off
	ds_read_b128 v[182:185], v168 offset:49152
	ds_read_b128 v[186:189], v168 offset:50176
	ds_read_b128 v[190:193], v168 offset:51200
	ds_read_b128 v[194:197], v168 offset:52224
	ds_read_b128 v[198:201], v168 offset:53248
	ds_read_b128 v[202:205], v168 offset:54272
	ds_read_b128 v[206:209], v168 offset:55296
	ds_read_b128 v[210:213], v168 offset:56320
	s_waitcnt vmcnt(8)
	s_waitcnt lgkmcnt(0)
	s_barrier
	s_setprio 0
	s_waitcnt lgkmcnt(0)
	v_mfma_f32_16x16x32_bf16 v[62:65], v[142:145], v[182:185], v[62:65]
	v_mfma_f32_16x16x32_bf16 v[58:61], v[150:153], v[182:185], v[58:61]
	v_mfma_f32_16x16x32_bf16 v[46:49], v[142:145], v[190:193], v[46:49]
	v_mfma_f32_16x16x32_bf16 v[42:45], v[150:153], v[190:193], v[42:45]
	v_mfma_f32_16x16x32_bf16 v[30:33], v[142:145], v[198:201], v[30:33]
	v_mfma_f32_16x16x32_bf16 v[26:29], v[150:153], v[198:201], v[26:29]
	v_mfma_f32_16x16x32_bf16 v[14:17], v[142:145], v[206:209], v[14:17]
	v_mfma_f32_16x16x32_bf16 v[10:13], v[150:153], v[206:209], v[10:13]
	v_mfma_f32_16x16x32_bf16 v[62:65], v[146:149], v[186:189], v[62:65]
	v_mfma_f32_16x16x32_bf16 v[58:61], v[154:157], v[186:189], v[58:61]
	v_mfma_f32_16x16x32_bf16 v[46:49], v[146:149], v[194:197], v[46:49]
	v_mfma_f32_16x16x32_bf16 v[42:45], v[154:157], v[194:197], v[42:45]
	v_mfma_f32_16x16x32_bf16 v[30:33], v[146:149], v[202:205], v[30:33]
	v_mfma_f32_16x16x32_bf16 v[26:29], v[154:157], v[202:205], v[26:29]
	v_mfma_f32_16x16x32_bf16 v[14:17], v[146:149], v[210:213], v[14:17]
	v_mfma_f32_16x16x32_bf16 v[10:13], v[154:157], v[210:213], v[10:13]
	s_setprio 2
	s_setprio 0
	v_mfma_f32_16x16x32_bf16 v[54:57], v[158:161], v[182:185], v[54:57]
	v_mfma_f32_16x16x32_bf16 v[50:53], v[174:177], v[182:185], v[50:53]
	v_mfma_f32_16x16x32_bf16 v[38:41], v[158:161], v[190:193], v[38:41]
	v_mfma_f32_16x16x32_bf16 v[34:37], v[174:177], v[190:193], v[34:37]
	v_mfma_f32_16x16x32_bf16 v[22:25], v[158:161], v[198:201], v[22:25]
	v_mfma_f32_16x16x32_bf16 v[18:21], v[174:177], v[198:201], v[18:21]
	v_mfma_f32_16x16x32_bf16 v[6:9], v[158:161], v[206:209], v[6:9]
	v_mfma_f32_16x16x32_bf16 v[2:5], v[174:177], v[206:209], v[2:5]
	v_mfma_f32_16x16x32_bf16 v[54:57], v[170:173], v[186:189], v[54:57]
	v_mfma_f32_16x16x32_bf16 v[50:53], v[178:181], v[186:189], v[50:53]
	v_mfma_f32_16x16x32_bf16 v[38:41], v[170:173], v[194:197], v[38:41]
	v_mfma_f32_16x16x32_bf16 v[34:37], v[178:181], v[194:197], v[34:37]
	v_mfma_f32_16x16x32_bf16 v[22:25], v[170:173], v[202:205], v[22:25]
	v_mfma_f32_16x16x32_bf16 v[18:21], v[178:181], v[202:205], v[18:21]
	v_mfma_f32_16x16x32_bf16 v[6:9], v[170:173], v[210:213], v[6:9]
	v_mfma_f32_16x16x32_bf16 v[2:5], v[178:181], v[210:213], v[2:5]
	s_setprio 2
	s_barrier
	s_movk_i32 s38, 0x100
	s_andn2_b64 vcc, exec, s[4:5]
	s_mov_b64 s[54:55], -1
	s_mov_b64 s[4:5], 0
	s_cbranch_vccz .LBB0_594
	s_and_b64 vcc, exec, s[20:21]
	s_cbranch_vccz .LBB0_597
	s_barrier

; #define PG8_STAGE(bufoff, gbase, voff) do { _Pragma("unroll") for (int _i = 0; _i < 2; ++_i) \
;         __builtin_amdgcn_global_load_lds((const unsigned*)((const char*)(gbase) + (voff)[_i]), (LAS unsigned*)(lds + (bufoff) + ldsw + _i * 8192), 16, 0, 0); } while (0)
; #define PG8_LDA(dst, b, h) do { _Pragma("unroll") for (int m = 0; m < 4; ++m) _Pragma("unroll") for (int k = 0; k < 2; ++k) dst[m][k] = *(const LAS bf16x8*)(lds + PG8_SA(b, h) + aoff + m * 2048 + k * 1024); } while (0)
; #define PG8_LDB(dst, b, h) do { _Pragma("unroll") for (int n = 0; n < 2; ++n) _Pragma("unroll") for (int k = 0; k < 2; ++k) dst[n][k] = *(const LAS bf16x8*)(lds + PG8_SB(b, h) + boff + n * 2048 + k * 1024); } while (0)
; #define PG8_MMA(ai, bj, At, Bt) do { __builtin_amdgcn_s_setprio(1); _Pragma("unroll") for (int m = 0; m < 4; ++m) _Pragma("unroll") for (int n = 0; n < 2; ++n) _Pragma("unroll") for (int k = 0; k < 2; ++k) \
;         acc[ai][bj][m][n] = __builtin_amdgcn_mfma_f32_16x16x32_bf16(Bt[n][k], At[m][k], acc[ai][bj][m][n], 0, 0, 0); __builtin_amdgcn_s_setprio(0); } while (0)
; #define PG8_WAIT_V(n) asm volatile("s_waitcnt vmcnt(" #n ")" ::: "memory")
; #define PG8_WAIT_L(n) asm volatile("s_waitcnt lgkmcnt(" #n ")" ::: "memory")
; #define PG8_BAR __builtin_amdgcn_s_barrier()
; #define PG8_SCHED __builtin_amdgcn_sched_barrier(0)
; template <class Epi>
; __device__ __forceinline__ void gemm_phase(LAS unsigned char* lds, const Gemm g, int G, int c, const Epi& E) {
;     ...
;             const char* a1 = cA + (size_t)(t + 1) * kstep;
;             const char* a2 = last ? nA : cA + (size_t)(t + 2) * kstep; const char* b2 = last ? nB : cB + (size_t)(t + 2) * kstep;
;             const char* a3 = a2 + kstep; const char* b3 = b2 + kstep;
;             PG8_LDB(B0, 0, 0); PG8_LDB(B1, 0, 1); PG8_SCHED; PG8_LDA(At, 0, 0); PG8_STAGE(PG8_SA(1, 1), a1 + hstepA, voffA);
;             PG8_WAIT_V(8); PG8_WAIT_L(0); PG8_BAR; PG8_MMA(0, 0, At, B0); PG8_MMA(0, 1, At, B1); PG8_BAR; PG8_SCHED;
;             PG8_LDA(At, 0, 1); PG8_STAGE(PG8_SB(0, 0), b2, voffB); PG8_STAGE(PG8_SB(0, 1), b2 + hstepB, voffB); PG8_STAGE(PG8_SA(0, 0), a2, voffA);
;             PG8_WAIT_V(8); PG8_WAIT_L(0); PG8_BAR; PG8_MMA(1, 0, At, B0); PG8_MMA(1, 1, At, B1); PG8_BAR; PG8_SCHED;
.LBB0_765:
	s_add_u32 s33, s44, 0xfff00080
	s_addc_u32 s46, s45, -1
	s_cmp_eq_u32 s83, 60
	s_cselect_b32 s53, s15, s46
	s_cselect_b32 s52, s78, s33
	s_cselect_b32 s47, s11, s82
	s_cselect_b32 s46, s13, s81
	v_lshl_add_u64 v[216:217], s[44:45], 0, v[138:139]
	s_add_i32 m0, s17, 0xc000
	s_nop 0
	global_load_lds_dwordx4 v[216:217], off
	v_lshl_add_u64 v[216:217], s[44:45], 0, v[140:141]
	s_add_i32 m0, s17, 0xe000
	s_nop 0
	global_load_lds_dwordx4 v[216:217], off
	ds_read_b128 v[146:149], v152
	ds_read_b128 v[156:159], v152 offset:1024
	ds_read_b128 v[160:163], v152 offset:2048
	ds_read_b128 v[164:167], v152 offset:3072
	ds_read_b128 v[168:171], v153
	ds_read_b128 v[172:175], v153 offset:1024
	ds_read_b128 v[176:179], v153 offset:2048
	ds_read_b128 v[180:183], v153 offset:3072
	ds_read_b128 v[184:187], v154
	ds_read_b128 v[188:191], v154 offset:1024
	ds_read_b128 v[192:195], v154 offset:2048
	ds_read_b128 v[196:199], v154 offset:3072
	ds_read_b128 v[200:203], v154 offset:4096
	ds_read_b128 v[204:207], v154 offset:5120
	ds_read_b128 v[208:211], v154 offset:6144
	ds_read_b128 v[212:215], v154 offset:7168
	s_waitcnt vmcnt(8)
	s_waitcnt lgkmcnt(0)
	s_barrier
	s_setprio 0
	s_waitcnt lgkmcnt(0)
	v_mfma_f32_16x16x32_bf16 v[126:129], v[146:149], v[184:187], v[126:129]
	v_mfma_f32_16x16x32_bf16 v[122:125], v[160:163], v[184:187], v[122:125]
	v_mfma_f32_16x16x32_bf16 v[118:121], v[146:149], v[192:195], v[118:121]
	v_mfma_f32_16x16x32_bf16 v[110:113], v[160:163], v[192:195], v[110:113]
	v_mfma_f32_16x16x32_bf16 v[102:105], v[146:149], v[200:203], v[102:105]
	v_mfma_f32_16x16x32_bf16 v[94:97], v[160:163], v[200:203], v[94:97]
	v_mfma_f32_16x16x32_bf16 v[86:89], v[146:149], v[208:211], v[86:89]
	v_mfma_f32_16x16x32_bf16 v[78:81], v[160:163], v[208:211], v[78:81]
	v_mfma_f32_16x16x32_bf16 v[126:129], v[156:159], v[188:191], v[126:129]
	v_mfma_f32_16x16x32_bf16 v[122:125], v[164:167], v[188:191], v[122:125]
	v_mfma_f32_16x16x32_bf16 v[118:121], v[156:159], v[196:199], v[118:121]
	v_mfma_f32_16x16x32_bf16 v[110:113], v[164:167], v[196:199], v[110:113]
	v_mfma_f32_16x16x32_bf16 v[102:105], v[156:159], v[204:207], v[102:105]
	v_mfma_f32_16x16x32_bf16 v[94:97], v[164:167], v[204:207], v[94:97]
	v_mfma_f32_16x16x32_bf16 v[86:89], v[156:159], v[212:215], v[86:89]
	v_mfma_f32_16x16x32_bf16 v[78:81], v[164:167], v[212:215], v[78:81]
	s_setprio 2
	s_setprio 0
	v_mfma_f32_16x16x32_bf16 v[114:117], v[168:171], v[184:187], v[114:117]
	v_mfma_f32_16x16x32_bf16 v[106:109], v[176:179], v[184:187], v[106:109]
	v_mfma_f32_16x16x32_bf16 v[98:101], v[168:171], v[192:195], v[98:101]
	v_mfma_f32_16x16x32_bf16 v[90:93], v[176:179], v[192:195], v[90:93]
	v_mfma_f32_16x16x32_bf16 v[82:85], v[168:171], v[200:203], v[82:85]
	v_mfma_f32_16x16x32_bf16 v[74:77], v[176:179], v[200:203], v[74:77]
	v_mfma_f32_16x16x32_bf16 v[70:73], v[168:171], v[208:211], v[70:73]
	v_mfma_f32_16x16x32_bf16 v[66:69], v[176:179], v[208:211], v[66:69]
	v_mfma_f32_16x16x32_bf16 v[114:117], v[172:175], v[188:191], v[114:117]
	v_mfma_f32_16x16x32_bf16 v[106:109], v[180:183], v[188:191], v[106:109]
	v_mfma_f32_16x16x32_bf16 v[98:101], v[172:175], v[196:199], v[98:101]
	v_mfma_f32_16x16x32_bf16 v[90:93], v[180:183], v[196:199], v[90:93]
	v_mfma_f32_16x16x32_bf16 v[82:85], v[172:175], v[204:207], v[82:85]
	v_mfma_f32_16x16x32_bf16 v[74:77], v[180:183], v[204:207], v[74:77]
	v_mfma_f32_16x16x32_bf16 v[70:73], v[172:175], v[212:215], v[70:73]
	v_mfma_f32_16x16x32_bf16 v[66:69], v[180:183], v[212:215], v[66:69]
	s_setprio 2
	s_barrier
	s_add_i32 s33, s72, s61
	v_lshl_add_u64 v[216:217], s[46:47], 0, v[134:135]
	s_mov_b32 m0, s33
	s_nop 0
	global_load_lds_dwordx4 v[216:217], off
	s_add_i32 m0, s33, 0x2000
	s_add_u32 s62, s46, 0x100000
	v_lshl_add_u64 v[218:219], s[46:47], 0, v[130:131]
	s_addc_u32 s63, s47, 0
	s_add_i32 s33, s73, s61
	global_load_lds_dwordx4 v[218:219], off
	v_lshl_add_u64 v[220:221], s[62:63], 0, v[134:135]
	s_mov_b32 m0, s33
	v_lshl_add_u64 v[224:225], s[52:53], 0, v[132:133]
	global_load_lds_dwordx4 v[220:221], off
	v_lshl_add_u64 v[220:221], s[62:63], 0, v[130:131]
	s_add_i32 m0, s33, 0x2000
	s_nop 0
	global_load_lds_dwordx4 v[220:221], off
	v_lshl_add_u64 v[220:221], s[52:53], 0, v[136:137]
	s_mov_b32 m0, s17
	s_nop 0
	global_load_lds_dwordx4 v[220:221], off
	s_mov_b32 m0, s39
	s_nop 0
	global_load_lds_dwordx4 v[224:225], off
	ds_read_b128 v[184:187], v154 offset:16384
	ds_read_b128 v[188:191], v154 offset:17408
	ds_read_b128 v[192:195], v154 offset:18432
	ds_read_b128 v[196:199], v154 offset:19456
	ds_read_b128 v[200:203], v154 offset:20480
	ds_read_b128 v[204:207], v154 offset:21504
	ds_read_b128 v[208:211], v154 offset:22528
	ds_read_b128 v[212:215], v154 offset:23552
	s_waitcnt vmcnt(8)
	s_waitcnt lgkmcnt(0)
	s_barrier
; #define PG8_STAGE(bufoff, gbase, voff) do { _Pragma("unroll") for (int _i = 0; _i < 2; ++_i) \
;         __builtin_amdgcn_global_load_lds((const unsigned*)((const char*)(gbase) + (voff)[_i]), (LAS unsigned*)(lds + (bufoff) + ldsw + _i * 8192), 16, 0, 0); } while (0)
; #define PG8_LDA(dst, b, h) do { _Pragma("unroll") for (int m = 0; m < 4; ++m) _Pragma("unroll") for (int k = 0; k < 2; ++k) dst[m][k] = *(const LAS bf16x8*)(lds + PG8_SA(b, h) + aoff + m * 2048 + k * 1024); } while (0)
; #define PG8_LDB(dst, b, h) do { _Pragma("unroll") for (int n = 0; n < 2; ++n) _Pragma("unroll") for (int k = 0; k < 2; ++k) dst[n][k] = *(const LAS bf16x8*)(lds + PG8_SB(b, h) + boff + n * 2048 + k * 1024); } while (0)
; #define PG8_MMA(ai, bj, At, Bt) do { __builtin_amdgcn_s_setprio(1); _Pragma("unroll") for (int m = 0; m < 4; ++m) _Pragma("unroll") for (int n = 0; n < 2; ++n) _Pragma("unroll") for (int k = 0; k < 2; ++k) \
;         acc[ai][bj][m][n] = __builtin_amdgcn_mfma_f32_16x16x32_bf16(Bt[n][k], At[m][k], acc[ai][bj][m][n], 0, 0, 0); __builtin_amdgcn_s_setprio(0); } while (0)
; #define PG8_WAIT_V(n) asm volatile("s_waitcnt vmcnt(" #n ")" ::: "memory")
; #define PG8_WAIT_L(n) asm volatile("s_waitcnt lgkmcnt(" #n ")" ::: "memory")
; #define PG8_BAR __builtin_amdgcn_s_barrier()
; #define PG8_SCHED __builtin_amdgcn_sched_barrier(0)
; template <class Epi>
; __device__ __forceinline__ void gemm_phase(LAS unsigned char* lds, const Gemm g, int G, int c, const Epi& E) {
;     ...
;             PG8_WAIT_V(8); PG8_WAIT_L(0); PG8_BAR; PG8_MMA(1, 0, At, B0); PG8_MMA(1, 1, At, B1); PG8_BAR; PG8_SCHED;
;             PG8_LDB(B0, 1, 0); PG8_LDB(B1, 1, 1); PG8_SCHED; PG8_LDA(At, 1, 0); PG8_STAGE(PG8_SA(0, 1), a2 + hstepA, voffA);
;             PG8_WAIT_V(8); PG8_WAIT_L(0); PG8_BAR; PG8_MMA(0, 0, At, B0); PG8_MMA(0, 1, At, B1); PG8_BAR; PG8_SCHED;
	s_setprio 0
	s_waitcnt lgkmcnt(0)
	v_mfma_f32_16x16x32_bf16 v[62:65], v[146:149], v[184:187], v[62:65]
	v_mfma_f32_16x16x32_bf16 v[58:61], v[160:163], v[184:187], v[58:61]
	v_mfma_f32_16x16x32_bf16 v[54:57], v[146:149], v[192:195], v[54:57]
	v_mfma_f32_16x16x32_bf16 v[46:49], v[160:163], v[192:195], v[46:49]
	v_mfma_f32_16x16x32_bf16 v[38:41], v[146:149], v[200:203], v[38:41]
	v_mfma_f32_16x16x32_bf16 v[30:33], v[160:163], v[200:203], v[30:33]
	v_mfma_f32_16x16x32_bf16 v[22:25], v[146:149], v[208:211], v[22:25]
	v_mfma_f32_16x16x32_bf16 v[14:17], v[160:163], v[208:211], v[14:17]
	v_mfma_f32_16x16x32_bf16 v[62:65], v[156:159], v[188:191], v[62:65]
	v_mfma_f32_16x16x32_bf16 v[58:61], v[164:167], v[188:191], v[58:61]
	v_mfma_f32_16x16x32_bf16 v[54:57], v[156:159], v[196:199], v[54:57]
	v_mfma_f32_16x16x32_bf16 v[46:49], v[164:167], v[196:199], v[46:49]
	v_mfma_f32_16x16x32_bf16 v[38:41], v[156:159], v[204:207], v[38:41]
	v_mfma_f32_16x16x32_bf16 v[30:33], v[164:167], v[204:207], v[30:33]
	v_mfma_f32_16x16x32_bf16 v[22:25], v[156:159], v[212:215], v[22:25]
	v_mfma_f32_16x16x32_bf16 v[14:17], v[164:167], v[212:215], v[14:17]
	s_setprio 2
	s_setprio 0
	v_mfma_f32_16x16x32_bf16 v[50:53], v[168:171], v[184:187], v[50:53]
	v_mfma_f32_16x16x32_bf16 v[42:45], v[176:179], v[184:187], v[42:45]
	v_mfma_f32_16x16x32_bf16 v[34:37], v[168:171], v[192:195], v[34:37]
	v_mfma_f32_16x16x32_bf16 v[26:29], v[176:179], v[192:195], v[26:29]
	v_mfma_f32_16x16x32_bf16 v[18:21], v[168:171], v[200:203], v[18:21]
	v_mfma_f32_16x16x32_bf16 v[10:13], v[176:179], v[200:203], v[10:13]
	v_mfma_f32_16x16x32_bf16 v[6:9], v[168:171], v[208:211], v[6:9]
	v_mfma_f32_16x16x32_bf16 v[2:5], v[176:179], v[208:211], v[2:5]
	v_mfma_f32_16x16x32_bf16 v[50:53], v[172:175], v[188:191], v[50:53]
	v_mfma_f32_16x16x32_bf16 v[42:45], v[180:183], v[188:191], v[42:45]
	v_mfma_f32_16x16x32_bf16 v[34:37], v[172:175], v[196:199], v[34:37]
	v_mfma_f32_16x16x32_bf16 v[26:29], v[180:183], v[196:199], v[26:29]
	v_mfma_f32_16x16x32_bf16 v[18:21], v[172:175], v[204:207], v[18:21]
	v_mfma_f32_16x16x32_bf16 v[10:13], v[180:183], v[204:207], v[10:13]
	v_mfma_f32_16x16x32_bf16 v[6:9], v[172:175], v[212:215], v[6:9]
	v_mfma_f32_16x16x32_bf16 v[2:5], v[180:183], v[212:215], v[2:5]
	s_setprio 2
	s_barrier
	s_add_i32 s33, 0, 0x18000
	s_add_i32 s62, 0, 0x1c000
	s_add_u32 s52, s52, 0x100000
	s_addc_u32 s53, s53, 0
	s_mov_b32 m0, s43
	v_lshl_add_u64 v[226:227], s[52:53], 0, v[136:137]
	global_load_lds_dwordx4 v[226:227], off
	v_lshl_add_u64 v[226:227], s[52:53], 0, v[132:133]
	s_mov_b32 m0, s66
	s_nop 0
	global_load_lds_dwordx4 v[226:227], off
	v_add_u32_e32 v155, s33, v151
	ds_read_b128 v[146:149], v155
	ds_read_b128 v[156:159], v155 offset:1024
	ds_read_b128 v[160:163], v155 offset:2048
	ds_read_b128 v[164:167], v155 offset:3072
	v_add_u32_e32 v155, s62, v151
	ds_read_b128 v[168:171], v155
	ds_read_b128 v[172:175], v155 offset:1024
	ds_read_b128 v[176:179], v155 offset:2048
	ds_read_b128 v[180:183], v155 offset:3072
	ds_read_b128 v[184:187], v154 offset:32768
	ds_read_b128 v[188:191], v154 offset:33792
	ds_read_b128 v[192:195], v154 offset:34816
	ds_read_b128 v[196:199], v154 offset:35840
	ds_read_b128 v[200:203], v154 offset:36864
	ds_read_b128 v[204:207], v154 offset:37888
	ds_read_b128 v[208:211], v154 offset:38912
	ds_read_b128 v[212:215], v154 offset:39936
	s_waitcnt vmcnt(8)
	s_waitcnt lgkmcnt(0)
	s_barrier
	s_setprio 0
	s_waitcnt lgkmcnt(0)
	v_mfma_f32_16x16x32_bf16 v[126:129], v[146:149], v[184:187], v[126:129]
	v_mfma_f32_16x16x32_bf16 v[122:125], v[160:163], v[184:187], v[122:125]
	v_mfma_f32_16x16x32_bf16 v[118:121], v[146:149], v[192:195], v[118:121]
	v_mfma_f32_16x16x32_bf16 v[110:113], v[160:163], v[192:195], v[110:113]
	v_mfma_f32_16x16x32_bf16 v[102:105], v[146:149], v[200:203], v[102:105]
	v_mfma_f32_16x16x32_bf16 v[94:97], v[160:163], v[200:203], v[94:97]
	v_mfma_f32_16x16x32_bf16 v[86:89], v[146:149], v[208:211], v[86:89]
	v_mfma_f32_16x16x32_bf16 v[78:81], v[160:163], v[208:211], v[78:81]
	v_mfma_f32_16x16x32_bf16 v[126:129], v[156:159], v[188:191], v[126:129]
	v_mfma_f32_16x16x32_bf16 v[122:125], v[164:167], v[188:191], v[122:125]
	v_mfma_f32_16x16x32_bf16 v[118:121], v[156:159], v[196:199], v[118:121]
	v_mfma_f32_16x16x32_bf16 v[110:113], v[164:167], v[196:199], v[110:113]
	v_mfma_f32_16x16x32_bf16 v[102:105], v[156:159], v[204:207], v[102:105]
	v_mfma_f32_16x16x32_bf16 v[94:97], v[164:167], v[204:207], v[94:97]
	v_mfma_f32_16x16x32_bf16 v[86:89], v[156:159], v[212:215], v[86:89]
	v_mfma_f32_16x16x32_bf16 v[78:81], v[164:167], v[212:215], v[78:81]
	s_setprio 2
	s_setprio 0
	v_mfma_f32_16x16x32_bf16 v[114:117], v[168:171], v[184:187], v[114:117]
	v_mfma_f32_16x16x32_bf16 v[106:109], v[176:179], v[184:187], v[106:109]
	v_mfma_f32_16x16x32_bf16 v[98:101], v[168:171], v[192:195], v[98:101]
	v_mfma_f32_16x16x32_bf16 v[90:93], v[176:179], v[192:195], v[90:93]
	v_mfma_f32_16x16x32_bf16 v[82:85], v[168:171], v[200:203], v[82:85]
	v_mfma_f32_16x16x32_bf16 v[74:77], v[176:179], v[200:203], v[74:77]
	v_mfma_f32_16x16x32_bf16 v[70:73], v[168:171], v[208:211], v[70:73]
	v_mfma_f32_16x16x32_bf16 v[66:69], v[176:179], v[208:211], v[66:69]
	v_mfma_f32_16x16x32_bf16 v[114:117], v[172:175], v[188:191], v[114:117]
	v_mfma_f32_16x16x32_bf16 v[106:109], v[180:183], v[188:191], v[106:109]
	v_mfma_f32_16x16x32_bf16 v[98:101], v[172:175], v[196:199], v[98:101]
	v_mfma_f32_16x16x32_bf16 v[90:93], v[180:183], v[196:199], v[90:93]
	v_mfma_f32_16x16x32_bf16 v[82:85], v[172:175], v[204:207], v[82:85]
	v_mfma_f32_16x16x32_bf16 v[74:77], v[180:183], v[204:207], v[74:77]
	v_mfma_f32_16x16x32_bf16 v[70:73], v[172:175], v[212:215], v[70:73]
	v_mfma_f32_16x16x32_bf16 v[66:69], v[180:183], v[212:215], v[66:69]
	s_setprio 2
	s_barrier
; #define PG8_STAGE(bufoff, gbase, voff) do { _Pragma("unroll") for (int _i = 0; _i < 2; ++_i) \
;         __builtin_amdgcn_global_load_lds((const unsigned*)((const char*)(gbase) + (voff)[_i]), (LAS unsigned*)(lds + (bufoff) + ldsw + _i * 8192), 16, 0, 0); } while (0)
; #define PG8_LDA(dst, b, h) do { _Pragma("unroll") for (int m = 0; m < 4; ++m) _Pragma("unroll") for (int k = 0; k < 2; ++k) dst[m][k] = *(const LAS bf16x8*)(lds + PG8_SA(b, h) + aoff + m * 2048 + k * 1024); } while (0)
; #define PG8_MMA(ai, bj, At, Bt) do { __builtin_amdgcn_s_setprio(1); _Pragma("unroll") for (int m = 0; m < 4; ++m) _Pragma("unroll") for (int n = 0; n < 2; ++n) _Pragma("unroll") for (int k = 0; k < 2; ++k) \
;         acc[ai][bj][m][n] = __builtin_amdgcn_mfma_f32_16x16x32_bf16(Bt[n][k], At[m][k], acc[ai][bj][m][n], 0, 0, 0); __builtin_amdgcn_s_setprio(0); } while (0)
; #define PG8_WAIT_V(n) asm volatile("s_waitcnt vmcnt(" #n ")" ::: "memory")
; #define PG8_WAIT_L(n) asm volatile("s_waitcnt lgkmcnt(" #n ")" ::: "memory")
; #define PG8_BAR __builtin_amdgcn_s_barrier()
; #define PG8_SCHED __builtin_amdgcn_sched_barrier(0)
; template <class Epi>
; __device__ __forceinline__ void gemm_phase(LAS unsigned char* lds, const Gemm g, int G, int c, const Epi& E) {
;     ...
;             PG8_LDA(At, 1, 1); PG8_STAGE(PG8_SB(1, 0), b3, voffB); PG8_STAGE(PG8_SB(1, 1), b3 + hstepB, voffB); PG8_STAGE(PG8_SA(1, 0), a3, voffA);
;             PG8_WAIT_V(8); PG8_WAIT_L(0); PG8_BAR; PG8_MMA(1, 0, At, B0); PG8_MMA(1, 1, At, B1); PG8_BAR; PG8_SCHED;
;         }
	s_add_i32 s33, s33, s61
	v_lshl_add_u64 v[216:217], v[216:217], 0, s[6:7]
	s_mov_b32 m0, s33
	s_nop 0
	global_load_lds_dwordx4 v[216:217], off
	s_add_i32 m0, s33, 0x2000
	s_add_u32 s46, s46, 0x100080
	v_lshl_add_u64 v[216:217], v[218:219], 0, s[6:7]
	s_addc_u32 s47, s47, 0
	s_add_i32 s33, s62, s61
	global_load_lds_dwordx4 v[216:217], off
	v_lshl_add_u64 v[216:217], s[46:47], 0, v[134:135]
	s_mov_b32 m0, s33
	s_nop 0
	global_load_lds_dwordx4 v[216:217], off
	v_lshl_add_u64 v[216:217], s[46:47], 0, v[130:131]
	s_add_i32 m0, s33, 0x2000
	s_nop 0
	global_load_lds_dwordx4 v[216:217], off
	v_lshl_add_u64 v[216:217], v[220:221], 0, s[6:7]
	s_mov_b32 m0, s70
	s_nop 0
	global_load_lds_dwordx4 v[216:217], off
	v_lshl_add_u64 v[216:217], v[224:225], 0, s[6:7]
	s_mov_b32 m0, s71
	s_nop 0
	global_load_lds_dwordx4 v[216:217], off
	ds_read_b128 v[184:187], v154 offset:49152
	ds_read_b128 v[188:191], v154 offset:50176
	ds_read_b128 v[192:195], v154 offset:51200
	ds_read_b128 v[196:199], v154 offset:52224
	ds_read_b128 v[200:203], v154 offset:53248
	ds_read_b128 v[204:207], v154 offset:54272
	ds_read_b128 v[208:211], v154 offset:55296
	ds_read_b128 v[212:215], v154 offset:56320
	s_waitcnt vmcnt(8)
	s_waitcnt lgkmcnt(0)
	s_barrier
	s_setprio 0
	s_waitcnt lgkmcnt(0)
	v_mfma_f32_16x16x32_bf16 v[62:65], v[146:149], v[184:187], v[62:65]
	v_mfma_f32_16x16x32_bf16 v[58:61], v[160:163], v[184:187], v[58:61]
	v_mfma_f32_16x16x32_bf16 v[54:57], v[146:149], v[192:195], v[54:57]
	v_mfma_f32_16x16x32_bf16 v[46:49], v[160:163], v[192:195], v[46:49]
	v_mfma_f32_16x16x32_bf16 v[38:41], v[146:149], v[200:203], v[38:41]
	v_mfma_f32_16x16x32_bf16 v[30:33], v[160:163], v[200:203], v[30:33]
	v_mfma_f32_16x16x32_bf16 v[22:25], v[146:149], v[208:211], v[22:25]
	v_mfma_f32_16x16x32_bf16 v[14:17], v[160:163], v[208:211], v[14:17]
	v_mfma_f32_16x16x32_bf16 v[62:65], v[156:159], v[188:191], v[62:65]
	v_mfma_f32_16x16x32_bf16 v[58:61], v[164:167], v[188:191], v[58:61]
	v_mfma_f32_16x16x32_bf16 v[54:57], v[156:159], v[196:199], v[54:57]
	v_mfma_f32_16x16x32_bf16 v[46:49], v[164:167], v[196:199], v[46:49]
	v_mfma_f32_16x16x32_bf16 v[38:41], v[156:159], v[204:207], v[38:41]
	v_mfma_f32_16x16x32_bf16 v[30:33], v[164:167], v[204:207], v[30:33]
	v_mfma_f32_16x16x32_bf16 v[22:25], v[156:159], v[212:215], v[22:25]
	v_mfma_f32_16x16x32_bf16 v[14:17], v[164:167], v[212:215], v[14:17]
	s_setprio 2
	s_setprio 0
	v_mfma_f32_16x16x32_bf16 v[50:53], v[168:171], v[184:187], v[50:53]
	v_mfma_f32_16x16x32_bf16 v[42:45], v[176:179], v[184:187], v[42:45]
	v_mfma_f32_16x16x32_bf16 v[34:37], v[168:171], v[192:195], v[34:37]
	v_mfma_f32_16x16x32_bf16 v[26:29], v[176:179], v[192:195], v[26:29]
	v_mfma_f32_16x16x32_bf16 v[18:21], v[168:171], v[200:203], v[18:21]
	v_mfma_f32_16x16x32_bf16 v[10:13], v[176:179], v[200:203], v[10:13]
	v_mfma_f32_16x16x32_bf16 v[6:9], v[168:171], v[208:211], v[6:9]
	v_mfma_f32_16x16x32_bf16 v[2:5], v[176:179], v[208:211], v[2:5]
	v_mfma_f32_16x16x32_bf16 v[50:53], v[172:175], v[188:191], v[50:53]
	v_mfma_f32_16x16x32_bf16 v[42:45], v[180:183], v[188:191], v[42:45]
	v_mfma_f32_16x16x32_bf16 v[34:37], v[172:175], v[196:199], v[34:37]
	v_mfma_f32_16x16x32_bf16 v[26:29], v[180:183], v[196:199], v[26:29]
	v_mfma_f32_16x16x32_bf16 v[18:21], v[172:175], v[204:207], v[18:21]
	v_mfma_f32_16x16x32_bf16 v[10:13], v[180:183], v[204:207], v[10:13]
	v_mfma_f32_16x16x32_bf16 v[6:9], v[172:175], v[212:215], v[6:9]
	v_mfma_f32_16x16x32_bf16 v[2:5], v[180:183], v[212:215], v[2:5]
	s_setprio 2
	s_barrier
	s_add_i32 s83, s83, 2
	s_add_u32 s44, s44, 0x100
	s_addc_u32 s45, s45, 0
	s_add_u32 s81, s81, 0x100
	s_addc_u32 s82, s82, 0
	s_cmp_gt_u32 s83, 61
	s_cbranch_scc0 .LBB0_765
	s_and_b64 vcc, exec, s[8:9]
	s_cbranch_vccz .LBB0_768
	s_barrier

; #define PG8_STAGE(bufoff, gbase, voff) do { _Pragma("unroll") for (int _i = 0; _i < 2; ++_i) \
;         __builtin_amdgcn_global_load_lds((const unsigned*)((const char*)(gbase) + (voff)[_i]), (LAS unsigned*)(lds + (bufoff) + ldsw + _i * 8192), 16, 0, 0); } while (0)
; #define PG8_LDA(dst, b, h) do { _Pragma("unroll") for (int m = 0; m < 4; ++m) _Pragma("unroll") for (int k = 0; k < 2; ++k) dst[m][k] = *(const LAS bf16x8*)(lds + PG8_SA(b, h) + aoff + m * 2048 + k * 1024); } while (0)
; #define PG8_LDB(dst, b, h) do { _Pragma("unroll") for (int n = 0; n < 2; ++n) _Pragma("unroll") for (int k = 0; k < 2; ++k) dst[n][k] = *(const LAS bf16x8*)(lds + PG8_SB(b, h) + boff + n * 2048 + k * 1024); } while (0)
; #define PG8_MMA(ai, bj, At, Bt) do { __builtin_amdgcn_s_setprio(1); _Pragma("unroll") for (int m = 0; m < 4; ++m) _Pragma("unroll") for (int n = 0; n < 2; ++n) _Pragma("unroll") for (int k = 0; k < 2; ++k) \
;         acc[ai][bj][m][n] = __builtin_amdgcn_mfma_f32_16x16x32_bf16(Bt[n][k], At[m][k], acc[ai][bj][m][n], 0, 0, 0); __builtin_amdgcn_s_setprio(0); } while (0)
; #define PG8_WAIT_V(n) asm volatile("s_waitcnt vmcnt(" #n ")" ::: "memory")
; #define PG8_WAIT_L(n) asm volatile("s_waitcnt lgkmcnt(" #n ")" ::: "memory")
; #define PG8_BAR __builtin_amdgcn_s_barrier()
; #define PG8_SCHED __builtin_amdgcn_sched_barrier(0)
; template <class Epi>
; __device__ __forceinline__ void gemm_phase(LAS unsigned char* lds, const Gemm g, int G, int c, const Epi& E) {
;     ...
;             const char* a1 = cA + (size_t)(t + 1) * kstep;
;             const char* a2 = last ? nA : cA + (size_t)(t + 2) * kstep; const char* b2 = last ? nB : cB + (size_t)(t + 2) * kstep;
;             const char* a3 = a2 + kstep; const char* b3 = b2 + kstep;
;             PG8_LDB(B0, 0, 0); PG8_LDB(B1, 0, 1); PG8_SCHED; PG8_LDA(At, 0, 0); PG8_STAGE(PG8_SA(1, 1), a1 + hstepA, voffA);
;             PG8_WAIT_V(8); PG8_WAIT_L(0); PG8_BAR; PG8_MMA(0, 0, At, B0); PG8_MMA(0, 1, At, B1); PG8_BAR; PG8_SCHED;
;             PG8_LDA(At, 0, 1); PG8_STAGE(PG8_SB(0, 0), b2, voffB); PG8_STAGE(PG8_SB(0, 1), b2 + hstepB, voffB); PG8_STAGE(PG8_SA(0, 0), a2, voffA);
;             PG8_WAIT_V(8); PG8_WAIT_L(0); PG8_BAR; PG8_MMA(1, 0, At, B0); PG8_MMA(1, 1, At, B1); PG8_BAR; PG8_SCHED;
.LBB0_781:
	s_mov_b32 m0, s83
	v_lshl_add_u64 v[142:143], v[138:139], 0, s[46:47]
	global_load_lds_dwordx4 v[142:143], off
	v_lshl_add_u64 v[142:143], v[140:141], 0, s[46:47]
	s_mov_b32 m0, s84
	s_nop 0
	global_load_lds_dwordx4 v[142:143], off
	ds_read_b128 v[150:153], v146
	ds_read_b128 v[154:157], v146 offset:1024
	ds_read_b128 v[158:161], v146 offset:2048
	ds_read_b128 v[162:165], v146 offset:3072
	ds_read_b128 v[166:169], v147
	ds_read_b128 v[170:173], v147 offset:1024
	ds_read_b128 v[174:177], v147 offset:2048
	ds_read_b128 v[178:181], v147 offset:3072
	s_add_u32 s52, s46, 0x100
	s_addc_u32 s53, s47, 0
	s_add_u32 s33, s90, s46
	s_addc_u32 s55, s91, s47
	s_cmp_eq_u32 s92, 4
	s_cselect_b32 s56, 0, s52
	s_cselect_b32 s57, 0, s53
	s_cselect_b32 s54, s89, s33
	s_cselect_b32 s55, s25, s55
	s_add_u32 s56, s2, s56
	s_addc_u32 s57, s3, s57
	ds_read_b128 v[182:185], v148
	ds_read_b128 v[186:189], v148 offset:1024
	ds_read_b128 v[190:193], v148 offset:2048
	ds_read_b128 v[194:197], v148 offset:3072
	ds_read_b128 v[198:201], v148 offset:4096
	ds_read_b128 v[202:205], v148 offset:5120
	ds_read_b128 v[206:209], v148 offset:6144
	ds_read_b128 v[210:213], v148 offset:7168
	s_waitcnt vmcnt(8)
	s_waitcnt lgkmcnt(0)
	s_barrier
	s_setprio 0
	s_waitcnt lgkmcnt(0)
	v_mfma_f32_16x16x32_bf16 v[126:129], v[150:153], v[182:185], v[126:129]
	v_mfma_f32_16x16x32_bf16 v[122:125], v[158:161], v[182:185], v[122:125]
	v_mfma_f32_16x16x32_bf16 v[118:121], v[150:153], v[190:193], v[118:121]
	v_mfma_f32_16x16x32_bf16 v[110:113], v[158:161], v[190:193], v[110:113]
	v_mfma_f32_16x16x32_bf16 v[102:105], v[150:153], v[198:201], v[102:105]
	v_mfma_f32_16x16x32_bf16 v[94:97], v[158:161], v[198:201], v[94:97]
	v_mfma_f32_16x16x32_bf16 v[86:89], v[150:153], v[206:209], v[86:89]
	v_mfma_f32_16x16x32_bf16 v[78:81], v[158:161], v[206:209], v[78:81]
	v_mfma_f32_16x16x32_bf16 v[126:129], v[154:157], v[186:189], v[126:129]
	v_mfma_f32_16x16x32_bf16 v[122:125], v[162:165], v[186:189], v[122:125]
	v_mfma_f32_16x16x32_bf16 v[118:121], v[154:157], v[194:197], v[118:121]
	v_mfma_f32_16x16x32_bf16 v[110:113], v[162:165], v[194:197], v[110:113]
	v_mfma_f32_16x16x32_bf16 v[102:105], v[154:157], v[202:205], v[102:105]
	v_mfma_f32_16x16x32_bf16 v[94:97], v[162:165], v[202:205], v[94:97]
	v_mfma_f32_16x16x32_bf16 v[86:89], v[154:157], v[210:213], v[86:89]
	v_mfma_f32_16x16x32_bf16 v[78:81], v[162:165], v[210:213], v[78:81]
	s_setprio 2
	s_setprio 0
	v_mfma_f32_16x16x32_bf16 v[114:117], v[166:169], v[182:185], v[114:117]
	v_mfma_f32_16x16x32_bf16 v[106:109], v[174:177], v[182:185], v[106:109]
	v_mfma_f32_16x16x32_bf16 v[98:101], v[166:169], v[190:193], v[98:101]
	v_mfma_f32_16x16x32_bf16 v[90:93], v[174:177], v[190:193], v[90:93]
	v_mfma_f32_16x16x32_bf16 v[82:85], v[166:169], v[198:201], v[82:85]
	v_mfma_f32_16x16x32_bf16 v[74:77], v[174:177], v[198:201], v[74:77]
	v_mfma_f32_16x16x32_bf16 v[70:73], v[166:169], v[206:209], v[70:73]
	v_mfma_f32_16x16x32_bf16 v[66:69], v[174:177], v[206:209], v[66:69]
	v_mfma_f32_16x16x32_bf16 v[114:117], v[170:173], v[186:189], v[114:117]
	v_mfma_f32_16x16x32_bf16 v[106:109], v[178:181], v[186:189], v[106:109]
	v_mfma_f32_16x16x32_bf16 v[98:101], v[170:173], v[194:197], v[98:101]
	v_mfma_f32_16x16x32_bf16 v[90:93], v[178:181], v[194:197], v[90:93]
	v_mfma_f32_16x16x32_bf16 v[82:85], v[170:173], v[202:205], v[82:85]
	v_mfma_f32_16x16x32_bf16 v[74:77], v[178:181], v[202:205], v[74:77]
	v_mfma_f32_16x16x32_bf16 v[70:73], v[170:173], v[210:213], v[70:73]
	v_mfma_f32_16x16x32_bf16 v[66:69], v[178:181], v[210:213], v[66:69]
	s_setprio 2
	s_barrier
	s_mov_b32 m0, s85
	v_lshl_add_u64 v[142:143], s[54:55], 0, v[134:135]
	s_add_u32 s46, s54, 0x20000
	global_load_lds_dwordx4 v[142:143], off
	v_lshl_add_u64 v[214:215], s[54:55], 0, v[130:131]
	s_mov_b32 m0, s86
	s_addc_u32 s47, s55, 0
	global_load_lds_dwordx4 v[214:215], off
	v_lshl_add_u64 v[216:217], s[46:47], 0, v[134:135]
	s_mov_b32 m0, s87
	v_lshl_add_u64 v[218:219], s[56:57], 0, v[132:133]
	global_load_lds_dwordx4 v[216:217], off
	v_lshl_add_u64 v[216:217], s[46:47], 0, v[130:131]
	s_mov_b32 m0, s88
	s_nop 0
	global_load_lds_dwordx4 v[216:217], off
	v_lshl_add_u64 v[216:217], s[56:57], 0, v[136:137]
	s_mov_b32 m0, s45
	s_nop 0
	global_load_lds_dwordx4 v[216:217], off
	s_mov_b32 m0, s61
	s_nop 0
	global_load_lds_dwordx4 v[218:219], off
	ds_read_b128 v[182:185], v148 offset:16384
	ds_read_b128 v[186:189], v148 offset:17408
	ds_read_b128 v[190:193], v148 offset:18432
	ds_read_b128 v[194:197], v148 offset:19456
	ds_read_b128 v[198:201], v148 offset:20480
	ds_read_b128 v[202:205], v148 offset:21504
	ds_read_b128 v[206:209], v148 offset:22528
	ds_read_b128 v[210:213], v148 offset:23552
	s_waitcnt vmcnt(8)
	s_waitcnt lgkmcnt(0)
	s_barrier
; #define PG8_STAGE(bufoff, gbase, voff) do { _Pragma("unroll") for (int _i = 0; _i < 2; ++_i) \
;         __builtin_amdgcn_global_load_lds((const unsigned*)((const char*)(gbase) + (voff)[_i]), (LAS unsigned*)(lds + (bufoff) + ldsw + _i * 8192), 16, 0, 0); } while (0)
; #define PG8_LDA(dst, b, h) do { _Pragma("unroll") for (int m = 0; m < 4; ++m) _Pragma("unroll") for (int k = 0; k < 2; ++k) dst[m][k] = *(const LAS bf16x8*)(lds + PG8_SA(b, h) + aoff + m * 2048 + k * 1024); } while (0)
; #define PG8_LDB(dst, b, h) do { _Pragma("unroll") for (int n = 0; n < 2; ++n) _Pragma("unroll") for (int k = 0; k < 2; ++k) dst[n][k] = *(const LAS bf16x8*)(lds + PG8_SB(b, h) + boff + n * 2048 + k * 1024); } while (0)
; #define PG8_MMA(ai, bj, At, Bt) do { __builtin_amdgcn_s_setprio(1); _Pragma("unroll") for (int m = 0; m < 4; ++m) _Pragma("unroll") for (int n = 0; n < 2; ++n) _Pragma("unroll") for (int k = 0; k < 2; ++k) \
;         acc[ai][bj][m][n] = __builtin_amdgcn_mfma_f32_16x16x32_bf16(Bt[n][k], At[m][k], acc[ai][bj][m][n], 0, 0, 0); __builtin_amdgcn_s_setprio(0); } while (0)
; #define PG8_WAIT_V(n) asm volatile("s_waitcnt vmcnt(" #n ")" ::: "memory")
; #define PG8_WAIT_L(n) asm volatile("s_waitcnt lgkmcnt(" #n ")" ::: "memory")
; #define PG8_BAR __builtin_amdgcn_s_barrier()
; #define PG8_SCHED __builtin_amdgcn_sched_barrier(0)
; template <class Epi>
; __device__ __forceinline__ void gemm_phase(LAS unsigned char* lds, const Gemm g, int G, int c, const Epi& E) {
;     ...
;             PG8_WAIT_V(8); PG8_WAIT_L(0); PG8_BAR; PG8_MMA(1, 0, At, B0); PG8_MMA(1, 1, At, B1); PG8_BAR; PG8_SCHED;
;             PG8_LDB(B0, 1, 0); PG8_LDB(B1, 1, 1); PG8_SCHED; PG8_LDA(At, 1, 0); PG8_STAGE(PG8_SA(0, 1), a2 + hstepA, voffA);
;             PG8_WAIT_V(8); PG8_WAIT_L(0); PG8_BAR; PG8_MMA(0, 0, At, B0); PG8_MMA(0, 1, At, B1); PG8_BAR; PG8_SCHED;
	s_setprio 0
	s_waitcnt lgkmcnt(0)
	v_mfma_f32_16x16x32_bf16 v[62:65], v[150:153], v[182:185], v[62:65]
	v_mfma_f32_16x16x32_bf16 v[58:61], v[158:161], v[182:185], v[58:61]
	v_mfma_f32_16x16x32_bf16 v[54:57], v[150:153], v[190:193], v[54:57]
	v_mfma_f32_16x16x32_bf16 v[46:49], v[158:161], v[190:193], v[46:49]
	v_mfma_f32_16x16x32_bf16 v[38:41], v[150:153], v[198:201], v[38:41]
	v_mfma_f32_16x16x32_bf16 v[30:33], v[158:161], v[198:201], v[30:33]
	v_mfma_f32_16x16x32_bf16 v[22:25], v[150:153], v[206:209], v[22:25]
	v_mfma_f32_16x16x32_bf16 v[14:17], v[158:161], v[206:209], v[14:17]
	v_mfma_f32_16x16x32_bf16 v[62:65], v[154:157], v[186:189], v[62:65]
	v_mfma_f32_16x16x32_bf16 v[58:61], v[162:165], v[186:189], v[58:61]
	v_mfma_f32_16x16x32_bf16 v[54:57], v[154:157], v[194:197], v[54:57]
	v_mfma_f32_16x16x32_bf16 v[46:49], v[162:165], v[194:197], v[46:49]
	v_mfma_f32_16x16x32_bf16 v[38:41], v[154:157], v[202:205], v[38:41]
	v_mfma_f32_16x16x32_bf16 v[30:33], v[162:165], v[202:205], v[30:33]
	v_mfma_f32_16x16x32_bf16 v[22:25], v[154:157], v[210:213], v[22:25]
	v_mfma_f32_16x16x32_bf16 v[14:17], v[162:165], v[210:213], v[14:17]
	s_setprio 2
	s_setprio 0
	v_mfma_f32_16x16x32_bf16 v[50:53], v[166:169], v[182:185], v[50:53]
	v_mfma_f32_16x16x32_bf16 v[42:45], v[174:177], v[182:185], v[42:45]
	v_mfma_f32_16x16x32_bf16 v[34:37], v[166:169], v[190:193], v[34:37]
	v_mfma_f32_16x16x32_bf16 v[26:29], v[174:177], v[190:193], v[26:29]
	v_mfma_f32_16x16x32_bf16 v[18:21], v[166:169], v[198:201], v[18:21]
	v_mfma_f32_16x16x32_bf16 v[10:13], v[174:177], v[198:201], v[10:13]
	v_mfma_f32_16x16x32_bf16 v[6:9], v[166:169], v[206:209], v[6:9]
	v_mfma_f32_16x16x32_bf16 v[2:5], v[174:177], v[206:209], v[2:5]
	v_mfma_f32_16x16x32_bf16 v[50:53], v[170:173], v[186:189], v[50:53]
	v_mfma_f32_16x16x32_bf16 v[42:45], v[178:181], v[186:189], v[42:45]
	v_mfma_f32_16x16x32_bf16 v[34:37], v[170:173], v[194:197], v[34:37]
	v_mfma_f32_16x16x32_bf16 v[26:29], v[178:181], v[194:197], v[26:29]
	v_mfma_f32_16x16x32_bf16 v[18:21], v[170:173], v[202:205], v[18:21]
	v_mfma_f32_16x16x32_bf16 v[10:13], v[178:181], v[202:205], v[10:13]
	v_mfma_f32_16x16x32_bf16 v[6:9], v[170:173], v[210:213], v[6:9]
	v_mfma_f32_16x16x32_bf16 v[2:5], v[178:181], v[210:213], v[2:5]
	s_setprio 2
	s_barrier
	s_add_i32 s33, 0, 0x18000
	s_add_i32 s62, 0, 0x1c000
	s_add_u32 s46, s56, 0x20000
	s_addc_u32 s47, s57, 0
	s_mov_b32 m0, s66
	v_lshl_add_u64 v[220:221], s[46:47], 0, v[136:137]
	global_load_lds_dwordx4 v[220:221], off
	v_lshl_add_u64 v[220:221], s[46:47], 0, v[132:133]
	s_mov_b32 m0, s67
	s_nop 0
	global_load_lds_dwordx4 v[220:221], off
	v_add_u32_e32 v149, s33, v145
	ds_read_b128 v[150:153], v149
	ds_read_b128 v[154:157], v149 offset:1024
	ds_read_b128 v[158:161], v149 offset:2048
	ds_read_b128 v[162:165], v149 offset:3072
	v_add_u32_e32 v149, s62, v145
	ds_read_b128 v[166:169], v149
	ds_read_b128 v[170:173], v149 offset:1024
	ds_read_b128 v[174:177], v149 offset:2048
	ds_read_b128 v[178:181], v149 offset:3072
	ds_read_b128 v[182:185], v148 offset:32768
	ds_read_b128 v[186:189], v148 offset:33792
	ds_read_b128 v[190:193], v148 offset:34816
	ds_read_b128 v[194:197], v148 offset:35840
	ds_read_b128 v[198:201], v148 offset:36864
	ds_read_b128 v[202:205], v148 offset:37888
	ds_read_b128 v[206:209], v148 offset:38912
	ds_read_b128 v[210:213], v148 offset:39936
	s_waitcnt vmcnt(8)
	s_waitcnt lgkmcnt(0)
	s_barrier
	s_setprio 0
	s_waitcnt lgkmcnt(0)
	v_mfma_f32_16x16x32_bf16 v[126:129], v[150:153], v[182:185], v[126:129]
	v_mfma_f32_16x16x32_bf16 v[122:125], v[158:161], v[182:185], v[122:125]
	v_mfma_f32_16x16x32_bf16 v[118:121], v[150:153], v[190:193], v[118:121]
	v_mfma_f32_16x16x32_bf16 v[110:113], v[158:161], v[190:193], v[110:113]
	v_mfma_f32_16x16x32_bf16 v[102:105], v[150:153], v[198:201], v[102:105]
	v_mfma_f32_16x16x32_bf16 v[94:97], v[158:161], v[198:201], v[94:97]
	v_mfma_f32_16x16x32_bf16 v[86:89], v[150:153], v[206:209], v[86:89]
	v_mfma_f32_16x16x32_bf16 v[78:81], v[158:161], v[206:209], v[78:81]
	v_mfma_f32_16x16x32_bf16 v[126:129], v[154:157], v[186:189], v[126:129]
	v_mfma_f32_16x16x32_bf16 v[122:125], v[162:165], v[186:189], v[122:125]
	v_mfma_f32_16x16x32_bf16 v[118:121], v[154:157], v[194:197], v[118:121]
	v_mfma_f32_16x16x32_bf16 v[110:113], v[162:165], v[194:197], v[110:113]
	v_mfma_f32_16x16x32_bf16 v[102:105], v[154:157], v[202:205], v[102:105]
	v_mfma_f32_16x16x32_bf16 v[94:97], v[162:165], v[202:205], v[94:97]
	v_mfma_f32_16x16x32_bf16 v[86:89], v[154:157], v[210:213], v[86:89]
	v_mfma_f32_16x16x32_bf16 v[78:81], v[162:165], v[210:213], v[78:81]
	s_setprio 2
	s_setprio 0
	v_mfma_f32_16x16x32_bf16 v[114:117], v[166:169], v[182:185], v[114:117]
	v_mfma_f32_16x16x32_bf16 v[106:109], v[174:177], v[182:185], v[106:109]
	v_mfma_f32_16x16x32_bf16 v[98:101], v[166:169], v[190:193], v[98:101]
	v_mfma_f32_16x16x32_bf16 v[90:93], v[174:177], v[190:193], v[90:93]
	v_mfma_f32_16x16x32_bf16 v[82:85], v[166:169], v[198:201], v[82:85]
	v_mfma_f32_16x16x32_bf16 v[74:77], v[174:177], v[198:201], v[74:77]
	v_mfma_f32_16x16x32_bf16 v[70:73], v[166:169], v[206:209], v[70:73]
	v_mfma_f32_16x16x32_bf16 v[66:69], v[174:177], v[206:209], v[66:69]
	v_mfma_f32_16x16x32_bf16 v[114:117], v[170:173], v[186:189], v[114:117]
	v_mfma_f32_16x16x32_bf16 v[106:109], v[178:181], v[186:189], v[106:109]
	v_mfma_f32_16x16x32_bf16 v[98:101], v[170:173], v[194:197], v[98:101]
	v_mfma_f32_16x16x32_bf16 v[90:93], v[178:181], v[194:197], v[90:93]
	v_mfma_f32_16x16x32_bf16 v[82:85], v[170:173], v[202:205], v[82:85]
	v_mfma_f32_16x16x32_bf16 v[74:77], v[178:181], v[202:205], v[74:77]
	v_mfma_f32_16x16x32_bf16 v[70:73], v[170:173], v[210:213], v[70:73]
	v_mfma_f32_16x16x32_bf16 v[66:69], v[178:181], v[210:213], v[66:69]
	s_setprio 2
	s_barrier
; #define PG8_STAGE(bufoff, gbase, voff) do { _Pragma("unroll") for (int _i = 0; _i < 2; ++_i) \
;         __builtin_amdgcn_global_load_lds((const unsigned*)((const char*)(gbase) + (voff)[_i]), (LAS unsigned*)(lds + (bufoff) + ldsw + _i * 8192), 16, 0, 0); } while (0)
; #define PG8_LDA(dst, b, h) do { _Pragma("unroll") for (int m = 0; m < 4; ++m) _Pragma("unroll") for (int k = 0; k < 2; ++k) dst[m][k] = *(const LAS bf16x8*)(lds + PG8_SA(b, h) + aoff + m * 2048 + k * 1024); } while (0)
; #define PG8_MMA(ai, bj, At, Bt) do { __builtin_amdgcn_s_setprio(1); _Pragma("unroll") for (int m = 0; m < 4; ++m) _Pragma("unroll") for (int n = 0; n < 2; ++n) _Pragma("unroll") for (int k = 0; k < 2; ++k) \
;         acc[ai][bj][m][n] = __builtin_amdgcn_mfma_f32_16x16x32_bf16(Bt[n][k], At[m][k], acc[ai][bj][m][n], 0, 0, 0); __builtin_amdgcn_s_setprio(0); } while (0)
; #define PG8_WAIT_V(n) asm volatile("s_waitcnt vmcnt(" #n ")" ::: "memory")
; #define PG8_WAIT_L(n) asm volatile("s_waitcnt lgkmcnt(" #n ")" ::: "memory")
; #define PG8_BAR __builtin_amdgcn_s_barrier()
; #define PG8_SCHED __builtin_amdgcn_sched_barrier(0)
; template <class Epi>
; __device__ __forceinline__ void gemm_phase(LAS unsigned char* lds, const Gemm g, int G, int c, const Epi& E) {
;     ...
;             PG8_LDA(At, 1, 1); PG8_STAGE(PG8_SB(1, 0), b3, voffB); PG8_STAGE(PG8_SB(1, 1), b3 + hstepB, voffB); PG8_STAGE(PG8_SA(1, 0), a3, voffA);
;             PG8_WAIT_V(8); PG8_WAIT_L(0); PG8_BAR; PG8_MMA(1, 0, At, B0); PG8_MMA(1, 1, At, B1); PG8_BAR; PG8_SCHED;
;         }
	s_add_i32 s33, s33, s58
	v_lshl_add_u64 v[142:143], v[142:143], 0, s[6:7]
	s_mov_b32 m0, s33
	s_nop 0
	global_load_lds_dwordx4 v[142:143], off
	s_add_i32 m0, s33, 0x2000
	s_add_u32 s46, s54, 0x20080
	v_lshl_add_u64 v[142:143], v[214:215], 0, s[6:7]
	s_addc_u32 s47, s55, 0
	s_add_i32 s33, s62, s58
	global_load_lds_dwordx4 v[142:143], off
	v_lshl_add_u64 v[142:143], s[46:47], 0, v[134:135]
	s_mov_b32 m0, s33
	s_nop 0
	global_load_lds_dwordx4 v[142:143], off
	v_lshl_add_u64 v[142:143], s[46:47], 0, v[130:131]
	s_add_i32 m0, s33, 0x2000
	s_nop 0
	global_load_lds_dwordx4 v[142:143], off
	v_lshl_add_u64 v[142:143], v[216:217], 0, s[6:7]
	s_mov_b32 m0, s71
	s_nop 0
	global_load_lds_dwordx4 v[142:143], off
	v_lshl_add_u64 v[142:143], v[218:219], 0, s[6:7]
	s_mov_b32 m0, s72
	s_nop 0
	global_load_lds_dwordx4 v[142:143], off
	ds_read_b128 v[182:185], v148 offset:49152
	ds_read_b128 v[186:189], v148 offset:50176
	ds_read_b128 v[190:193], v148 offset:51200
	ds_read_b128 v[194:197], v148 offset:52224
	ds_read_b128 v[198:201], v148 offset:53248
	ds_read_b128 v[202:205], v148 offset:54272
	ds_read_b128 v[206:209], v148 offset:55296
	ds_read_b128 v[210:213], v148 offset:56320
	s_waitcnt vmcnt(8)
	s_waitcnt lgkmcnt(0)
	s_barrier
	s_setprio 0
	s_waitcnt lgkmcnt(0)
	v_mfma_f32_16x16x32_bf16 v[62:65], v[150:153], v[182:185], v[62:65]
	v_mfma_f32_16x16x32_bf16 v[58:61], v[158:161], v[182:185], v[58:61]
	v_mfma_f32_16x16x32_bf16 v[54:57], v[150:153], v[190:193], v[54:57]
	v_mfma_f32_16x16x32_bf16 v[46:49], v[158:161], v[190:193], v[46:49]
	v_mfma_f32_16x16x32_bf16 v[38:41], v[150:153], v[198:201], v[38:41]
	v_mfma_f32_16x16x32_bf16 v[30:33], v[158:161], v[198:201], v[30:33]
	v_mfma_f32_16x16x32_bf16 v[22:25], v[150:153], v[206:209], v[22:25]
	v_mfma_f32_16x16x32_bf16 v[14:17], v[158:161], v[206:209], v[14:17]
	v_mfma_f32_16x16x32_bf16 v[62:65], v[154:157], v[186:189], v[62:65]
	v_mfma_f32_16x16x32_bf16 v[58:61], v[162:165], v[186:189], v[58:61]
	v_mfma_f32_16x16x32_bf16 v[54:57], v[154:157], v[194:197], v[54:57]
	v_mfma_f32_16x16x32_bf16 v[46:49], v[162:165], v[194:197], v[46:49]
	v_mfma_f32_16x16x32_bf16 v[38:41], v[154:157], v[202:205], v[38:41]
	v_mfma_f32_16x16x32_bf16 v[30:33], v[162:165], v[202:205], v[30:33]
	v_mfma_f32_16x16x32_bf16 v[22:25], v[154:157], v[210:213], v[22:25]
	v_mfma_f32_16x16x32_bf16 v[14:17], v[162:165], v[210:213], v[14:17]
	s_setprio 2
	s_setprio 0
	v_mfma_f32_16x16x32_bf16 v[50:53], v[166:169], v[182:185], v[50:53]
	v_mfma_f32_16x16x32_bf16 v[42:45], v[174:177], v[182:185], v[42:45]
	v_mfma_f32_16x16x32_bf16 v[34:37], v[166:169], v[190:193], v[34:37]
	v_mfma_f32_16x16x32_bf16 v[26:29], v[174:177], v[190:193], v[26:29]
	v_mfma_f32_16x16x32_bf16 v[18:21], v[166:169], v[198:201], v[18:21]
	v_mfma_f32_16x16x32_bf16 v[10:13], v[174:177], v[198:201], v[10:13]
	v_mfma_f32_16x16x32_bf16 v[6:9], v[166:169], v[206:209], v[6:9]
	v_mfma_f32_16x16x32_bf16 v[2:5], v[174:177], v[206:209], v[2:5]
	v_mfma_f32_16x16x32_bf16 v[50:53], v[170:173], v[186:189], v[50:53]
	v_mfma_f32_16x16x32_bf16 v[42:45], v[178:181], v[186:189], v[42:45]
	v_mfma_f32_16x16x32_bf16 v[34:37], v[170:173], v[194:197], v[34:37]
	v_mfma_f32_16x16x32_bf16 v[26:29], v[178:181], v[194:197], v[26:29]
	v_mfma_f32_16x16x32_bf16 v[18:21], v[170:173], v[202:205], v[18:21]
	v_mfma_f32_16x16x32_bf16 v[10:13], v[178:181], v[202:205], v[10:13]
	v_mfma_f32_16x16x32_bf16 v[6:9], v[170:173], v[210:213], v[6:9]
	v_mfma_f32_16x16x32_bf16 v[2:5], v[178:181], v[210:213], v[2:5]
	s_setprio 2
	s_barrier
	s_add_i32 s92, s92, 2
	s_cmp_gt_u32 s92, 5
	s_mov_b64 s[46:47], s[52:53]
	s_cbranch_scc0 .LBB0_781
	s_and_b64 vcc, exec, s[8:9]
	s_cbranch_vccz .LBB0_784
	s_barrier

; #define PG8_STAGE(bufoff, gbase, voff) do { _Pragma("unroll") for (int _i = 0; _i < 2; ++_i) \
;         __builtin_amdgcn_global_load_lds((const unsigned*)((const char*)(gbase) + (voff)[_i]), (LAS unsigned*)(lds + (bufoff) + ldsw + _i * 8192), 16, 0, 0); } while (0)
; #define PG8_LDA(dst, b, h) do { _Pragma("unroll") for (int m = 0; m < 4; ++m) _Pragma("unroll") for (int k = 0; k < 2; ++k) dst[m][k] = *(const LAS bf16x8*)(lds + PG8_SA(b, h) + aoff + m * 2048 + k * 1024); } while (0)
; #define PG8_LDB(dst, b, h) do { _Pragma("unroll") for (int n = 0; n < 2; ++n) _Pragma("unroll") for (int k = 0; k < 2; ++k) dst[n][k] = *(const LAS bf16x8*)(lds + PG8_SB(b, h) + boff + n * 2048 + k * 1024); } while (0)
; #define PG8_MMA(ai, bj, At, Bt) do { __builtin_amdgcn_s_setprio(1); _Pragma("unroll") for (int m = 0; m < 4; ++m) _Pragma("unroll") for (int n = 0; n < 2; ++n) _Pragma("unroll") for (int k = 0; k < 2; ++k) \
;         acc[ai][bj][m][n] = __builtin_amdgcn_mfma_f32_16x16x32_bf16(Bt[n][k], At[m][k], acc[ai][bj][m][n], 0, 0, 0); __builtin_amdgcn_s_setprio(0); } while (0)
; #define PG8_WAIT_V(n) asm volatile("s_waitcnt vmcnt(" #n ")" ::: "memory")
; #define PG8_WAIT_L(n) asm volatile("s_waitcnt lgkmcnt(" #n ")" ::: "memory")
; #define PG8_BAR __builtin_amdgcn_s_barrier()
; #define PG8_SCHED __builtin_amdgcn_sched_barrier(0)
; template <class Epi>
; __device__ __forceinline__ void gemm_phase(LAS unsigned char* lds, const Gemm g, int G, int c, const Epi& E) {
;     ...
;             const char* a1 = cA + (size_t)(t + 1) * kstep;
;             const char* a2 = last ? nA : cA + (size_t)(t + 2) * kstep; const char* b2 = last ? nB : cB + (size_t)(t + 2) * kstep;
;             const char* a3 = a2 + kstep; const char* b3 = b2 + kstep;
;             PG8_LDB(B0, 0, 0); PG8_LDB(B1, 0, 1); PG8_SCHED; PG8_LDA(At, 0, 0); PG8_STAGE(PG8_SA(1, 1), a1 + hstepA, voffA);
;             PG8_WAIT_V(8); PG8_WAIT_L(0); PG8_BAR; PG8_MMA(0, 0, At, B0); PG8_MMA(0, 1, At, B1); PG8_BAR; PG8_SCHED;
;             PG8_LDA(At, 0, 1); PG8_STAGE(PG8_SB(0, 0), b2, voffB); PG8_STAGE(PG8_SB(0, 1), b2 + hstepB, voffB); PG8_STAGE(PG8_SA(0, 0), a2, voffA);
;             PG8_WAIT_V(8); PG8_WAIT_L(0); PG8_BAR; PG8_MMA(1, 0, At, B0); PG8_MMA(1, 1, At, B1); PG8_BAR; PG8_SCHED;
.LBB0_903:
	s_add_u32 s33, s4, 0xfffc0080
	s_addc_u32 s42, s5, -1
	s_cmp_eq_u32 s46, 12
	s_cselect_b32 s45, s19, s42
	s_cselect_b32 s44, s18, s33
	s_cselect_b32 s43, s15, s39
	s_cselect_b32 s42, s17, s23
	v_lshl_add_u64 v[166:167], s[4:5], 0, v[154:155]
	s_add_i32 m0, s25, 0xc000
	s_nop 0
	global_load_lds_dwordx4 v[166:167], off
	v_lshl_add_u64 v[166:167], s[4:5], 0, v[156:157]
	s_add_i32 m0, s25, 0xe000
	s_nop 0
	global_load_lds_dwordx4 v[166:167], off
	ds_read_b128 v[130:133], v170
	ds_read_b128 v[134:137], v170 offset:1024
	ds_read_b128 v[138:141], v170 offset:2048
	ds_read_b128 v[142:145], v170 offset:3072
	ds_read_b128 v[162:165], v171
	ds_read_b128 v[174:177], v171 offset:1024
	ds_read_b128 v[178:181], v171 offset:2048
	ds_read_b128 v[182:185], v171 offset:3072
	ds_read_b128 v[186:189], v172
	ds_read_b128 v[190:193], v172 offset:1024
	ds_read_b128 v[194:197], v172 offset:2048
	ds_read_b128 v[198:201], v172 offset:3072
	ds_read_b128 v[202:205], v172 offset:4096
	ds_read_b128 v[206:209], v172 offset:5120
	ds_read_b128 v[210:213], v172 offset:6144
	ds_read_b128 v[214:217], v172 offset:7168
	s_waitcnt vmcnt(8)
	s_waitcnt lgkmcnt(0)
	s_barrier
	s_setprio 0
	s_waitcnt lgkmcnt(0)
	v_mfma_f32_16x16x32_bf16 v[126:129], v[130:133], v[186:189], v[126:129]
	v_mfma_f32_16x16x32_bf16 v[122:125], v[138:141], v[186:189], v[122:125]
	v_mfma_f32_16x16x32_bf16 v[110:113], v[130:133], v[194:197], v[110:113]
	v_mfma_f32_16x16x32_bf16 v[106:109], v[138:141], v[194:197], v[106:109]
	v_mfma_f32_16x16x32_bf16 v[94:97], v[130:133], v[202:205], v[94:97]
	v_mfma_f32_16x16x32_bf16 v[90:93], v[138:141], v[202:205], v[90:93]
	v_mfma_f32_16x16x32_bf16 v[78:81], v[130:133], v[210:213], v[78:81]
	v_mfma_f32_16x16x32_bf16 v[74:77], v[138:141], v[210:213], v[74:77]
	v_mfma_f32_16x16x32_bf16 v[126:129], v[134:137], v[190:193], v[126:129]
	v_mfma_f32_16x16x32_bf16 v[122:125], v[142:145], v[190:193], v[122:125]
	v_mfma_f32_16x16x32_bf16 v[110:113], v[134:137], v[198:201], v[110:113]
	v_mfma_f32_16x16x32_bf16 v[106:109], v[142:145], v[198:201], v[106:109]
	v_mfma_f32_16x16x32_bf16 v[94:97], v[134:137], v[206:209], v[94:97]
	v_mfma_f32_16x16x32_bf16 v[90:93], v[142:145], v[206:209], v[90:93]
	v_mfma_f32_16x16x32_bf16 v[78:81], v[134:137], v[214:217], v[78:81]
	v_mfma_f32_16x16x32_bf16 v[74:77], v[142:145], v[214:217], v[74:77]
	s_setprio 2
	s_setprio 0
	v_mfma_f32_16x16x32_bf16 v[118:121], v[162:165], v[186:189], v[118:121]
	v_mfma_f32_16x16x32_bf16 v[114:117], v[178:181], v[186:189], v[114:117]
	v_mfma_f32_16x16x32_bf16 v[102:105], v[162:165], v[194:197], v[102:105]
	v_mfma_f32_16x16x32_bf16 v[98:101], v[178:181], v[194:197], v[98:101]
	v_mfma_f32_16x16x32_bf16 v[86:89], v[162:165], v[202:205], v[86:89]
	v_mfma_f32_16x16x32_bf16 v[82:85], v[178:181], v[202:205], v[82:85]
	v_mfma_f32_16x16x32_bf16 v[70:73], v[162:165], v[210:213], v[70:73]
	v_mfma_f32_16x16x32_bf16 v[66:69], v[178:181], v[210:213], v[66:69]
	v_mfma_f32_16x16x32_bf16 v[118:121], v[174:177], v[190:193], v[118:121]
	v_mfma_f32_16x16x32_bf16 v[114:117], v[182:185], v[190:193], v[114:117]
	v_mfma_f32_16x16x32_bf16 v[102:105], v[174:177], v[198:201], v[102:105]
	v_mfma_f32_16x16x32_bf16 v[98:101], v[182:185], v[198:201], v[98:101]
	v_mfma_f32_16x16x32_bf16 v[86:89], v[174:177], v[206:209], v[86:89]
	v_mfma_f32_16x16x32_bf16 v[82:85], v[182:185], v[206:209], v[82:85]
	v_mfma_f32_16x16x32_bf16 v[70:73], v[174:177], v[214:217], v[70:73]
	v_mfma_f32_16x16x32_bf16 v[66:69], v[182:185], v[214:217], v[66:69]
	s_setprio 2
	s_barrier
	s_add_i32 s33, s72, s54
	v_lshl_add_u64 v[166:167], s[42:43], 0, v[150:151]
	s_mov_b32 m0, s33
	s_nop 0
	global_load_lds_dwordx4 v[166:167], off
	s_add_i32 m0, s33, 0x2000
	s_add_u32 s62, s42, 0x40000
	v_lshl_add_u64 v[218:219], s[42:43], 0, v[146:147]
	s_addc_u32 s63, s43, 0
	s_add_i32 s33, s73, s54
	global_load_lds_dwordx4 v[218:219], off
	v_lshl_add_u64 v[220:221], s[62:63], 0, v[150:151]
	s_mov_b32 m0, s33
	v_lshl_add_u64 v[222:223], s[44:45], 0, v[148:149]
	global_load_lds_dwordx4 v[220:221], off
	v_lshl_add_u64 v[220:221], s[62:63], 0, v[146:147]
	s_add_i32 m0, s33, 0x2000
	s_nop 0
	global_load_lds_dwordx4 v[220:221], off
	v_lshl_add_u64 v[220:221], s[44:45], 0, v[152:153]
	s_mov_b32 m0, s25
	s_nop 0
	global_load_lds_dwordx4 v[220:221], off
	s_mov_b32 m0, s57
	s_nop 0
	global_load_lds_dwordx4 v[222:223], off
	ds_read_b128 v[186:189], v172 offset:16384
	ds_read_b128 v[190:193], v172 offset:17408
	ds_read_b128 v[194:197], v172 offset:18432
	ds_read_b128 v[198:201], v172 offset:19456
	ds_read_b128 v[202:205], v172 offset:20480
	ds_read_b128 v[206:209], v172 offset:21504
	ds_read_b128 v[210:213], v172 offset:22528
	ds_read_b128 v[214:217], v172 offset:23552
	s_waitcnt vmcnt(8)
	s_waitcnt lgkmcnt(0)
	s_barrier
; #define PG8_STAGE(bufoff, gbase, voff) do { _Pragma("unroll") for (int _i = 0; _i < 2; ++_i) \
;         __builtin_amdgcn_global_load_lds((const unsigned*)((const char*)(gbase) + (voff)[_i]), (LAS unsigned*)(lds + (bufoff) + ldsw + _i * 8192), 16, 0, 0); } while (0)
; #define PG8_LDA(dst, b, h) do { _Pragma("unroll") for (int m = 0; m < 4; ++m) _Pragma("unroll") for (int k = 0; k < 2; ++k) dst[m][k] = *(const LAS bf16x8*)(lds + PG8_SA(b, h) + aoff + m * 2048 + k * 1024); } while (0)
; #define PG8_LDB(dst, b, h) do { _Pragma("unroll") for (int n = 0; n < 2; ++n) _Pragma("unroll") for (int k = 0; k < 2; ++k) dst[n][k] = *(const LAS bf16x8*)(lds + PG8_SB(b, h) + boff + n * 2048 + k * 1024); } while (0)
; #define PG8_MMA(ai, bj, At, Bt) do { __builtin_amdgcn_s_setprio(1); _Pragma("unroll") for (int m = 0; m < 4; ++m) _Pragma("unroll") for (int n = 0; n < 2; ++n) _Pragma("unroll") for (int k = 0; k < 2; ++k) \
;         acc[ai][bj][m][n] = __builtin_amdgcn_mfma_f32_16x16x32_bf16(Bt[n][k], At[m][k], acc[ai][bj][m][n], 0, 0, 0); __builtin_amdgcn_s_setprio(0); } while (0)
; #define PG8_WAIT_V(n) asm volatile("s_waitcnt vmcnt(" #n ")" ::: "memory")
; #define PG8_WAIT_L(n) asm volatile("s_waitcnt lgkmcnt(" #n ")" ::: "memory")
; #define PG8_BAR __builtin_amdgcn_s_barrier()
; #define PG8_SCHED __builtin_amdgcn_sched_barrier(0)
; template <class Epi>
; __device__ __forceinline__ void gemm_phase(LAS unsigned char* lds, const Gemm g, int G, int c, const Epi& E) {
;     ...
;             PG8_WAIT_V(8); PG8_WAIT_L(0); PG8_BAR; PG8_MMA(1, 0, At, B0); PG8_MMA(1, 1, At, B1); PG8_BAR; PG8_SCHED;
;             PG8_LDB(B0, 1, 0); PG8_LDB(B1, 1, 1); PG8_SCHED; PG8_LDA(At, 1, 0); PG8_STAGE(PG8_SA(0, 1), a2 + hstepA, voffA);
;             PG8_WAIT_V(8); PG8_WAIT_L(0); PG8_BAR; PG8_MMA(0, 0, At, B0); PG8_MMA(0, 1, At, B1); PG8_BAR; PG8_SCHED;
	s_setprio 0
	s_waitcnt lgkmcnt(0)
	v_mfma_f32_16x16x32_bf16 v[62:65], v[130:133], v[186:189], v[62:65]
	v_mfma_f32_16x16x32_bf16 v[58:61], v[138:141], v[186:189], v[58:61]
	v_mfma_f32_16x16x32_bf16 v[46:49], v[130:133], v[194:197], v[46:49]
	v_mfma_f32_16x16x32_bf16 v[42:45], v[138:141], v[194:197], v[42:45]
	v_mfma_f32_16x16x32_bf16 v[30:33], v[130:133], v[202:205], v[30:33]
	v_mfma_f32_16x16x32_bf16 v[26:29], v[138:141], v[202:205], v[26:29]
	v_mfma_f32_16x16x32_bf16 v[14:17], v[130:133], v[210:213], v[14:17]
	v_mfma_f32_16x16x32_bf16 v[10:13], v[138:141], v[210:213], v[10:13]
	v_mfma_f32_16x16x32_bf16 v[62:65], v[134:137], v[190:193], v[62:65]
	v_mfma_f32_16x16x32_bf16 v[58:61], v[142:145], v[190:193], v[58:61]
	v_mfma_f32_16x16x32_bf16 v[46:49], v[134:137], v[198:201], v[46:49]
	v_mfma_f32_16x16x32_bf16 v[42:45], v[142:145], v[198:201], v[42:45]
	v_mfma_f32_16x16x32_bf16 v[30:33], v[134:137], v[206:209], v[30:33]
	v_mfma_f32_16x16x32_bf16 v[26:29], v[142:145], v[206:209], v[26:29]
	v_mfma_f32_16x16x32_bf16 v[14:17], v[134:137], v[214:217], v[14:17]
	v_mfma_f32_16x16x32_bf16 v[10:13], v[142:145], v[214:217], v[10:13]
	s_setprio 2
	s_setprio 0
	v_mfma_f32_16x16x32_bf16 v[54:57], v[162:165], v[186:189], v[54:57]
	v_mfma_f32_16x16x32_bf16 v[50:53], v[178:181], v[186:189], v[50:53]
	v_mfma_f32_16x16x32_bf16 v[38:41], v[162:165], v[194:197], v[38:41]
	v_mfma_f32_16x16x32_bf16 v[34:37], v[178:181], v[194:197], v[34:37]
	v_mfma_f32_16x16x32_bf16 v[22:25], v[162:165], v[202:205], v[22:25]
	v_mfma_f32_16x16x32_bf16 v[18:21], v[178:181], v[202:205], v[18:21]
	v_mfma_f32_16x16x32_bf16 v[6:9], v[162:165], v[210:213], v[6:9]
	v_mfma_f32_16x16x32_bf16 v[2:5], v[178:181], v[210:213], v[2:5]
	v_mfma_f32_16x16x32_bf16 v[54:57], v[174:177], v[190:193], v[54:57]
	v_mfma_f32_16x16x32_bf16 v[50:53], v[182:185], v[190:193], v[50:53]
	v_mfma_f32_16x16x32_bf16 v[38:41], v[174:177], v[198:201], v[38:41]
	v_mfma_f32_16x16x32_bf16 v[34:37], v[182:185], v[198:201], v[34:37]
	v_mfma_f32_16x16x32_bf16 v[22:25], v[174:177], v[206:209], v[22:25]
	v_mfma_f32_16x16x32_bf16 v[18:21], v[182:185], v[206:209], v[18:21]
	v_mfma_f32_16x16x32_bf16 v[6:9], v[174:177], v[214:217], v[6:9]
	v_mfma_f32_16x16x32_bf16 v[2:5], v[182:185], v[214:217], v[2:5]
	s_setprio 2
	s_barrier
	s_add_i32 s33, 0, 0x18000
	s_add_i32 s47, 0, 0x1c000
	s_add_u32 s44, s44, 0x40000
	s_addc_u32 s45, s45, 0
	s_mov_b32 m0, s58
	v_lshl_add_u64 v[224:225], s[44:45], 0, v[152:153]
	global_load_lds_dwordx4 v[224:225], off
	v_lshl_add_u64 v[224:225], s[44:45], 0, v[148:149]
	s_mov_b32 m0, s59
	s_nop 0
	global_load_lds_dwordx4 v[224:225], off
	v_add_u32_e32 v142, s33, v169
	v_add_u32_e32 v173, s47, v169
	ds_read_b128 v[130:133], v142
	ds_read_b128 v[134:137], v142 offset:1024
	ds_read_b128 v[138:141], v142 offset:2048
	ds_read_b128 v[142:145], v142 offset:3072
	ds_read_b128 v[162:165], v173
	ds_read_b128 v[174:177], v173 offset:1024
	ds_read_b128 v[178:181], v173 offset:2048
	ds_read_b128 v[182:185], v173 offset:3072
	ds_read_b128 v[186:189], v172 offset:32768
	ds_read_b128 v[190:193], v172 offset:33792
	ds_read_b128 v[194:197], v172 offset:34816
	ds_read_b128 v[198:201], v172 offset:35840
	ds_read_b128 v[202:205], v172 offset:36864
	ds_read_b128 v[206:209], v172 offset:37888
	ds_read_b128 v[210:213], v172 offset:38912
	ds_read_b128 v[214:217], v172 offset:39936
	s_waitcnt vmcnt(8)
	s_waitcnt lgkmcnt(0)
	s_barrier
	s_setprio 0
	s_waitcnt lgkmcnt(0)
	v_mfma_f32_16x16x32_bf16 v[126:129], v[130:133], v[186:189], v[126:129]
	v_mfma_f32_16x16x32_bf16 v[122:125], v[138:141], v[186:189], v[122:125]
	v_mfma_f32_16x16x32_bf16 v[110:113], v[130:133], v[194:197], v[110:113]
	v_mfma_f32_16x16x32_bf16 v[106:109], v[138:141], v[194:197], v[106:109]
	v_mfma_f32_16x16x32_bf16 v[94:97], v[130:133], v[202:205], v[94:97]
	v_mfma_f32_16x16x32_bf16 v[90:93], v[138:141], v[202:205], v[90:93]
	v_mfma_f32_16x16x32_bf16 v[78:81], v[130:133], v[210:213], v[78:81]
	v_mfma_f32_16x16x32_bf16 v[74:77], v[138:141], v[210:213], v[74:77]
	v_mfma_f32_16x16x32_bf16 v[126:129], v[134:137], v[190:193], v[126:129]
	v_mfma_f32_16x16x32_bf16 v[122:125], v[142:145], v[190:193], v[122:125]
	v_mfma_f32_16x16x32_bf16 v[110:113], v[134:137], v[198:201], v[110:113]
	v_mfma_f32_16x16x32_bf16 v[106:109], v[142:145], v[198:201], v[106:109]
	v_mfma_f32_16x16x32_bf16 v[94:97], v[134:137], v[206:209], v[94:97]
	v_mfma_f32_16x16x32_bf16 v[90:93], v[142:145], v[206:209], v[90:93]
	v_mfma_f32_16x16x32_bf16 v[78:81], v[134:137], v[214:217], v[78:81]
	v_mfma_f32_16x16x32_bf16 v[74:77], v[142:145], v[214:217], v[74:77]
	s_setprio 2
	s_setprio 0
	v_mfma_f32_16x16x32_bf16 v[118:121], v[162:165], v[186:189], v[118:121]
	v_mfma_f32_16x16x32_bf16 v[114:117], v[178:181], v[186:189], v[114:117]
	v_mfma_f32_16x16x32_bf16 v[102:105], v[162:165], v[194:197], v[102:105]
	v_mfma_f32_16x16x32_bf16 v[98:101], v[178:181], v[194:197], v[98:101]
	v_mfma_f32_16x16x32_bf16 v[86:89], v[162:165], v[202:205], v[86:89]
	v_mfma_f32_16x16x32_bf16 v[82:85], v[178:181], v[202:205], v[82:85]
	v_mfma_f32_16x16x32_bf16 v[70:73], v[162:165], v[210:213], v[70:73]
	v_mfma_f32_16x16x32_bf16 v[66:69], v[178:181], v[210:213], v[66:69]
	v_mfma_f32_16x16x32_bf16 v[118:121], v[174:177], v[190:193], v[118:121]
	v_mfma_f32_16x16x32_bf16 v[114:117], v[182:185], v[190:193], v[114:117]
	v_mfma_f32_16x16x32_bf16 v[102:105], v[174:177], v[198:201], v[102:105]
	v_mfma_f32_16x16x32_bf16 v[98:101], v[182:185], v[198:201], v[98:101]
	v_mfma_f32_16x16x32_bf16 v[86:89], v[174:177], v[206:209], v[86:89]
	v_mfma_f32_16x16x32_bf16 v[82:85], v[182:185], v[206:209], v[82:85]
	v_mfma_f32_16x16x32_bf16 v[70:73], v[174:177], v[214:217], v[70:73]
	v_mfma_f32_16x16x32_bf16 v[66:69], v[182:185], v[214:217], v[66:69]
	s_setprio 2
	s_barrier
; #define PG8_STAGE(bufoff, gbase, voff) do { _Pragma("unroll") for (int _i = 0; _i < 2; ++_i) \
;         __builtin_amdgcn_global_load_lds((const unsigned*)((const char*)(gbase) + (voff)[_i]), (LAS unsigned*)(lds + (bufoff) + ldsw + _i * 8192), 16, 0, 0); } while (0)
; #define PG8_LDA(dst, b, h) do { _Pragma("unroll") for (int m = 0; m < 4; ++m) _Pragma("unroll") for (int k = 0; k < 2; ++k) dst[m][k] = *(const LAS bf16x8*)(lds + PG8_SA(b, h) + aoff + m * 2048 + k * 1024); } while (0)
; #define PG8_MMA(ai, bj, At, Bt) do { __builtin_amdgcn_s_setprio(1); _Pragma("unroll") for (int m = 0; m < 4; ++m) _Pragma("unroll") for (int n = 0; n < 2; ++n) _Pragma("unroll") for (int k = 0; k < 2; ++k) \
;         acc[ai][bj][m][n] = __builtin_amdgcn_mfma_f32_16x16x32_bf16(Bt[n][k], At[m][k], acc[ai][bj][m][n], 0, 0, 0); __builtin_amdgcn_s_setprio(0); } while (0)
; #define PG8_WAIT_V(n) asm volatile("s_waitcnt vmcnt(" #n ")" ::: "memory")
; #define PG8_WAIT_L(n) asm volatile("s_waitcnt lgkmcnt(" #n ")" ::: "memory")
; #define PG8_BAR __builtin_amdgcn_s_barrier()
; #define PG8_SCHED __builtin_amdgcn_sched_barrier(0)
; template <class Epi>
; __device__ __forceinline__ void gemm_phase(LAS unsigned char* lds, const Gemm g, int G, int c, const Epi& E) {
;     ...
;             PG8_LDA(At, 1, 1); PG8_STAGE(PG8_SB(1, 0), b3, voffB); PG8_STAGE(PG8_SB(1, 1), b3 + hstepB, voffB); PG8_STAGE(PG8_SA(1, 0), a3, voffA);
;             PG8_WAIT_V(8); PG8_WAIT_L(0); PG8_BAR; PG8_MMA(1, 0, At, B0); PG8_MMA(1, 1, At, B1); PG8_BAR; PG8_SCHED;
;         }
;         if (wr == 0) PG8_BAR;
	s_add_i32 s33, s33, s54
	v_lshl_add_u64 v[166:167], v[166:167], 0, s[10:11]
	s_mov_b32 m0, s33
	s_nop 0
	global_load_lds_dwordx4 v[166:167], off
	s_add_i32 m0, s33, 0x2000
	s_add_u32 s42, s42, 0x40080
	v_lshl_add_u64 v[166:167], v[218:219], 0, s[10:11]
	s_addc_u32 s43, s43, 0
	s_add_i32 s33, s47, s54
	global_load_lds_dwordx4 v[166:167], off
	v_lshl_add_u64 v[166:167], s[42:43], 0, v[150:151]
	s_mov_b32 m0, s33
	s_nop 0
	global_load_lds_dwordx4 v[166:167], off
	v_lshl_add_u64 v[166:167], s[42:43], 0, v[146:147]
	s_add_i32 m0, s33, 0x2000
	s_nop 0
	global_load_lds_dwordx4 v[166:167], off
	v_lshl_add_u64 v[166:167], v[220:221], 0, s[10:11]
	s_mov_b32 m0, s69
	s_nop 0
	global_load_lds_dwordx4 v[166:167], off
	v_lshl_add_u64 v[166:167], v[222:223], 0, s[10:11]
	s_mov_b32 m0, s70
	s_nop 0
	global_load_lds_dwordx4 v[166:167], off
	ds_read_b128 v[186:189], v172 offset:49152
	ds_read_b128 v[190:193], v172 offset:50176
	ds_read_b128 v[194:197], v172 offset:51200
	ds_read_b128 v[198:201], v172 offset:52224
	ds_read_b128 v[202:205], v172 offset:53248
	ds_read_b128 v[206:209], v172 offset:54272
	ds_read_b128 v[210:213], v172 offset:55296
	ds_read_b128 v[214:217], v172 offset:56320
	s_waitcnt vmcnt(8)
	s_waitcnt lgkmcnt(0)
	s_barrier
	s_setprio 0
	s_waitcnt lgkmcnt(0)
	v_mfma_f32_16x16x32_bf16 v[62:65], v[130:133], v[186:189], v[62:65]
	v_mfma_f32_16x16x32_bf16 v[58:61], v[138:141], v[186:189], v[58:61]
	v_mfma_f32_16x16x32_bf16 v[46:49], v[130:133], v[194:197], v[46:49]
	v_mfma_f32_16x16x32_bf16 v[42:45], v[138:141], v[194:197], v[42:45]
	v_mfma_f32_16x16x32_bf16 v[30:33], v[130:133], v[202:205], v[30:33]
	v_mfma_f32_16x16x32_bf16 v[26:29], v[138:141], v[202:205], v[26:29]
	v_mfma_f32_16x16x32_bf16 v[14:17], v[130:133], v[210:213], v[14:17]
	v_mfma_f32_16x16x32_bf16 v[10:13], v[138:141], v[210:213], v[10:13]
	v_mfma_f32_16x16x32_bf16 v[62:65], v[134:137], v[190:193], v[62:65]
	v_mfma_f32_16x16x32_bf16 v[58:61], v[142:145], v[190:193], v[58:61]
	v_mfma_f32_16x16x32_bf16 v[46:49], v[134:137], v[198:201], v[46:49]
	v_mfma_f32_16x16x32_bf16 v[42:45], v[142:145], v[198:201], v[42:45]
	v_mfma_f32_16x16x32_bf16 v[30:33], v[134:137], v[206:209], v[30:33]
	v_mfma_f32_16x16x32_bf16 v[26:29], v[142:145], v[206:209], v[26:29]
	v_mfma_f32_16x16x32_bf16 v[14:17], v[134:137], v[214:217], v[14:17]
	v_mfma_f32_16x16x32_bf16 v[10:13], v[142:145], v[214:217], v[10:13]
	s_setprio 2
	s_setprio 0
	v_mfma_f32_16x16x32_bf16 v[54:57], v[162:165], v[186:189], v[54:57]
	v_mfma_f32_16x16x32_bf16 v[50:53], v[178:181], v[186:189], v[50:53]
	v_mfma_f32_16x16x32_bf16 v[38:41], v[162:165], v[194:197], v[38:41]
	v_mfma_f32_16x16x32_bf16 v[34:37], v[178:181], v[194:197], v[34:37]
	v_mfma_f32_16x16x32_bf16 v[22:25], v[162:165], v[202:205], v[22:25]
	v_mfma_f32_16x16x32_bf16 v[18:21], v[178:181], v[202:205], v[18:21]
	v_mfma_f32_16x16x32_bf16 v[6:9], v[162:165], v[210:213], v[6:9]
	v_mfma_f32_16x16x32_bf16 v[2:5], v[178:181], v[210:213], v[2:5]
	v_mfma_f32_16x16x32_bf16 v[54:57], v[174:177], v[190:193], v[54:57]
	v_mfma_f32_16x16x32_bf16 v[50:53], v[182:185], v[190:193], v[50:53]
	v_mfma_f32_16x16x32_bf16 v[38:41], v[174:177], v[198:201], v[38:41]
	v_mfma_f32_16x16x32_bf16 v[34:37], v[182:185], v[198:201], v[34:37]
	v_mfma_f32_16x16x32_bf16 v[22:25], v[174:177], v[206:209], v[22:25]
	v_mfma_f32_16x16x32_bf16 v[18:21], v[182:185], v[206:209], v[18:21]
	v_mfma_f32_16x16x32_bf16 v[6:9], v[174:177], v[214:217], v[6:9]
	v_mfma_f32_16x16x32_bf16 v[2:5], v[182:185], v[214:217], v[2:5]
	s_setprio 2
	s_barrier
	s_add_i32 s46, s46, 2
	s_add_u32 s4, s4, 0x100
	s_addc_u32 s5, s5, 0
	s_add_u32 s23, s23, 0x100
	s_addc_u32 s39, s39, 0
	s_cmp_gt_u32 s46, 13
	s_cbranch_scc0 .LBB0_903
	s_and_b64 vcc, exec, s[12:13]
	s_cbranch_vccz .LBB0_906
	s_barrier

; #define PG8_STAGE(bufoff, gbase, voff) do { _Pragma("unroll") for (int _i = 0; _i < 2; ++_i) \
;         __builtin_amdgcn_global_load_lds((const unsigned*)((const char*)(gbase) + (voff)[_i]), (LAS unsigned*)(lds + (bufoff) + ldsw + _i * 8192), 16, 0, 0); } while (0)
; #define PG8_LDA(dst, b, h) do { _Pragma("unroll") for (int m = 0; m < 4; ++m) _Pragma("unroll") for (int k = 0; k < 2; ++k) dst[m][k] = *(const LAS bf16x8*)(lds + PG8_SA(b, h) + aoff + m * 2048 + k * 1024); } while (0)
; #define PG8_LDB(dst, b, h) do { _Pragma("unroll") for (int n = 0; n < 2; ++n) _Pragma("unroll") for (int k = 0; k < 2; ++k) dst[n][k] = *(const LAS bf16x8*)(lds + PG8_SB(b, h) + boff + n * 2048 + k * 1024); } while (0)
; #define PG8_MMA(ai, bj, At, Bt) do { __builtin_amdgcn_s_setprio(1); _Pragma("unroll") for (int m = 0; m < 4; ++m) _Pragma("unroll") for (int n = 0; n < 2; ++n) _Pragma("unroll") for (int k = 0; k < 2; ++k) \
;         acc[ai][bj][m][n] = __builtin_amdgcn_mfma_f32_16x16x32_bf16(Bt[n][k], At[m][k], acc[ai][bj][m][n], 0, 0, 0); __builtin_amdgcn_s_setprio(0); } while (0)
; #define PG8_WAIT_V(n) asm volatile("s_waitcnt vmcnt(" #n ")" ::: "memory")
; #define PG8_WAIT_L(n) asm volatile("s_waitcnt lgkmcnt(" #n ")" ::: "memory")
; #define PG8_BAR __builtin_amdgcn_s_barrier()
; #define PG8_SCHED __builtin_amdgcn_sched_barrier(0)
; template <class Epi>
; __device__ __forceinline__ void gemm_phase(LAS unsigned char* lds, const Gemm g, int G, int c, const Epi& E) {
;     ...
;             const bool last = (t == nt - 2);
;             const char* a1 = cA + (size_t)(t + 1) * kstep;
;             const char* a2 = last ? nA : cA + (size_t)(t + 2) * kstep; const char* b2 = last ? nB : cB + (size_t)(t + 2) * kstep;
;             const char* a3 = a2 + kstep; const char* b3 = b2 + kstep;
;             PG8_LDB(B0, 0, 0); PG8_LDB(B1, 0, 1); PG8_SCHED; PG8_LDA(At, 0, 0); PG8_STAGE(PG8_SA(1, 1), a1 + hstepA, voffA);
;             PG8_WAIT_V(8); PG8_WAIT_L(0); PG8_BAR; PG8_MMA(0, 0, At, B0); PG8_MMA(0, 1, At, B1); PG8_BAR; PG8_SCHED;
;             PG8_LDA(At, 0, 1); PG8_STAGE(PG8_SB(0, 0), b2, voffB); PG8_STAGE(PG8_SB(0, 1), b2 + hstepB, voffB); PG8_STAGE(PG8_SA(0, 0), a2, voffA);
.LBB0_1058:
	s_add_u32 s33, s4, 0xfffc0080
	s_addc_u32 s38, s5, -1
	s_cmp_eq_u32 s80, 12
	s_cselect_b32 s41, s21, s38
	s_cselect_b32 s40, s20, s33
	s_cselect_b32 s39, s17, s79
	s_cselect_b32 s38, s19, s78
	v_lshl_add_u64 v[216:217], s[4:5], 0, v[138:139]
	s_add_i32 m0, s25, 0xc000
	s_nop 0
	global_load_lds_dwordx4 v[216:217], off
	v_lshl_add_u64 v[216:217], s[4:5], 0, v[140:141]
	s_add_i32 m0, s25, 0xe000
	s_nop 0
	global_load_lds_dwordx4 v[216:217], off
	ds_read_b128 v[152:155], v148
	ds_read_b128 v[156:159], v148 offset:1024
	ds_read_b128 v[160:163], v148 offset:2048
	ds_read_b128 v[164:167], v148 offset:3072
	ds_read_b128 v[168:171], v149
	ds_read_b128 v[172:175], v149 offset:1024
	ds_read_b128 v[176:179], v149 offset:2048
	ds_read_b128 v[180:183], v149 offset:3072
	ds_read_b128 v[184:187], v150
	ds_read_b128 v[188:191], v150 offset:1024
	ds_read_b128 v[192:195], v150 offset:2048
	ds_read_b128 v[196:199], v150 offset:3072
	ds_read_b128 v[200:203], v150 offset:4096
	ds_read_b128 v[204:207], v150 offset:5120
	ds_read_b128 v[208:211], v150 offset:6144
	ds_read_b128 v[212:215], v150 offset:7168
	s_waitcnt vmcnt(8)
	s_waitcnt lgkmcnt(0)
	s_barrier
	s_setprio 0
	s_waitcnt lgkmcnt(0)
	v_mfma_f32_16x16x32_bf16 v[126:129], v[152:155], v[184:187], v[126:129]
	v_mfma_f32_16x16x32_bf16 v[122:125], v[160:163], v[184:187], v[122:125]
	v_mfma_f32_16x16x32_bf16 v[110:113], v[152:155], v[192:195], v[110:113]
	v_mfma_f32_16x16x32_bf16 v[106:109], v[160:163], v[192:195], v[106:109]
	v_mfma_f32_16x16x32_bf16 v[94:97], v[152:155], v[200:203], v[94:97]
	v_mfma_f32_16x16x32_bf16 v[90:93], v[160:163], v[200:203], v[90:93]
	v_mfma_f32_16x16x32_bf16 v[78:81], v[152:155], v[208:211], v[78:81]
	v_mfma_f32_16x16x32_bf16 v[74:77], v[160:163], v[208:211], v[74:77]
	v_mfma_f32_16x16x32_bf16 v[126:129], v[156:159], v[188:191], v[126:129]
	v_mfma_f32_16x16x32_bf16 v[122:125], v[164:167], v[188:191], v[122:125]
	v_mfma_f32_16x16x32_bf16 v[110:113], v[156:159], v[196:199], v[110:113]
	v_mfma_f32_16x16x32_bf16 v[106:109], v[164:167], v[196:199], v[106:109]
	v_mfma_f32_16x16x32_bf16 v[94:97], v[156:159], v[204:207], v[94:97]
	v_mfma_f32_16x16x32_bf16 v[90:93], v[164:167], v[204:207], v[90:93]
	v_mfma_f32_16x16x32_bf16 v[78:81], v[156:159], v[212:215], v[78:81]
	v_mfma_f32_16x16x32_bf16 v[74:77], v[164:167], v[212:215], v[74:77]
	s_setprio 2
	s_setprio 0
	v_mfma_f32_16x16x32_bf16 v[118:121], v[168:171], v[184:187], v[118:121]
	v_mfma_f32_16x16x32_bf16 v[114:117], v[176:179], v[184:187], v[114:117]
	v_mfma_f32_16x16x32_bf16 v[102:105], v[168:171], v[192:195], v[102:105]
	v_mfma_f32_16x16x32_bf16 v[98:101], v[176:179], v[192:195], v[98:101]
	v_mfma_f32_16x16x32_bf16 v[86:89], v[168:171], v[200:203], v[86:89]
	v_mfma_f32_16x16x32_bf16 v[82:85], v[176:179], v[200:203], v[82:85]
	v_mfma_f32_16x16x32_bf16 v[70:73], v[168:171], v[208:211], v[70:73]
	v_mfma_f32_16x16x32_bf16 v[66:69], v[176:179], v[208:211], v[66:69]
	v_mfma_f32_16x16x32_bf16 v[118:121], v[172:175], v[188:191], v[118:121]
	v_mfma_f32_16x16x32_bf16 v[114:117], v[180:183], v[188:191], v[114:117]
	v_mfma_f32_16x16x32_bf16 v[102:105], v[172:175], v[196:199], v[102:105]
	v_mfma_f32_16x16x32_bf16 v[98:101], v[180:183], v[196:199], v[98:101]
	v_mfma_f32_16x16x32_bf16 v[86:89], v[172:175], v[204:207], v[86:89]
	v_mfma_f32_16x16x32_bf16 v[82:85], v[180:183], v[204:207], v[82:85]
	v_mfma_f32_16x16x32_bf16 v[70:73], v[172:175], v[212:215], v[70:73]
	v_mfma_f32_16x16x32_bf16 v[66:69], v[180:183], v[212:215], v[66:69]
	s_setprio 2
	s_barrier
	s_add_i32 s33, s60, s46
	v_lshl_add_u64 v[216:217], s[38:39], 0, v[134:135]
	s_mov_b32 m0, s33
	s_nop 0
	global_load_lds_dwordx4 v[216:217], off
	s_add_i32 m0, s33, 0x2000
	s_add_u32 s62, s38, 0x40000
	v_lshl_add_u64 v[218:219], s[38:39], 0, v[130:131]
	s_addc_u32 s63, s39, 0
	s_add_i32 s33, s61, s46
	global_load_lds_dwordx4 v[218:219], off
	v_lshl_add_u64 v[220:221], s[62:63], 0, v[134:135]
	s_mov_b32 m0, s33
	v_lshl_add_u64 v[222:223], s[40:41], 0, v[132:133]
	global_load_lds_dwordx4 v[220:221], off
	v_lshl_add_u64 v[220:221], s[62:63], 0, v[130:131]
	s_add_i32 m0, s33, 0x2000
	s_nop 0
	global_load_lds_dwordx4 v[220:221], off
	v_lshl_add_u64 v[220:221], s[40:41], 0, v[136:137]
	s_mov_b32 m0, s25
	s_nop 0
	global_load_lds_dwordx4 v[220:221], off
	s_mov_b32 m0, s37
	s_nop 0
	global_load_lds_dwordx4 v[222:223], off
	ds_read_b128 v[184:187], v150 offset:16384
	ds_read_b128 v[188:191], v150 offset:17408
	ds_read_b128 v[192:195], v150 offset:18432
	ds_read_b128 v[196:199], v150 offset:19456
	ds_read_b128 v[200:203], v150 offset:20480
	ds_read_b128 v[204:207], v150 offset:21504
	ds_read_b128 v[208:211], v150 offset:22528
	ds_read_b128 v[212:215], v150 offset:23552
	s_waitcnt vmcnt(8)
	s_waitcnt lgkmcnt(0)
	s_barrier
; #define PG8_STAGE(bufoff, gbase, voff) do { _Pragma("unroll") for (int _i = 0; _i < 2; ++_i) \
;         __builtin_amdgcn_global_load_lds((const unsigned*)((const char*)(gbase) + (voff)[_i]), (LAS unsigned*)(lds + (bufoff) + ldsw + _i * 8192), 16, 0, 0); } while (0)
; #define PG8_LDA(dst, b, h) do { _Pragma("unroll") for (int m = 0; m < 4; ++m) _Pragma("unroll") for (int k = 0; k < 2; ++k) dst[m][k] = *(const LAS bf16x8*)(lds + PG8_SA(b, h) + aoff + m * 2048 + k * 1024); } while (0)
; #define PG8_LDB(dst, b, h) do { _Pragma("unroll") for (int n = 0; n < 2; ++n) _Pragma("unroll") for (int k = 0; k < 2; ++k) dst[n][k] = *(const LAS bf16x8*)(lds + PG8_SB(b, h) + boff + n * 2048 + k * 1024); } while (0)
; #define PG8_MMA(ai, bj, At, Bt) do { __builtin_amdgcn_s_setprio(1); _Pragma("unroll") for (int m = 0; m < 4; ++m) _Pragma("unroll") for (int n = 0; n < 2; ++n) _Pragma("unroll") for (int k = 0; k < 2; ++k) \
;         acc[ai][bj][m][n] = __builtin_amdgcn_mfma_f32_16x16x32_bf16(Bt[n][k], At[m][k], acc[ai][bj][m][n], 0, 0, 0); __builtin_amdgcn_s_setprio(0); } while (0)
; #define PG8_WAIT_V(n) asm volatile("s_waitcnt vmcnt(" #n ")" ::: "memory")
; #define PG8_WAIT_L(n) asm volatile("s_waitcnt lgkmcnt(" #n ")" ::: "memory")
; #define PG8_BAR __builtin_amdgcn_s_barrier()
; #define PG8_SCHED __builtin_amdgcn_sched_barrier(0)
; template <class Epi>
; __device__ __forceinline__ void gemm_phase(LAS unsigned char* lds, const Gemm g, int G, int c, const Epi& E) {
;     ...
;             PG8_WAIT_V(8); PG8_WAIT_L(0); PG8_BAR; PG8_MMA(1, 0, At, B0); PG8_MMA(1, 1, At, B1); PG8_BAR; PG8_SCHED;
;             PG8_LDB(B0, 1, 0); PG8_LDB(B1, 1, 1); PG8_SCHED; PG8_LDA(At, 1, 0); PG8_STAGE(PG8_SA(0, 1), a2 + hstepA, voffA);
;             PG8_WAIT_V(8); PG8_WAIT_L(0); PG8_BAR; PG8_MMA(0, 0, At, B0); PG8_MMA(0, 1, At, B1); PG8_BAR; PG8_SCHED;
	s_setprio 0
	s_waitcnt lgkmcnt(0)
	v_mfma_f32_16x16x32_bf16 v[62:65], v[152:155], v[184:187], v[62:65]
	v_mfma_f32_16x16x32_bf16 v[58:61], v[160:163], v[184:187], v[58:61]
	v_mfma_f32_16x16x32_bf16 v[46:49], v[152:155], v[192:195], v[46:49]
	v_mfma_f32_16x16x32_bf16 v[42:45], v[160:163], v[192:195], v[42:45]
	v_mfma_f32_16x16x32_bf16 v[30:33], v[152:155], v[200:203], v[30:33]
	v_mfma_f32_16x16x32_bf16 v[26:29], v[160:163], v[200:203], v[26:29]
	v_mfma_f32_16x16x32_bf16 v[14:17], v[152:155], v[208:211], v[14:17]
	v_mfma_f32_16x16x32_bf16 v[10:13], v[160:163], v[208:211], v[10:13]
	v_mfma_f32_16x16x32_bf16 v[62:65], v[156:159], v[188:191], v[62:65]
	v_mfma_f32_16x16x32_bf16 v[58:61], v[164:167], v[188:191], v[58:61]
	v_mfma_f32_16x16x32_bf16 v[46:49], v[156:159], v[196:199], v[46:49]
	v_mfma_f32_16x16x32_bf16 v[42:45], v[164:167], v[196:199], v[42:45]
	v_mfma_f32_16x16x32_bf16 v[30:33], v[156:159], v[204:207], v[30:33]
	v_mfma_f32_16x16x32_bf16 v[26:29], v[164:167], v[204:207], v[26:29]
	v_mfma_f32_16x16x32_bf16 v[14:17], v[156:159], v[212:215], v[14:17]
	v_mfma_f32_16x16x32_bf16 v[10:13], v[164:167], v[212:215], v[10:13]
	s_setprio 2
	s_setprio 0
	v_mfma_f32_16x16x32_bf16 v[54:57], v[168:171], v[184:187], v[54:57]
	v_mfma_f32_16x16x32_bf16 v[50:53], v[176:179], v[184:187], v[50:53]
	v_mfma_f32_16x16x32_bf16 v[38:41], v[168:171], v[192:195], v[38:41]
	v_mfma_f32_16x16x32_bf16 v[34:37], v[176:179], v[192:195], v[34:37]
	v_mfma_f32_16x16x32_bf16 v[22:25], v[168:171], v[200:203], v[22:25]
	v_mfma_f32_16x16x32_bf16 v[18:21], v[176:179], v[200:203], v[18:21]
	v_mfma_f32_16x16x32_bf16 v[6:9], v[168:171], v[208:211], v[6:9]
	v_mfma_f32_16x16x32_bf16 v[2:5], v[176:179], v[208:211], v[2:5]
	v_mfma_f32_16x16x32_bf16 v[54:57], v[172:175], v[188:191], v[54:57]
	v_mfma_f32_16x16x32_bf16 v[50:53], v[180:183], v[188:191], v[50:53]
	v_mfma_f32_16x16x32_bf16 v[38:41], v[172:175], v[196:199], v[38:41]
	v_mfma_f32_16x16x32_bf16 v[34:37], v[180:183], v[196:199], v[34:37]
	v_mfma_f32_16x16x32_bf16 v[22:25], v[172:175], v[204:207], v[22:25]
	v_mfma_f32_16x16x32_bf16 v[18:21], v[180:183], v[204:207], v[18:21]
	v_mfma_f32_16x16x32_bf16 v[6:9], v[172:175], v[212:215], v[6:9]
	v_mfma_f32_16x16x32_bf16 v[2:5], v[180:183], v[212:215], v[2:5]
	s_setprio 2
	s_barrier
	s_add_i32 s33, 0, 0x18000
	s_add_i32 s62, 0, 0x1c000
	s_add_u32 s40, s40, 0x40000
	s_addc_u32 s41, s41, 0
	s_mov_b32 m0, s47
	v_lshl_add_u64 v[224:225], s[40:41], 0, v[136:137]
	global_load_lds_dwordx4 v[224:225], off
	v_lshl_add_u64 v[224:225], s[40:41], 0, v[132:133]
	s_mov_b32 m0, s52
	s_nop 0
	global_load_lds_dwordx4 v[224:225], off
	v_add_u32_e32 v164, s33, v147
	v_add_u32_e32 v180, s62, v147
	ds_read_b128 v[152:155], v164
	ds_read_b128 v[156:159], v164 offset:1024
	ds_read_b128 v[160:163], v164 offset:2048
	ds_read_b128 v[164:167], v164 offset:3072
	ds_read_b128 v[168:171], v180
	ds_read_b128 v[172:175], v180 offset:1024
	ds_read_b128 v[176:179], v180 offset:2048
	ds_read_b128 v[180:183], v180 offset:3072
	ds_read_b128 v[184:187], v150 offset:32768
	ds_read_b128 v[188:191], v150 offset:33792
	ds_read_b128 v[192:195], v150 offset:34816
	ds_read_b128 v[196:199], v150 offset:35840
	ds_read_b128 v[200:203], v150 offset:36864
	ds_read_b128 v[204:207], v150 offset:37888
	ds_read_b128 v[208:211], v150 offset:38912
	ds_read_b128 v[212:215], v150 offset:39936
	s_waitcnt vmcnt(8)
	s_waitcnt lgkmcnt(0)
	s_barrier
	s_setprio 0
	s_waitcnt lgkmcnt(0)
	v_mfma_f32_16x16x32_bf16 v[126:129], v[152:155], v[184:187], v[126:129]
	v_mfma_f32_16x16x32_bf16 v[122:125], v[160:163], v[184:187], v[122:125]
	v_mfma_f32_16x16x32_bf16 v[110:113], v[152:155], v[192:195], v[110:113]
	v_mfma_f32_16x16x32_bf16 v[106:109], v[160:163], v[192:195], v[106:109]
	v_mfma_f32_16x16x32_bf16 v[94:97], v[152:155], v[200:203], v[94:97]
	v_mfma_f32_16x16x32_bf16 v[90:93], v[160:163], v[200:203], v[90:93]
	v_mfma_f32_16x16x32_bf16 v[78:81], v[152:155], v[208:211], v[78:81]
	v_mfma_f32_16x16x32_bf16 v[74:77], v[160:163], v[208:211], v[74:77]
	v_mfma_f32_16x16x32_bf16 v[126:129], v[156:159], v[188:191], v[126:129]
	v_mfma_f32_16x16x32_bf16 v[122:125], v[164:167], v[188:191], v[122:125]
	v_mfma_f32_16x16x32_bf16 v[110:113], v[156:159], v[196:199], v[110:113]
	v_mfma_f32_16x16x32_bf16 v[106:109], v[164:167], v[196:199], v[106:109]
	v_mfma_f32_16x16x32_bf16 v[94:97], v[156:159], v[204:207], v[94:97]
	v_mfma_f32_16x16x32_bf16 v[90:93], v[164:167], v[204:207], v[90:93]
	v_mfma_f32_16x16x32_bf16 v[78:81], v[156:159], v[212:215], v[78:81]
	v_mfma_f32_16x16x32_bf16 v[74:77], v[164:167], v[212:215], v[74:77]
	s_setprio 2
	s_setprio 0
	v_mfma_f32_16x16x32_bf16 v[118:121], v[168:171], v[184:187], v[118:121]
	v_mfma_f32_16x16x32_bf16 v[114:117], v[176:179], v[184:187], v[114:117]
	v_mfma_f32_16x16x32_bf16 v[102:105], v[168:171], v[192:195], v[102:105]
	v_mfma_f32_16x16x32_bf16 v[98:101], v[176:179], v[192:195], v[98:101]
	v_mfma_f32_16x16x32_bf16 v[86:89], v[168:171], v[200:203], v[86:89]
	v_mfma_f32_16x16x32_bf16 v[82:85], v[176:179], v[200:203], v[82:85]
	v_mfma_f32_16x16x32_bf16 v[70:73], v[168:171], v[208:211], v[70:73]
	v_mfma_f32_16x16x32_bf16 v[66:69], v[176:179], v[208:211], v[66:69]
	v_mfma_f32_16x16x32_bf16 v[118:121], v[172:175], v[188:191], v[118:121]
	v_mfma_f32_16x16x32_bf16 v[114:117], v[180:183], v[188:191], v[114:117]
	v_mfma_f32_16x16x32_bf16 v[102:105], v[172:175], v[196:199], v[102:105]
	v_mfma_f32_16x16x32_bf16 v[98:101], v[180:183], v[196:199], v[98:101]
	v_mfma_f32_16x16x32_bf16 v[86:89], v[172:175], v[204:207], v[86:89]
	v_mfma_f32_16x16x32_bf16 v[82:85], v[180:183], v[204:207], v[82:85]
	v_mfma_f32_16x16x32_bf16 v[70:73], v[172:175], v[212:215], v[70:73]
	v_mfma_f32_16x16x32_bf16 v[66:69], v[180:183], v[212:215], v[66:69]
	s_setprio 2
	s_barrier
; #define PG8_STAGE(bufoff, gbase, voff) do { _Pragma("unroll") for (int _i = 0; _i < 2; ++_i) \
;         __builtin_amdgcn_global_load_lds((const unsigned*)((const char*)(gbase) + (voff)[_i]), (LAS unsigned*)(lds + (bufoff) + ldsw + _i * 8192), 16, 0, 0); } while (0)
; #define PG8_LDA(dst, b, h) do { _Pragma("unroll") for (int m = 0; m < 4; ++m) _Pragma("unroll") for (int k = 0; k < 2; ++k) dst[m][k] = *(const LAS bf16x8*)(lds + PG8_SA(b, h) + aoff + m * 2048 + k * 1024); } while (0)
; #define PG8_MMA(ai, bj, At, Bt) do { __builtin_amdgcn_s_setprio(1); _Pragma("unroll") for (int m = 0; m < 4; ++m) _Pragma("unroll") for (int n = 0; n < 2; ++n) _Pragma("unroll") for (int k = 0; k < 2; ++k) \
;         acc[ai][bj][m][n] = __builtin_amdgcn_mfma_f32_16x16x32_bf16(Bt[n][k], At[m][k], acc[ai][bj][m][n], 0, 0, 0); __builtin_amdgcn_s_setprio(0); } while (0)
; #define PG8_WAIT_V(n) asm volatile("s_waitcnt vmcnt(" #n ")" ::: "memory")
; #define PG8_WAIT_L(n) asm volatile("s_waitcnt lgkmcnt(" #n ")" ::: "memory")
; #define PG8_BAR __builtin_amdgcn_s_barrier()
; #define PG8_SCHED __builtin_amdgcn_sched_barrier(0)
; template <class Epi>
; __device__ __forceinline__ void gemm_phase(LAS unsigned char* lds, const Gemm g, int G, int c, const Epi& E) {
;     ...
;             PG8_LDA(At, 1, 1); PG8_STAGE(PG8_SB(1, 0), b3, voffB); PG8_STAGE(PG8_SB(1, 1), b3 + hstepB, voffB); PG8_STAGE(PG8_SA(1, 0), a3, voffA);
;             PG8_WAIT_V(8); PG8_WAIT_L(0); PG8_BAR; PG8_MMA(1, 0, At, B0); PG8_MMA(1, 1, At, B1); PG8_BAR; PG8_SCHED;
;         }
;         if (wr == 0) PG8_BAR;
	s_add_i32 s33, s33, s46
	v_lshl_add_u64 v[216:217], v[216:217], 0, s[12:13]
	s_mov_b32 m0, s33
	s_nop 0
	global_load_lds_dwordx4 v[216:217], off
	s_add_i32 m0, s33, 0x2000
	s_add_u32 s38, s38, 0x40080
	v_lshl_add_u64 v[216:217], v[218:219], 0, s[12:13]
	s_addc_u32 s39, s39, 0
	s_add_i32 s33, s62, s46
	global_load_lds_dwordx4 v[216:217], off
	v_lshl_add_u64 v[216:217], s[38:39], 0, v[134:135]
	s_mov_b32 m0, s33
	s_nop 0
	global_load_lds_dwordx4 v[216:217], off
	v_lshl_add_u64 v[216:217], s[38:39], 0, v[130:131]
	s_add_i32 m0, s33, 0x2000
	s_nop 0
	global_load_lds_dwordx4 v[216:217], off
	v_lshl_add_u64 v[216:217], v[220:221], 0, s[12:13]
	s_mov_b32 m0, s57
	s_nop 0
	global_load_lds_dwordx4 v[216:217], off
	v_lshl_add_u64 v[216:217], v[222:223], 0, s[12:13]
	s_mov_b32 m0, s58
	s_nop 0
	global_load_lds_dwordx4 v[216:217], off
	ds_read_b128 v[184:187], v150 offset:49152
	ds_read_b128 v[188:191], v150 offset:50176
	ds_read_b128 v[192:195], v150 offset:51200
	ds_read_b128 v[196:199], v150 offset:52224
	ds_read_b128 v[200:203], v150 offset:53248
	ds_read_b128 v[204:207], v150 offset:54272
	ds_read_b128 v[208:211], v150 offset:55296
	ds_read_b128 v[212:215], v150 offset:56320
	s_waitcnt vmcnt(8)
	s_waitcnt lgkmcnt(0)
	s_barrier
	s_setprio 0
	s_waitcnt lgkmcnt(0)
	v_mfma_f32_16x16x32_bf16 v[62:65], v[152:155], v[184:187], v[62:65]
	v_mfma_f32_16x16x32_bf16 v[58:61], v[160:163], v[184:187], v[58:61]
	v_mfma_f32_16x16x32_bf16 v[46:49], v[152:155], v[192:195], v[46:49]
	v_mfma_f32_16x16x32_bf16 v[42:45], v[160:163], v[192:195], v[42:45]
	v_mfma_f32_16x16x32_bf16 v[30:33], v[152:155], v[200:203], v[30:33]
	v_mfma_f32_16x16x32_bf16 v[26:29], v[160:163], v[200:203], v[26:29]
	v_mfma_f32_16x16x32_bf16 v[14:17], v[152:155], v[208:211], v[14:17]
	v_mfma_f32_16x16x32_bf16 v[10:13], v[160:163], v[208:211], v[10:13]
	v_mfma_f32_16x16x32_bf16 v[62:65], v[156:159], v[188:191], v[62:65]
	v_mfma_f32_16x16x32_bf16 v[58:61], v[164:167], v[188:191], v[58:61]
	v_mfma_f32_16x16x32_bf16 v[46:49], v[156:159], v[196:199], v[46:49]
	v_mfma_f32_16x16x32_bf16 v[42:45], v[164:167], v[196:199], v[42:45]
	v_mfma_f32_16x16x32_bf16 v[30:33], v[156:159], v[204:207], v[30:33]
	v_mfma_f32_16x16x32_bf16 v[26:29], v[164:167], v[204:207], v[26:29]
	v_mfma_f32_16x16x32_bf16 v[14:17], v[156:159], v[212:215], v[14:17]
	v_mfma_f32_16x16x32_bf16 v[10:13], v[164:167], v[212:215], v[10:13]
	s_setprio 2
	s_setprio 0
	v_mfma_f32_16x16x32_bf16 v[54:57], v[168:171], v[184:187], v[54:57]
	v_mfma_f32_16x16x32_bf16 v[50:53], v[176:179], v[184:187], v[50:53]
	v_mfma_f32_16x16x32_bf16 v[38:41], v[168:171], v[192:195], v[38:41]
	v_mfma_f32_16x16x32_bf16 v[34:37], v[176:179], v[192:195], v[34:37]
	v_mfma_f32_16x16x32_bf16 v[22:25], v[168:171], v[200:203], v[22:25]
	v_mfma_f32_16x16x32_bf16 v[18:21], v[176:179], v[200:203], v[18:21]
	v_mfma_f32_16x16x32_bf16 v[6:9], v[168:171], v[208:211], v[6:9]
	v_mfma_f32_16x16x32_bf16 v[2:5], v[176:179], v[208:211], v[2:5]
	v_mfma_f32_16x16x32_bf16 v[54:57], v[172:175], v[188:191], v[54:57]
	v_mfma_f32_16x16x32_bf16 v[50:53], v[180:183], v[188:191], v[50:53]
	v_mfma_f32_16x16x32_bf16 v[38:41], v[172:175], v[196:199], v[38:41]
	v_mfma_f32_16x16x32_bf16 v[34:37], v[180:183], v[196:199], v[34:37]
	v_mfma_f32_16x16x32_bf16 v[22:25], v[172:175], v[204:207], v[22:25]
	v_mfma_f32_16x16x32_bf16 v[18:21], v[180:183], v[204:207], v[18:21]
	v_mfma_f32_16x16x32_bf16 v[6:9], v[172:175], v[212:215], v[6:9]
	v_mfma_f32_16x16x32_bf16 v[2:5], v[180:183], v[212:215], v[2:5]
	s_setprio 2
	s_barrier
	s_add_i32 s80, s80, 2
	s_add_u32 s4, s4, 0x100
	s_addc_u32 s5, s5, 0
	s_add_u32 s78, s78, 0x100
	s_addc_u32 s79, s79, 0
	s_cmp_gt_u32 s80, 13
	s_cbranch_scc0 .LBB0_1058
	s_and_b64 vcc, exec, s[14:15]
	s_cbranch_vccz .LBB0_1061
	s_barrier

; #define PG8_STAGE(bufoff, gbase, voff) do { _Pragma("unroll") for (int _i = 0; _i < 2; ++_i) \
;         __builtin_amdgcn_global_load_lds((const unsigned*)((const char*)(gbase) + (voff)[_i]), (LAS unsigned*)(lds + (bufoff) + ldsw + _i * 8192), 16, 0, 0); } while (0)
; #define PG8_LDA(dst, b, h) do { _Pragma("unroll") for (int m = 0; m < 4; ++m) _Pragma("unroll") for (int k = 0; k < 2; ++k) dst[m][k] = *(const LAS bf16x8*)(lds + PG8_SA(b, h) + aoff + m * 2048 + k * 1024); } while (0)
; #define PG8_LDB(dst, b, h) do { _Pragma("unroll") for (int n = 0; n < 2; ++n) _Pragma("unroll") for (int k = 0; k < 2; ++k) dst[n][k] = *(const LAS bf16x8*)(lds + PG8_SB(b, h) + boff + n * 2048 + k * 1024); } while (0)
; #define PG8_MMA(ai, bj, At, Bt) do { __builtin_amdgcn_s_setprio(1); _Pragma("unroll") for (int m = 0; m < 4; ++m) _Pragma("unroll") for (int n = 0; n < 2; ++n) _Pragma("unroll") for (int k = 0; k < 2; ++k) \
;         acc[ai][bj][m][n] = __builtin_amdgcn_mfma_f32_16x16x32_bf16(Bt[n][k], At[m][k], acc[ai][bj][m][n], 0, 0, 0); __builtin_amdgcn_s_setprio(0); } while (0)
; #define PG8_WAIT_V(n) asm volatile("s_waitcnt vmcnt(" #n ")" ::: "memory")
; #define PG8_WAIT_L(n) asm volatile("s_waitcnt lgkmcnt(" #n ")" ::: "memory")
; #define PG8_BAR __builtin_amdgcn_s_barrier()
; #define PG8_SCHED __builtin_amdgcn_sched_barrier(0)
; template <class Epi>
; __device__ __forceinline__ void gemm_phase(LAS unsigned char* lds, const Gemm g, int G, int c, const Epi& E) {
;     ...
;             const bool last = (t == nt - 2);
;             const char* a1 = cA + (size_t)(t + 1) * kstep;
;             const char* a2 = last ? nA : cA + (size_t)(t + 2) * kstep; const char* b2 = last ? nB : cB + (size_t)(t + 2) * kstep;
;             const char* a3 = a2 + kstep; const char* b3 = b2 + kstep;
;             PG8_LDB(B0, 0, 0); PG8_LDB(B1, 0, 1); PG8_SCHED; PG8_LDA(At, 0, 0); PG8_STAGE(PG8_SA(1, 1), a1 + hstepA, voffA);
;             PG8_WAIT_V(8); PG8_WAIT_L(0); PG8_BAR; PG8_MMA(0, 0, At, B0); PG8_MMA(0, 1, At, B1); PG8_BAR; PG8_SCHED;
;             PG8_LDA(At, 0, 1); PG8_STAGE(PG8_SB(0, 0), b2, voffB); PG8_STAGE(PG8_SB(0, 1), b2 + hstepB, voffB); PG8_STAGE(PG8_SA(0, 0), a2, voffA);
.LBB0_1143:
	s_add_u32 s18, s16, 0x100
	s_addc_u32 s19, s17, 0
	s_cmp_eq_u32 s68, 40
	s_cselect_b32 s23, s5, s19
	s_cselect_b32 s22, s4, s18
	s_cselect_b32 s21, s15, s67
	s_cselect_b32 s20, s14, s66
	v_lshl_add_u64 v[216:217], s[16:17], 0, v[154:155]
	s_add_i32 m0, s38, 0xc000
	s_nop 0
	global_load_lds_dwordx4 v[216:217], off
	v_lshl_add_u64 v[216:217], s[16:17], 0, v[156:157]
	s_add_i32 m0, s38, 0xe000
	s_nop 0
	global_load_lds_dwordx4 v[216:217], off
	ds_read_b128 v[122:125], v168
	ds_read_b128 v[126:129], v168 offset:1024
	ds_read_b128 v[130:133], v168 offset:2048
	ds_read_b128 v[134:137], v168 offset:3072
	ds_read_b128 v[162:165], v169
	ds_read_b128 v[172:175], v169 offset:1024
	ds_read_b128 v[176:179], v169 offset:2048
	ds_read_b128 v[180:183], v169 offset:3072
	ds_read_b128 v[184:187], v170
	ds_read_b128 v[188:191], v170 offset:1024
	ds_read_b128 v[192:195], v170 offset:2048
	ds_read_b128 v[196:199], v170 offset:3072
	ds_read_b128 v[200:203], v170 offset:4096
	ds_read_b128 v[204:207], v170 offset:5120
	ds_read_b128 v[208:211], v170 offset:6144
	ds_read_b128 v[212:215], v170 offset:7168
	s_waitcnt vmcnt(8)
	s_waitcnt lgkmcnt(0)
	s_barrier
	s_setprio 0
	s_waitcnt lgkmcnt(0)
	v_mfma_f32_16x16x32_bf16 v[142:145], v[122:125], v[184:187], v[142:145]
	v_mfma_f32_16x16x32_bf16 v[138:141], v[130:133], v[184:187], v[138:141]
	v_mfma_f32_16x16x32_bf16 v[118:121], v[122:125], v[192:195], v[118:121]
	v_mfma_f32_16x16x32_bf16 v[106:109], v[130:133], v[192:195], v[106:109]
	v_mfma_f32_16x16x32_bf16 v[102:105], v[122:125], v[200:203], v[102:105]
	v_mfma_f32_16x16x32_bf16 v[90:93], v[130:133], v[200:203], v[90:93]
	v_mfma_f32_16x16x32_bf16 v[86:89], v[122:125], v[208:211], v[86:89]
	v_mfma_f32_16x16x32_bf16 v[74:77], v[130:133], v[208:211], v[74:77]
	v_mfma_f32_16x16x32_bf16 v[142:145], v[126:129], v[188:191], v[142:145]
	v_mfma_f32_16x16x32_bf16 v[138:141], v[134:137], v[188:191], v[138:141]
	v_mfma_f32_16x16x32_bf16 v[118:121], v[126:129], v[196:199], v[118:121]
	v_mfma_f32_16x16x32_bf16 v[106:109], v[134:137], v[196:199], v[106:109]
	v_mfma_f32_16x16x32_bf16 v[102:105], v[126:129], v[204:207], v[102:105]
	v_mfma_f32_16x16x32_bf16 v[90:93], v[134:137], v[204:207], v[90:93]
	v_mfma_f32_16x16x32_bf16 v[86:89], v[126:129], v[212:215], v[86:89]
	v_mfma_f32_16x16x32_bf16 v[74:77], v[134:137], v[212:215], v[74:77]
	s_setprio 2
	s_setprio 0
	v_mfma_f32_16x16x32_bf16 v[114:117], v[162:165], v[184:187], v[114:117]
	v_mfma_f32_16x16x32_bf16 v[110:113], v[176:179], v[184:187], v[110:113]
	v_mfma_f32_16x16x32_bf16 v[98:101], v[162:165], v[192:195], v[98:101]
	v_mfma_f32_16x16x32_bf16 v[94:97], v[176:179], v[192:195], v[94:97]
	v_mfma_f32_16x16x32_bf16 v[82:85], v[162:165], v[200:203], v[82:85]
	v_mfma_f32_16x16x32_bf16 v[78:81], v[176:179], v[200:203], v[78:81]
	v_mfma_f32_16x16x32_bf16 v[70:73], v[162:165], v[208:211], v[70:73]
	v_mfma_f32_16x16x32_bf16 v[66:69], v[176:179], v[208:211], v[66:69]
	v_mfma_f32_16x16x32_bf16 v[114:117], v[172:175], v[188:191], v[114:117]
	v_mfma_f32_16x16x32_bf16 v[110:113], v[180:183], v[188:191], v[110:113]
	v_mfma_f32_16x16x32_bf16 v[98:101], v[172:175], v[196:199], v[98:101]
	v_mfma_f32_16x16x32_bf16 v[94:97], v[180:183], v[196:199], v[94:97]
	v_mfma_f32_16x16x32_bf16 v[82:85], v[172:175], v[204:207], v[82:85]
	v_mfma_f32_16x16x32_bf16 v[78:81], v[180:183], v[204:207], v[78:81]
	v_mfma_f32_16x16x32_bf16 v[70:73], v[172:175], v[212:215], v[70:73]
	v_mfma_f32_16x16x32_bf16 v[66:69], v[180:183], v[212:215], v[66:69]
	s_setprio 2
	s_barrier
	s_add_i32 s16, s54, s36
	v_lshl_add_u64 v[216:217], s[20:21], 0, v[150:151]
	s_mov_b32 m0, s16
	s_nop 0
	global_load_lds_dwordx4 v[216:217], off
	s_add_i32 m0, s16, 0x2000
	s_add_u32 s16, s20, 0xb0000
	v_lshl_add_u64 v[218:219], s[20:21], 0, v[146:147]
	s_addc_u32 s17, s21, 0
	s_add_i32 s33, s55, s36
	global_load_lds_dwordx4 v[218:219], off
	v_lshl_add_u64 v[220:221], s[16:17], 0, v[150:151]
	s_mov_b32 m0, s33
	v_lshl_add_u64 v[222:223], s[22:23], 0, v[148:149]
	global_load_lds_dwordx4 v[220:221], off
	v_lshl_add_u64 v[220:221], s[16:17], 0, v[146:147]
	s_add_i32 m0, s33, 0x2000
	s_nop 0
	global_load_lds_dwordx4 v[220:221], off
	v_lshl_add_u64 v[220:221], s[22:23], 0, v[152:153]
	s_mov_b32 m0, s38
	s_nop 0
	global_load_lds_dwordx4 v[220:221], off
	s_mov_b32 m0, s39
	s_nop 0
	global_load_lds_dwordx4 v[222:223], off
	ds_read_b128 v[184:187], v170 offset:16384
	ds_read_b128 v[188:191], v170 offset:17408
	ds_read_b128 v[192:195], v170 offset:18432
	ds_read_b128 v[196:199], v170 offset:19456
	ds_read_b128 v[200:203], v170 offset:20480
	ds_read_b128 v[204:207], v170 offset:21504
	ds_read_b128 v[208:211], v170 offset:22528
	ds_read_b128 v[212:215], v170 offset:23552
	s_waitcnt vmcnt(8)
	s_waitcnt lgkmcnt(0)
	s_barrier
; #define PG8_STAGE(bufoff, gbase, voff) do { _Pragma("unroll") for (int _i = 0; _i < 2; ++_i) \
;         __builtin_amdgcn_global_load_lds((const unsigned*)((const char*)(gbase) + (voff)[_i]), (LAS unsigned*)(lds + (bufoff) + ldsw + _i * 8192), 16, 0, 0); } while (0)
; #define PG8_LDA(dst, b, h) do { _Pragma("unroll") for (int m = 0; m < 4; ++m) _Pragma("unroll") for (int k = 0; k < 2; ++k) dst[m][k] = *(const LAS bf16x8*)(lds + PG8_SA(b, h) + aoff + m * 2048 + k * 1024); } while (0)
; #define PG8_LDB(dst, b, h) do { _Pragma("unroll") for (int n = 0; n < 2; ++n) _Pragma("unroll") for (int k = 0; k < 2; ++k) dst[n][k] = *(const LAS bf16x8*)(lds + PG8_SB(b, h) + boff + n * 2048 + k * 1024); } while (0)
; #define PG8_MMA(ai, bj, At, Bt) do { __builtin_amdgcn_s_setprio(1); _Pragma("unroll") for (int m = 0; m < 4; ++m) _Pragma("unroll") for (int n = 0; n < 2; ++n) _Pragma("unroll") for (int k = 0; k < 2; ++k) \
;         acc[ai][bj][m][n] = __builtin_amdgcn_mfma_f32_16x16x32_bf16(Bt[n][k], At[m][k], acc[ai][bj][m][n], 0, 0, 0); __builtin_amdgcn_s_setprio(0); } while (0)
; #define PG8_WAIT_V(n) asm volatile("s_waitcnt vmcnt(" #n ")" ::: "memory")
; #define PG8_WAIT_L(n) asm volatile("s_waitcnt lgkmcnt(" #n ")" ::: "memory")
; #define PG8_BAR __builtin_amdgcn_s_barrier()
; #define PG8_SCHED __builtin_amdgcn_sched_barrier(0)
; template <class Epi>
; __device__ __forceinline__ void gemm_phase(LAS unsigned char* lds, const Gemm g, int G, int c, const Epi& E) {
;     ...
;             PG8_WAIT_V(8); PG8_WAIT_L(0); PG8_BAR; PG8_MMA(1, 0, At, B0); PG8_MMA(1, 1, At, B1); PG8_BAR; PG8_SCHED;
;             PG8_LDB(B0, 1, 0); PG8_LDB(B1, 1, 1); PG8_SCHED; PG8_LDA(At, 1, 0); PG8_STAGE(PG8_SA(0, 1), a2 + hstepA, voffA);
;             PG8_WAIT_V(8); PG8_WAIT_L(0); PG8_BAR; PG8_MMA(0, 0, At, B0); PG8_MMA(0, 1, At, B1); PG8_BAR; PG8_SCHED;
	s_setprio 0
	s_waitcnt lgkmcnt(0)
	v_mfma_f32_16x16x32_bf16 v[62:65], v[122:125], v[184:187], v[62:65]
	v_mfma_f32_16x16x32_bf16 v[58:61], v[130:133], v[184:187], v[58:61]
	v_mfma_f32_16x16x32_bf16 v[54:57], v[122:125], v[192:195], v[54:57]
	v_mfma_f32_16x16x32_bf16 v[42:45], v[130:133], v[192:195], v[42:45]
	v_mfma_f32_16x16x32_bf16 v[38:41], v[122:125], v[200:203], v[38:41]
	v_mfma_f32_16x16x32_bf16 v[26:29], v[130:133], v[200:203], v[26:29]
	v_mfma_f32_16x16x32_bf16 v[22:25], v[122:125], v[208:211], v[22:25]
	v_mfma_f32_16x16x32_bf16 v[10:13], v[130:133], v[208:211], v[10:13]
	v_mfma_f32_16x16x32_bf16 v[62:65], v[126:129], v[188:191], v[62:65]
	v_mfma_f32_16x16x32_bf16 v[58:61], v[134:137], v[188:191], v[58:61]
	v_mfma_f32_16x16x32_bf16 v[54:57], v[126:129], v[196:199], v[54:57]
	v_mfma_f32_16x16x32_bf16 v[42:45], v[134:137], v[196:199], v[42:45]
	v_mfma_f32_16x16x32_bf16 v[38:41], v[126:129], v[204:207], v[38:41]
	v_mfma_f32_16x16x32_bf16 v[26:29], v[134:137], v[204:207], v[26:29]
	v_mfma_f32_16x16x32_bf16 v[22:25], v[126:129], v[212:215], v[22:25]
	v_mfma_f32_16x16x32_bf16 v[10:13], v[134:137], v[212:215], v[10:13]
	s_setprio 2
	s_setprio 0
	v_mfma_f32_16x16x32_bf16 v[50:53], v[162:165], v[184:187], v[50:53]
	v_mfma_f32_16x16x32_bf16 v[46:49], v[176:179], v[184:187], v[46:49]
	v_mfma_f32_16x16x32_bf16 v[34:37], v[162:165], v[192:195], v[34:37]
	v_mfma_f32_16x16x32_bf16 v[30:33], v[176:179], v[192:195], v[30:33]
	v_mfma_f32_16x16x32_bf16 v[18:21], v[162:165], v[200:203], v[18:21]
	v_mfma_f32_16x16x32_bf16 v[14:17], v[176:179], v[200:203], v[14:17]
	v_mfma_f32_16x16x32_bf16 v[6:9], v[162:165], v[208:211], v[6:9]
	v_mfma_f32_16x16x32_bf16 v[2:5], v[176:179], v[208:211], v[2:5]
	v_mfma_f32_16x16x32_bf16 v[50:53], v[172:175], v[188:191], v[50:53]
	v_mfma_f32_16x16x32_bf16 v[46:49], v[180:183], v[188:191], v[46:49]
	v_mfma_f32_16x16x32_bf16 v[34:37], v[172:175], v[196:199], v[34:37]
	v_mfma_f32_16x16x32_bf16 v[30:33], v[180:183], v[196:199], v[30:33]
	v_mfma_f32_16x16x32_bf16 v[18:21], v[172:175], v[204:207], v[18:21]
	v_mfma_f32_16x16x32_bf16 v[14:17], v[180:183], v[204:207], v[14:17]
	v_mfma_f32_16x16x32_bf16 v[6:9], v[172:175], v[212:215], v[6:9]
	v_mfma_f32_16x16x32_bf16 v[2:5], v[180:183], v[212:215], v[2:5]
	s_setprio 2
	s_barrier
	s_add_i32 s33, 0, 0x18000
	s_add_i32 s62, 0, 0x1c000
	s_add_u32 s16, s22, 0xb0000
	s_addc_u32 s17, s23, 0
	s_mov_b32 m0, s40
	v_lshl_add_u64 v[224:225], s[16:17], 0, v[152:153]
	global_load_lds_dwordx4 v[224:225], off
	v_lshl_add_u64 v[224:225], s[16:17], 0, v[148:149]
	s_mov_b32 m0, s41
	s_nop 0
	global_load_lds_dwordx4 v[224:225], off
	v_add_u32_e32 v134, s33, v167
	v_add_u32_e32 v171, s62, v167
	ds_read_b128 v[122:125], v134
	ds_read_b128 v[126:129], v134 offset:1024
	ds_read_b128 v[130:133], v134 offset:2048
	ds_read_b128 v[134:137], v134 offset:3072
	ds_read_b128 v[162:165], v171
	ds_read_b128 v[172:175], v171 offset:1024
	ds_read_b128 v[176:179], v171 offset:2048
	ds_read_b128 v[180:183], v171 offset:3072
	ds_read_b128 v[184:187], v170 offset:32768
	ds_read_b128 v[188:191], v170 offset:33792
	ds_read_b128 v[192:195], v170 offset:34816
	ds_read_b128 v[196:199], v170 offset:35840
	ds_read_b128 v[200:203], v170 offset:36864
	ds_read_b128 v[204:207], v170 offset:37888
	ds_read_b128 v[208:211], v170 offset:38912
	ds_read_b128 v[212:215], v170 offset:39936
	s_waitcnt vmcnt(8)
	s_waitcnt lgkmcnt(0)
	s_barrier
	s_setprio 0
	s_waitcnt lgkmcnt(0)
	v_mfma_f32_16x16x32_bf16 v[142:145], v[122:125], v[184:187], v[142:145]
	v_mfma_f32_16x16x32_bf16 v[138:141], v[130:133], v[184:187], v[138:141]
	v_mfma_f32_16x16x32_bf16 v[118:121], v[122:125], v[192:195], v[118:121]
	v_mfma_f32_16x16x32_bf16 v[106:109], v[130:133], v[192:195], v[106:109]
	v_mfma_f32_16x16x32_bf16 v[102:105], v[122:125], v[200:203], v[102:105]
	v_mfma_f32_16x16x32_bf16 v[90:93], v[130:133], v[200:203], v[90:93]
	v_mfma_f32_16x16x32_bf16 v[86:89], v[122:125], v[208:211], v[86:89]
	v_mfma_f32_16x16x32_bf16 v[74:77], v[130:133], v[208:211], v[74:77]
	v_mfma_f32_16x16x32_bf16 v[142:145], v[126:129], v[188:191], v[142:145]
	v_mfma_f32_16x16x32_bf16 v[138:141], v[134:137], v[188:191], v[138:141]
	v_mfma_f32_16x16x32_bf16 v[118:121], v[126:129], v[196:199], v[118:121]
	v_mfma_f32_16x16x32_bf16 v[106:109], v[134:137], v[196:199], v[106:109]
	v_mfma_f32_16x16x32_bf16 v[102:105], v[126:129], v[204:207], v[102:105]
	v_mfma_f32_16x16x32_bf16 v[90:93], v[134:137], v[204:207], v[90:93]
	v_mfma_f32_16x16x32_bf16 v[86:89], v[126:129], v[212:215], v[86:89]
	v_mfma_f32_16x16x32_bf16 v[74:77], v[134:137], v[212:215], v[74:77]
	s_setprio 2
	s_setprio 0
	v_mfma_f32_16x16x32_bf16 v[114:117], v[162:165], v[184:187], v[114:117]
	v_mfma_f32_16x16x32_bf16 v[110:113], v[176:179], v[184:187], v[110:113]
	v_mfma_f32_16x16x32_bf16 v[98:101], v[162:165], v[192:195], v[98:101]
	v_mfma_f32_16x16x32_bf16 v[94:97], v[176:179], v[192:195], v[94:97]
	v_mfma_f32_16x16x32_bf16 v[82:85], v[162:165], v[200:203], v[82:85]
	v_mfma_f32_16x16x32_bf16 v[78:81], v[176:179], v[200:203], v[78:81]
	v_mfma_f32_16x16x32_bf16 v[70:73], v[162:165], v[208:211], v[70:73]
	v_mfma_f32_16x16x32_bf16 v[66:69], v[176:179], v[208:211], v[66:69]
	v_mfma_f32_16x16x32_bf16 v[114:117], v[172:175], v[188:191], v[114:117]
	v_mfma_f32_16x16x32_bf16 v[110:113], v[180:183], v[188:191], v[110:113]
	v_mfma_f32_16x16x32_bf16 v[98:101], v[172:175], v[196:199], v[98:101]
	v_mfma_f32_16x16x32_bf16 v[94:97], v[180:183], v[196:199], v[94:97]
	v_mfma_f32_16x16x32_bf16 v[82:85], v[172:175], v[204:207], v[82:85]
	v_mfma_f32_16x16x32_bf16 v[78:81], v[180:183], v[204:207], v[78:81]
	v_mfma_f32_16x16x32_bf16 v[70:73], v[172:175], v[212:215], v[70:73]
	v_mfma_f32_16x16x32_bf16 v[66:69], v[180:183], v[212:215], v[66:69]
	s_setprio 2
	s_barrier
; #define PG8_STAGE(bufoff, gbase, voff) do { _Pragma("unroll") for (int _i = 0; _i < 2; ++_i) \
;         __builtin_amdgcn_global_load_lds((const unsigned*)((const char*)(gbase) + (voff)[_i]), (LAS unsigned*)(lds + (bufoff) + ldsw + _i * 8192), 16, 0, 0); } while (0)
; #define PG8_LDA(dst, b, h) do { _Pragma("unroll") for (int m = 0; m < 4; ++m) _Pragma("unroll") for (int k = 0; k < 2; ++k) dst[m][k] = *(const LAS bf16x8*)(lds + PG8_SA(b, h) + aoff + m * 2048 + k * 1024); } while (0)
; #define PG8_MMA(ai, bj, At, Bt) do { __builtin_amdgcn_s_setprio(1); _Pragma("unroll") for (int m = 0; m < 4; ++m) _Pragma("unroll") for (int n = 0; n < 2; ++n) _Pragma("unroll") for (int k = 0; k < 2; ++k) \
;         acc[ai][bj][m][n] = __builtin_amdgcn_mfma_f32_16x16x32_bf16(Bt[n][k], At[m][k], acc[ai][bj][m][n], 0, 0, 0); __builtin_amdgcn_s_setprio(0); } while (0)
; #define PG8_WAIT_V(n) asm volatile("s_waitcnt vmcnt(" #n ")" ::: "memory")
; #define PG8_WAIT_L(n) asm volatile("s_waitcnt lgkmcnt(" #n ")" ::: "memory")
; #define PG8_BAR __builtin_amdgcn_s_barrier()
; #define PG8_SCHED __builtin_amdgcn_sched_barrier(0)
; template <class Epi>
; __device__ __forceinline__ void gemm_phase(LAS unsigned char* lds, const Gemm g, int G, int c, const Epi& E) {
;     ...
;             PG8_LDA(At, 1, 1); PG8_STAGE(PG8_SB(1, 0), b3, voffB); PG8_STAGE(PG8_SB(1, 1), b3 + hstepB, voffB); PG8_STAGE(PG8_SA(1, 0), a3, voffA);
;             PG8_WAIT_V(8); PG8_WAIT_L(0); PG8_BAR; PG8_MMA(1, 0, At, B0); PG8_MMA(1, 1, At, B1); PG8_BAR; PG8_SCHED;
;         }
;         if (wr == 0) PG8_BAR;
	s_add_i32 s16, s33, s36
	v_lshl_add_u64 v[216:217], v[216:217], 0, s[10:11]
	s_mov_b32 m0, s16
	s_nop 0
	global_load_lds_dwordx4 v[216:217], off
	s_add_i32 m0, s16, 0x2000
	s_add_u32 s16, s20, 0xb0080
	v_lshl_add_u64 v[216:217], v[218:219], 0, s[10:11]
	s_addc_u32 s17, s21, 0
	s_add_i32 s20, s62, s36
	global_load_lds_dwordx4 v[216:217], off
	v_lshl_add_u64 v[216:217], s[16:17], 0, v[150:151]
	s_mov_b32 m0, s20
	s_nop 0
	global_load_lds_dwordx4 v[216:217], off
	v_lshl_add_u64 v[216:217], s[16:17], 0, v[146:147]
	s_add_i32 m0, s20, 0x2000
	s_nop 0
	global_load_lds_dwordx4 v[216:217], off
	v_lshl_add_u64 v[216:217], v[220:221], 0, s[10:11]
	s_mov_b32 m0, s47
	s_nop 0
	global_load_lds_dwordx4 v[216:217], off
	v_lshl_add_u64 v[216:217], v[222:223], 0, s[10:11]
	s_mov_b32 m0, s52
	s_nop 0
	global_load_lds_dwordx4 v[216:217], off
	ds_read_b128 v[184:187], v170 offset:49152
	ds_read_b128 v[188:191], v170 offset:50176
	ds_read_b128 v[192:195], v170 offset:51200
	ds_read_b128 v[196:199], v170 offset:52224
	ds_read_b128 v[200:203], v170 offset:53248
	ds_read_b128 v[204:207], v170 offset:54272
	ds_read_b128 v[208:211], v170 offset:55296
	ds_read_b128 v[212:215], v170 offset:56320
	s_waitcnt vmcnt(8)
	s_waitcnt lgkmcnt(0)
	s_barrier
	s_setprio 0
	s_waitcnt lgkmcnt(0)
	v_mfma_f32_16x16x32_bf16 v[62:65], v[122:125], v[184:187], v[62:65]
	v_mfma_f32_16x16x32_bf16 v[58:61], v[130:133], v[184:187], v[58:61]
	v_mfma_f32_16x16x32_bf16 v[54:57], v[122:125], v[192:195], v[54:57]
	v_mfma_f32_16x16x32_bf16 v[42:45], v[130:133], v[192:195], v[42:45]
	v_mfma_f32_16x16x32_bf16 v[38:41], v[122:125], v[200:203], v[38:41]
	v_mfma_f32_16x16x32_bf16 v[26:29], v[130:133], v[200:203], v[26:29]
	v_mfma_f32_16x16x32_bf16 v[22:25], v[122:125], v[208:211], v[22:25]
	v_mfma_f32_16x16x32_bf16 v[10:13], v[130:133], v[208:211], v[10:13]
	v_mfma_f32_16x16x32_bf16 v[62:65], v[126:129], v[188:191], v[62:65]
	v_mfma_f32_16x16x32_bf16 v[58:61], v[134:137], v[188:191], v[58:61]
	v_mfma_f32_16x16x32_bf16 v[54:57], v[126:129], v[196:199], v[54:57]
	v_mfma_f32_16x16x32_bf16 v[42:45], v[134:137], v[196:199], v[42:45]
	v_mfma_f32_16x16x32_bf16 v[38:41], v[126:129], v[204:207], v[38:41]
	v_mfma_f32_16x16x32_bf16 v[26:29], v[134:137], v[204:207], v[26:29]
	v_mfma_f32_16x16x32_bf16 v[22:25], v[126:129], v[212:215], v[22:25]
	v_mfma_f32_16x16x32_bf16 v[10:13], v[134:137], v[212:215], v[10:13]
	s_setprio 2
	s_setprio 0
	v_mfma_f32_16x16x32_bf16 v[50:53], v[162:165], v[184:187], v[50:53]
	v_mfma_f32_16x16x32_bf16 v[46:49], v[176:179], v[184:187], v[46:49]
	v_mfma_f32_16x16x32_bf16 v[34:37], v[162:165], v[192:195], v[34:37]
	v_mfma_f32_16x16x32_bf16 v[30:33], v[176:179], v[192:195], v[30:33]
	v_mfma_f32_16x16x32_bf16 v[18:21], v[162:165], v[200:203], v[18:21]
	v_mfma_f32_16x16x32_bf16 v[14:17], v[176:179], v[200:203], v[14:17]
	v_mfma_f32_16x16x32_bf16 v[6:9], v[162:165], v[208:211], v[6:9]
	v_mfma_f32_16x16x32_bf16 v[2:5], v[176:179], v[208:211], v[2:5]
	v_mfma_f32_16x16x32_bf16 v[50:53], v[172:175], v[188:191], v[50:53]
	v_mfma_f32_16x16x32_bf16 v[46:49], v[180:183], v[188:191], v[46:49]
	v_mfma_f32_16x16x32_bf16 v[34:37], v[172:175], v[196:199], v[34:37]
	v_mfma_f32_16x16x32_bf16 v[30:33], v[180:183], v[196:199], v[30:33]
	v_mfma_f32_16x16x32_bf16 v[18:21], v[172:175], v[204:207], v[18:21]
	v_mfma_f32_16x16x32_bf16 v[14:17], v[180:183], v[204:207], v[14:17]
	v_mfma_f32_16x16x32_bf16 v[6:9], v[172:175], v[212:215], v[6:9]
	v_mfma_f32_16x16x32_bf16 v[2:5], v[180:183], v[212:215], v[2:5]
	s_setprio 2
	s_barrier
	s_add_i32 s68, s68, 2
	s_add_u32 s66, s66, 0x100
	s_addc_u32 s67, s67, 0
	s_cmp_gt_u32 s68, 41
	s_mov_b64 s[16:17], s[18:19]
	s_cbranch_scc0 .LBB0_1143
	s_and_b64 vcc, exec, s[12:13]
	s_cbranch_vccz .LBB0_1146
	s_barrier

; #define PG8_STAGE(bufoff, gbase, voff) do { _Pragma("unroll") for (int _i = 0; _i < 2; ++_i) \
;         __builtin_amdgcn_global_load_lds((const unsigned*)((const char*)(gbase) + (voff)[_i]), (LAS unsigned*)(lds + (bufoff) + ldsw + _i * 8192), 16, 0, 0); } while (0)
; #define PG8_LDA(dst, b, h) do { _Pragma("unroll") for (int m = 0; m < 4; ++m) _Pragma("unroll") for (int k = 0; k < 2; ++k) dst[m][k] = *(const LAS bf16x8*)(lds + PG8_SA(b, h) + aoff + m * 2048 + k * 1024); } while (0)
; #define PG8_LDB(dst, b, h) do { _Pragma("unroll") for (int n = 0; n < 2; ++n) _Pragma("unroll") for (int k = 0; k < 2; ++k) dst[n][k] = *(const LAS bf16x8*)(lds + PG8_SB(b, h) + boff + n * 2048 + k * 1024); } while (0)
; #define PG8_MMA(ai, bj, At, Bt) do { __builtin_amdgcn_s_setprio(1); _Pragma("unroll") for (int m = 0; m < 4; ++m) _Pragma("unroll") for (int n = 0; n < 2; ++n) _Pragma("unroll") for (int k = 0; k < 2; ++k) \
;         acc[ai][bj][m][n] = __builtin_amdgcn_mfma_f32_16x16x32_bf16(Bt[n][k], At[m][k], acc[ai][bj][m][n], 0, 0, 0); __builtin_amdgcn_s_setprio(0); } while (0)
; #define PG8_WAIT_V(n) asm volatile("s_waitcnt vmcnt(" #n ")" ::: "memory")
; #define PG8_WAIT_L(n) asm volatile("s_waitcnt lgkmcnt(" #n ")" ::: "memory")
; #define PG8_BAR __builtin_amdgcn_s_barrier()
; #define PG8_SCHED __builtin_amdgcn_sched_barrier(0)
; template <class Epi>
; __device__ __forceinline__ void gemm_phase(LAS unsigned char* lds, const Gemm g, int G, int c, const Epi& E) {
;     ...
;             const bool last = (t == nt - 2);
;             const char* a1 = cA + (size_t)(t + 1) * kstep;
;             const char* a2 = last ? nA : cA + (size_t)(t + 2) * kstep; const char* b2 = last ? nB : cB + (size_t)(t + 2) * kstep;
;             const char* a3 = a2 + kstep; const char* b3 = b2 + kstep;
;             PG8_LDB(B0, 0, 0); PG8_LDB(B1, 0, 1); PG8_SCHED; PG8_LDA(At, 0, 0); PG8_STAGE(PG8_SA(1, 1), a1 + hstepA, voffA);
;             PG8_WAIT_V(8); PG8_WAIT_L(0); PG8_BAR; PG8_MMA(0, 0, At, B0); PG8_MMA(0, 1, At, B1); PG8_BAR; PG8_SCHED;
;             PG8_LDA(At, 0, 1); PG8_STAGE(PG8_SB(0, 0), b2, voffB); PG8_STAGE(PG8_SB(0, 1), b2 + hstepB, voffB); PG8_STAGE(PG8_SA(0, 0), a2, voffA);
.LBB0_1297:
	s_add_u32 s33, s4, 0xfffc0080
	s_addc_u32 s46, s5, -1
	s_cmp_eq_u32 s81, 12
	s_cselect_b32 s49, s43, s46
	s_cselect_b32 s48, s42, s33
	s_cselect_b32 s47, s7, s80
	s_cselect_b32 s46, s39, s41
	v_lshl_add_u64 v[218:219], s[4:5], 0, v[138:139]
	s_add_i32 m0, s11, 0xc000
	s_nop 0
	global_load_lds_dwordx4 v[218:219], off
	v_lshl_add_u64 v[218:219], s[4:5], 0, v[140:141]
	s_add_i32 m0, s11, 0xe000
	s_nop 0
	global_load_lds_dwordx4 v[218:219], off
	ds_read_b128 v[146:149], v152
	ds_read_b128 v[158:161], v152 offset:1024
	ds_read_b128 v[162:165], v152 offset:2048
	ds_read_b128 v[166:169], v152 offset:3072
	ds_read_b128 v[170:173], v153
	ds_read_b128 v[174:177], v153 offset:1024
	ds_read_b128 v[178:181], v153 offset:2048
	ds_read_b128 v[182:185], v153 offset:3072
	ds_read_b128 v[186:189], v154
	ds_read_b128 v[190:193], v154 offset:1024
	ds_read_b128 v[194:197], v154 offset:2048
	ds_read_b128 v[198:201], v154 offset:3072
	ds_read_b128 v[202:205], v154 offset:4096
	ds_read_b128 v[206:209], v154 offset:5120
	ds_read_b128 v[210:213], v154 offset:6144
	ds_read_b128 v[214:217], v154 offset:7168
	s_waitcnt vmcnt(8)
	s_waitcnt lgkmcnt(0)
	s_barrier
	s_setprio 0
	s_waitcnt lgkmcnt(0)
	v_mfma_f32_16x16x32_bf16 v[126:129], v[146:149], v[186:189], v[126:129]
	v_mfma_f32_16x16x32_bf16 v[122:125], v[162:165], v[186:189], v[122:125]
	v_mfma_f32_16x16x32_bf16 v[110:113], v[146:149], v[194:197], v[110:113]
	v_mfma_f32_16x16x32_bf16 v[106:109], v[162:165], v[194:197], v[106:109]
	v_mfma_f32_16x16x32_bf16 v[94:97], v[146:149], v[202:205], v[94:97]
	v_mfma_f32_16x16x32_bf16 v[90:93], v[162:165], v[202:205], v[90:93]
	v_mfma_f32_16x16x32_bf16 v[78:81], v[146:149], v[210:213], v[78:81]
	v_mfma_f32_16x16x32_bf16 v[74:77], v[162:165], v[210:213], v[74:77]
	v_mfma_f32_16x16x32_bf16 v[126:129], v[158:161], v[190:193], v[126:129]
	v_mfma_f32_16x16x32_bf16 v[122:125], v[166:169], v[190:193], v[122:125]
	v_mfma_f32_16x16x32_bf16 v[110:113], v[158:161], v[198:201], v[110:113]
	v_mfma_f32_16x16x32_bf16 v[106:109], v[166:169], v[198:201], v[106:109]
	v_mfma_f32_16x16x32_bf16 v[94:97], v[158:161], v[206:209], v[94:97]
	v_mfma_f32_16x16x32_bf16 v[90:93], v[166:169], v[206:209], v[90:93]
	v_mfma_f32_16x16x32_bf16 v[78:81], v[158:161], v[214:217], v[78:81]
	v_mfma_f32_16x16x32_bf16 v[74:77], v[166:169], v[214:217], v[74:77]
	s_setprio 2
	s_setprio 0
	v_mfma_f32_16x16x32_bf16 v[118:121], v[170:173], v[186:189], v[118:121]
	v_mfma_f32_16x16x32_bf16 v[114:117], v[178:181], v[186:189], v[114:117]
	v_mfma_f32_16x16x32_bf16 v[102:105], v[170:173], v[194:197], v[102:105]
	v_mfma_f32_16x16x32_bf16 v[98:101], v[178:181], v[194:197], v[98:101]
	v_mfma_f32_16x16x32_bf16 v[86:89], v[170:173], v[202:205], v[86:89]
	v_mfma_f32_16x16x32_bf16 v[82:85], v[178:181], v[202:205], v[82:85]
	v_mfma_f32_16x16x32_bf16 v[70:73], v[170:173], v[210:213], v[70:73]
	v_mfma_f32_16x16x32_bf16 v[66:69], v[178:181], v[210:213], v[66:69]
	v_mfma_f32_16x16x32_bf16 v[118:121], v[174:177], v[190:193], v[118:121]
	v_mfma_f32_16x16x32_bf16 v[114:117], v[182:185], v[190:193], v[114:117]
	v_mfma_f32_16x16x32_bf16 v[102:105], v[174:177], v[198:201], v[102:105]
	v_mfma_f32_16x16x32_bf16 v[98:101], v[182:185], v[198:201], v[98:101]
	v_mfma_f32_16x16x32_bf16 v[86:89], v[174:177], v[206:209], v[86:89]
	v_mfma_f32_16x16x32_bf16 v[82:85], v[182:185], v[206:209], v[82:85]
	v_mfma_f32_16x16x32_bf16 v[70:73], v[174:177], v[214:217], v[70:73]
	v_mfma_f32_16x16x32_bf16 v[66:69], v[182:185], v[214:217], v[66:69]
	s_setprio 2
	s_barrier
	s_add_i32 s33, s71, s56
	v_lshl_add_u64 v[218:219], s[46:47], 0, v[132:133]
	s_mov_b32 m0, s33
	s_nop 0
	global_load_lds_dwordx4 v[218:219], off
	s_add_i32 m0, s33, 0x2000
	s_add_u32 s62, s46, 0x40000
	v_lshl_add_u64 v[220:221], s[46:47], 0, v[136:137]
	s_addc_u32 s63, s47, 0
	s_add_i32 s33, s72, s56
	global_load_lds_dwordx4 v[220:221], off
	v_lshl_add_u64 v[222:223], s[62:63], 0, v[132:133]
	s_mov_b32 m0, s33
	v_lshl_add_u64 v[224:225], s[48:49], 0, v[134:135]
	global_load_lds_dwordx4 v[222:223], off
	v_lshl_add_u64 v[222:223], s[62:63], 0, v[136:137]
	s_add_i32 m0, s33, 0x2000
	s_nop 0
	global_load_lds_dwordx4 v[222:223], off
	v_lshl_add_u64 v[222:223], s[48:49], 0, v[130:131]
	s_mov_b32 m0, s11
	s_nop 0
	global_load_lds_dwordx4 v[222:223], off
	s_mov_b32 m0, s57
	s_nop 0
	global_load_lds_dwordx4 v[224:225], off
	ds_read_b128 v[186:189], v154 offset:16384
	ds_read_b128 v[190:193], v154 offset:17408
	ds_read_b128 v[194:197], v154 offset:18432
	ds_read_b128 v[198:201], v154 offset:19456
	ds_read_b128 v[202:205], v154 offset:20480
	ds_read_b128 v[206:209], v154 offset:21504
	ds_read_b128 v[210:213], v154 offset:22528
	ds_read_b128 v[214:217], v154 offset:23552
	s_waitcnt vmcnt(8)
	s_waitcnt lgkmcnt(0)
	s_barrier
; #define PG8_STAGE(bufoff, gbase, voff) do { _Pragma("unroll") for (int _i = 0; _i < 2; ++_i) \
;         __builtin_amdgcn_global_load_lds((const unsigned*)((const char*)(gbase) + (voff)[_i]), (LAS unsigned*)(lds + (bufoff) + ldsw + _i * 8192), 16, 0, 0); } while (0)
; #define PG8_LDA(dst, b, h) do { _Pragma("unroll") for (int m = 0; m < 4; ++m) _Pragma("unroll") for (int k = 0; k < 2; ++k) dst[m][k] = *(const LAS bf16x8*)(lds + PG8_SA(b, h) + aoff + m * 2048 + k * 1024); } while (0)
; #define PG8_LDB(dst, b, h) do { _Pragma("unroll") for (int n = 0; n < 2; ++n) _Pragma("unroll") for (int k = 0; k < 2; ++k) dst[n][k] = *(const LAS bf16x8*)(lds + PG8_SB(b, h) + boff + n * 2048 + k * 1024); } while (0)
; #define PG8_MMA(ai, bj, At, Bt) do { __builtin_amdgcn_s_setprio(1); _Pragma("unroll") for (int m = 0; m < 4; ++m) _Pragma("unroll") for (int n = 0; n < 2; ++n) _Pragma("unroll") for (int k = 0; k < 2; ++k) \
;         acc[ai][bj][m][n] = __builtin_amdgcn_mfma_f32_16x16x32_bf16(Bt[n][k], At[m][k], acc[ai][bj][m][n], 0, 0, 0); __builtin_amdgcn_s_setprio(0); } while (0)
; #define PG8_WAIT_V(n) asm volatile("s_waitcnt vmcnt(" #n ")" ::: "memory")
; #define PG8_WAIT_L(n) asm volatile("s_waitcnt lgkmcnt(" #n ")" ::: "memory")
; #define PG8_BAR __builtin_amdgcn_s_barrier()
; #define PG8_SCHED __builtin_amdgcn_sched_barrier(0)
; template <class Epi>
; __device__ __forceinline__ void gemm_phase(LAS unsigned char* lds, const Gemm g, int G, int c, const Epi& E) {
;     ...
;             PG8_WAIT_V(8); PG8_WAIT_L(0); PG8_BAR; PG8_MMA(1, 0, At, B0); PG8_MMA(1, 1, At, B1); PG8_BAR; PG8_SCHED;
;             PG8_LDB(B0, 1, 0); PG8_LDB(B1, 1, 1); PG8_SCHED; PG8_LDA(At, 1, 0); PG8_STAGE(PG8_SA(0, 1), a2 + hstepA, voffA);
;             PG8_WAIT_V(8); PG8_WAIT_L(0); PG8_BAR; PG8_MMA(0, 0, At, B0); PG8_MMA(0, 1, At, B1); PG8_BAR; PG8_SCHED;
	s_setprio 0
	s_waitcnt lgkmcnt(0)
	v_mfma_f32_16x16x32_bf16 v[62:65], v[146:149], v[186:189], v[62:65]
	v_mfma_f32_16x16x32_bf16 v[58:61], v[162:165], v[186:189], v[58:61]
	v_mfma_f32_16x16x32_bf16 v[46:49], v[146:149], v[194:197], v[46:49]
	v_mfma_f32_16x16x32_bf16 v[42:45], v[162:165], v[194:197], v[42:45]
	v_mfma_f32_16x16x32_bf16 v[30:33], v[146:149], v[202:205], v[30:33]
	v_mfma_f32_16x16x32_bf16 v[26:29], v[162:165], v[202:205], v[26:29]
	v_mfma_f32_16x16x32_bf16 v[14:17], v[146:149], v[210:213], v[14:17]
	v_mfma_f32_16x16x32_bf16 v[10:13], v[162:165], v[210:213], v[10:13]
	v_mfma_f32_16x16x32_bf16 v[62:65], v[158:161], v[190:193], v[62:65]
	v_mfma_f32_16x16x32_bf16 v[58:61], v[166:169], v[190:193], v[58:61]
	v_mfma_f32_16x16x32_bf16 v[46:49], v[158:161], v[198:201], v[46:49]
	v_mfma_f32_16x16x32_bf16 v[42:45], v[166:169], v[198:201], v[42:45]
	v_mfma_f32_16x16x32_bf16 v[30:33], v[158:161], v[206:209], v[30:33]
	v_mfma_f32_16x16x32_bf16 v[26:29], v[166:169], v[206:209], v[26:29]
	v_mfma_f32_16x16x32_bf16 v[14:17], v[158:161], v[214:217], v[14:17]
	v_mfma_f32_16x16x32_bf16 v[10:13], v[166:169], v[214:217], v[10:13]
	s_setprio 2
	s_setprio 0
	v_mfma_f32_16x16x32_bf16 v[54:57], v[170:173], v[186:189], v[54:57]
	v_mfma_f32_16x16x32_bf16 v[50:53], v[178:181], v[186:189], v[50:53]
	v_mfma_f32_16x16x32_bf16 v[38:41], v[170:173], v[194:197], v[38:41]
	v_mfma_f32_16x16x32_bf16 v[34:37], v[178:181], v[194:197], v[34:37]
	v_mfma_f32_16x16x32_bf16 v[22:25], v[170:173], v[202:205], v[22:25]
	v_mfma_f32_16x16x32_bf16 v[18:21], v[178:181], v[202:205], v[18:21]
	v_mfma_f32_16x16x32_bf16 v[6:9], v[170:173], v[210:213], v[6:9]
	v_mfma_f32_16x16x32_bf16 v[2:5], v[178:181], v[210:213], v[2:5]
	v_mfma_f32_16x16x32_bf16 v[54:57], v[174:177], v[190:193], v[54:57]
	v_mfma_f32_16x16x32_bf16 v[50:53], v[182:185], v[190:193], v[50:53]
	v_mfma_f32_16x16x32_bf16 v[38:41], v[174:177], v[198:201], v[38:41]
	v_mfma_f32_16x16x32_bf16 v[34:37], v[182:185], v[198:201], v[34:37]
	v_mfma_f32_16x16x32_bf16 v[22:25], v[174:177], v[206:209], v[22:25]
	v_mfma_f32_16x16x32_bf16 v[18:21], v[182:185], v[206:209], v[18:21]
	v_mfma_f32_16x16x32_bf16 v[6:9], v[174:177], v[214:217], v[6:9]
	v_mfma_f32_16x16x32_bf16 v[2:5], v[182:185], v[214:217], v[2:5]
	s_setprio 2
	s_barrier
	s_add_i32 s33, 0, 0x18000
	s_add_i32 s62, 0, 0x1c000
	s_add_u32 s48, s48, 0x40000
	s_addc_u32 s49, s49, 0
	s_mov_b32 m0, s58
	v_lshl_add_u64 v[226:227], s[48:49], 0, v[130:131]
	global_load_lds_dwordx4 v[226:227], off
	v_lshl_add_u64 v[226:227], s[48:49], 0, v[134:135]
	s_mov_b32 m0, s59
	s_nop 0
	global_load_lds_dwordx4 v[226:227], off
	v_add_u32_e32 v157, s33, v151
	ds_read_b128 v[146:149], v157
	ds_read_b128 v[158:161], v157 offset:1024
	ds_read_b128 v[162:165], v157 offset:2048
	ds_read_b128 v[166:169], v157 offset:3072
	v_add_u32_e32 v157, s62, v151
	ds_read_b128 v[170:173], v157
	ds_read_b128 v[174:177], v157 offset:1024
	ds_read_b128 v[178:181], v157 offset:2048
	ds_read_b128 v[182:185], v157 offset:3072
	ds_read_b128 v[186:189], v154 offset:32768
	ds_read_b128 v[190:193], v154 offset:33792
	ds_read_b128 v[194:197], v154 offset:34816
	ds_read_b128 v[198:201], v154 offset:35840
	ds_read_b128 v[202:205], v154 offset:36864
	ds_read_b128 v[206:209], v154 offset:37888
	ds_read_b128 v[210:213], v154 offset:38912
	ds_read_b128 v[214:217], v154 offset:39936
	s_waitcnt vmcnt(8)
	s_waitcnt lgkmcnt(0)
	s_barrier
	s_setprio 0
	s_waitcnt lgkmcnt(0)
	v_mfma_f32_16x16x32_bf16 v[126:129], v[146:149], v[186:189], v[126:129]
	v_mfma_f32_16x16x32_bf16 v[122:125], v[162:165], v[186:189], v[122:125]
	v_mfma_f32_16x16x32_bf16 v[110:113], v[146:149], v[194:197], v[110:113]
	v_mfma_f32_16x16x32_bf16 v[106:109], v[162:165], v[194:197], v[106:109]
	v_mfma_f32_16x16x32_bf16 v[94:97], v[146:149], v[202:205], v[94:97]
	v_mfma_f32_16x16x32_bf16 v[90:93], v[162:165], v[202:205], v[90:93]
	v_mfma_f32_16x16x32_bf16 v[78:81], v[146:149], v[210:213], v[78:81]
	v_mfma_f32_16x16x32_bf16 v[74:77], v[162:165], v[210:213], v[74:77]
	v_mfma_f32_16x16x32_bf16 v[126:129], v[158:161], v[190:193], v[126:129]
	v_mfma_f32_16x16x32_bf16 v[122:125], v[166:169], v[190:193], v[122:125]
	v_mfma_f32_16x16x32_bf16 v[110:113], v[158:161], v[198:201], v[110:113]
	v_mfma_f32_16x16x32_bf16 v[106:109], v[166:169], v[198:201], v[106:109]
	v_mfma_f32_16x16x32_bf16 v[94:97], v[158:161], v[206:209], v[94:97]
	v_mfma_f32_16x16x32_bf16 v[90:93], v[166:169], v[206:209], v[90:93]
	v_mfma_f32_16x16x32_bf16 v[78:81], v[158:161], v[214:217], v[78:81]
	v_mfma_f32_16x16x32_bf16 v[74:77], v[166:169], v[214:217], v[74:77]
	s_setprio 2
	s_setprio 0
	v_mfma_f32_16x16x32_bf16 v[118:121], v[170:173], v[186:189], v[118:121]
	v_mfma_f32_16x16x32_bf16 v[114:117], v[178:181], v[186:189], v[114:117]
	v_mfma_f32_16x16x32_bf16 v[102:105], v[170:173], v[194:197], v[102:105]
	v_mfma_f32_16x16x32_bf16 v[98:101], v[178:181], v[194:197], v[98:101]
	v_mfma_f32_16x16x32_bf16 v[86:89], v[170:173], v[202:205], v[86:89]
	v_mfma_f32_16x16x32_bf16 v[82:85], v[178:181], v[202:205], v[82:85]
	v_mfma_f32_16x16x32_bf16 v[70:73], v[170:173], v[210:213], v[70:73]
	v_mfma_f32_16x16x32_bf16 v[66:69], v[178:181], v[210:213], v[66:69]
	v_mfma_f32_16x16x32_bf16 v[118:121], v[174:177], v[190:193], v[118:121]
	v_mfma_f32_16x16x32_bf16 v[114:117], v[182:185], v[190:193], v[114:117]
	v_mfma_f32_16x16x32_bf16 v[102:105], v[174:177], v[198:201], v[102:105]
	v_mfma_f32_16x16x32_bf16 v[98:101], v[182:185], v[198:201], v[98:101]
	v_mfma_f32_16x16x32_bf16 v[86:89], v[174:177], v[206:209], v[86:89]
	v_mfma_f32_16x16x32_bf16 v[82:85], v[182:185], v[206:209], v[82:85]
	v_mfma_f32_16x16x32_bf16 v[70:73], v[174:177], v[214:217], v[70:73]
	v_mfma_f32_16x16x32_bf16 v[66:69], v[182:185], v[214:217], v[66:69]
	s_setprio 2
	s_barrier
; #define PG8_STAGE(bufoff, gbase, voff) do { _Pragma("unroll") for (int _i = 0; _i < 2; ++_i) \
;         __builtin_amdgcn_global_load_lds((const unsigned*)((const char*)(gbase) + (voff)[_i]), (LAS unsigned*)(lds + (bufoff) + ldsw + _i * 8192), 16, 0, 0); } while (0)
; #define PG8_LDA(dst, b, h) do { _Pragma("unroll") for (int m = 0; m < 4; ++m) _Pragma("unroll") for (int k = 0; k < 2; ++k) dst[m][k] = *(const LAS bf16x8*)(lds + PG8_SA(b, h) + aoff + m * 2048 + k * 1024); } while (0)
; #define PG8_MMA(ai, bj, At, Bt) do { __builtin_amdgcn_s_setprio(1); _Pragma("unroll") for (int m = 0; m < 4; ++m) _Pragma("unroll") for (int n = 0; n < 2; ++n) _Pragma("unroll") for (int k = 0; k < 2; ++k) \
;         acc[ai][bj][m][n] = __builtin_amdgcn_mfma_f32_16x16x32_bf16(Bt[n][k], At[m][k], acc[ai][bj][m][n], 0, 0, 0); __builtin_amdgcn_s_setprio(0); } while (0)
; #define PG8_WAIT_V(n) asm volatile("s_waitcnt vmcnt(" #n ")" ::: "memory")
; #define PG8_WAIT_L(n) asm volatile("s_waitcnt lgkmcnt(" #n ")" ::: "memory")
; #define PG8_BAR __builtin_amdgcn_s_barrier()
; #define PG8_SCHED __builtin_amdgcn_sched_barrier(0)
; template <class Epi>
; __device__ __forceinline__ void gemm_phase(LAS unsigned char* lds, const Gemm g, int G, int c, const Epi& E) {
;     ...
;             PG8_LDA(At, 1, 1); PG8_STAGE(PG8_SB(1, 0), b3, voffB); PG8_STAGE(PG8_SB(1, 1), b3 + hstepB, voffB); PG8_STAGE(PG8_SA(1, 0), a3, voffA);
;             PG8_WAIT_V(8); PG8_WAIT_L(0); PG8_BAR; PG8_MMA(1, 0, At, B0); PG8_MMA(1, 1, At, B1); PG8_BAR; PG8_SCHED;
;         }
;         if (wr == 0) PG8_BAR;
	s_add_i32 s33, s33, s56
	v_lshl_add_u64 v[218:219], v[218:219], 0, s[20:21]
	s_mov_b32 m0, s33
	s_nop 0
	global_load_lds_dwordx4 v[218:219], off
	s_add_i32 m0, s33, 0x2000
	s_add_u32 s46, s46, 0x40080
	v_lshl_add_u64 v[218:219], v[220:221], 0, s[20:21]
	s_addc_u32 s47, s47, 0
	s_add_i32 s33, s62, s56
	global_load_lds_dwordx4 v[218:219], off
	v_lshl_add_u64 v[218:219], s[46:47], 0, v[132:133]
	s_mov_b32 m0, s33
	s_nop 0
	global_load_lds_dwordx4 v[218:219], off
	v_lshl_add_u64 v[218:219], s[46:47], 0, v[136:137]
	s_add_i32 m0, s33, 0x2000
	s_nop 0
	global_load_lds_dwordx4 v[218:219], off
	v_lshl_add_u64 v[218:219], v[222:223], 0, s[20:21]
	s_mov_b32 m0, s67
	s_nop 0
	global_load_lds_dwordx4 v[218:219], off
	v_lshl_add_u64 v[218:219], v[224:225], 0, s[20:21]
	s_mov_b32 m0, s68
	s_nop 0
	global_load_lds_dwordx4 v[218:219], off
	ds_read_b128 v[186:189], v154 offset:49152
	ds_read_b128 v[190:193], v154 offset:50176
	ds_read_b128 v[194:197], v154 offset:51200
	ds_read_b128 v[198:201], v154 offset:52224
	ds_read_b128 v[202:205], v154 offset:53248
	ds_read_b128 v[206:209], v154 offset:54272
	ds_read_b128 v[210:213], v154 offset:55296
	ds_read_b128 v[214:217], v154 offset:56320
	s_waitcnt vmcnt(8)
	s_waitcnt lgkmcnt(0)
	s_barrier
	s_setprio 0
	s_waitcnt lgkmcnt(0)
	v_mfma_f32_16x16x32_bf16 v[62:65], v[146:149], v[186:189], v[62:65]
	v_mfma_f32_16x16x32_bf16 v[58:61], v[162:165], v[186:189], v[58:61]
	v_mfma_f32_16x16x32_bf16 v[46:49], v[146:149], v[194:197], v[46:49]
	v_mfma_f32_16x16x32_bf16 v[42:45], v[162:165], v[194:197], v[42:45]
	v_mfma_f32_16x16x32_bf16 v[30:33], v[146:149], v[202:205], v[30:33]
	v_mfma_f32_16x16x32_bf16 v[26:29], v[162:165], v[202:205], v[26:29]
	v_mfma_f32_16x16x32_bf16 v[14:17], v[146:149], v[210:213], v[14:17]
	v_mfma_f32_16x16x32_bf16 v[10:13], v[162:165], v[210:213], v[10:13]
	v_mfma_f32_16x16x32_bf16 v[62:65], v[158:161], v[190:193], v[62:65]
	v_mfma_f32_16x16x32_bf16 v[58:61], v[166:169], v[190:193], v[58:61]
	v_mfma_f32_16x16x32_bf16 v[46:49], v[158:161], v[198:201], v[46:49]
	v_mfma_f32_16x16x32_bf16 v[42:45], v[166:169], v[198:201], v[42:45]
	v_mfma_f32_16x16x32_bf16 v[30:33], v[158:161], v[206:209], v[30:33]
	v_mfma_f32_16x16x32_bf16 v[26:29], v[166:169], v[206:209], v[26:29]
	v_mfma_f32_16x16x32_bf16 v[14:17], v[158:161], v[214:217], v[14:17]
	v_mfma_f32_16x16x32_bf16 v[10:13], v[166:169], v[214:217], v[10:13]
	s_setprio 2
	s_setprio 0
	v_mfma_f32_16x16x32_bf16 v[54:57], v[170:173], v[186:189], v[54:57]
	v_mfma_f32_16x16x32_bf16 v[50:53], v[178:181], v[186:189], v[50:53]
	v_mfma_f32_16x16x32_bf16 v[38:41], v[170:173], v[194:197], v[38:41]
	v_mfma_f32_16x16x32_bf16 v[34:37], v[178:181], v[194:197], v[34:37]
	v_mfma_f32_16x16x32_bf16 v[22:25], v[170:173], v[202:205], v[22:25]
	v_mfma_f32_16x16x32_bf16 v[18:21], v[178:181], v[202:205], v[18:21]
	v_mfma_f32_16x16x32_bf16 v[6:9], v[170:173], v[210:213], v[6:9]
	v_mfma_f32_16x16x32_bf16 v[2:5], v[178:181], v[210:213], v[2:5]
	v_mfma_f32_16x16x32_bf16 v[54:57], v[174:177], v[190:193], v[54:57]
	v_mfma_f32_16x16x32_bf16 v[50:53], v[182:185], v[190:193], v[50:53]
	v_mfma_f32_16x16x32_bf16 v[38:41], v[174:177], v[198:201], v[38:41]
	v_mfma_f32_16x16x32_bf16 v[34:37], v[182:185], v[198:201], v[34:37]
	v_mfma_f32_16x16x32_bf16 v[22:25], v[174:177], v[206:209], v[22:25]
	v_mfma_f32_16x16x32_bf16 v[18:21], v[182:185], v[206:209], v[18:21]
	v_mfma_f32_16x16x32_bf16 v[6:9], v[174:177], v[214:217], v[6:9]
	v_mfma_f32_16x16x32_bf16 v[2:5], v[182:185], v[214:217], v[2:5]
	s_setprio 2
	s_barrier
	s_add_i32 s81, s81, 2
	s_add_u32 s4, s4, 0x100
	s_addc_u32 s5, s5, 0
	s_add_u32 s41, s41, 0x100
	s_addc_u32 s80, s80, 0
	s_cmp_gt_u32 s81, 13
	s_cbranch_scc0 .LBB0_1297
	s_and_b64 vcc, exec, s[22:23]
	s_cbranch_vccz .LBB0_1300
	s_barrier

; #define PG8_STAGE(bufoff, gbase, voff) do { _Pragma("unroll") for (int _i = 0; _i < 2; ++_i) \
;         __builtin_amdgcn_global_load_lds((const unsigned*)((const char*)(gbase) + (voff)[_i]), (LAS unsigned*)(lds + (bufoff) + ldsw + _i * 8192), 16, 0, 0); } while (0)
; #define PG8_LDA(dst, b, h) do { _Pragma("unroll") for (int m = 0; m < 4; ++m) _Pragma("unroll") for (int k = 0; k < 2; ++k) dst[m][k] = *(const LAS bf16x8*)(lds + PG8_SA(b, h) + aoff + m * 2048 + k * 1024); } while (0)
; #define PG8_LDB(dst, b, h) do { _Pragma("unroll") for (int n = 0; n < 2; ++n) _Pragma("unroll") for (int k = 0; k < 2; ++k) dst[n][k] = *(const LAS bf16x8*)(lds + PG8_SB(b, h) + boff + n * 2048 + k * 1024); } while (0)
; #define PG8_MMA(ai, bj, At, Bt) do { __builtin_amdgcn_s_setprio(1); _Pragma("unroll") for (int m = 0; m < 4; ++m) _Pragma("unroll") for (int n = 0; n < 2; ++n) _Pragma("unroll") for (int k = 0; k < 2; ++k) \
;         acc[ai][bj][m][n] = __builtin_amdgcn_mfma_f32_16x16x32_bf16(Bt[n][k], At[m][k], acc[ai][bj][m][n], 0, 0, 0); __builtin_amdgcn_s_setprio(0); } while (0)
; #define PG8_WAIT_V(n) asm volatile("s_waitcnt vmcnt(" #n ")" ::: "memory")
; #define PG8_WAIT_L(n) asm volatile("s_waitcnt lgkmcnt(" #n ")" ::: "memory")
; #define PG8_BAR __builtin_amdgcn_s_barrier()
; #define PG8_SCHED __builtin_amdgcn_sched_barrier(0)
; template <class Epi>
; __device__ __forceinline__ void gemm_phase(LAS unsigned char* lds, const Gemm g, int G, int c, const Epi& E) {
;     ...
;             const bool last = (t == nt - 2);
;             const char* a1 = cA + (size_t)(t + 1) * kstep;
;             const char* a2 = last ? nA : cA + (size_t)(t + 2) * kstep; const char* b2 = last ? nB : cB + (size_t)(t + 2) * kstep;
;             const char* a3 = a2 + kstep; const char* b3 = b2 + kstep;
;             PG8_LDB(B0, 0, 0); PG8_LDB(B1, 0, 1); PG8_SCHED; PG8_LDA(At, 0, 0); PG8_STAGE(PG8_SA(1, 1), a1 + hstepA, voffA);
;             PG8_WAIT_V(8); PG8_WAIT_L(0); PG8_BAR; PG8_MMA(0, 0, At, B0); PG8_MMA(0, 1, At, B1); PG8_BAR; PG8_SCHED;
;             PG8_LDA(At, 0, 1); PG8_STAGE(PG8_SB(0, 0), b2, voffB); PG8_STAGE(PG8_SB(0, 1), b2 + hstepB, voffB); PG8_STAGE(PG8_SA(0, 0), a2, voffA);
.LBB0_1429:
	s_add_u32 s33, s18, s13
	s_addc_u32 s42, s19, 0
	s_add_u32 s38, s33, 0x100
	s_addc_u32 s39, s42, 0
	s_and_b64 s[24:25], s[22:23], exec
	s_cselect_b32 s39, s5, s39
	s_cselect_b32 s38, s4, s38
	s_add_u32 s13, s16, s13
	s_addc_u32 s24, s17, 0
	s_add_u32 s13, s13, 0x100
	s_addc_u32 s24, s24, 0
	s_and_b64 s[22:23], s[22:23], exec
	s_cselect_b32 s41, s15, s24
	s_cselect_b32 s40, s14, s13
	s_add_u32 s44, s33, 0xb0080
	s_addc_u32 s45, s42, 0
	s_add_i32 s65, s72, s48
	s_add_i32 m0, s49, 0xc000
	s_add_i32 s85, s49, 0xe000
	v_lshl_add_u64 v[212:213], s[44:45], 0, v[136:137]
	global_load_lds_dwordx4 v[212:213], off
	v_lshl_add_u64 v[212:213], s[44:45], 0, v[132:133]
	s_mov_b32 m0, s85
	s_nop 0
	global_load_lds_dwordx4 v[212:213], off
	ds_read_b128 v[142:145], v148
	ds_read_b128 v[152:155], v148 offset:1024
	ds_read_b128 v[156:159], v148 offset:2048
	ds_read_b128 v[160:163], v148 offset:3072
	ds_read_b128 v[164:167], v149
	ds_read_b128 v[168:171], v149 offset:1024
	ds_read_b128 v[172:175], v149 offset:2048
	ds_read_b128 v[176:179], v149 offset:3072
	s_add_i32 s62, s65, 0x2000
	s_add_u32 s42, s40, 0xb0000
	s_addc_u32 s43, s41, 0
	s_add_i32 s64, s73, s48
	s_add_i32 s63, s64, 0x2000
	s_add_i32 s84, 0, 0x18000
	s_add_i32 s33, 0, 0x1c000
	s_add_u32 s24, s38, 0xb0000
	s_addc_u32 s25, s39, 0
	s_add_i32 s83, s84, s48
	s_add_i32 s13, s83, 0x2000
	s_add_u32 s22, s40, 0xb0080
	s_addc_u32 s23, s41, 0
	s_add_i32 s75, s33, s48
	s_add_i32 s74, s75, 0x2000
	ds_read_b128 v[180:183], v150
	ds_read_b128 v[184:187], v150 offset:1024
	ds_read_b128 v[188:191], v150 offset:2048
	ds_read_b128 v[192:195], v150 offset:3072
	ds_read_b128 v[196:199], v150 offset:4096
	ds_read_b128 v[200:203], v150 offset:5120
	ds_read_b128 v[204:207], v150 offset:6144
	ds_read_b128 v[208:211], v150 offset:7168
	s_waitcnt vmcnt(8)
	s_waitcnt lgkmcnt(0)
	s_barrier
	s_setprio 0
	s_waitcnt lgkmcnt(0)
	v_mfma_f32_16x16x32_bf16 v[126:129], v[142:145], v[180:183], v[126:129]
	v_mfma_f32_16x16x32_bf16 v[122:125], v[156:159], v[180:183], v[122:125]
	v_mfma_f32_16x16x32_bf16 v[118:121], v[142:145], v[188:191], v[118:121]
	v_mfma_f32_16x16x32_bf16 v[110:113], v[156:159], v[188:191], v[110:113]
	v_mfma_f32_16x16x32_bf16 v[102:105], v[142:145], v[196:199], v[102:105]
	v_mfma_f32_16x16x32_bf16 v[94:97], v[156:159], v[196:199], v[94:97]
	v_mfma_f32_16x16x32_bf16 v[86:89], v[142:145], v[204:207], v[86:89]
	v_mfma_f32_16x16x32_bf16 v[78:81], v[156:159], v[204:207], v[78:81]
	v_mfma_f32_16x16x32_bf16 v[126:129], v[152:155], v[184:187], v[126:129]
	v_mfma_f32_16x16x32_bf16 v[122:125], v[160:163], v[184:187], v[122:125]
	v_mfma_f32_16x16x32_bf16 v[118:121], v[152:155], v[192:195], v[118:121]
	v_mfma_f32_16x16x32_bf16 v[110:113], v[160:163], v[192:195], v[110:113]
	v_mfma_f32_16x16x32_bf16 v[102:105], v[152:155], v[200:203], v[102:105]
	v_mfma_f32_16x16x32_bf16 v[94:97], v[160:163], v[200:203], v[94:97]
	v_mfma_f32_16x16x32_bf16 v[86:89], v[152:155], v[208:211], v[86:89]
	v_mfma_f32_16x16x32_bf16 v[78:81], v[160:163], v[208:211], v[78:81]
	s_setprio 2
	s_setprio 0
	v_mfma_f32_16x16x32_bf16 v[114:117], v[164:167], v[180:183], v[114:117]
	v_mfma_f32_16x16x32_bf16 v[106:109], v[172:175], v[180:183], v[106:109]
	v_mfma_f32_16x16x32_bf16 v[98:101], v[164:167], v[188:191], v[98:101]
	v_mfma_f32_16x16x32_bf16 v[90:93], v[172:175], v[188:191], v[90:93]
	v_mfma_f32_16x16x32_bf16 v[82:85], v[164:167], v[196:199], v[82:85]
	v_mfma_f32_16x16x32_bf16 v[74:77], v[172:175], v[196:199], v[74:77]
	v_mfma_f32_16x16x32_bf16 v[70:73], v[164:167], v[204:207], v[70:73]
	v_mfma_f32_16x16x32_bf16 v[66:69], v[172:175], v[204:207], v[66:69]
	v_mfma_f32_16x16x32_bf16 v[114:117], v[168:171], v[184:187], v[114:117]
	v_mfma_f32_16x16x32_bf16 v[106:109], v[176:179], v[184:187], v[106:109]
	v_mfma_f32_16x16x32_bf16 v[98:101], v[168:171], v[192:195], v[98:101]
	v_mfma_f32_16x16x32_bf16 v[90:93], v[176:179], v[192:195], v[90:93]
	v_mfma_f32_16x16x32_bf16 v[82:85], v[168:171], v[200:203], v[82:85]
	v_mfma_f32_16x16x32_bf16 v[74:77], v[176:179], v[200:203], v[74:77]
	v_mfma_f32_16x16x32_bf16 v[70:73], v[168:171], v[208:211], v[70:73]
	v_mfma_f32_16x16x32_bf16 v[66:69], v[176:179], v[208:211], v[66:69]
	s_setprio 2
	s_barrier
	s_mov_b32 m0, s65
	v_lshl_add_u64 v[212:213], s[40:41], 0, v[134:135]
	global_load_lds_dwordx4 v[212:213], off
	v_lshl_add_u64 v[214:215], s[40:41], 0, v[130:131]
	s_mov_b32 m0, s62
	v_lshl_add_u64 v[216:217], s[42:43], 0, v[134:135]
	global_load_lds_dwordx4 v[214:215], off
	s_mov_b32 m0, s64
	v_lshl_add_u64 v[218:219], s[38:39], 0, v[132:133]
	global_load_lds_dwordx4 v[216:217], off
	v_lshl_add_u64 v[216:217], s[42:43], 0, v[130:131]
	s_mov_b32 m0, s63
	s_nop 0
	global_load_lds_dwordx4 v[216:217], off
	v_lshl_add_u64 v[216:217], s[38:39], 0, v[136:137]
	s_mov_b32 m0, s49
	s_nop 0
	global_load_lds_dwordx4 v[216:217], off
	s_mov_b32 m0, s52
	s_nop 0
	global_load_lds_dwordx4 v[218:219], off
	ds_read_b128 v[180:183], v150 offset:16384
	ds_read_b128 v[184:187], v150 offset:17408
	ds_read_b128 v[188:191], v150 offset:18432
	ds_read_b128 v[192:195], v150 offset:19456
	ds_read_b128 v[196:199], v150 offset:20480
	ds_read_b128 v[200:203], v150 offset:21504
	ds_read_b128 v[204:207], v150 offset:22528
	ds_read_b128 v[208:211], v150 offset:23552
	s_waitcnt vmcnt(8)
	s_waitcnt lgkmcnt(0)
	s_barrier
; #define PG8_STAGE(bufoff, gbase, voff) do { _Pragma("unroll") for (int _i = 0; _i < 2; ++_i) \
;         __builtin_amdgcn_global_load_lds((const unsigned*)((const char*)(gbase) + (voff)[_i]), (LAS unsigned*)(lds + (bufoff) + ldsw + _i * 8192), 16, 0, 0); } while (0)
; #define PG8_LDA(dst, b, h) do { _Pragma("unroll") for (int m = 0; m < 4; ++m) _Pragma("unroll") for (int k = 0; k < 2; ++k) dst[m][k] = *(const LAS bf16x8*)(lds + PG8_SA(b, h) + aoff + m * 2048 + k * 1024); } while (0)
; #define PG8_LDB(dst, b, h) do { _Pragma("unroll") for (int n = 0; n < 2; ++n) _Pragma("unroll") for (int k = 0; k < 2; ++k) dst[n][k] = *(const LAS bf16x8*)(lds + PG8_SB(b, h) + boff + n * 2048 + k * 1024); } while (0)
; #define PG8_MMA(ai, bj, At, Bt) do { __builtin_amdgcn_s_setprio(1); _Pragma("unroll") for (int m = 0; m < 4; ++m) _Pragma("unroll") for (int n = 0; n < 2; ++n) _Pragma("unroll") for (int k = 0; k < 2; ++k) \
;         acc[ai][bj][m][n] = __builtin_amdgcn_mfma_f32_16x16x32_bf16(Bt[n][k], At[m][k], acc[ai][bj][m][n], 0, 0, 0); __builtin_amdgcn_s_setprio(0); } while (0)
; #define PG8_WAIT_V(n) asm volatile("s_waitcnt vmcnt(" #n ")" ::: "memory")
; #define PG8_WAIT_L(n) asm volatile("s_waitcnt lgkmcnt(" #n ")" ::: "memory")
; #define PG8_BAR __builtin_amdgcn_s_barrier()
; #define PG8_SCHED __builtin_amdgcn_sched_barrier(0)
; template <class Epi>
; __device__ __forceinline__ void gemm_phase(LAS unsigned char* lds, const Gemm g, int G, int c, const Epi& E) {
;     ...
;             PG8_WAIT_V(8); PG8_WAIT_L(0); PG8_BAR; PG8_MMA(1, 0, At, B0); PG8_MMA(1, 1, At, B1); PG8_BAR; PG8_SCHED;
;             PG8_LDB(B0, 1, 0); PG8_LDB(B1, 1, 1); PG8_SCHED; PG8_LDA(At, 1, 0); PG8_STAGE(PG8_SA(0, 1), a2 + hstepA, voffA);
;             PG8_WAIT_V(8); PG8_WAIT_L(0); PG8_BAR; PG8_MMA(0, 0, At, B0); PG8_MMA(0, 1, At, B1); PG8_BAR; PG8_SCHED;
	s_setprio 0
	s_waitcnt lgkmcnt(0)
	v_mfma_f32_16x16x32_bf16 v[62:65], v[142:145], v[180:183], v[62:65]
	v_mfma_f32_16x16x32_bf16 v[58:61], v[156:159], v[180:183], v[58:61]
	v_mfma_f32_16x16x32_bf16 v[54:57], v[142:145], v[188:191], v[54:57]
	v_mfma_f32_16x16x32_bf16 v[46:49], v[156:159], v[188:191], v[46:49]
	v_mfma_f32_16x16x32_bf16 v[38:41], v[142:145], v[196:199], v[38:41]
	v_mfma_f32_16x16x32_bf16 v[30:33], v[156:159], v[196:199], v[30:33]
	v_mfma_f32_16x16x32_bf16 v[22:25], v[142:145], v[204:207], v[22:25]
	v_mfma_f32_16x16x32_bf16 v[14:17], v[156:159], v[204:207], v[14:17]
	v_mfma_f32_16x16x32_bf16 v[62:65], v[152:155], v[184:187], v[62:65]
	v_mfma_f32_16x16x32_bf16 v[58:61], v[160:163], v[184:187], v[58:61]
	v_mfma_f32_16x16x32_bf16 v[54:57], v[152:155], v[192:195], v[54:57]
	v_mfma_f32_16x16x32_bf16 v[46:49], v[160:163], v[192:195], v[46:49]
	v_mfma_f32_16x16x32_bf16 v[38:41], v[152:155], v[200:203], v[38:41]
	v_mfma_f32_16x16x32_bf16 v[30:33], v[160:163], v[200:203], v[30:33]
	v_mfma_f32_16x16x32_bf16 v[22:25], v[152:155], v[208:211], v[22:25]
	v_mfma_f32_16x16x32_bf16 v[14:17], v[160:163], v[208:211], v[14:17]
	s_setprio 2
	s_setprio 0
	v_mfma_f32_16x16x32_bf16 v[50:53], v[164:167], v[180:183], v[50:53]
	v_mfma_f32_16x16x32_bf16 v[42:45], v[172:175], v[180:183], v[42:45]
	v_mfma_f32_16x16x32_bf16 v[34:37], v[164:167], v[188:191], v[34:37]
	v_mfma_f32_16x16x32_bf16 v[26:29], v[172:175], v[188:191], v[26:29]
	v_mfma_f32_16x16x32_bf16 v[18:21], v[164:167], v[196:199], v[18:21]
	v_mfma_f32_16x16x32_bf16 v[10:13], v[172:175], v[196:199], v[10:13]
	v_mfma_f32_16x16x32_bf16 v[6:9], v[164:167], v[204:207], v[6:9]
	v_mfma_f32_16x16x32_bf16 v[2:5], v[172:175], v[204:207], v[2:5]
	v_mfma_f32_16x16x32_bf16 v[50:53], v[168:171], v[184:187], v[50:53]
	v_mfma_f32_16x16x32_bf16 v[42:45], v[176:179], v[184:187], v[42:45]
	v_mfma_f32_16x16x32_bf16 v[34:37], v[168:171], v[192:195], v[34:37]
	v_mfma_f32_16x16x32_bf16 v[26:29], v[176:179], v[192:195], v[26:29]
	v_mfma_f32_16x16x32_bf16 v[18:21], v[168:171], v[200:203], v[18:21]
	v_mfma_f32_16x16x32_bf16 v[10:13], v[176:179], v[200:203], v[10:13]
	v_mfma_f32_16x16x32_bf16 v[6:9], v[168:171], v[208:211], v[6:9]
	v_mfma_f32_16x16x32_bf16 v[2:5], v[176:179], v[208:211], v[2:5]
	s_setprio 2
	s_barrier
	s_mov_b32 m0, s53
	v_lshl_add_u64 v[220:221], s[24:25], 0, v[136:137]
	global_load_lds_dwordx4 v[220:221], off
	v_lshl_add_u64 v[220:221], s[24:25], 0, v[132:133]
	s_mov_b32 m0, s54
	s_nop 0
	global_load_lds_dwordx4 v[220:221], off
	v_add_u32_e32 v151, s84, v147
	ds_read_b128 v[142:145], v151
	ds_read_b128 v[152:155], v151 offset:1024
	ds_read_b128 v[156:159], v151 offset:2048
	ds_read_b128 v[160:163], v151 offset:3072
	v_add_u32_e32 v151, s33, v147
	ds_read_b128 v[164:167], v151
	ds_read_b128 v[168:171], v151 offset:1024
	ds_read_b128 v[172:175], v151 offset:2048
	ds_read_b128 v[176:179], v151 offset:3072
	ds_read_b128 v[180:183], v150 offset:32768
	ds_read_b128 v[184:187], v150 offset:33792
	ds_read_b128 v[188:191], v150 offset:34816
	ds_read_b128 v[192:195], v150 offset:35840
	ds_read_b128 v[196:199], v150 offset:36864
	ds_read_b128 v[200:203], v150 offset:37888
	ds_read_b128 v[204:207], v150 offset:38912
	ds_read_b128 v[208:211], v150 offset:39936
	s_waitcnt vmcnt(8)
	s_waitcnt lgkmcnt(0)
	s_barrier
	s_setprio 0
	s_waitcnt lgkmcnt(0)
	v_mfma_f32_16x16x32_bf16 v[126:129], v[142:145], v[180:183], v[126:129]
	v_mfma_f32_16x16x32_bf16 v[122:125], v[156:159], v[180:183], v[122:125]
	v_mfma_f32_16x16x32_bf16 v[118:121], v[142:145], v[188:191], v[118:121]
	v_mfma_f32_16x16x32_bf16 v[110:113], v[156:159], v[188:191], v[110:113]
	v_mfma_f32_16x16x32_bf16 v[102:105], v[142:145], v[196:199], v[102:105]
	v_mfma_f32_16x16x32_bf16 v[94:97], v[156:159], v[196:199], v[94:97]
	v_mfma_f32_16x16x32_bf16 v[86:89], v[142:145], v[204:207], v[86:89]
	v_mfma_f32_16x16x32_bf16 v[78:81], v[156:159], v[204:207], v[78:81]
	v_mfma_f32_16x16x32_bf16 v[126:129], v[152:155], v[184:187], v[126:129]
	v_mfma_f32_16x16x32_bf16 v[122:125], v[160:163], v[184:187], v[122:125]
	v_mfma_f32_16x16x32_bf16 v[118:121], v[152:155], v[192:195], v[118:121]
	v_mfma_f32_16x16x32_bf16 v[110:113], v[160:163], v[192:195], v[110:113]
	v_mfma_f32_16x16x32_bf16 v[102:105], v[152:155], v[200:203], v[102:105]
	v_mfma_f32_16x16x32_bf16 v[94:97], v[160:163], v[200:203], v[94:97]
	v_mfma_f32_16x16x32_bf16 v[86:89], v[152:155], v[208:211], v[86:89]
	v_mfma_f32_16x16x32_bf16 v[78:81], v[160:163], v[208:211], v[78:81]
	s_setprio 2
	s_setprio 0
	v_mfma_f32_16x16x32_bf16 v[114:117], v[164:167], v[180:183], v[114:117]
	v_mfma_f32_16x16x32_bf16 v[106:109], v[172:175], v[180:183], v[106:109]
	v_mfma_f32_16x16x32_bf16 v[98:101], v[164:167], v[188:191], v[98:101]
	v_mfma_f32_16x16x32_bf16 v[90:93], v[172:175], v[188:191], v[90:93]
	v_mfma_f32_16x16x32_bf16 v[82:85], v[164:167], v[196:199], v[82:85]
	v_mfma_f32_16x16x32_bf16 v[74:77], v[172:175], v[196:199], v[74:77]
	v_mfma_f32_16x16x32_bf16 v[70:73], v[164:167], v[204:207], v[70:73]
	v_mfma_f32_16x16x32_bf16 v[66:69], v[172:175], v[204:207], v[66:69]
	v_mfma_f32_16x16x32_bf16 v[114:117], v[168:171], v[184:187], v[114:117]
	v_mfma_f32_16x16x32_bf16 v[106:109], v[176:179], v[184:187], v[106:109]
	v_mfma_f32_16x16x32_bf16 v[98:101], v[168:171], v[192:195], v[98:101]
	v_mfma_f32_16x16x32_bf16 v[90:93], v[176:179], v[192:195], v[90:93]
	v_mfma_f32_16x16x32_bf16 v[82:85], v[168:171], v[200:203], v[82:85]
	v_mfma_f32_16x16x32_bf16 v[74:77], v[176:179], v[200:203], v[74:77]
	v_mfma_f32_16x16x32_bf16 v[70:73], v[168:171], v[208:211], v[70:73]
	v_mfma_f32_16x16x32_bf16 v[66:69], v[176:179], v[208:211], v[66:69]
	s_setprio 2
	s_barrier
; #define PG8_STAGE(bufoff, gbase, voff) do { _Pragma("unroll") for (int _i = 0; _i < 2; ++_i) \
;         __builtin_amdgcn_global_load_lds((const unsigned*)((const char*)(gbase) + (voff)[_i]), (LAS unsigned*)(lds + (bufoff) + ldsw + _i * 8192), 16, 0, 0); } while (0)
; #define PG8_LDA(dst, b, h) do { _Pragma("unroll") for (int m = 0; m < 4; ++m) _Pragma("unroll") for (int k = 0; k < 2; ++k) dst[m][k] = *(const LAS bf16x8*)(lds + PG8_SA(b, h) + aoff + m * 2048 + k * 1024); } while (0)
; #define PG8_MMA(ai, bj, At, Bt) do { __builtin_amdgcn_s_setprio(1); _Pragma("unroll") for (int m = 0; m < 4; ++m) _Pragma("unroll") for (int n = 0; n < 2; ++n) _Pragma("unroll") for (int k = 0; k < 2; ++k) \
;         acc[ai][bj][m][n] = __builtin_amdgcn_mfma_f32_16x16x32_bf16(Bt[n][k], At[m][k], acc[ai][bj][m][n], 0, 0, 0); __builtin_amdgcn_s_setprio(0); } while (0)
; #define PG8_WAIT_V(n) asm volatile("s_waitcnt vmcnt(" #n ")" ::: "memory")
; #define PG8_WAIT_L(n) asm volatile("s_waitcnt lgkmcnt(" #n ")" ::: "memory")
; #define PG8_BAR __builtin_amdgcn_s_barrier()
; #define PG8_SCHED __builtin_amdgcn_sched_barrier(0)
; template <class Epi>
; __device__ __forceinline__ void gemm_phase(LAS unsigned char* lds, const Gemm g, int G, int c, const Epi& E) {
;     ...
;             PG8_LDA(At, 1, 1); PG8_STAGE(PG8_SB(1, 0), b3, voffB); PG8_STAGE(PG8_SB(1, 1), b3 + hstepB, voffB); PG8_STAGE(PG8_SA(1, 0), a3, voffA);
;             PG8_WAIT_V(8); PG8_WAIT_L(0); PG8_BAR; PG8_MMA(1, 0, At, B0); PG8_MMA(1, 1, At, B1); PG8_BAR; PG8_SCHED;
;         }
;         if (wr == 0) PG8_BAR;
	s_mov_b32 m0, s83
	v_lshl_add_u64 v[212:213], v[212:213], 0, s[8:9]
	global_load_lds_dwordx4 v[212:213], off
	v_lshl_add_u64 v[212:213], v[214:215], 0, s[8:9]
	s_mov_b32 m0, s13
	s_nop 0
	global_load_lds_dwordx4 v[212:213], off
	v_lshl_add_u64 v[212:213], s[22:23], 0, v[134:135]
	s_mov_b32 m0, s75
	s_nop 0
	global_load_lds_dwordx4 v[212:213], off
	v_lshl_add_u64 v[212:213], s[22:23], 0, v[130:131]
	s_mov_b32 m0, s74
	s_nop 0
	global_load_lds_dwordx4 v[212:213], off
	v_lshl_add_u64 v[212:213], v[216:217], 0, s[8:9]
	s_mov_b32 m0, s70
	s_nop 0
	global_load_lds_dwordx4 v[212:213], off
	v_lshl_add_u64 v[212:213], v[218:219], 0, s[8:9]
	s_mov_b32 m0, s71
	s_nop 0
	global_load_lds_dwordx4 v[212:213], off
	ds_read_b128 v[180:183], v150 offset:49152
	ds_read_b128 v[184:187], v150 offset:50176
	ds_read_b128 v[188:191], v150 offset:51200
	ds_read_b128 v[192:195], v150 offset:52224
	ds_read_b128 v[196:199], v150 offset:53248
	ds_read_b128 v[200:203], v150 offset:54272
	ds_read_b128 v[204:207], v150 offset:55296
	ds_read_b128 v[208:211], v150 offset:56320
	s_waitcnt vmcnt(8)
	s_waitcnt lgkmcnt(0)
	s_barrier
	s_setprio 0
	s_waitcnt lgkmcnt(0)
	v_mfma_f32_16x16x32_bf16 v[62:65], v[142:145], v[180:183], v[62:65]
	v_mfma_f32_16x16x32_bf16 v[58:61], v[156:159], v[180:183], v[58:61]
	v_mfma_f32_16x16x32_bf16 v[54:57], v[142:145], v[188:191], v[54:57]
	v_mfma_f32_16x16x32_bf16 v[46:49], v[156:159], v[188:191], v[46:49]
	v_mfma_f32_16x16x32_bf16 v[38:41], v[142:145], v[196:199], v[38:41]
	v_mfma_f32_16x16x32_bf16 v[30:33], v[156:159], v[196:199], v[30:33]
	v_mfma_f32_16x16x32_bf16 v[22:25], v[142:145], v[204:207], v[22:25]
	v_mfma_f32_16x16x32_bf16 v[14:17], v[156:159], v[204:207], v[14:17]
	v_mfma_f32_16x16x32_bf16 v[62:65], v[152:155], v[184:187], v[62:65]
	v_mfma_f32_16x16x32_bf16 v[58:61], v[160:163], v[184:187], v[58:61]
	v_mfma_f32_16x16x32_bf16 v[54:57], v[152:155], v[192:195], v[54:57]
	v_mfma_f32_16x16x32_bf16 v[46:49], v[160:163], v[192:195], v[46:49]
	v_mfma_f32_16x16x32_bf16 v[38:41], v[152:155], v[200:203], v[38:41]
	v_mfma_f32_16x16x32_bf16 v[30:33], v[160:163], v[200:203], v[30:33]
	v_mfma_f32_16x16x32_bf16 v[22:25], v[152:155], v[208:211], v[22:25]
	v_mfma_f32_16x16x32_bf16 v[14:17], v[160:163], v[208:211], v[14:17]
	s_setprio 2
	s_setprio 0
	v_mfma_f32_16x16x32_bf16 v[50:53], v[164:167], v[180:183], v[50:53]
	v_mfma_f32_16x16x32_bf16 v[42:45], v[172:175], v[180:183], v[42:45]
	v_mfma_f32_16x16x32_bf16 v[34:37], v[164:167], v[188:191], v[34:37]
	v_mfma_f32_16x16x32_bf16 v[26:29], v[172:175], v[188:191], v[26:29]
	v_mfma_f32_16x16x32_bf16 v[18:21], v[164:167], v[196:199], v[18:21]
	v_mfma_f32_16x16x32_bf16 v[10:13], v[172:175], v[196:199], v[10:13]
	v_mfma_f32_16x16x32_bf16 v[6:9], v[164:167], v[204:207], v[6:9]
	v_mfma_f32_16x16x32_bf16 v[2:5], v[172:175], v[204:207], v[2:5]
	v_mfma_f32_16x16x32_bf16 v[50:53], v[168:171], v[184:187], v[50:53]
	v_mfma_f32_16x16x32_bf16 v[42:45], v[176:179], v[184:187], v[42:45]
	v_mfma_f32_16x16x32_bf16 v[34:37], v[168:171], v[192:195], v[34:37]
	v_mfma_f32_16x16x32_bf16 v[26:29], v[176:179], v[192:195], v[26:29]
	v_mfma_f32_16x16x32_bf16 v[18:21], v[168:171], v[200:203], v[18:21]
	v_mfma_f32_16x16x32_bf16 v[10:13], v[176:179], v[200:203], v[10:13]
	v_mfma_f32_16x16x32_bf16 v[6:9], v[168:171], v[208:211], v[6:9]
	v_mfma_f32_16x16x32_bf16 v[2:5], v[176:179], v[208:211], v[2:5]
	s_setprio 2
	s_barrier
	s_movk_i32 s13, 0x100
	s_andn2_b64 vcc, exec, s[20:21]
	s_mov_b64 s[22:23], -1
	s_mov_b64 s[20:21], 0
	s_cbranch_vccz .LBB0_1429
	s_and_b64 vcc, exec, s[10:11]
	s_cbranch_vccz .LBB0_1432
	s_barrier

; #define PG8_STAGE(bufoff, gbase, voff) do { _Pragma("unroll") for (int _i = 0; _i < 2; ++_i) \
;         __builtin_amdgcn_global_load_lds((const unsigned*)((const char*)(gbase) + (voff)[_i]), (LAS unsigned*)(lds + (bufoff) + ldsw + _i * 8192), 16, 0, 0); } while (0)
; #define PG8_LDA(dst, b, h) do { _Pragma("unroll") for (int m = 0; m < 4; ++m) _Pragma("unroll") for (int k = 0; k < 2; ++k) dst[m][k] = *(const LAS bf16x8*)(lds + PG8_SA(b, h) + aoff + m * 2048 + k * 1024); } while (0)
; #define PG8_LDB(dst, b, h) do { _Pragma("unroll") for (int n = 0; n < 2; ++n) _Pragma("unroll") for (int k = 0; k < 2; ++k) dst[n][k] = *(const LAS bf16x8*)(lds + PG8_SB(b, h) + boff + n * 2048 + k * 1024); } while (0)
; #define PG8_MMA(ai, bj, At, Bt) do { __builtin_amdgcn_s_setprio(1); _Pragma("unroll") for (int m = 0; m < 4; ++m) _Pragma("unroll") for (int n = 0; n < 2; ++n) _Pragma("unroll") for (int k = 0; k < 2; ++k) \
;         acc[ai][bj][m][n] = __builtin_amdgcn_mfma_f32_16x16x32_bf16(Bt[n][k], At[m][k], acc[ai][bj][m][n], 0, 0, 0); __builtin_amdgcn_s_setprio(0); } while (0)
; #define PG8_WAIT_V(n) asm volatile("s_waitcnt vmcnt(" #n ")" ::: "memory")
; #define PG8_WAIT_L(n) asm volatile("s_waitcnt lgkmcnt(" #n ")" ::: "memory")
; #define PG8_BAR __builtin_amdgcn_s_barrier()
; #define PG8_SCHED __builtin_amdgcn_sched_barrier(0)
; template <class Epi>
; __device__ __forceinline__ void gemm_phase(LAS unsigned char* lds, const Gemm g, int G, int c, const Epi& E) {
;     ...
;             const bool last = (t == nt - 2);
;             const char* a1 = cA + (size_t)(t + 1) * kstep;
;             const char* a2 = last ? nA : cA + (size_t)(t + 2) * kstep; const char* b2 = last ? nB : cB + (size_t)(t + 2) * kstep;
;             const char* a3 = a2 + kstep; const char* b3 = b2 + kstep;
;             PG8_LDB(B0, 0, 0); PG8_LDB(B1, 0, 1); PG8_SCHED; PG8_LDA(At, 0, 0); PG8_STAGE(PG8_SA(1, 1), a1 + hstepA, voffA);
;             PG8_WAIT_V(8); PG8_WAIT_L(0); PG8_BAR; PG8_MMA(0, 0, At, B0); PG8_MMA(0, 1, At, B1); PG8_BAR; PG8_SCHED;
;             PG8_LDA(At, 0, 1); PG8_STAGE(PG8_SB(0, 0), b2, voffB); PG8_STAGE(PG8_SB(0, 1), b2 + hstepB, voffB); PG8_STAGE(PG8_SA(0, 0), a2, voffA);
.LBB0_1451:
	s_add_u32 s33, s8, s44
	s_addc_u32 s45, s9, 0
	s_add_u32 s48, s33, 0x100
	s_addc_u32 s49, s45, 0
	s_and_b64 s[46:47], s[10:11], exec
	s_cselect_b32 s47, s41, s49
	s_cselect_b32 s46, s40, s48
	s_add_u32 s44, s6, s44
	s_addc_u32 s48, s7, 0
	s_add_u32 s44, s44, 0x100
	s_addc_u32 s48, s48, 0
	s_and_b64 s[10:11], s[10:11], exec
	s_cselect_b32 s49, s43, s48
	s_cselect_b32 s48, s42, s44
	s_add_u32 s54, s33, 0xb0080
	s_addc_u32 s55, s45, 0
	s_add_i32 s65, s82, s66
	s_add_i32 m0, s69, 0xc000
	s_add_i32 s74, s69, 0xe000
	v_lshl_add_u64 v[214:215], s[54:55], 0, v[130:131]
	global_load_lds_dwordx4 v[214:215], off
	v_lshl_add_u64 v[214:215], s[54:55], 0, v[134:135]
	s_mov_b32 m0, s74
	s_nop 0
	global_load_lds_dwordx4 v[214:215], off
	ds_read_b128 v[142:145], v160
	ds_read_b128 v[146:149], v160 offset:1024
	ds_read_b128 v[150:153], v160 offset:2048
	ds_read_b128 v[154:157], v160 offset:3072
	ds_read_b128 v[166:169], v161
	ds_read_b128 v[170:173], v161 offset:1024
	ds_read_b128 v[174:177], v161 offset:2048
	ds_read_b128 v[178:181], v161 offset:3072
	s_add_i32 s62, s65, 0x2000
	s_add_u32 s52, s48, 0xb0000
	s_addc_u32 s53, s49, 0
	s_add_i32 s64, s83, s66
	s_add_i32 s63, s64, 0x2000
	s_add_i32 s97, 0, 0x18000
	s_add_i32 s33, 0, 0x1c000
	s_add_u32 s44, s46, 0xb0000
	s_addc_u32 s45, s47, 0
	s_add_i32 s96, s97, s66
	s_add_i32 s94, s96, 0x2000
	s_add_u32 s10, s48, 0xb0080
	s_addc_u32 s11, s49, 0
	s_add_i32 s95, s33, s66
	s_add_i32 s93, s95, 0x2000
	ds_read_b128 v[182:185], v162
	ds_read_b128 v[186:189], v162 offset:1024
	ds_read_b128 v[190:193], v162 offset:2048
	ds_read_b128 v[194:197], v162 offset:3072
	ds_read_b128 v[198:201], v162 offset:4096
	ds_read_b128 v[202:205], v162 offset:5120
	ds_read_b128 v[206:209], v162 offset:6144
	ds_read_b128 v[210:213], v162 offset:7168
	s_waitcnt vmcnt(8)
	s_waitcnt lgkmcnt(0)
	s_barrier
	s_setprio 0
	s_waitcnt lgkmcnt(0)
	v_mfma_f32_16x16x32_bf16 v[126:129], v[142:145], v[182:185], v[126:129]
	v_mfma_f32_16x16x32_bf16 v[122:125], v[150:153], v[182:185], v[122:125]
	v_mfma_f32_16x16x32_bf16 v[110:113], v[142:145], v[190:193], v[110:113]
	v_mfma_f32_16x16x32_bf16 v[106:109], v[150:153], v[190:193], v[106:109]
	v_mfma_f32_16x16x32_bf16 v[94:97], v[142:145], v[198:201], v[94:97]
	v_mfma_f32_16x16x32_bf16 v[90:93], v[150:153], v[198:201], v[90:93]
	v_mfma_f32_16x16x32_bf16 v[78:81], v[142:145], v[206:209], v[78:81]
	v_mfma_f32_16x16x32_bf16 v[74:77], v[150:153], v[206:209], v[74:77]
	v_mfma_f32_16x16x32_bf16 v[126:129], v[146:149], v[186:189], v[126:129]
	v_mfma_f32_16x16x32_bf16 v[122:125], v[154:157], v[186:189], v[122:125]
	v_mfma_f32_16x16x32_bf16 v[110:113], v[146:149], v[194:197], v[110:113]
	v_mfma_f32_16x16x32_bf16 v[106:109], v[154:157], v[194:197], v[106:109]
	v_mfma_f32_16x16x32_bf16 v[94:97], v[146:149], v[202:205], v[94:97]
	v_mfma_f32_16x16x32_bf16 v[90:93], v[154:157], v[202:205], v[90:93]
	v_mfma_f32_16x16x32_bf16 v[78:81], v[146:149], v[210:213], v[78:81]
	v_mfma_f32_16x16x32_bf16 v[74:77], v[154:157], v[210:213], v[74:77]
	s_setprio 2
	s_setprio 0
	v_mfma_f32_16x16x32_bf16 v[118:121], v[166:169], v[182:185], v[118:121]
	v_mfma_f32_16x16x32_bf16 v[114:117], v[174:177], v[182:185], v[114:117]
	v_mfma_f32_16x16x32_bf16 v[102:105], v[166:169], v[190:193], v[102:105]
	v_mfma_f32_16x16x32_bf16 v[98:101], v[174:177], v[190:193], v[98:101]
	v_mfma_f32_16x16x32_bf16 v[86:89], v[166:169], v[198:201], v[86:89]
	v_mfma_f32_16x16x32_bf16 v[82:85], v[174:177], v[198:201], v[82:85]
	v_mfma_f32_16x16x32_bf16 v[70:73], v[166:169], v[206:209], v[70:73]
	v_mfma_f32_16x16x32_bf16 v[66:69], v[174:177], v[206:209], v[66:69]
	v_mfma_f32_16x16x32_bf16 v[118:121], v[170:173], v[186:189], v[118:121]
	v_mfma_f32_16x16x32_bf16 v[114:117], v[178:181], v[186:189], v[114:117]
	v_mfma_f32_16x16x32_bf16 v[102:105], v[170:173], v[194:197], v[102:105]
	v_mfma_f32_16x16x32_bf16 v[98:101], v[178:181], v[194:197], v[98:101]
	v_mfma_f32_16x16x32_bf16 v[86:89], v[170:173], v[202:205], v[86:89]
	v_mfma_f32_16x16x32_bf16 v[82:85], v[178:181], v[202:205], v[82:85]
	v_mfma_f32_16x16x32_bf16 v[70:73], v[170:173], v[210:213], v[70:73]
	v_mfma_f32_16x16x32_bf16 v[66:69], v[178:181], v[210:213], v[66:69]
	s_setprio 2
	s_barrier
	s_mov_b32 m0, s65
	v_lshl_add_u64 v[214:215], s[48:49], 0, v[132:133]
	global_load_lds_dwordx4 v[214:215], off
	v_lshl_add_u64 v[216:217], s[48:49], 0, v[136:137]
	s_mov_b32 m0, s62
	v_lshl_add_u64 v[218:219], s[52:53], 0, v[132:133]
	global_load_lds_dwordx4 v[216:217], off
	s_mov_b32 m0, s64
	v_lshl_add_u64 v[220:221], s[46:47], 0, v[134:135]
	global_load_lds_dwordx4 v[218:219], off
	v_lshl_add_u64 v[218:219], s[52:53], 0, v[136:137]
	s_mov_b32 m0, s63
	s_nop 0
	global_load_lds_dwordx4 v[218:219], off
	v_lshl_add_u64 v[218:219], s[46:47], 0, v[130:131]
	s_mov_b32 m0, s69
	s_nop 0
	global_load_lds_dwordx4 v[218:219], off
	s_mov_b32 m0, s70
	s_nop 0
	global_load_lds_dwordx4 v[220:221], off
	ds_read_b128 v[182:185], v162 offset:16384
	ds_read_b128 v[186:189], v162 offset:17408
	ds_read_b128 v[190:193], v162 offset:18432
	ds_read_b128 v[194:197], v162 offset:19456
	ds_read_b128 v[198:201], v162 offset:20480
	ds_read_b128 v[202:205], v162 offset:21504
	ds_read_b128 v[206:209], v162 offset:22528
	ds_read_b128 v[210:213], v162 offset:23552
	s_waitcnt vmcnt(8)
	s_waitcnt lgkmcnt(0)
	s_barrier
; #define PG8_STAGE(bufoff, gbase, voff) do { _Pragma("unroll") for (int _i = 0; _i < 2; ++_i) \
;         __builtin_amdgcn_global_load_lds((const unsigned*)((const char*)(gbase) + (voff)[_i]), (LAS unsigned*)(lds + (bufoff) + ldsw + _i * 8192), 16, 0, 0); } while (0)
; #define PG8_LDA(dst, b, h) do { _Pragma("unroll") for (int m = 0; m < 4; ++m) _Pragma("unroll") for (int k = 0; k < 2; ++k) dst[m][k] = *(const LAS bf16x8*)(lds + PG8_SA(b, h) + aoff + m * 2048 + k * 1024); } while (0)
; #define PG8_LDB(dst, b, h) do { _Pragma("unroll") for (int n = 0; n < 2; ++n) _Pragma("unroll") for (int k = 0; k < 2; ++k) dst[n][k] = *(const LAS bf16x8*)(lds + PG8_SB(b, h) + boff + n * 2048 + k * 1024); } while (0)
; #define PG8_MMA(ai, bj, At, Bt) do { __builtin_amdgcn_s_setprio(1); _Pragma("unroll") for (int m = 0; m < 4; ++m) _Pragma("unroll") for (int n = 0; n < 2; ++n) _Pragma("unroll") for (int k = 0; k < 2; ++k) \
;         acc[ai][bj][m][n] = __builtin_amdgcn_mfma_f32_16x16x32_bf16(Bt[n][k], At[m][k], acc[ai][bj][m][n], 0, 0, 0); __builtin_amdgcn_s_setprio(0); } while (0)
; #define PG8_WAIT_V(n) asm volatile("s_waitcnt vmcnt(" #n ")" ::: "memory")
; #define PG8_WAIT_L(n) asm volatile("s_waitcnt lgkmcnt(" #n ")" ::: "memory")
; #define PG8_BAR __builtin_amdgcn_s_barrier()
; #define PG8_SCHED __builtin_amdgcn_sched_barrier(0)
; template <class Epi>
; __device__ __forceinline__ void gemm_phase(LAS unsigned char* lds, const Gemm g, int G, int c, const Epi& E) {
;     ...
;             PG8_WAIT_V(8); PG8_WAIT_L(0); PG8_BAR; PG8_MMA(1, 0, At, B0); PG8_MMA(1, 1, At, B1); PG8_BAR; PG8_SCHED;
;             PG8_LDB(B0, 1, 0); PG8_LDB(B1, 1, 1); PG8_SCHED; PG8_LDA(At, 1, 0); PG8_STAGE(PG8_SA(0, 1), a2 + hstepA, voffA);
;             PG8_WAIT_V(8); PG8_WAIT_L(0); PG8_BAR; PG8_MMA(0, 0, At, B0); PG8_MMA(0, 1, At, B1); PG8_BAR; PG8_SCHED;
	s_setprio 0
	s_waitcnt lgkmcnt(0)
	v_mfma_f32_16x16x32_bf16 v[62:65], v[142:145], v[182:185], v[62:65]
	v_mfma_f32_16x16x32_bf16 v[58:61], v[150:153], v[182:185], v[58:61]
	v_mfma_f32_16x16x32_bf16 v[46:49], v[142:145], v[190:193], v[46:49]
	v_mfma_f32_16x16x32_bf16 v[42:45], v[150:153], v[190:193], v[42:45]
	v_mfma_f32_16x16x32_bf16 v[30:33], v[142:145], v[198:201], v[30:33]
	v_mfma_f32_16x16x32_bf16 v[26:29], v[150:153], v[198:201], v[26:29]
	v_mfma_f32_16x16x32_bf16 v[14:17], v[142:145], v[206:209], v[14:17]
	v_mfma_f32_16x16x32_bf16 v[10:13], v[150:153], v[206:209], v[10:13]
	v_mfma_f32_16x16x32_bf16 v[62:65], v[146:149], v[186:189], v[62:65]
	v_mfma_f32_16x16x32_bf16 v[58:61], v[154:157], v[186:189], v[58:61]
	v_mfma_f32_16x16x32_bf16 v[46:49], v[146:149], v[194:197], v[46:49]
	v_mfma_f32_16x16x32_bf16 v[42:45], v[154:157], v[194:197], v[42:45]
	v_mfma_f32_16x16x32_bf16 v[30:33], v[146:149], v[202:205], v[30:33]
	v_mfma_f32_16x16x32_bf16 v[26:29], v[154:157], v[202:205], v[26:29]
	v_mfma_f32_16x16x32_bf16 v[14:17], v[146:149], v[210:213], v[14:17]
	v_mfma_f32_16x16x32_bf16 v[10:13], v[154:157], v[210:213], v[10:13]
	s_setprio 2
	s_setprio 0
	v_mfma_f32_16x16x32_bf16 v[54:57], v[166:169], v[182:185], v[54:57]
	v_mfma_f32_16x16x32_bf16 v[50:53], v[174:177], v[182:185], v[50:53]
	v_mfma_f32_16x16x32_bf16 v[38:41], v[166:169], v[190:193], v[38:41]
	v_mfma_f32_16x16x32_bf16 v[34:37], v[174:177], v[190:193], v[34:37]
	v_mfma_f32_16x16x32_bf16 v[22:25], v[166:169], v[198:201], v[22:25]
	v_mfma_f32_16x16x32_bf16 v[18:21], v[174:177], v[198:201], v[18:21]
	v_mfma_f32_16x16x32_bf16 v[6:9], v[166:169], v[206:209], v[6:9]
	v_mfma_f32_16x16x32_bf16 v[2:5], v[174:177], v[206:209], v[2:5]
	v_mfma_f32_16x16x32_bf16 v[54:57], v[170:173], v[186:189], v[54:57]
	v_mfma_f32_16x16x32_bf16 v[50:53], v[178:181], v[186:189], v[50:53]
	v_mfma_f32_16x16x32_bf16 v[38:41], v[170:173], v[194:197], v[38:41]
	v_mfma_f32_16x16x32_bf16 v[34:37], v[178:181], v[194:197], v[34:37]
	v_mfma_f32_16x16x32_bf16 v[22:25], v[170:173], v[202:205], v[22:25]
	v_mfma_f32_16x16x32_bf16 v[18:21], v[178:181], v[202:205], v[18:21]
	v_mfma_f32_16x16x32_bf16 v[6:9], v[170:173], v[210:213], v[6:9]
	v_mfma_f32_16x16x32_bf16 v[2:5], v[178:181], v[210:213], v[2:5]
	s_setprio 2
	s_barrier
	s_mov_b32 m0, s71
	v_lshl_add_u64 v[222:223], s[44:45], 0, v[130:131]
	global_load_lds_dwordx4 v[222:223], off
	v_lshl_add_u64 v[222:223], s[44:45], 0, v[134:135]
	s_mov_b32 m0, s72
	s_nop 0
	global_load_lds_dwordx4 v[222:223], off
	v_add_u32_e32 v154, s97, v159
	v_add_u32_e32 v178, s33, v159
	ds_read_b128 v[142:145], v154
	ds_read_b128 v[146:149], v154 offset:1024
	ds_read_b128 v[150:153], v154 offset:2048
	ds_read_b128 v[154:157], v154 offset:3072
	ds_read_b128 v[166:169], v178
	ds_read_b128 v[170:173], v178 offset:1024
	ds_read_b128 v[174:177], v178 offset:2048
	ds_read_b128 v[178:181], v178 offset:3072
	ds_read_b128 v[182:185], v162 offset:32768
	ds_read_b128 v[186:189], v162 offset:33792
	ds_read_b128 v[190:193], v162 offset:34816
	ds_read_b128 v[194:197], v162 offset:35840
	ds_read_b128 v[198:201], v162 offset:36864
	ds_read_b128 v[202:205], v162 offset:37888
	ds_read_b128 v[206:209], v162 offset:38912
	ds_read_b128 v[210:213], v162 offset:39936
	s_waitcnt vmcnt(8)
	s_waitcnt lgkmcnt(0)
	s_barrier
	s_setprio 0
	s_waitcnt lgkmcnt(0)
	v_mfma_f32_16x16x32_bf16 v[126:129], v[142:145], v[182:185], v[126:129]
	v_mfma_f32_16x16x32_bf16 v[122:125], v[150:153], v[182:185], v[122:125]
	v_mfma_f32_16x16x32_bf16 v[110:113], v[142:145], v[190:193], v[110:113]
	v_mfma_f32_16x16x32_bf16 v[106:109], v[150:153], v[190:193], v[106:109]
	v_mfma_f32_16x16x32_bf16 v[94:97], v[142:145], v[198:201], v[94:97]
	v_mfma_f32_16x16x32_bf16 v[90:93], v[150:153], v[198:201], v[90:93]
	v_mfma_f32_16x16x32_bf16 v[78:81], v[142:145], v[206:209], v[78:81]
	v_mfma_f32_16x16x32_bf16 v[74:77], v[150:153], v[206:209], v[74:77]
	v_mfma_f32_16x16x32_bf16 v[126:129], v[146:149], v[186:189], v[126:129]
	v_mfma_f32_16x16x32_bf16 v[122:125], v[154:157], v[186:189], v[122:125]
	v_mfma_f32_16x16x32_bf16 v[110:113], v[146:149], v[194:197], v[110:113]
	v_mfma_f32_16x16x32_bf16 v[106:109], v[154:157], v[194:197], v[106:109]
	v_mfma_f32_16x16x32_bf16 v[94:97], v[146:149], v[202:205], v[94:97]
	v_mfma_f32_16x16x32_bf16 v[90:93], v[154:157], v[202:205], v[90:93]
	v_mfma_f32_16x16x32_bf16 v[78:81], v[146:149], v[210:213], v[78:81]
	v_mfma_f32_16x16x32_bf16 v[74:77], v[154:157], v[210:213], v[74:77]
	s_setprio 2
	s_setprio 0
	v_mfma_f32_16x16x32_bf16 v[118:121], v[166:169], v[182:185], v[118:121]
	v_mfma_f32_16x16x32_bf16 v[114:117], v[174:177], v[182:185], v[114:117]
	v_mfma_f32_16x16x32_bf16 v[102:105], v[166:169], v[190:193], v[102:105]
	v_mfma_f32_16x16x32_bf16 v[98:101], v[174:177], v[190:193], v[98:101]
	v_mfma_f32_16x16x32_bf16 v[86:89], v[166:169], v[198:201], v[86:89]
	v_mfma_f32_16x16x32_bf16 v[82:85], v[174:177], v[198:201], v[82:85]
	v_mfma_f32_16x16x32_bf16 v[70:73], v[166:169], v[206:209], v[70:73]
	v_mfma_f32_16x16x32_bf16 v[66:69], v[174:177], v[206:209], v[66:69]
	v_mfma_f32_16x16x32_bf16 v[118:121], v[170:173], v[186:189], v[118:121]
	v_mfma_f32_16x16x32_bf16 v[114:117], v[178:181], v[186:189], v[114:117]
	v_mfma_f32_16x16x32_bf16 v[102:105], v[170:173], v[194:197], v[102:105]
	v_mfma_f32_16x16x32_bf16 v[98:101], v[178:181], v[194:197], v[98:101]
	v_mfma_f32_16x16x32_bf16 v[86:89], v[170:173], v[202:205], v[86:89]
	v_mfma_f32_16x16x32_bf16 v[82:85], v[178:181], v[202:205], v[82:85]
	v_mfma_f32_16x16x32_bf16 v[70:73], v[170:173], v[210:213], v[70:73]
	v_mfma_f32_16x16x32_bf16 v[66:69], v[178:181], v[210:213], v[66:69]
	s_setprio 2
	s_barrier
; #define PG8_STAGE(bufoff, gbase, voff) do { _Pragma("unroll") for (int _i = 0; _i < 2; ++_i) \
;         __builtin_amdgcn_global_load_lds((const unsigned*)((const char*)(gbase) + (voff)[_i]), (LAS unsigned*)(lds + (bufoff) + ldsw + _i * 8192), 16, 0, 0); } while (0)
; #define PG8_LDA(dst, b, h) do { _Pragma("unroll") for (int m = 0; m < 4; ++m) _Pragma("unroll") for (int k = 0; k < 2; ++k) dst[m][k] = *(const LAS bf16x8*)(lds + PG8_SA(b, h) + aoff + m * 2048 + k * 1024); } while (0)
; #define PG8_MMA(ai, bj, At, Bt) do { __builtin_amdgcn_s_setprio(1); _Pragma("unroll") for (int m = 0; m < 4; ++m) _Pragma("unroll") for (int n = 0; n < 2; ++n) _Pragma("unroll") for (int k = 0; k < 2; ++k) \
;         acc[ai][bj][m][n] = __builtin_amdgcn_mfma_f32_16x16x32_bf16(Bt[n][k], At[m][k], acc[ai][bj][m][n], 0, 0, 0); __builtin_amdgcn_s_setprio(0); } while (0)
; #define PG8_WAIT_V(n) asm volatile("s_waitcnt vmcnt(" #n ")" ::: "memory")
; #define PG8_WAIT_L(n) asm volatile("s_waitcnt lgkmcnt(" #n ")" ::: "memory")
; #define PG8_BAR __builtin_amdgcn_s_barrier()
; #define PG8_SCHED __builtin_amdgcn_sched_barrier(0)
; template <class Epi>
; __device__ __forceinline__ void gemm_phase(LAS unsigned char* lds, const Gemm g, int G, int c, const Epi& E) {
;     ...
;             PG8_LDA(At, 1, 1); PG8_STAGE(PG8_SB(1, 0), b3, voffB); PG8_STAGE(PG8_SB(1, 1), b3 + hstepB, voffB); PG8_STAGE(PG8_SA(1, 0), a3, voffA);
;             PG8_WAIT_V(8); PG8_WAIT_L(0); PG8_BAR; PG8_MMA(1, 0, At, B0); PG8_MMA(1, 1, At, B1); PG8_BAR; PG8_SCHED;
;         }
;         if (wr == 0) PG8_BAR;
	s_mov_b32 m0, s96
	v_lshl_add_u64 v[214:215], v[214:215], 0, s[22:23]
	global_load_lds_dwordx4 v[214:215], off
	v_lshl_add_u64 v[214:215], v[216:217], 0, s[22:23]
	s_mov_b32 m0, s94
	s_nop 0
	global_load_lds_dwordx4 v[214:215], off
	v_lshl_add_u64 v[214:215], s[10:11], 0, v[132:133]
	s_mov_b32 m0, s95
	s_nop 0
	global_load_lds_dwordx4 v[214:215], off
	v_lshl_add_u64 v[214:215], s[10:11], 0, v[136:137]
	s_mov_b32 m0, s93
	s_nop 0
	global_load_lds_dwordx4 v[214:215], off
	v_lshl_add_u64 v[214:215], v[218:219], 0, s[22:23]
	s_mov_b32 m0, s80
	s_nop 0
	global_load_lds_dwordx4 v[214:215], off
	v_lshl_add_u64 v[214:215], v[220:221], 0, s[22:23]
	s_mov_b32 m0, s81
	s_nop 0
	global_load_lds_dwordx4 v[214:215], off
	ds_read_b128 v[182:185], v162 offset:49152
	ds_read_b128 v[186:189], v162 offset:50176
	ds_read_b128 v[190:193], v162 offset:51200
	ds_read_b128 v[194:197], v162 offset:52224
	ds_read_b128 v[198:201], v162 offset:53248
	ds_read_b128 v[202:205], v162 offset:54272
	ds_read_b128 v[206:209], v162 offset:55296
	ds_read_b128 v[210:213], v162 offset:56320
	s_waitcnt vmcnt(8)
	s_waitcnt lgkmcnt(0)
	s_barrier
	s_setprio 0
	s_waitcnt lgkmcnt(0)
	v_mfma_f32_16x16x32_bf16 v[62:65], v[142:145], v[182:185], v[62:65]
	v_mfma_f32_16x16x32_bf16 v[58:61], v[150:153], v[182:185], v[58:61]
	v_mfma_f32_16x16x32_bf16 v[46:49], v[142:145], v[190:193], v[46:49]
	v_mfma_f32_16x16x32_bf16 v[42:45], v[150:153], v[190:193], v[42:45]
	v_mfma_f32_16x16x32_bf16 v[30:33], v[142:145], v[198:201], v[30:33]
	v_mfma_f32_16x16x32_bf16 v[26:29], v[150:153], v[198:201], v[26:29]
	v_mfma_f32_16x16x32_bf16 v[14:17], v[142:145], v[206:209], v[14:17]
	v_mfma_f32_16x16x32_bf16 v[10:13], v[150:153], v[206:209], v[10:13]
	v_mfma_f32_16x16x32_bf16 v[62:65], v[146:149], v[186:189], v[62:65]
	v_mfma_f32_16x16x32_bf16 v[58:61], v[154:157], v[186:189], v[58:61]
	v_mfma_f32_16x16x32_bf16 v[46:49], v[146:149], v[194:197], v[46:49]
	v_mfma_f32_16x16x32_bf16 v[42:45], v[154:157], v[194:197], v[42:45]
	v_mfma_f32_16x16x32_bf16 v[30:33], v[146:149], v[202:205], v[30:33]
	v_mfma_f32_16x16x32_bf16 v[26:29], v[154:157], v[202:205], v[26:29]
	v_mfma_f32_16x16x32_bf16 v[14:17], v[146:149], v[210:213], v[14:17]
	v_mfma_f32_16x16x32_bf16 v[10:13], v[154:157], v[210:213], v[10:13]
	s_setprio 2
	s_setprio 0
	v_mfma_f32_16x16x32_bf16 v[54:57], v[166:169], v[182:185], v[54:57]
	v_mfma_f32_16x16x32_bf16 v[50:53], v[174:177], v[182:185], v[50:53]
	v_mfma_f32_16x16x32_bf16 v[38:41], v[166:169], v[190:193], v[38:41]
	v_mfma_f32_16x16x32_bf16 v[34:37], v[174:177], v[190:193], v[34:37]
	v_mfma_f32_16x16x32_bf16 v[22:25], v[166:169], v[198:201], v[22:25]
	v_mfma_f32_16x16x32_bf16 v[18:21], v[174:177], v[198:201], v[18:21]
	v_mfma_f32_16x16x32_bf16 v[6:9], v[166:169], v[206:209], v[6:9]
	v_mfma_f32_16x16x32_bf16 v[2:5], v[174:177], v[206:209], v[2:5]
	v_mfma_f32_16x16x32_bf16 v[54:57], v[170:173], v[186:189], v[54:57]
	v_mfma_f32_16x16x32_bf16 v[50:53], v[178:181], v[186:189], v[50:53]
	v_mfma_f32_16x16x32_bf16 v[38:41], v[170:173], v[194:197], v[38:41]
	v_mfma_f32_16x16x32_bf16 v[34:37], v[178:181], v[194:197], v[34:37]
	v_mfma_f32_16x16x32_bf16 v[22:25], v[170:173], v[202:205], v[22:25]
	v_mfma_f32_16x16x32_bf16 v[18:21], v[178:181], v[202:205], v[18:21]
	v_mfma_f32_16x16x32_bf16 v[6:9], v[170:173], v[210:213], v[6:9]
	v_mfma_f32_16x16x32_bf16 v[2:5], v[178:181], v[210:213], v[2:5]
	s_setprio 2
	s_barrier
	s_movk_i32 s44, 0x100
	s_andn2_b64 vcc, exec, s[4:5]
	s_mov_b64 s[10:11], -1
	s_mov_b64 s[4:5], 0
	s_cbranch_vccz .LBB0_1451
	s_and_b64 vcc, exec, s[24:25]
	s_cbranch_vccz .LBB0_1454
	s_barrier

; #define PG8_STAGE(bufoff, gbase, voff) do { _Pragma("unroll") for (int _i = 0; _i < 2; ++_i) \
;         __builtin_amdgcn_global_load_lds((const unsigned*)((const char*)(gbase) + (voff)[_i]), (LAS unsigned*)(lds + (bufoff) + ldsw + _i * 8192), 16, 0, 0); } while (0)
; #define PG8_LDA(dst, b, h) do { _Pragma("unroll") for (int m = 0; m < 4; ++m) _Pragma("unroll") for (int k = 0; k < 2; ++k) dst[m][k] = *(const LAS bf16x8*)(lds + PG8_SA(b, h) + aoff + m * 2048 + k * 1024); } while (0)
; #define PG8_LDB(dst, b, h) do { _Pragma("unroll") for (int n = 0; n < 2; ++n) _Pragma("unroll") for (int k = 0; k < 2; ++k) dst[n][k] = *(const LAS bf16x8*)(lds + PG8_SB(b, h) + boff + n * 2048 + k * 1024); } while (0)
; #define PG8_MMA(ai, bj, At, Bt) do { __builtin_amdgcn_s_setprio(1); _Pragma("unroll") for (int m = 0; m < 4; ++m) _Pragma("unroll") for (int n = 0; n < 2; ++n) _Pragma("unroll") for (int k = 0; k < 2; ++k) \
;         acc[ai][bj][m][n] = __builtin_amdgcn_mfma_f32_16x16x32_bf16(Bt[n][k], At[m][k], acc[ai][bj][m][n], 0, 0, 0); __builtin_amdgcn_s_setprio(0); } while (0)
; #define PG8_WAIT_V(n) asm volatile("s_waitcnt vmcnt(" #n ")" ::: "memory")
; #define PG8_WAIT_L(n) asm volatile("s_waitcnt lgkmcnt(" #n ")" ::: "memory")
; #define PG8_BAR __builtin_amdgcn_s_barrier()
; #define PG8_SCHED __builtin_amdgcn_sched_barrier(0)
; template <class Epi>
; __device__ __forceinline__ void gemm_phase(LAS unsigned char* lds, const Gemm g, int G, int c, const Epi& E) {
;     ...
;             const bool last = (t == nt - 2);
;             const char* a1 = cA + (size_t)(t + 1) * kstep;
;             const char* a2 = last ? nA : cA + (size_t)(t + 2) * kstep; const char* b2 = last ? nB : cB + (size_t)(t + 2) * kstep;
;             const char* a3 = a2 + kstep; const char* b3 = b2 + kstep;
;             PG8_LDB(B0, 0, 0); PG8_LDB(B1, 0, 1); PG8_SCHED; PG8_LDA(At, 0, 0); PG8_STAGE(PG8_SA(1, 1), a1 + hstepA, voffA);
;             PG8_WAIT_V(8); PG8_WAIT_L(0); PG8_BAR; PG8_MMA(0, 0, At, B0); PG8_MMA(0, 1, At, B1); PG8_BAR; PG8_SCHED;
;             PG8_LDA(At, 0, 1); PG8_STAGE(PG8_SB(0, 0), b2, voffB); PG8_STAGE(PG8_SB(0, 1), b2 + hstepB, voffB); PG8_STAGE(PG8_SA(0, 0), a2, voffA);
.LBB0_1537:
	s_add_u32 s33, s8, s44
	s_addc_u32 s45, s9, 0
	s_add_u32 s48, s33, 0x100
	s_addc_u32 s49, s45, 0
	s_and_b64 s[46:47], s[10:11], exec
	s_cselect_b32 s47, s41, s49
	s_cselect_b32 s46, s40, s48
	s_add_u32 s44, s6, s44
	s_addc_u32 s48, s7, 0
	s_add_u32 s44, s44, 0x100
	s_addc_u32 s48, s48, 0
	s_and_b64 s[10:11], s[10:11], exec
	s_cselect_b32 s49, s43, s48
	s_cselect_b32 s48, s42, s44
	s_add_u32 s54, s33, 0xb0080
	s_addc_u32 s55, s45, 0
	s_add_i32 s63, s87, s70
	s_add_i32 m0, s73, 0xc000
	s_add_i32 s64, s73, 0xe000
	v_lshl_add_u64 v[162:163], s[54:55], 0, v[138:139]
	global_load_lds_dwordx4 v[162:163], off
	v_lshl_add_u64 v[162:163], s[54:55], 0, v[142:143]
	s_mov_b32 m0, s64
	s_nop 0
	global_load_lds_dwordx4 v[162:163], off
	ds_read_b128 v[130:133], v166
	ds_read_b128 v[134:137], v166 offset:1024
	ds_read_b128 v[150:153], v166 offset:2048
	ds_read_b128 v[154:157], v166 offset:3072
	ds_read_b128 v[158:161], v167
	ds_read_b128 v[172:175], v167 offset:1024
	ds_read_b128 v[176:179], v167 offset:2048
	ds_read_b128 v[180:183], v167 offset:3072
	s_add_i32 s74, s63, 0x2000
	s_add_u32 s52, s48, 0xb0000
	s_addc_u32 s53, s49, 0
	s_add_i32 s62, s88, s70
	s_add_i32 s75, s62, 0x2000
	s_add_i32 s97, 0, 0x18000
	s_add_i32 s33, 0, 0x1c000
	s_add_u32 s44, s46, 0xb0000
	s_addc_u32 s45, s47, 0
	s_add_i32 s96, s97, s70
	s_add_i32 s94, s96, 0x2000
	s_add_u32 s10, s48, 0xb0080
	s_addc_u32 s11, s49, 0
	s_add_i32 s95, s33, s70
	s_add_i32 s93, s95, 0x2000
	ds_read_b128 v[184:187], v168
	ds_read_b128 v[188:191], v168 offset:1024
	ds_read_b128 v[192:195], v168 offset:2048
	ds_read_b128 v[196:199], v168 offset:3072
	ds_read_b128 v[200:203], v168 offset:4096
	ds_read_b128 v[204:207], v168 offset:5120
	ds_read_b128 v[208:211], v168 offset:6144
	ds_read_b128 v[212:215], v168 offset:7168
	s_waitcnt vmcnt(8)
	s_waitcnt lgkmcnt(0)
	s_barrier
	s_setprio 0
	s_waitcnt lgkmcnt(0)
	v_mfma_f32_16x16x32_bf16 v[126:129], v[130:133], v[184:187], v[126:129]
	v_mfma_f32_16x16x32_bf16 v[122:125], v[150:153], v[184:187], v[122:125]
	v_mfma_f32_16x16x32_bf16 v[110:113], v[130:133], v[192:195], v[110:113]
	v_mfma_f32_16x16x32_bf16 v[106:109], v[150:153], v[192:195], v[106:109]
	v_mfma_f32_16x16x32_bf16 v[94:97], v[130:133], v[200:203], v[94:97]
	v_mfma_f32_16x16x32_bf16 v[90:93], v[150:153], v[200:203], v[90:93]
	v_mfma_f32_16x16x32_bf16 v[78:81], v[130:133], v[208:211], v[78:81]
	v_mfma_f32_16x16x32_bf16 v[74:77], v[150:153], v[208:211], v[74:77]
	v_mfma_f32_16x16x32_bf16 v[126:129], v[134:137], v[188:191], v[126:129]
	v_mfma_f32_16x16x32_bf16 v[122:125], v[154:157], v[188:191], v[122:125]
	v_mfma_f32_16x16x32_bf16 v[110:113], v[134:137], v[196:199], v[110:113]
	v_mfma_f32_16x16x32_bf16 v[106:109], v[154:157], v[196:199], v[106:109]
	v_mfma_f32_16x16x32_bf16 v[94:97], v[134:137], v[204:207], v[94:97]
	v_mfma_f32_16x16x32_bf16 v[90:93], v[154:157], v[204:207], v[90:93]
	v_mfma_f32_16x16x32_bf16 v[78:81], v[134:137], v[212:215], v[78:81]
	v_mfma_f32_16x16x32_bf16 v[74:77], v[154:157], v[212:215], v[74:77]
	s_setprio 2
	s_setprio 0
	v_mfma_f32_16x16x32_bf16 v[118:121], v[158:161], v[184:187], v[118:121]
	v_mfma_f32_16x16x32_bf16 v[114:117], v[176:179], v[184:187], v[114:117]
	v_mfma_f32_16x16x32_bf16 v[102:105], v[158:161], v[192:195], v[102:105]
	v_mfma_f32_16x16x32_bf16 v[98:101], v[176:179], v[192:195], v[98:101]
	v_mfma_f32_16x16x32_bf16 v[86:89], v[158:161], v[200:203], v[86:89]
	v_mfma_f32_16x16x32_bf16 v[82:85], v[176:179], v[200:203], v[82:85]
	v_mfma_f32_16x16x32_bf16 v[70:73], v[158:161], v[208:211], v[70:73]
	v_mfma_f32_16x16x32_bf16 v[66:69], v[176:179], v[208:211], v[66:69]
	v_mfma_f32_16x16x32_bf16 v[118:121], v[172:175], v[188:191], v[118:121]
	v_mfma_f32_16x16x32_bf16 v[114:117], v[180:183], v[188:191], v[114:117]
	v_mfma_f32_16x16x32_bf16 v[102:105], v[172:175], v[196:199], v[102:105]
	v_mfma_f32_16x16x32_bf16 v[98:101], v[180:183], v[196:199], v[98:101]
	v_mfma_f32_16x16x32_bf16 v[86:89], v[172:175], v[204:207], v[86:89]
	v_mfma_f32_16x16x32_bf16 v[82:85], v[180:183], v[204:207], v[82:85]
	v_mfma_f32_16x16x32_bf16 v[70:73], v[172:175], v[212:215], v[70:73]
	v_mfma_f32_16x16x32_bf16 v[66:69], v[180:183], v[212:215], v[66:69]
	s_setprio 2
	s_barrier
	s_mov_b32 m0, s63
	v_lshl_add_u64 v[162:163], s[48:49], 0, v[140:141]
	global_load_lds_dwordx4 v[162:163], off
	v_lshl_add_u64 v[216:217], s[48:49], 0, v[144:145]
	s_mov_b32 m0, s74
	v_lshl_add_u64 v[218:219], s[52:53], 0, v[140:141]
	global_load_lds_dwordx4 v[216:217], off
	s_mov_b32 m0, s62
	v_lshl_add_u64 v[220:221], s[46:47], 0, v[142:143]
	global_load_lds_dwordx4 v[218:219], off
	v_lshl_add_u64 v[218:219], s[52:53], 0, v[144:145]
	s_mov_b32 m0, s75
	s_nop 0
	global_load_lds_dwordx4 v[218:219], off
	v_lshl_add_u64 v[218:219], s[46:47], 0, v[138:139]
	s_mov_b32 m0, s73
	s_nop 0
	global_load_lds_dwordx4 v[218:219], off
	s_mov_b32 m0, s79
	s_nop 0
	global_load_lds_dwordx4 v[220:221], off
	ds_read_b128 v[184:187], v168 offset:16384
	ds_read_b128 v[188:191], v168 offset:17408
	ds_read_b128 v[192:195], v168 offset:18432
	ds_read_b128 v[196:199], v168 offset:19456
	ds_read_b128 v[200:203], v168 offset:20480
	ds_read_b128 v[204:207], v168 offset:21504
	ds_read_b128 v[208:211], v168 offset:22528
	ds_read_b128 v[212:215], v168 offset:23552
	s_waitcnt vmcnt(8)
	s_waitcnt lgkmcnt(0)
	s_barrier
; #define PG8_STAGE(bufoff, gbase, voff) do { _Pragma("unroll") for (int _i = 0; _i < 2; ++_i) \
;         __builtin_amdgcn_global_load_lds((const unsigned*)((const char*)(gbase) + (voff)[_i]), (LAS unsigned*)(lds + (bufoff) + ldsw + _i * 8192), 16, 0, 0); } while (0)
; #define PG8_LDA(dst, b, h) do { _Pragma("unroll") for (int m = 0; m < 4; ++m) _Pragma("unroll") for (int k = 0; k < 2; ++k) dst[m][k] = *(const LAS bf16x8*)(lds + PG8_SA(b, h) + aoff + m * 2048 + k * 1024); } while (0)
; #define PG8_LDB(dst, b, h) do { _Pragma("unroll") for (int n = 0; n < 2; ++n) _Pragma("unroll") for (int k = 0; k < 2; ++k) dst[n][k] = *(const LAS bf16x8*)(lds + PG8_SB(b, h) + boff + n * 2048 + k * 1024); } while (0)
; #define PG8_MMA(ai, bj, At, Bt) do { __builtin_amdgcn_s_setprio(1); _Pragma("unroll") for (int m = 0; m < 4; ++m) _Pragma("unroll") for (int n = 0; n < 2; ++n) _Pragma("unroll") for (int k = 0; k < 2; ++k) \
;         acc[ai][bj][m][n] = __builtin_amdgcn_mfma_f32_16x16x32_bf16(Bt[n][k], At[m][k], acc[ai][bj][m][n], 0, 0, 0); __builtin_amdgcn_s_setprio(0); } while (0)
; #define PG8_WAIT_V(n) asm volatile("s_waitcnt vmcnt(" #n ")" ::: "memory")
; #define PG8_WAIT_L(n) asm volatile("s_waitcnt lgkmcnt(" #n ")" ::: "memory")
; #define PG8_BAR __builtin_amdgcn_s_barrier()
; #define PG8_SCHED __builtin_amdgcn_sched_barrier(0)
; template <class Epi>
; __device__ __forceinline__ void gemm_phase(LAS unsigned char* lds, const Gemm g, int G, int c, const Epi& E) {
;     ...
;             PG8_WAIT_V(8); PG8_WAIT_L(0); PG8_BAR; PG8_MMA(1, 0, At, B0); PG8_MMA(1, 1, At, B1); PG8_BAR; PG8_SCHED;
;             PG8_LDB(B0, 1, 0); PG8_LDB(B1, 1, 1); PG8_SCHED; PG8_LDA(At, 1, 0); PG8_STAGE(PG8_SA(0, 1), a2 + hstepA, voffA);
;             PG8_WAIT_V(8); PG8_WAIT_L(0); PG8_BAR; PG8_MMA(0, 0, At, B0); PG8_MMA(0, 1, At, B1); PG8_BAR; PG8_SCHED;
	s_setprio 0
	s_waitcnt lgkmcnt(0)
	v_mfma_f32_16x16x32_bf16 v[62:65], v[130:133], v[184:187], v[62:65]
	v_mfma_f32_16x16x32_bf16 v[58:61], v[150:153], v[184:187], v[58:61]
	v_mfma_f32_16x16x32_bf16 v[46:49], v[130:133], v[192:195], v[46:49]
	v_mfma_f32_16x16x32_bf16 v[42:45], v[150:153], v[192:195], v[42:45]
	v_mfma_f32_16x16x32_bf16 v[30:33], v[130:133], v[200:203], v[30:33]
	v_mfma_f32_16x16x32_bf16 v[26:29], v[150:153], v[200:203], v[26:29]
	v_mfma_f32_16x16x32_bf16 v[14:17], v[130:133], v[208:211], v[14:17]
	v_mfma_f32_16x16x32_bf16 v[10:13], v[150:153], v[208:211], v[10:13]
	v_mfma_f32_16x16x32_bf16 v[62:65], v[134:137], v[188:191], v[62:65]
	v_mfma_f32_16x16x32_bf16 v[58:61], v[154:157], v[188:191], v[58:61]
	v_mfma_f32_16x16x32_bf16 v[46:49], v[134:137], v[196:199], v[46:49]
	v_mfma_f32_16x16x32_bf16 v[42:45], v[154:157], v[196:199], v[42:45]
	v_mfma_f32_16x16x32_bf16 v[30:33], v[134:137], v[204:207], v[30:33]
	v_mfma_f32_16x16x32_bf16 v[26:29], v[154:157], v[204:207], v[26:29]
	v_mfma_f32_16x16x32_bf16 v[14:17], v[134:137], v[212:215], v[14:17]
	v_mfma_f32_16x16x32_bf16 v[10:13], v[154:157], v[212:215], v[10:13]
	s_setprio 2
	s_setprio 0
	v_mfma_f32_16x16x32_bf16 v[54:57], v[158:161], v[184:187], v[54:57]
	v_mfma_f32_16x16x32_bf16 v[50:53], v[176:179], v[184:187], v[50:53]
	v_mfma_f32_16x16x32_bf16 v[38:41], v[158:161], v[192:195], v[38:41]
	v_mfma_f32_16x16x32_bf16 v[34:37], v[176:179], v[192:195], v[34:37]
	v_mfma_f32_16x16x32_bf16 v[22:25], v[158:161], v[200:203], v[22:25]
	v_mfma_f32_16x16x32_bf16 v[18:21], v[176:179], v[200:203], v[18:21]
	v_mfma_f32_16x16x32_bf16 v[6:9], v[158:161], v[208:211], v[6:9]
	v_mfma_f32_16x16x32_bf16 v[2:5], v[176:179], v[208:211], v[2:5]
	v_mfma_f32_16x16x32_bf16 v[54:57], v[172:175], v[188:191], v[54:57]
	v_mfma_f32_16x16x32_bf16 v[50:53], v[180:183], v[188:191], v[50:53]
	v_mfma_f32_16x16x32_bf16 v[38:41], v[172:175], v[196:199], v[38:41]
	v_mfma_f32_16x16x32_bf16 v[34:37], v[180:183], v[196:199], v[34:37]
	v_mfma_f32_16x16x32_bf16 v[22:25], v[172:175], v[204:207], v[22:25]
	v_mfma_f32_16x16x32_bf16 v[18:21], v[180:183], v[204:207], v[18:21]
	v_mfma_f32_16x16x32_bf16 v[6:9], v[172:175], v[212:215], v[6:9]
	v_mfma_f32_16x16x32_bf16 v[2:5], v[180:183], v[212:215], v[2:5]
	s_setprio 2
	s_barrier
	s_mov_b32 m0, s80
	v_lshl_add_u64 v[222:223], s[44:45], 0, v[138:139]
	global_load_lds_dwordx4 v[222:223], off
	v_lshl_add_u64 v[222:223], s[44:45], 0, v[142:143]
	s_mov_b32 m0, s81
	s_nop 0
	global_load_lds_dwordx4 v[222:223], off
	v_add_u32_e32 v154, s97, v165
	v_add_u32_e32 v180, s33, v165
	ds_read_b128 v[130:133], v154
	ds_read_b128 v[134:137], v154 offset:1024
	ds_read_b128 v[150:153], v154 offset:2048
	ds_read_b128 v[154:157], v154 offset:3072
	ds_read_b128 v[158:161], v180
	ds_read_b128 v[172:175], v180 offset:1024
	ds_read_b128 v[176:179], v180 offset:2048
	ds_read_b128 v[180:183], v180 offset:3072
	ds_read_b128 v[184:187], v168 offset:32768
	ds_read_b128 v[188:191], v168 offset:33792
	ds_read_b128 v[192:195], v168 offset:34816
	ds_read_b128 v[196:199], v168 offset:35840
	ds_read_b128 v[200:203], v168 offset:36864
	ds_read_b128 v[204:207], v168 offset:37888
	ds_read_b128 v[208:211], v168 offset:38912
	ds_read_b128 v[212:215], v168 offset:39936
	s_waitcnt vmcnt(8)
	s_waitcnt lgkmcnt(0)
	s_barrier
	s_setprio 0
	s_waitcnt lgkmcnt(0)
	v_mfma_f32_16x16x32_bf16 v[126:129], v[130:133], v[184:187], v[126:129]
	v_mfma_f32_16x16x32_bf16 v[122:125], v[150:153], v[184:187], v[122:125]
	v_mfma_f32_16x16x32_bf16 v[110:113], v[130:133], v[192:195], v[110:113]
	v_mfma_f32_16x16x32_bf16 v[106:109], v[150:153], v[192:195], v[106:109]
	v_mfma_f32_16x16x32_bf16 v[94:97], v[130:133], v[200:203], v[94:97]
	v_mfma_f32_16x16x32_bf16 v[90:93], v[150:153], v[200:203], v[90:93]
	v_mfma_f32_16x16x32_bf16 v[78:81], v[130:133], v[208:211], v[78:81]
	v_mfma_f32_16x16x32_bf16 v[74:77], v[150:153], v[208:211], v[74:77]
	v_mfma_f32_16x16x32_bf16 v[126:129], v[134:137], v[188:191], v[126:129]
	v_mfma_f32_16x16x32_bf16 v[122:125], v[154:157], v[188:191], v[122:125]
	v_mfma_f32_16x16x32_bf16 v[110:113], v[134:137], v[196:199], v[110:113]
	v_mfma_f32_16x16x32_bf16 v[106:109], v[154:157], v[196:199], v[106:109]
	v_mfma_f32_16x16x32_bf16 v[94:97], v[134:137], v[204:207], v[94:97]
	v_mfma_f32_16x16x32_bf16 v[90:93], v[154:157], v[204:207], v[90:93]
	v_mfma_f32_16x16x32_bf16 v[78:81], v[134:137], v[212:215], v[78:81]
	v_mfma_f32_16x16x32_bf16 v[74:77], v[154:157], v[212:215], v[74:77]
	s_setprio 2
	s_setprio 0
	v_mfma_f32_16x16x32_bf16 v[118:121], v[158:161], v[184:187], v[118:121]
	v_mfma_f32_16x16x32_bf16 v[114:117], v[176:179], v[184:187], v[114:117]
	v_mfma_f32_16x16x32_bf16 v[102:105], v[158:161], v[192:195], v[102:105]
	v_mfma_f32_16x16x32_bf16 v[98:101], v[176:179], v[192:195], v[98:101]
	v_mfma_f32_16x16x32_bf16 v[86:89], v[158:161], v[200:203], v[86:89]
	v_mfma_f32_16x16x32_bf16 v[82:85], v[176:179], v[200:203], v[82:85]
	v_mfma_f32_16x16x32_bf16 v[70:73], v[158:161], v[208:211], v[70:73]
	v_mfma_f32_16x16x32_bf16 v[66:69], v[176:179], v[208:211], v[66:69]
	v_mfma_f32_16x16x32_bf16 v[118:121], v[172:175], v[188:191], v[118:121]
	v_mfma_f32_16x16x32_bf16 v[114:117], v[180:183], v[188:191], v[114:117]
	v_mfma_f32_16x16x32_bf16 v[102:105], v[172:175], v[196:199], v[102:105]
	v_mfma_f32_16x16x32_bf16 v[98:101], v[180:183], v[196:199], v[98:101]
	v_mfma_f32_16x16x32_bf16 v[86:89], v[172:175], v[204:207], v[86:89]
	v_mfma_f32_16x16x32_bf16 v[82:85], v[180:183], v[204:207], v[82:85]
	v_mfma_f32_16x16x32_bf16 v[70:73], v[172:175], v[212:215], v[70:73]
	v_mfma_f32_16x16x32_bf16 v[66:69], v[180:183], v[212:215], v[66:69]
	s_setprio 2
	s_barrier
; #define PG8_STAGE(bufoff, gbase, voff) do { _Pragma("unroll") for (int _i = 0; _i < 2; ++_i) \
;         __builtin_amdgcn_global_load_lds((const unsigned*)((const char*)(gbase) + (voff)[_i]), (LAS unsigned*)(lds + (bufoff) + ldsw + _i * 8192), 16, 0, 0); } while (0)
; #define PG8_LDA(dst, b, h) do { _Pragma("unroll") for (int m = 0; m < 4; ++m) _Pragma("unroll") for (int k = 0; k < 2; ++k) dst[m][k] = *(const LAS bf16x8*)(lds + PG8_SA(b, h) + aoff + m * 2048 + k * 1024); } while (0)
; #define PG8_MMA(ai, bj, At, Bt) do { __builtin_amdgcn_s_setprio(1); _Pragma("unroll") for (int m = 0; m < 4; ++m) _Pragma("unroll") for (int n = 0; n < 2; ++n) _Pragma("unroll") for (int k = 0; k < 2; ++k) \
;         acc[ai][bj][m][n] = __builtin_amdgcn_mfma_f32_16x16x32_bf16(Bt[n][k], At[m][k], acc[ai][bj][m][n], 0, 0, 0); __builtin_amdgcn_s_setprio(0); } while (0)
; #define PG8_WAIT_V(n) asm volatile("s_waitcnt vmcnt(" #n ")" ::: "memory")
; #define PG8_WAIT_L(n) asm volatile("s_waitcnt lgkmcnt(" #n ")" ::: "memory")
; #define PG8_BAR __builtin_amdgcn_s_barrier()
; #define PG8_SCHED __builtin_amdgcn_sched_barrier(0)
; template <class Epi>
; __device__ __forceinline__ void gemm_phase(LAS unsigned char* lds, const Gemm g, int G, int c, const Epi& E) {
;     ...
;             PG8_LDA(At, 1, 1); PG8_STAGE(PG8_SB(1, 0), b3, voffB); PG8_STAGE(PG8_SB(1, 1), b3 + hstepB, voffB); PG8_STAGE(PG8_SA(1, 0), a3, voffA);
;             PG8_WAIT_V(8); PG8_WAIT_L(0); PG8_BAR; PG8_MMA(1, 0, At, B0); PG8_MMA(1, 1, At, B1); PG8_BAR; PG8_SCHED;
;         }
;         if (wr == 0) PG8_BAR;
	s_mov_b32 m0, s96
	v_lshl_add_u64 v[162:163], v[162:163], 0, s[22:23]
	global_load_lds_dwordx4 v[162:163], off
	v_lshl_add_u64 v[162:163], v[216:217], 0, s[22:23]
	s_mov_b32 m0, s94
	s_nop 0
	global_load_lds_dwordx4 v[162:163], off
	v_lshl_add_u64 v[162:163], s[10:11], 0, v[140:141]
	s_mov_b32 m0, s95
	s_nop 0
	global_load_lds_dwordx4 v[162:163], off
	v_lshl_add_u64 v[162:163], s[10:11], 0, v[144:145]
	s_mov_b32 m0, s93
	s_nop 0
	global_load_lds_dwordx4 v[162:163], off
	v_lshl_add_u64 v[162:163], v[218:219], 0, s[22:23]
	s_mov_b32 m0, s85
	s_nop 0
	global_load_lds_dwordx4 v[162:163], off
	v_lshl_add_u64 v[162:163], v[220:221], 0, s[22:23]
	s_mov_b32 m0, s86
	s_nop 0
	global_load_lds_dwordx4 v[162:163], off
	ds_read_b128 v[184:187], v168 offset:49152
	ds_read_b128 v[188:191], v168 offset:50176
	ds_read_b128 v[192:195], v168 offset:51200
	ds_read_b128 v[196:199], v168 offset:52224
	ds_read_b128 v[200:203], v168 offset:53248
	ds_read_b128 v[204:207], v168 offset:54272
	ds_read_b128 v[208:211], v168 offset:55296
	ds_read_b128 v[212:215], v168 offset:56320
	s_waitcnt vmcnt(8)
	s_waitcnt lgkmcnt(0)
	s_barrier
	s_setprio 0
	s_waitcnt lgkmcnt(0)
	v_mfma_f32_16x16x32_bf16 v[62:65], v[130:133], v[184:187], v[62:65]
	v_mfma_f32_16x16x32_bf16 v[58:61], v[150:153], v[184:187], v[58:61]
	v_mfma_f32_16x16x32_bf16 v[46:49], v[130:133], v[192:195], v[46:49]
	v_mfma_f32_16x16x32_bf16 v[42:45], v[150:153], v[192:195], v[42:45]
	v_mfma_f32_16x16x32_bf16 v[30:33], v[130:133], v[200:203], v[30:33]
	v_mfma_f32_16x16x32_bf16 v[26:29], v[150:153], v[200:203], v[26:29]
	v_mfma_f32_16x16x32_bf16 v[14:17], v[130:133], v[208:211], v[14:17]
	v_mfma_f32_16x16x32_bf16 v[10:13], v[150:153], v[208:211], v[10:13]
	v_mfma_f32_16x16x32_bf16 v[62:65], v[134:137], v[188:191], v[62:65]
	v_mfma_f32_16x16x32_bf16 v[58:61], v[154:157], v[188:191], v[58:61]
	v_mfma_f32_16x16x32_bf16 v[46:49], v[134:137], v[196:199], v[46:49]
	v_mfma_f32_16x16x32_bf16 v[42:45], v[154:157], v[196:199], v[42:45]
	v_mfma_f32_16x16x32_bf16 v[30:33], v[134:137], v[204:207], v[30:33]
	v_mfma_f32_16x16x32_bf16 v[26:29], v[154:157], v[204:207], v[26:29]
	v_mfma_f32_16x16x32_bf16 v[14:17], v[134:137], v[212:215], v[14:17]
	v_mfma_f32_16x16x32_bf16 v[10:13], v[154:157], v[212:215], v[10:13]
	s_setprio 2
	s_setprio 0
	v_mfma_f32_16x16x32_bf16 v[54:57], v[158:161], v[184:187], v[54:57]
	v_mfma_f32_16x16x32_bf16 v[50:53], v[176:179], v[184:187], v[50:53]
	v_mfma_f32_16x16x32_bf16 v[38:41], v[158:161], v[192:195], v[38:41]
	v_mfma_f32_16x16x32_bf16 v[34:37], v[176:179], v[192:195], v[34:37]
	v_mfma_f32_16x16x32_bf16 v[22:25], v[158:161], v[200:203], v[22:25]
	v_mfma_f32_16x16x32_bf16 v[18:21], v[176:179], v[200:203], v[18:21]
	v_mfma_f32_16x16x32_bf16 v[6:9], v[158:161], v[208:211], v[6:9]
	v_mfma_f32_16x16x32_bf16 v[2:5], v[176:179], v[208:211], v[2:5]
	v_mfma_f32_16x16x32_bf16 v[54:57], v[172:175], v[188:191], v[54:57]
	v_mfma_f32_16x16x32_bf16 v[50:53], v[180:183], v[188:191], v[50:53]
	v_mfma_f32_16x16x32_bf16 v[38:41], v[172:175], v[196:199], v[38:41]
	v_mfma_f32_16x16x32_bf16 v[34:37], v[180:183], v[196:199], v[34:37]
	v_mfma_f32_16x16x32_bf16 v[22:25], v[172:175], v[204:207], v[22:25]
	v_mfma_f32_16x16x32_bf16 v[18:21], v[180:183], v[204:207], v[18:21]
	v_mfma_f32_16x16x32_bf16 v[6:9], v[172:175], v[212:215], v[6:9]
	v_mfma_f32_16x16x32_bf16 v[2:5], v[180:183], v[212:215], v[2:5]
	s_setprio 2
	s_barrier
	s_movk_i32 s44, 0x100
	s_andn2_b64 vcc, exec, s[4:5]
	s_mov_b64 s[10:11], -1
	s_mov_b64 s[4:5], 0
	s_cbranch_vccz .LBB0_1537
	s_and_b64 vcc, exec, s[24:25]
	s_cbranch_vccz .LBB0_1540
	s_barrier

; #define PG8_STAGE(bufoff, gbase, voff) do { _Pragma("unroll") for (int _i = 0; _i < 2; ++_i) \
;         __builtin_amdgcn_global_load_lds((const unsigned*)((const char*)(gbase) + (voff)[_i]), (LAS unsigned*)(lds + (bufoff) + ldsw + _i * 8192), 16, 0, 0); } while (0)
; #define PG8_LDA(dst, b, h) do { _Pragma("unroll") for (int m = 0; m < 4; ++m) _Pragma("unroll") for (int k = 0; k < 2; ++k) dst[m][k] = *(const LAS bf16x8*)(lds + PG8_SA(b, h) + aoff + m * 2048 + k * 1024); } while (0)
; #define PG8_LDB(dst, b, h) do { _Pragma("unroll") for (int n = 0; n < 2; ++n) _Pragma("unroll") for (int k = 0; k < 2; ++k) dst[n][k] = *(const LAS bf16x8*)(lds + PG8_SB(b, h) + boff + n * 2048 + k * 1024); } while (0)
; #define PG8_MMA(ai, bj, At, Bt) do { __builtin_amdgcn_s_setprio(1); _Pragma("unroll") for (int m = 0; m < 4; ++m) _Pragma("unroll") for (int n = 0; n < 2; ++n) _Pragma("unroll") for (int k = 0; k < 2; ++k) \
;         acc[ai][bj][m][n] = __builtin_amdgcn_mfma_f32_16x16x32_bf16(Bt[n][k], At[m][k], acc[ai][bj][m][n], 0, 0, 0); __builtin_amdgcn_s_setprio(0); } while (0)
; #define PG8_WAIT_V(n) asm volatile("s_waitcnt vmcnt(" #n ")" ::: "memory")
; #define PG8_WAIT_L(n) asm volatile("s_waitcnt lgkmcnt(" #n ")" ::: "memory")
; #define PG8_BAR __builtin_amdgcn_s_barrier()
; #define PG8_SCHED __builtin_amdgcn_sched_barrier(0)
; template <class Epi>
; __device__ __forceinline__ void gemm_phase(LAS unsigned char* lds, const Gemm g, int G, int c, const Epi& E) {
;     ...
;             const bool last = (t == nt - 2);
;             const char* a1 = cA + (size_t)(t + 1) * kstep;
;             const char* a2 = last ? nA : cA + (size_t)(t + 2) * kstep; const char* b2 = last ? nB : cB + (size_t)(t + 2) * kstep;
;             const char* a3 = a2 + kstep; const char* b3 = b2 + kstep;
;             PG8_LDB(B0, 0, 0); PG8_LDB(B1, 0, 1); PG8_SCHED; PG8_LDA(At, 0, 0); PG8_STAGE(PG8_SA(1, 1), a1 + hstepA, voffA);
;             PG8_WAIT_V(8); PG8_WAIT_L(0); PG8_BAR; PG8_MMA(0, 0, At, B0); PG8_MMA(0, 1, At, B1); PG8_BAR; PG8_SCHED;
;             PG8_LDA(At, 0, 1); PG8_STAGE(PG8_SB(0, 0), b2, voffB); PG8_STAGE(PG8_SB(0, 1), b2 + hstepB, voffB); PG8_STAGE(PG8_SA(0, 0), a2, voffA);
.LBB0_1653:
	s_add_u32 s33, s8, s48
	s_addc_u32 s49, s9, 0
	s_add_u32 s54, s33, 0x100
	s_addc_u32 s55, s49, 0
	s_and_b64 s[52:53], s[46:47], exec
	s_cselect_b32 s53, s41, s55
	s_cselect_b32 s52, s40, s54
	s_add_u32 s48, s6, s48
	s_addc_u32 s54, s7, 0
	s_add_u32 s48, s48, 0x100
	s_addc_u32 s54, s54, 0
	s_and_b64 s[46:47], s[46:47], exec
	s_cselect_b32 s55, s43, s54
	s_cselect_b32 s54, s42, s48
	s_add_u32 s58, s33, 0xb0080
	s_addc_u32 s59, s49, 0
	s_add_i32 s63, s80, s23
	s_add_i32 m0, s68, 0xc000
	s_add_i32 s64, s68, 0xe000
	v_lshl_add_u64 v[162:163], s[58:59], 0, v[136:137]
	global_load_lds_dwordx4 v[162:163], off
	v_lshl_add_u64 v[162:163], s[58:59], 0, v[132:133]
	s_mov_b32 m0, s64
	s_nop 0
	global_load_lds_dwordx4 v[162:163], off
	ds_read_b128 v[142:145], v166
	ds_read_b128 v[146:149], v166 offset:1024
	ds_read_b128 v[150:153], v166 offset:2048
	ds_read_b128 v[154:157], v166 offset:3072
	ds_read_b128 v[158:161], v167
	ds_read_b128 v[170:173], v167 offset:1024
	ds_read_b128 v[174:177], v167 offset:2048
	ds_read_b128 v[178:181], v167 offset:3072
	s_add_i32 s74, s63, 0x2000
	s_add_u32 s56, s54, 0xb0000
	s_addc_u32 s57, s55, 0
	s_add_i32 s62, s81, s23
	s_add_i32 s75, s62, 0x2000
	s_add_i32 s93, 0, 0x18000
	s_add_i32 s33, 0, 0x1c000
	s_add_u32 s48, s52, 0xb0000
	s_addc_u32 s49, s53, 0
	s_add_i32 s92, s93, s23
	s_add_i32 s90, s92, 0x2000
	s_add_u32 s46, s54, 0xb0080
	s_addc_u32 s47, s55, 0
	s_add_i32 s91, s33, s23
	s_add_i32 s89, s91, 0x2000
	ds_read_b128 v[182:185], v168
	ds_read_b128 v[186:189], v168 offset:1024
	ds_read_b128 v[190:193], v168 offset:2048
	ds_read_b128 v[194:197], v168 offset:3072
	ds_read_b128 v[198:201], v168 offset:4096
	ds_read_b128 v[202:205], v168 offset:5120
	ds_read_b128 v[206:209], v168 offset:6144
	ds_read_b128 v[210:213], v168 offset:7168
	s_waitcnt vmcnt(8)
	s_waitcnt lgkmcnt(0)
	s_barrier
	s_setprio 0
	s_waitcnt lgkmcnt(0)
	v_mfma_f32_16x16x32_bf16 v[126:129], v[142:145], v[182:185], v[126:129]
	v_mfma_f32_16x16x32_bf16 v[122:125], v[150:153], v[182:185], v[122:125]
	v_mfma_f32_16x16x32_bf16 v[110:113], v[142:145], v[190:193], v[110:113]
	v_mfma_f32_16x16x32_bf16 v[106:109], v[150:153], v[190:193], v[106:109]
	v_mfma_f32_16x16x32_bf16 v[94:97], v[142:145], v[198:201], v[94:97]
	v_mfma_f32_16x16x32_bf16 v[90:93], v[150:153], v[198:201], v[90:93]
	v_mfma_f32_16x16x32_bf16 v[78:81], v[142:145], v[206:209], v[78:81]
	v_mfma_f32_16x16x32_bf16 v[74:77], v[150:153], v[206:209], v[74:77]
	v_mfma_f32_16x16x32_bf16 v[126:129], v[146:149], v[186:189], v[126:129]
	v_mfma_f32_16x16x32_bf16 v[122:125], v[154:157], v[186:189], v[122:125]
	v_mfma_f32_16x16x32_bf16 v[110:113], v[146:149], v[194:197], v[110:113]
	v_mfma_f32_16x16x32_bf16 v[106:109], v[154:157], v[194:197], v[106:109]
	v_mfma_f32_16x16x32_bf16 v[94:97], v[146:149], v[202:205], v[94:97]
	v_mfma_f32_16x16x32_bf16 v[90:93], v[154:157], v[202:205], v[90:93]
	v_mfma_f32_16x16x32_bf16 v[78:81], v[146:149], v[210:213], v[78:81]
	v_mfma_f32_16x16x32_bf16 v[74:77], v[154:157], v[210:213], v[74:77]
	s_setprio 2
	s_setprio 0
	v_mfma_f32_16x16x32_bf16 v[118:121], v[158:161], v[182:185], v[118:121]
	v_mfma_f32_16x16x32_bf16 v[114:117], v[174:177], v[182:185], v[114:117]
	v_mfma_f32_16x16x32_bf16 v[102:105], v[158:161], v[190:193], v[102:105]
	v_mfma_f32_16x16x32_bf16 v[98:101], v[174:177], v[190:193], v[98:101]
	v_mfma_f32_16x16x32_bf16 v[86:89], v[158:161], v[198:201], v[86:89]
	v_mfma_f32_16x16x32_bf16 v[82:85], v[174:177], v[198:201], v[82:85]
	v_mfma_f32_16x16x32_bf16 v[70:73], v[158:161], v[206:209], v[70:73]
	v_mfma_f32_16x16x32_bf16 v[66:69], v[174:177], v[206:209], v[66:69]
	v_mfma_f32_16x16x32_bf16 v[118:121], v[170:173], v[186:189], v[118:121]
	v_mfma_f32_16x16x32_bf16 v[114:117], v[178:181], v[186:189], v[114:117]
	v_mfma_f32_16x16x32_bf16 v[102:105], v[170:173], v[194:197], v[102:105]
	v_mfma_f32_16x16x32_bf16 v[98:101], v[178:181], v[194:197], v[98:101]
	v_mfma_f32_16x16x32_bf16 v[86:89], v[170:173], v[202:205], v[86:89]
	v_mfma_f32_16x16x32_bf16 v[82:85], v[178:181], v[202:205], v[82:85]
	v_mfma_f32_16x16x32_bf16 v[70:73], v[170:173], v[210:213], v[70:73]
	v_mfma_f32_16x16x32_bf16 v[66:69], v[178:181], v[210:213], v[66:69]
	s_setprio 2
	s_barrier
	s_mov_b32 m0, s63
	v_lshl_add_u64 v[162:163], s[54:55], 0, v[134:135]
	global_load_lds_dwordx4 v[162:163], off
	v_lshl_add_u64 v[214:215], s[54:55], 0, v[130:131]
	s_mov_b32 m0, s74
	v_lshl_add_u64 v[216:217], s[56:57], 0, v[134:135]
	global_load_lds_dwordx4 v[214:215], off
	s_mov_b32 m0, s62
	v_lshl_add_u64 v[218:219], s[52:53], 0, v[132:133]
	global_load_lds_dwordx4 v[216:217], off
	v_lshl_add_u64 v[216:217], s[56:57], 0, v[130:131]
	s_mov_b32 m0, s75
	s_nop 0
	global_load_lds_dwordx4 v[216:217], off
	v_lshl_add_u64 v[216:217], s[52:53], 0, v[136:137]
	s_mov_b32 m0, s68
	s_nop 0
	global_load_lds_dwordx4 v[216:217], off
	s_mov_b32 m0, s69
	s_nop 0
	global_load_lds_dwordx4 v[218:219], off
	ds_read_b128 v[182:185], v168 offset:16384
	ds_read_b128 v[186:189], v168 offset:17408
	ds_read_b128 v[190:193], v168 offset:18432
	ds_read_b128 v[194:197], v168 offset:19456
	ds_read_b128 v[198:201], v168 offset:20480
	ds_read_b128 v[202:205], v168 offset:21504
	ds_read_b128 v[206:209], v168 offset:22528
	ds_read_b128 v[210:213], v168 offset:23552
	s_waitcnt vmcnt(8)
	s_waitcnt lgkmcnt(0)
	s_barrier
; #define PG8_STAGE(bufoff, gbase, voff) do { _Pragma("unroll") for (int _i = 0; _i < 2; ++_i) \
;         __builtin_amdgcn_global_load_lds((const unsigned*)((const char*)(gbase) + (voff)[_i]), (LAS unsigned*)(lds + (bufoff) + ldsw + _i * 8192), 16, 0, 0); } while (0)
; #define PG8_LDA(dst, b, h) do { _Pragma("unroll") for (int m = 0; m < 4; ++m) _Pragma("unroll") for (int k = 0; k < 2; ++k) dst[m][k] = *(const LAS bf16x8*)(lds + PG8_SA(b, h) + aoff + m * 2048 + k * 1024); } while (0)
; #define PG8_LDB(dst, b, h) do { _Pragma("unroll") for (int n = 0; n < 2; ++n) _Pragma("unroll") for (int k = 0; k < 2; ++k) dst[n][k] = *(const LAS bf16x8*)(lds + PG8_SB(b, h) + boff + n * 2048 + k * 1024); } while (0)
; #define PG8_MMA(ai, bj, At, Bt) do { __builtin_amdgcn_s_setprio(1); _Pragma("unroll") for (int m = 0; m < 4; ++m) _Pragma("unroll") for (int n = 0; n < 2; ++n) _Pragma("unroll") for (int k = 0; k < 2; ++k) \
;         acc[ai][bj][m][n] = __builtin_amdgcn_mfma_f32_16x16x32_bf16(Bt[n][k], At[m][k], acc[ai][bj][m][n], 0, 0, 0); __builtin_amdgcn_s_setprio(0); } while (0)
; #define PG8_WAIT_V(n) asm volatile("s_waitcnt vmcnt(" #n ")" ::: "memory")
; #define PG8_WAIT_L(n) asm volatile("s_waitcnt lgkmcnt(" #n ")" ::: "memory")
; #define PG8_BAR __builtin_amdgcn_s_barrier()
; #define PG8_SCHED __builtin_amdgcn_sched_barrier(0)
; template <class Epi>
; __device__ __forceinline__ void gemm_phase(LAS unsigned char* lds, const Gemm g, int G, int c, const Epi& E) {
;     ...
;             PG8_WAIT_V(8); PG8_WAIT_L(0); PG8_BAR; PG8_MMA(1, 0, At, B0); PG8_MMA(1, 1, At, B1); PG8_BAR; PG8_SCHED;
;             PG8_LDB(B0, 1, 0); PG8_LDB(B1, 1, 1); PG8_SCHED; PG8_LDA(At, 1, 0); PG8_STAGE(PG8_SA(0, 1), a2 + hstepA, voffA);
;             PG8_WAIT_V(8); PG8_WAIT_L(0); PG8_BAR; PG8_MMA(0, 0, At, B0); PG8_MMA(0, 1, At, B1); PG8_BAR; PG8_SCHED;
	s_setprio 0
	s_waitcnt lgkmcnt(0)
	v_mfma_f32_16x16x32_bf16 v[62:65], v[142:145], v[182:185], v[62:65]
	v_mfma_f32_16x16x32_bf16 v[58:61], v[150:153], v[182:185], v[58:61]
	v_mfma_f32_16x16x32_bf16 v[46:49], v[142:145], v[190:193], v[46:49]
	v_mfma_f32_16x16x32_bf16 v[42:45], v[150:153], v[190:193], v[42:45]
	v_mfma_f32_16x16x32_bf16 v[30:33], v[142:145], v[198:201], v[30:33]
	v_mfma_f32_16x16x32_bf16 v[26:29], v[150:153], v[198:201], v[26:29]
	v_mfma_f32_16x16x32_bf16 v[14:17], v[142:145], v[206:209], v[14:17]
	v_mfma_f32_16x16x32_bf16 v[10:13], v[150:153], v[206:209], v[10:13]
	v_mfma_f32_16x16x32_bf16 v[62:65], v[146:149], v[186:189], v[62:65]
	v_mfma_f32_16x16x32_bf16 v[58:61], v[154:157], v[186:189], v[58:61]
	v_mfma_f32_16x16x32_bf16 v[46:49], v[146:149], v[194:197], v[46:49]
	v_mfma_f32_16x16x32_bf16 v[42:45], v[154:157], v[194:197], v[42:45]
	v_mfma_f32_16x16x32_bf16 v[30:33], v[146:149], v[202:205], v[30:33]
	v_mfma_f32_16x16x32_bf16 v[26:29], v[154:157], v[202:205], v[26:29]
	v_mfma_f32_16x16x32_bf16 v[14:17], v[146:149], v[210:213], v[14:17]
	v_mfma_f32_16x16x32_bf16 v[10:13], v[154:157], v[210:213], v[10:13]
	s_setprio 2
	s_setprio 0
	v_mfma_f32_16x16x32_bf16 v[54:57], v[158:161], v[182:185], v[54:57]
	v_mfma_f32_16x16x32_bf16 v[50:53], v[174:177], v[182:185], v[50:53]
	v_mfma_f32_16x16x32_bf16 v[38:41], v[158:161], v[190:193], v[38:41]
	v_mfma_f32_16x16x32_bf16 v[34:37], v[174:177], v[190:193], v[34:37]
	v_mfma_f32_16x16x32_bf16 v[22:25], v[158:161], v[198:201], v[22:25]
	v_mfma_f32_16x16x32_bf16 v[18:21], v[174:177], v[198:201], v[18:21]
	v_mfma_f32_16x16x32_bf16 v[6:9], v[158:161], v[206:209], v[6:9]
	v_mfma_f32_16x16x32_bf16 v[2:5], v[174:177], v[206:209], v[2:5]
	v_mfma_f32_16x16x32_bf16 v[54:57], v[170:173], v[186:189], v[54:57]
	v_mfma_f32_16x16x32_bf16 v[50:53], v[178:181], v[186:189], v[50:53]
	v_mfma_f32_16x16x32_bf16 v[38:41], v[170:173], v[194:197], v[38:41]
	v_mfma_f32_16x16x32_bf16 v[34:37], v[178:181], v[194:197], v[34:37]
	v_mfma_f32_16x16x32_bf16 v[22:25], v[170:173], v[202:205], v[22:25]
	v_mfma_f32_16x16x32_bf16 v[18:21], v[178:181], v[202:205], v[18:21]
	v_mfma_f32_16x16x32_bf16 v[6:9], v[170:173], v[210:213], v[6:9]
	v_mfma_f32_16x16x32_bf16 v[2:5], v[178:181], v[210:213], v[2:5]
	s_setprio 2
	s_barrier
	s_mov_b32 m0, s70
	v_lshl_add_u64 v[220:221], s[48:49], 0, v[136:137]
	global_load_lds_dwordx4 v[220:221], off
	v_lshl_add_u64 v[220:221], s[48:49], 0, v[132:133]
	s_mov_b32 m0, s71
	s_nop 0
	global_load_lds_dwordx4 v[220:221], off
	v_add_u32_e32 v154, s93, v165
	v_add_u32_e32 v178, s33, v165
	ds_read_b128 v[142:145], v154
	ds_read_b128 v[146:149], v154 offset:1024
	ds_read_b128 v[150:153], v154 offset:2048
	ds_read_b128 v[154:157], v154 offset:3072
	ds_read_b128 v[158:161], v178
	ds_read_b128 v[170:173], v178 offset:1024
	ds_read_b128 v[174:177], v178 offset:2048
	ds_read_b128 v[178:181], v178 offset:3072
	ds_read_b128 v[182:185], v168 offset:32768
	ds_read_b128 v[186:189], v168 offset:33792
	ds_read_b128 v[190:193], v168 offset:34816
	ds_read_b128 v[194:197], v168 offset:35840
	ds_read_b128 v[198:201], v168 offset:36864
	ds_read_b128 v[202:205], v168 offset:37888
	ds_read_b128 v[206:209], v168 offset:38912
	ds_read_b128 v[210:213], v168 offset:39936
	s_waitcnt vmcnt(8)
	s_waitcnt lgkmcnt(0)
	s_barrier
	s_setprio 0
	s_waitcnt lgkmcnt(0)
	v_mfma_f32_16x16x32_bf16 v[126:129], v[142:145], v[182:185], v[126:129]
	v_mfma_f32_16x16x32_bf16 v[122:125], v[150:153], v[182:185], v[122:125]
	v_mfma_f32_16x16x32_bf16 v[110:113], v[142:145], v[190:193], v[110:113]
	v_mfma_f32_16x16x32_bf16 v[106:109], v[150:153], v[190:193], v[106:109]
	v_mfma_f32_16x16x32_bf16 v[94:97], v[142:145], v[198:201], v[94:97]
	v_mfma_f32_16x16x32_bf16 v[90:93], v[150:153], v[198:201], v[90:93]
	v_mfma_f32_16x16x32_bf16 v[78:81], v[142:145], v[206:209], v[78:81]
	v_mfma_f32_16x16x32_bf16 v[74:77], v[150:153], v[206:209], v[74:77]
	v_mfma_f32_16x16x32_bf16 v[126:129], v[146:149], v[186:189], v[126:129]
	v_mfma_f32_16x16x32_bf16 v[122:125], v[154:157], v[186:189], v[122:125]
	v_mfma_f32_16x16x32_bf16 v[110:113], v[146:149], v[194:197], v[110:113]
	v_mfma_f32_16x16x32_bf16 v[106:109], v[154:157], v[194:197], v[106:109]
	v_mfma_f32_16x16x32_bf16 v[94:97], v[146:149], v[202:205], v[94:97]
	v_mfma_f32_16x16x32_bf16 v[90:93], v[154:157], v[202:205], v[90:93]
	v_mfma_f32_16x16x32_bf16 v[78:81], v[146:149], v[210:213], v[78:81]
	v_mfma_f32_16x16x32_bf16 v[74:77], v[154:157], v[210:213], v[74:77]
	s_setprio 2
	s_setprio 0
	v_mfma_f32_16x16x32_bf16 v[118:121], v[158:161], v[182:185], v[118:121]
	v_mfma_f32_16x16x32_bf16 v[114:117], v[174:177], v[182:185], v[114:117]
	v_mfma_f32_16x16x32_bf16 v[102:105], v[158:161], v[190:193], v[102:105]
	v_mfma_f32_16x16x32_bf16 v[98:101], v[174:177], v[190:193], v[98:101]
	v_mfma_f32_16x16x32_bf16 v[86:89], v[158:161], v[198:201], v[86:89]
	v_mfma_f32_16x16x32_bf16 v[82:85], v[174:177], v[198:201], v[82:85]
	v_mfma_f32_16x16x32_bf16 v[70:73], v[158:161], v[206:209], v[70:73]
	v_mfma_f32_16x16x32_bf16 v[66:69], v[174:177], v[206:209], v[66:69]
	v_mfma_f32_16x16x32_bf16 v[118:121], v[170:173], v[186:189], v[118:121]
	v_mfma_f32_16x16x32_bf16 v[114:117], v[178:181], v[186:189], v[114:117]
	v_mfma_f32_16x16x32_bf16 v[102:105], v[170:173], v[194:197], v[102:105]
	v_mfma_f32_16x16x32_bf16 v[98:101], v[178:181], v[194:197], v[98:101]
	v_mfma_f32_16x16x32_bf16 v[86:89], v[170:173], v[202:205], v[86:89]
	v_mfma_f32_16x16x32_bf16 v[82:85], v[178:181], v[202:205], v[82:85]
	v_mfma_f32_16x16x32_bf16 v[70:73], v[170:173], v[210:213], v[70:73]
	v_mfma_f32_16x16x32_bf16 v[66:69], v[178:181], v[210:213], v[66:69]
	s_setprio 2
	s_barrier
; #define PG8_STAGE(bufoff, gbase, voff) do { _Pragma("unroll") for (int _i = 0; _i < 2; ++_i) \
;         __builtin_amdgcn_global_load_lds((const unsigned*)((const char*)(gbase) + (voff)[_i]), (LAS unsigned*)(lds + (bufoff) + ldsw + _i * 8192), 16, 0, 0); } while (0)
; #define PG8_LDA(dst, b, h) do { _Pragma("unroll") for (int m = 0; m < 4; ++m) _Pragma("unroll") for (int k = 0; k < 2; ++k) dst[m][k] = *(const LAS bf16x8*)(lds + PG8_SA(b, h) + aoff + m * 2048 + k * 1024); } while (0)
; #define PG8_MMA(ai, bj, At, Bt) do { __builtin_amdgcn_s_setprio(1); _Pragma("unroll") for (int m = 0; m < 4; ++m) _Pragma("unroll") for (int n = 0; n < 2; ++n) _Pragma("unroll") for (int k = 0; k < 2; ++k) \
;         acc[ai][bj][m][n] = __builtin_amdgcn_mfma_f32_16x16x32_bf16(Bt[n][k], At[m][k], acc[ai][bj][m][n], 0, 0, 0); __builtin_amdgcn_s_setprio(0); } while (0)
; #define PG8_WAIT_V(n) asm volatile("s_waitcnt vmcnt(" #n ")" ::: "memory")
; #define PG8_WAIT_L(n) asm volatile("s_waitcnt lgkmcnt(" #n ")" ::: "memory")
; #define PG8_BAR __builtin_amdgcn_s_barrier()
; #define PG8_SCHED __builtin_amdgcn_sched_barrier(0)
; template <class Epi>
; __device__ __forceinline__ void gemm_phase(LAS unsigned char* lds, const Gemm g, int G, int c, const Epi& E) {
;     ...
;             PG8_LDA(At, 1, 1); PG8_STAGE(PG8_SB(1, 0), b3, voffB); PG8_STAGE(PG8_SB(1, 1), b3 + hstepB, voffB); PG8_STAGE(PG8_SA(1, 0), a3, voffA);
;             PG8_WAIT_V(8); PG8_WAIT_L(0); PG8_BAR; PG8_MMA(1, 0, At, B0); PG8_MMA(1, 1, At, B1); PG8_BAR; PG8_SCHED;
;         }
;         if (wr == 0) PG8_BAR;
	s_mov_b32 m0, s92
	v_lshl_add_u64 v[162:163], v[162:163], 0, s[18:19]
	global_load_lds_dwordx4 v[162:163], off
	v_lshl_add_u64 v[162:163], v[214:215], 0, s[18:19]
	s_mov_b32 m0, s90
	s_nop 0
	global_load_lds_dwordx4 v[162:163], off
	v_lshl_add_u64 v[162:163], s[46:47], 0, v[134:135]
	s_mov_b32 m0, s91
	s_nop 0
	global_load_lds_dwordx4 v[162:163], off
	v_lshl_add_u64 v[162:163], s[46:47], 0, v[130:131]
	s_mov_b32 m0, s89
	s_nop 0
	global_load_lds_dwordx4 v[162:163], off
	v_lshl_add_u64 v[162:163], v[216:217], 0, s[18:19]
	s_mov_b32 m0, s78
	s_nop 0
	global_load_lds_dwordx4 v[162:163], off
	v_lshl_add_u64 v[162:163], v[218:219], 0, s[18:19]
	s_mov_b32 m0, s79
	s_nop 0
	global_load_lds_dwordx4 v[162:163], off
	ds_read_b128 v[182:185], v168 offset:49152
	ds_read_b128 v[186:189], v168 offset:50176
	ds_read_b128 v[190:193], v168 offset:51200
	ds_read_b128 v[194:197], v168 offset:52224
	ds_read_b128 v[198:201], v168 offset:53248
	ds_read_b128 v[202:205], v168 offset:54272
	ds_read_b128 v[206:209], v168 offset:55296
	ds_read_b128 v[210:213], v168 offset:56320
	s_waitcnt vmcnt(8)
	s_waitcnt lgkmcnt(0)
	s_barrier
	s_setprio 0
	s_waitcnt lgkmcnt(0)
	v_mfma_f32_16x16x32_bf16 v[62:65], v[142:145], v[182:185], v[62:65]
	v_mfma_f32_16x16x32_bf16 v[58:61], v[150:153], v[182:185], v[58:61]
	v_mfma_f32_16x16x32_bf16 v[46:49], v[142:145], v[190:193], v[46:49]
	v_mfma_f32_16x16x32_bf16 v[42:45], v[150:153], v[190:193], v[42:45]
	v_mfma_f32_16x16x32_bf16 v[30:33], v[142:145], v[198:201], v[30:33]
	v_mfma_f32_16x16x32_bf16 v[26:29], v[150:153], v[198:201], v[26:29]
	v_mfma_f32_16x16x32_bf16 v[14:17], v[142:145], v[206:209], v[14:17]
	v_mfma_f32_16x16x32_bf16 v[10:13], v[150:153], v[206:209], v[10:13]
	v_mfma_f32_16x16x32_bf16 v[62:65], v[146:149], v[186:189], v[62:65]
	v_mfma_f32_16x16x32_bf16 v[58:61], v[154:157], v[186:189], v[58:61]
	v_mfma_f32_16x16x32_bf16 v[46:49], v[146:149], v[194:197], v[46:49]
	v_mfma_f32_16x16x32_bf16 v[42:45], v[154:157], v[194:197], v[42:45]
	v_mfma_f32_16x16x32_bf16 v[30:33], v[146:149], v[202:205], v[30:33]
	v_mfma_f32_16x16x32_bf16 v[26:29], v[154:157], v[202:205], v[26:29]
	v_mfma_f32_16x16x32_bf16 v[14:17], v[146:149], v[210:213], v[14:17]
	v_mfma_f32_16x16x32_bf16 v[10:13], v[154:157], v[210:213], v[10:13]
	s_setprio 2
	s_setprio 0
	v_mfma_f32_16x16x32_bf16 v[54:57], v[158:161], v[182:185], v[54:57]
	v_mfma_f32_16x16x32_bf16 v[50:53], v[174:177], v[182:185], v[50:53]
	v_mfma_f32_16x16x32_bf16 v[38:41], v[158:161], v[190:193], v[38:41]
	v_mfma_f32_16x16x32_bf16 v[34:37], v[174:177], v[190:193], v[34:37]
	v_mfma_f32_16x16x32_bf16 v[22:25], v[158:161], v[198:201], v[22:25]
	v_mfma_f32_16x16x32_bf16 v[18:21], v[174:177], v[198:201], v[18:21]
	v_mfma_f32_16x16x32_bf16 v[6:9], v[158:161], v[206:209], v[6:9]
	v_mfma_f32_16x16x32_bf16 v[2:5], v[174:177], v[206:209], v[2:5]
	v_mfma_f32_16x16x32_bf16 v[54:57], v[170:173], v[186:189], v[54:57]
	v_mfma_f32_16x16x32_bf16 v[50:53], v[178:181], v[186:189], v[50:53]
	v_mfma_f32_16x16x32_bf16 v[38:41], v[170:173], v[194:197], v[38:41]
	v_mfma_f32_16x16x32_bf16 v[34:37], v[178:181], v[194:197], v[34:37]
	v_mfma_f32_16x16x32_bf16 v[22:25], v[170:173], v[202:205], v[22:25]
	v_mfma_f32_16x16x32_bf16 v[18:21], v[178:181], v[202:205], v[18:21]
	v_mfma_f32_16x16x32_bf16 v[6:9], v[170:173], v[210:213], v[6:9]
	v_mfma_f32_16x16x32_bf16 v[2:5], v[178:181], v[210:213], v[2:5]
	s_setprio 2
	s_barrier
	s_movk_i32 s48, 0x100
	s_andn2_b64 vcc, exec, s[4:5]
	s_mov_b64 s[46:47], -1
	s_mov_b64 s[4:5], 0
	s_cbranch_vccz .LBB0_1653
	s_and_b64 vcc, exec, s[20:21]
	s_cbranch_vccz .LBB0_1656
	s_barrier

; #define PG8_STAGE(bufoff, gbase, voff) do { _Pragma("unroll") for (int _i = 0; _i < 2; ++_i) \
;         __builtin_amdgcn_global_load_lds((const unsigned*)((const char*)(gbase) + (voff)[_i]), (LAS unsigned*)(lds + (bufoff) + ldsw + _i * 8192), 16, 0, 0); } while (0)
; #define PG8_LDA(dst, b, h) do { _Pragma("unroll") for (int m = 0; m < 4; ++m) _Pragma("unroll") for (int k = 0; k < 2; ++k) dst[m][k] = *(const LAS bf16x8*)(lds + PG8_SA(b, h) + aoff + m * 2048 + k * 1024); } while (0)
; #define PG8_LDB(dst, b, h) do { _Pragma("unroll") for (int n = 0; n < 2; ++n) _Pragma("unroll") for (int k = 0; k < 2; ++k) dst[n][k] = *(const LAS bf16x8*)(lds + PG8_SB(b, h) + boff + n * 2048 + k * 1024); } while (0)
; #define PG8_MMA(ai, bj, At, Bt) do { __builtin_amdgcn_s_setprio(1); _Pragma("unroll") for (int m = 0; m < 4; ++m) _Pragma("unroll") for (int n = 0; n < 2; ++n) _Pragma("unroll") for (int k = 0; k < 2; ++k) \
;         acc[ai][bj][m][n] = __builtin_amdgcn_mfma_f32_16x16x32_bf16(Bt[n][k], At[m][k], acc[ai][bj][m][n], 0, 0, 0); __builtin_amdgcn_s_setprio(0); } while (0)
; #define PG8_WAIT_V(n) asm volatile("s_waitcnt vmcnt(" #n ")" ::: "memory")
; #define PG8_WAIT_L(n) asm volatile("s_waitcnt lgkmcnt(" #n ")" ::: "memory")
; #define PG8_BAR __builtin_amdgcn_s_barrier()
; #define PG8_SCHED __builtin_amdgcn_sched_barrier(0)
; template <class Epi>
; __device__ __forceinline__ void gemm_phase(LAS unsigned char* lds, const Gemm g, int G, int c, const Epi& E) {
;     ...
;             const char* a1 = cA + (size_t)(t + 1) * kstep;
;             const char* a2 = last ? nA : cA + (size_t)(t + 2) * kstep; const char* b2 = last ? nB : cB + (size_t)(t + 2) * kstep;
;             const char* a3 = a2 + kstep; const char* b3 = b2 + kstep;
;             PG8_LDB(B0, 0, 0); PG8_LDB(B1, 0, 1); PG8_SCHED; PG8_LDA(At, 0, 0); PG8_STAGE(PG8_SA(1, 1), a1 + hstepA, voffA);
;             PG8_WAIT_V(8); PG8_WAIT_L(0); PG8_BAR; PG8_MMA(0, 0, At, B0); PG8_MMA(0, 1, At, B1); PG8_BAR; PG8_SCHED;
;             PG8_LDA(At, 0, 1); PG8_STAGE(PG8_SB(0, 0), b2, voffB); PG8_STAGE(PG8_SB(0, 1), b2 + hstepB, voffB); PG8_STAGE(PG8_SA(0, 0), a2, voffA);
;             PG8_WAIT_V(8); PG8_WAIT_L(0); PG8_BAR; PG8_MMA(1, 0, At, B0); PG8_MMA(1, 1, At, B1); PG8_BAR; PG8_SCHED;
.LBB0_1825:
	s_add_u32 s33, s40, 0xfff00080
	s_addc_u32 s42, s41, -1
	s_cmp_eq_u32 s68, 60
	s_cselect_b32 s45, s15, s42
	s_cselect_b32 s44, s63, s33
	s_cselect_b32 s43, s11, s67
	s_cselect_b32 s42, s13, s66
	v_lshl_add_u64 v[216:217], s[40:41], 0, v[138:139]
	s_add_i32 m0, s17, 0xc000
	s_nop 0
	global_load_lds_dwordx4 v[216:217], off
	v_lshl_add_u64 v[216:217], s[40:41], 0, v[140:141]
	s_add_i32 m0, s17, 0xe000
	s_nop 0
	global_load_lds_dwordx4 v[216:217], off
	ds_read_b128 v[146:149], v152
	ds_read_b128 v[156:159], v152 offset:1024
	ds_read_b128 v[160:163], v152 offset:2048
	ds_read_b128 v[164:167], v152 offset:3072
	ds_read_b128 v[168:171], v153
	ds_read_b128 v[172:175], v153 offset:1024
	ds_read_b128 v[176:179], v153 offset:2048
	ds_read_b128 v[180:183], v153 offset:3072
	ds_read_b128 v[184:187], v154
	ds_read_b128 v[188:191], v154 offset:1024
	ds_read_b128 v[192:195], v154 offset:2048
	ds_read_b128 v[196:199], v154 offset:3072
	ds_read_b128 v[200:203], v154 offset:4096
	ds_read_b128 v[204:207], v154 offset:5120
	ds_read_b128 v[208:211], v154 offset:6144
	ds_read_b128 v[212:215], v154 offset:7168
	s_waitcnt vmcnt(8)
	s_waitcnt lgkmcnt(0)
	s_barrier
	s_setprio 0
	s_waitcnt lgkmcnt(0)
	v_mfma_f32_16x16x32_bf16 v[126:129], v[146:149], v[184:187], v[126:129]
	v_mfma_f32_16x16x32_bf16 v[122:125], v[160:163], v[184:187], v[122:125]
	v_mfma_f32_16x16x32_bf16 v[118:121], v[146:149], v[192:195], v[118:121]
	v_mfma_f32_16x16x32_bf16 v[110:113], v[160:163], v[192:195], v[110:113]
	v_mfma_f32_16x16x32_bf16 v[102:105], v[146:149], v[200:203], v[102:105]
	v_mfma_f32_16x16x32_bf16 v[94:97], v[160:163], v[200:203], v[94:97]
	v_mfma_f32_16x16x32_bf16 v[86:89], v[146:149], v[208:211], v[86:89]
	v_mfma_f32_16x16x32_bf16 v[78:81], v[160:163], v[208:211], v[78:81]
	v_mfma_f32_16x16x32_bf16 v[126:129], v[156:159], v[188:191], v[126:129]
	v_mfma_f32_16x16x32_bf16 v[122:125], v[164:167], v[188:191], v[122:125]
	v_mfma_f32_16x16x32_bf16 v[118:121], v[156:159], v[196:199], v[118:121]
	v_mfma_f32_16x16x32_bf16 v[110:113], v[164:167], v[196:199], v[110:113]
	v_mfma_f32_16x16x32_bf16 v[102:105], v[156:159], v[204:207], v[102:105]
	v_mfma_f32_16x16x32_bf16 v[94:97], v[164:167], v[204:207], v[94:97]
	v_mfma_f32_16x16x32_bf16 v[86:89], v[156:159], v[212:215], v[86:89]
	v_mfma_f32_16x16x32_bf16 v[78:81], v[164:167], v[212:215], v[78:81]
	s_setprio 2
	s_setprio 0
	v_mfma_f32_16x16x32_bf16 v[114:117], v[168:171], v[184:187], v[114:117]
	v_mfma_f32_16x16x32_bf16 v[106:109], v[176:179], v[184:187], v[106:109]
	v_mfma_f32_16x16x32_bf16 v[98:101], v[168:171], v[192:195], v[98:101]
	v_mfma_f32_16x16x32_bf16 v[90:93], v[176:179], v[192:195], v[90:93]
	v_mfma_f32_16x16x32_bf16 v[82:85], v[168:171], v[200:203], v[82:85]
	v_mfma_f32_16x16x32_bf16 v[74:77], v[176:179], v[200:203], v[74:77]
	v_mfma_f32_16x16x32_bf16 v[70:73], v[168:171], v[208:211], v[70:73]
	v_mfma_f32_16x16x32_bf16 v[66:69], v[176:179], v[208:211], v[66:69]
	v_mfma_f32_16x16x32_bf16 v[114:117], v[172:175], v[188:191], v[114:117]
	v_mfma_f32_16x16x32_bf16 v[106:109], v[180:183], v[188:191], v[106:109]
	v_mfma_f32_16x16x32_bf16 v[98:101], v[172:175], v[196:199], v[98:101]
	v_mfma_f32_16x16x32_bf16 v[90:93], v[180:183], v[196:199], v[90:93]
	v_mfma_f32_16x16x32_bf16 v[82:85], v[172:175], v[204:207], v[82:85]
	v_mfma_f32_16x16x32_bf16 v[74:77], v[180:183], v[204:207], v[74:77]
	v_mfma_f32_16x16x32_bf16 v[70:73], v[172:175], v[212:215], v[70:73]
	v_mfma_f32_16x16x32_bf16 v[66:69], v[180:183], v[212:215], v[66:69]
	s_setprio 2
	s_barrier
	s_add_i32 s33, s61, s52
	v_lshl_add_u64 v[216:217], s[42:43], 0, v[134:135]
	s_mov_b32 m0, s33
	s_nop 0
	global_load_lds_dwordx4 v[216:217], off
	s_add_i32 m0, s33, 0x2000
	s_add_u32 s64, s42, 0x100000
	v_lshl_add_u64 v[218:219], s[42:43], 0, v[130:131]
	s_addc_u32 s65, s43, 0
	s_add_i32 s33, s62, s52
	global_load_lds_dwordx4 v[218:219], off
	v_lshl_add_u64 v[220:221], s[64:65], 0, v[134:135]
	s_mov_b32 m0, s33
	v_lshl_add_u64 v[222:223], s[44:45], 0, v[132:133]
	global_load_lds_dwordx4 v[220:221], off
	v_lshl_add_u64 v[220:221], s[64:65], 0, v[130:131]
	s_add_i32 m0, s33, 0x2000
	s_nop 0
	global_load_lds_dwordx4 v[220:221], off
	v_lshl_add_u64 v[220:221], s[44:45], 0, v[136:137]
	s_mov_b32 m0, s17
	s_nop 0
	global_load_lds_dwordx4 v[220:221], off
	s_mov_b32 m0, s37
	s_nop 0
	global_load_lds_dwordx4 v[222:223], off
	ds_read_b128 v[184:187], v154 offset:16384
	ds_read_b128 v[188:191], v154 offset:17408
	ds_read_b128 v[192:195], v154 offset:18432
	ds_read_b128 v[196:199], v154 offset:19456
	ds_read_b128 v[200:203], v154 offset:20480
	ds_read_b128 v[204:207], v154 offset:21504
	ds_read_b128 v[208:211], v154 offset:22528
	ds_read_b128 v[212:215], v154 offset:23552
	s_waitcnt vmcnt(8)
	s_waitcnt lgkmcnt(0)
	s_barrier
; #define PG8_STAGE(bufoff, gbase, voff) do { _Pragma("unroll") for (int _i = 0; _i < 2; ++_i) \
;         __builtin_amdgcn_global_load_lds((const unsigned*)((const char*)(gbase) + (voff)[_i]), (LAS unsigned*)(lds + (bufoff) + ldsw + _i * 8192), 16, 0, 0); } while (0)
; #define PG8_LDA(dst, b, h) do { _Pragma("unroll") for (int m = 0; m < 4; ++m) _Pragma("unroll") for (int k = 0; k < 2; ++k) dst[m][k] = *(const LAS bf16x8*)(lds + PG8_SA(b, h) + aoff + m * 2048 + k * 1024); } while (0)
; #define PG8_LDB(dst, b, h) do { _Pragma("unroll") for (int n = 0; n < 2; ++n) _Pragma("unroll") for (int k = 0; k < 2; ++k) dst[n][k] = *(const LAS bf16x8*)(lds + PG8_SB(b, h) + boff + n * 2048 + k * 1024); } while (0)
; #define PG8_MMA(ai, bj, At, Bt) do { __builtin_amdgcn_s_setprio(1); _Pragma("unroll") for (int m = 0; m < 4; ++m) _Pragma("unroll") for (int n = 0; n < 2; ++n) _Pragma("unroll") for (int k = 0; k < 2; ++k) \
;         acc[ai][bj][m][n] = __builtin_amdgcn_mfma_f32_16x16x32_bf16(Bt[n][k], At[m][k], acc[ai][bj][m][n], 0, 0, 0); __builtin_amdgcn_s_setprio(0); } while (0)
; #define PG8_WAIT_V(n) asm volatile("s_waitcnt vmcnt(" #n ")" ::: "memory")
; #define PG8_WAIT_L(n) asm volatile("s_waitcnt lgkmcnt(" #n ")" ::: "memory")
; #define PG8_BAR __builtin_amdgcn_s_barrier()
; #define PG8_SCHED __builtin_amdgcn_sched_barrier(0)
; template <class Epi>
; __device__ __forceinline__ void gemm_phase(LAS unsigned char* lds, const Gemm g, int G, int c, const Epi& E) {
;     ...
;             PG8_WAIT_V(8); PG8_WAIT_L(0); PG8_BAR; PG8_MMA(1, 0, At, B0); PG8_MMA(1, 1, At, B1); PG8_BAR; PG8_SCHED;
;             PG8_LDB(B0, 1, 0); PG8_LDB(B1, 1, 1); PG8_SCHED; PG8_LDA(At, 1, 0); PG8_STAGE(PG8_SA(0, 1), a2 + hstepA, voffA);
;             PG8_WAIT_V(8); PG8_WAIT_L(0); PG8_BAR; PG8_MMA(0, 0, At, B0); PG8_MMA(0, 1, At, B1); PG8_BAR; PG8_SCHED;
	s_setprio 0
	s_waitcnt lgkmcnt(0)
	v_mfma_f32_16x16x32_bf16 v[62:65], v[146:149], v[184:187], v[62:65]
	v_mfma_f32_16x16x32_bf16 v[58:61], v[160:163], v[184:187], v[58:61]
	v_mfma_f32_16x16x32_bf16 v[54:57], v[146:149], v[192:195], v[54:57]
	v_mfma_f32_16x16x32_bf16 v[46:49], v[160:163], v[192:195], v[46:49]
	v_mfma_f32_16x16x32_bf16 v[38:41], v[146:149], v[200:203], v[38:41]
	v_mfma_f32_16x16x32_bf16 v[30:33], v[160:163], v[200:203], v[30:33]
	v_mfma_f32_16x16x32_bf16 v[22:25], v[146:149], v[208:211], v[22:25]
	v_mfma_f32_16x16x32_bf16 v[14:17], v[160:163], v[208:211], v[14:17]
	v_mfma_f32_16x16x32_bf16 v[62:65], v[156:159], v[188:191], v[62:65]
	v_mfma_f32_16x16x32_bf16 v[58:61], v[164:167], v[188:191], v[58:61]
	v_mfma_f32_16x16x32_bf16 v[54:57], v[156:159], v[196:199], v[54:57]
	v_mfma_f32_16x16x32_bf16 v[46:49], v[164:167], v[196:199], v[46:49]
	v_mfma_f32_16x16x32_bf16 v[38:41], v[156:159], v[204:207], v[38:41]
	v_mfma_f32_16x16x32_bf16 v[30:33], v[164:167], v[204:207], v[30:33]
	v_mfma_f32_16x16x32_bf16 v[22:25], v[156:159], v[212:215], v[22:25]
	v_mfma_f32_16x16x32_bf16 v[14:17], v[164:167], v[212:215], v[14:17]
	s_setprio 2
	s_setprio 0
	v_mfma_f32_16x16x32_bf16 v[50:53], v[168:171], v[184:187], v[50:53]
	v_mfma_f32_16x16x32_bf16 v[42:45], v[176:179], v[184:187], v[42:45]
	v_mfma_f32_16x16x32_bf16 v[34:37], v[168:171], v[192:195], v[34:37]
	v_mfma_f32_16x16x32_bf16 v[26:29], v[176:179], v[192:195], v[26:29]
	v_mfma_f32_16x16x32_bf16 v[18:21], v[168:171], v[200:203], v[18:21]
	v_mfma_f32_16x16x32_bf16 v[10:13], v[176:179], v[200:203], v[10:13]
	v_mfma_f32_16x16x32_bf16 v[6:9], v[168:171], v[208:211], v[6:9]
	v_mfma_f32_16x16x32_bf16 v[2:5], v[176:179], v[208:211], v[2:5]
	v_mfma_f32_16x16x32_bf16 v[50:53], v[172:175], v[188:191], v[50:53]
	v_mfma_f32_16x16x32_bf16 v[42:45], v[180:183], v[188:191], v[42:45]
	v_mfma_f32_16x16x32_bf16 v[34:37], v[172:175], v[196:199], v[34:37]
	v_mfma_f32_16x16x32_bf16 v[26:29], v[180:183], v[196:199], v[26:29]
	v_mfma_f32_16x16x32_bf16 v[18:21], v[172:175], v[204:207], v[18:21]
	v_mfma_f32_16x16x32_bf16 v[10:13], v[180:183], v[204:207], v[10:13]
	v_mfma_f32_16x16x32_bf16 v[6:9], v[172:175], v[212:215], v[6:9]
	v_mfma_f32_16x16x32_bf16 v[2:5], v[180:183], v[212:215], v[2:5]
	s_setprio 2
	s_barrier
	s_add_i32 s33, 0, 0x18000
	s_add_i32 s64, 0, 0x1c000
	s_add_u32 s44, s44, 0x100000
	s_addc_u32 s45, s45, 0
	s_mov_b32 m0, s39
	v_lshl_add_u64 v[226:227], s[44:45], 0, v[136:137]
	global_load_lds_dwordx4 v[226:227], off
	v_lshl_add_u64 v[226:227], s[44:45], 0, v[132:133]
	s_mov_b32 m0, s53
	s_nop 0
	global_load_lds_dwordx4 v[226:227], off
	v_add_u32_e32 v155, s33, v151
	ds_read_b128 v[146:149], v155
	ds_read_b128 v[156:159], v155 offset:1024
	ds_read_b128 v[160:163], v155 offset:2048
	ds_read_b128 v[164:167], v155 offset:3072
	v_add_u32_e32 v155, s64, v151
	ds_read_b128 v[168:171], v155
	ds_read_b128 v[172:175], v155 offset:1024
	ds_read_b128 v[176:179], v155 offset:2048
	ds_read_b128 v[180:183], v155 offset:3072
	ds_read_b128 v[184:187], v154 offset:32768
	ds_read_b128 v[188:191], v154 offset:33792
	ds_read_b128 v[192:195], v154 offset:34816
	ds_read_b128 v[196:199], v154 offset:35840
	ds_read_b128 v[200:203], v154 offset:36864
	ds_read_b128 v[204:207], v154 offset:37888
	ds_read_b128 v[208:211], v154 offset:38912
	ds_read_b128 v[212:215], v154 offset:39936
	s_waitcnt vmcnt(8)
	s_waitcnt lgkmcnt(0)
	s_barrier
	s_setprio 0
	s_waitcnt lgkmcnt(0)
	v_mfma_f32_16x16x32_bf16 v[126:129], v[146:149], v[184:187], v[126:129]
	v_mfma_f32_16x16x32_bf16 v[122:125], v[160:163], v[184:187], v[122:125]
	v_mfma_f32_16x16x32_bf16 v[118:121], v[146:149], v[192:195], v[118:121]
	v_mfma_f32_16x16x32_bf16 v[110:113], v[160:163], v[192:195], v[110:113]
	v_mfma_f32_16x16x32_bf16 v[102:105], v[146:149], v[200:203], v[102:105]
	v_mfma_f32_16x16x32_bf16 v[94:97], v[160:163], v[200:203], v[94:97]
	v_mfma_f32_16x16x32_bf16 v[86:89], v[146:149], v[208:211], v[86:89]
	v_mfma_f32_16x16x32_bf16 v[78:81], v[160:163], v[208:211], v[78:81]
	v_mfma_f32_16x16x32_bf16 v[126:129], v[156:159], v[188:191], v[126:129]
	v_mfma_f32_16x16x32_bf16 v[122:125], v[164:167], v[188:191], v[122:125]
	v_mfma_f32_16x16x32_bf16 v[118:121], v[156:159], v[196:199], v[118:121]
	v_mfma_f32_16x16x32_bf16 v[110:113], v[164:167], v[196:199], v[110:113]
	v_mfma_f32_16x16x32_bf16 v[102:105], v[156:159], v[204:207], v[102:105]
	v_mfma_f32_16x16x32_bf16 v[94:97], v[164:167], v[204:207], v[94:97]
	v_mfma_f32_16x16x32_bf16 v[86:89], v[156:159], v[212:215], v[86:89]
	v_mfma_f32_16x16x32_bf16 v[78:81], v[164:167], v[212:215], v[78:81]
	s_setprio 2
	s_setprio 0
	v_mfma_f32_16x16x32_bf16 v[114:117], v[168:171], v[184:187], v[114:117]
	v_mfma_f32_16x16x32_bf16 v[106:109], v[176:179], v[184:187], v[106:109]
	v_mfma_f32_16x16x32_bf16 v[98:101], v[168:171], v[192:195], v[98:101]
	v_mfma_f32_16x16x32_bf16 v[90:93], v[176:179], v[192:195], v[90:93]
	v_mfma_f32_16x16x32_bf16 v[82:85], v[168:171], v[200:203], v[82:85]
	v_mfma_f32_16x16x32_bf16 v[74:77], v[176:179], v[200:203], v[74:77]
	v_mfma_f32_16x16x32_bf16 v[70:73], v[168:171], v[208:211], v[70:73]
	v_mfma_f32_16x16x32_bf16 v[66:69], v[176:179], v[208:211], v[66:69]
	v_mfma_f32_16x16x32_bf16 v[114:117], v[172:175], v[188:191], v[114:117]
	v_mfma_f32_16x16x32_bf16 v[106:109], v[180:183], v[188:191], v[106:109]
	v_mfma_f32_16x16x32_bf16 v[98:101], v[172:175], v[196:199], v[98:101]
	v_mfma_f32_16x16x32_bf16 v[90:93], v[180:183], v[196:199], v[90:93]
	v_mfma_f32_16x16x32_bf16 v[82:85], v[172:175], v[204:207], v[82:85]
	v_mfma_f32_16x16x32_bf16 v[74:77], v[180:183], v[204:207], v[74:77]
	v_mfma_f32_16x16x32_bf16 v[70:73], v[172:175], v[212:215], v[70:73]
	v_mfma_f32_16x16x32_bf16 v[66:69], v[180:183], v[212:215], v[66:69]
	s_setprio 2
	s_barrier
; #define PG8_STAGE(bufoff, gbase, voff) do { _Pragma("unroll") for (int _i = 0; _i < 2; ++_i) \
;         __builtin_amdgcn_global_load_lds((const unsigned*)((const char*)(gbase) + (voff)[_i]), (LAS unsigned*)(lds + (bufoff) + ldsw + _i * 8192), 16, 0, 0); } while (0)
; #define PG8_LDA(dst, b, h) do { _Pragma("unroll") for (int m = 0; m < 4; ++m) _Pragma("unroll") for (int k = 0; k < 2; ++k) dst[m][k] = *(const LAS bf16x8*)(lds + PG8_SA(b, h) + aoff + m * 2048 + k * 1024); } while (0)
; #define PG8_MMA(ai, bj, At, Bt) do { __builtin_amdgcn_s_setprio(1); _Pragma("unroll") for (int m = 0; m < 4; ++m) _Pragma("unroll") for (int n = 0; n < 2; ++n) _Pragma("unroll") for (int k = 0; k < 2; ++k) \
;         acc[ai][bj][m][n] = __builtin_amdgcn_mfma_f32_16x16x32_bf16(Bt[n][k], At[m][k], acc[ai][bj][m][n], 0, 0, 0); __builtin_amdgcn_s_setprio(0); } while (0)
; #define PG8_WAIT_V(n) asm volatile("s_waitcnt vmcnt(" #n ")" ::: "memory")
; #define PG8_WAIT_L(n) asm volatile("s_waitcnt lgkmcnt(" #n ")" ::: "memory")
; #define PG8_BAR __builtin_amdgcn_s_barrier()
; #define PG8_SCHED __builtin_amdgcn_sched_barrier(0)
; template <class Epi>
; __device__ __forceinline__ void gemm_phase(LAS unsigned char* lds, const Gemm g, int G, int c, const Epi& E) {
;     ...
;             PG8_LDA(At, 1, 1); PG8_STAGE(PG8_SB(1, 0), b3, voffB); PG8_STAGE(PG8_SB(1, 1), b3 + hstepB, voffB); PG8_STAGE(PG8_SA(1, 0), a3, voffA);
;             PG8_WAIT_V(8); PG8_WAIT_L(0); PG8_BAR; PG8_MMA(1, 0, At, B0); PG8_MMA(1, 1, At, B1); PG8_BAR; PG8_SCHED;
;         }
;         if (wr == 0) PG8_BAR;
	s_add_i32 s33, s33, s52
	v_lshl_add_u64 v[216:217], v[216:217], 0, s[6:7]
	s_mov_b32 m0, s33
	s_nop 0
	global_load_lds_dwordx4 v[216:217], off
	s_add_i32 m0, s33, 0x2000
	s_add_u32 s42, s42, 0x100080
	v_lshl_add_u64 v[216:217], v[218:219], 0, s[6:7]
	s_addc_u32 s43, s43, 0
	s_add_i32 s33, s64, s52
	global_load_lds_dwordx4 v[216:217], off
	v_lshl_add_u64 v[216:217], s[42:43], 0, v[134:135]
	s_mov_b32 m0, s33
	s_nop 0
	global_load_lds_dwordx4 v[216:217], off
	v_lshl_add_u64 v[216:217], s[42:43], 0, v[130:131]
	s_add_i32 m0, s33, 0x2000
	s_nop 0
	global_load_lds_dwordx4 v[216:217], off
	v_lshl_add_u64 v[216:217], v[220:221], 0, s[6:7]
	s_mov_b32 m0, s59
	s_nop 0
	global_load_lds_dwordx4 v[216:217], off
	v_lshl_add_u64 v[216:217], v[222:223], 0, s[6:7]
	s_mov_b32 m0, s60
	s_nop 0
	global_load_lds_dwordx4 v[216:217], off
	ds_read_b128 v[184:187], v154 offset:49152
	ds_read_b128 v[188:191], v154 offset:50176
	ds_read_b128 v[192:195], v154 offset:51200
	ds_read_b128 v[196:199], v154 offset:52224
	ds_read_b128 v[200:203], v154 offset:53248
	ds_read_b128 v[204:207], v154 offset:54272
	ds_read_b128 v[208:211], v154 offset:55296
	ds_read_b128 v[212:215], v154 offset:56320
	s_waitcnt vmcnt(8)
	s_waitcnt lgkmcnt(0)
	s_barrier
	s_setprio 0
	s_waitcnt lgkmcnt(0)
	v_mfma_f32_16x16x32_bf16 v[62:65], v[146:149], v[184:187], v[62:65]
	v_mfma_f32_16x16x32_bf16 v[58:61], v[160:163], v[184:187], v[58:61]
	v_mfma_f32_16x16x32_bf16 v[54:57], v[146:149], v[192:195], v[54:57]
	v_mfma_f32_16x16x32_bf16 v[46:49], v[160:163], v[192:195], v[46:49]
	v_mfma_f32_16x16x32_bf16 v[38:41], v[146:149], v[200:203], v[38:41]
	v_mfma_f32_16x16x32_bf16 v[30:33], v[160:163], v[200:203], v[30:33]
	v_mfma_f32_16x16x32_bf16 v[22:25], v[146:149], v[208:211], v[22:25]
	v_mfma_f32_16x16x32_bf16 v[14:17], v[160:163], v[208:211], v[14:17]
	v_mfma_f32_16x16x32_bf16 v[62:65], v[156:159], v[188:191], v[62:65]
	v_mfma_f32_16x16x32_bf16 v[58:61], v[164:167], v[188:191], v[58:61]
	v_mfma_f32_16x16x32_bf16 v[54:57], v[156:159], v[196:199], v[54:57]
	v_mfma_f32_16x16x32_bf16 v[46:49], v[164:167], v[196:199], v[46:49]
	v_mfma_f32_16x16x32_bf16 v[38:41], v[156:159], v[204:207], v[38:41]
	v_mfma_f32_16x16x32_bf16 v[30:33], v[164:167], v[204:207], v[30:33]
	v_mfma_f32_16x16x32_bf16 v[22:25], v[156:159], v[212:215], v[22:25]
	v_mfma_f32_16x16x32_bf16 v[14:17], v[164:167], v[212:215], v[14:17]
	s_setprio 2
	s_setprio 0
	v_mfma_f32_16x16x32_bf16 v[50:53], v[168:171], v[184:187], v[50:53]
	v_mfma_f32_16x16x32_bf16 v[42:45], v[176:179], v[184:187], v[42:45]
	v_mfma_f32_16x16x32_bf16 v[34:37], v[168:171], v[192:195], v[34:37]
	v_mfma_f32_16x16x32_bf16 v[26:29], v[176:179], v[192:195], v[26:29]
	v_mfma_f32_16x16x32_bf16 v[18:21], v[168:171], v[200:203], v[18:21]
	v_mfma_f32_16x16x32_bf16 v[10:13], v[176:179], v[200:203], v[10:13]
	v_mfma_f32_16x16x32_bf16 v[6:9], v[168:171], v[208:211], v[6:9]
	v_mfma_f32_16x16x32_bf16 v[2:5], v[176:179], v[208:211], v[2:5]
	v_mfma_f32_16x16x32_bf16 v[50:53], v[172:175], v[188:191], v[50:53]
	v_mfma_f32_16x16x32_bf16 v[42:45], v[180:183], v[188:191], v[42:45]
	v_mfma_f32_16x16x32_bf16 v[34:37], v[172:175], v[196:199], v[34:37]
	v_mfma_f32_16x16x32_bf16 v[26:29], v[180:183], v[196:199], v[26:29]
	v_mfma_f32_16x16x32_bf16 v[18:21], v[172:175], v[204:207], v[18:21]
	v_mfma_f32_16x16x32_bf16 v[10:13], v[180:183], v[204:207], v[10:13]
	v_mfma_f32_16x16x32_bf16 v[6:9], v[172:175], v[212:215], v[6:9]
	v_mfma_f32_16x16x32_bf16 v[2:5], v[180:183], v[212:215], v[2:5]
	s_setprio 2
	s_barrier
	s_add_i32 s68, s68, 2
	s_add_u32 s40, s40, 0x100
	s_addc_u32 s41, s41, 0
	s_add_u32 s66, s66, 0x100
	s_addc_u32 s67, s67, 0
	s_cmp_gt_u32 s68, 61
	s_cbranch_scc0 .LBB0_1825
	s_and_b64 vcc, exec, s[8:9]
	s_cbranch_vccz .LBB0_1828
	s_barrier

; #define PG8_STAGE(bufoff, gbase, voff) do { _Pragma("unroll") for (int _i = 0; _i < 2; ++_i) \
;         __builtin_amdgcn_global_load_lds((const unsigned*)((const char*)(gbase) + (voff)[_i]), (LAS unsigned*)(lds + (bufoff) + ldsw + _i * 8192), 16, 0, 0); } while (0)
; #define PG8_LDA(dst, b, h) do { _Pragma("unroll") for (int m = 0; m < 4; ++m) _Pragma("unroll") for (int k = 0; k < 2; ++k) dst[m][k] = *(const LAS bf16x8*)(lds + PG8_SA(b, h) + aoff + m * 2048 + k * 1024); } while (0)
; #define PG8_LDB(dst, b, h) do { _Pragma("unroll") for (int n = 0; n < 2; ++n) _Pragma("unroll") for (int k = 0; k < 2; ++k) dst[n][k] = *(const LAS bf16x8*)(lds + PG8_SB(b, h) + boff + n * 2048 + k * 1024); } while (0)
; #define PG8_MMA(ai, bj, At, Bt) do { __builtin_amdgcn_s_setprio(1); _Pragma("unroll") for (int m = 0; m < 4; ++m) _Pragma("unroll") for (int n = 0; n < 2; ++n) _Pragma("unroll") for (int k = 0; k < 2; ++k) \
;         acc[ai][bj][m][n] = __builtin_amdgcn_mfma_f32_16x16x32_bf16(Bt[n][k], At[m][k], acc[ai][bj][m][n], 0, 0, 0); __builtin_amdgcn_s_setprio(0); } while (0)
; #define PG8_WAIT_V(n) asm volatile("s_waitcnt vmcnt(" #n ")" ::: "memory")
; #define PG8_WAIT_L(n) asm volatile("s_waitcnt lgkmcnt(" #n ")" ::: "memory")
; #define PG8_BAR __builtin_amdgcn_s_barrier()
; #define PG8_SCHED __builtin_amdgcn_sched_barrier(0)
; template <class Epi>
; __device__ __forceinline__ void gemm_phase(LAS unsigned char* lds, const Gemm g, int G, int c, const Epi& E) {
;     ...
;             const char* a1 = cA + (size_t)(t + 1) * kstep;
;             const char* a2 = last ? nA : cA + (size_t)(t + 2) * kstep; const char* b2 = last ? nB : cB + (size_t)(t + 2) * kstep;
;             const char* a3 = a2 + kstep; const char* b3 = b2 + kstep;
;             PG8_LDB(B0, 0, 0); PG8_LDB(B1, 0, 1); PG8_SCHED; PG8_LDA(At, 0, 0); PG8_STAGE(PG8_SA(1, 1), a1 + hstepA, voffA);
;             PG8_WAIT_V(8); PG8_WAIT_L(0); PG8_BAR; PG8_MMA(0, 0, At, B0); PG8_MMA(0, 1, At, B1); PG8_BAR; PG8_SCHED;
;             PG8_LDA(At, 0, 1); PG8_STAGE(PG8_SB(0, 0), b2, voffB); PG8_STAGE(PG8_SB(0, 1), b2 + hstepB, voffB); PG8_STAGE(PG8_SA(0, 0), a2, voffA);
;             PG8_WAIT_V(8); PG8_WAIT_L(0); PG8_BAR; PG8_MMA(1, 0, At, B0); PG8_MMA(1, 1, At, B1); PG8_BAR; PG8_SCHED;
.LBB0_1931:
	s_add_u32 s33, s4, 0xfffc0080
	s_addc_u32 s36, s5, -1
	s_cmp_eq_u32 s62, 12
	s_cselect_b32 s39, s19, s36
	s_cselect_b32 s38, s18, s33
	s_cselect_b32 s37, s15, s61
	s_cselect_b32 s36, s17, s60
	v_lshl_add_u64 v[216:217], s[4:5], 0, v[154:155]
	s_add_i32 m0, s23, 0xc000
	s_nop 0
	global_load_lds_dwordx4 v[216:217], off
	v_lshl_add_u64 v[216:217], s[4:5], 0, v[156:157]
	s_add_i32 m0, s23, 0xe000
	s_nop 0
	global_load_lds_dwordx4 v[216:217], off
	ds_read_b128 v[122:125], v168
	ds_read_b128 v[126:129], v168 offset:1024
	ds_read_b128 v[130:133], v168 offset:2048
	ds_read_b128 v[134:137], v168 offset:3072
	ds_read_b128 v[162:165], v169
	ds_read_b128 v[172:175], v169 offset:1024
	ds_read_b128 v[176:179], v169 offset:2048
	ds_read_b128 v[180:183], v169 offset:3072
	ds_read_b128 v[184:187], v170
	ds_read_b128 v[188:191], v170 offset:1024
	ds_read_b128 v[192:195], v170 offset:2048
	ds_read_b128 v[196:199], v170 offset:3072
	ds_read_b128 v[200:203], v170 offset:4096
	ds_read_b128 v[204:207], v170 offset:5120
	ds_read_b128 v[208:211], v170 offset:6144
	ds_read_b128 v[212:215], v170 offset:7168
	s_waitcnt vmcnt(8)
	s_waitcnt lgkmcnt(0)
	s_barrier
	s_setprio 0
	s_waitcnt lgkmcnt(0)
	v_mfma_f32_16x16x32_bf16 v[142:145], v[122:125], v[184:187], v[142:145]
	v_mfma_f32_16x16x32_bf16 v[138:141], v[130:133], v[184:187], v[138:141]
	v_mfma_f32_16x16x32_bf16 v[118:121], v[122:125], v[192:195], v[118:121]
	v_mfma_f32_16x16x32_bf16 v[106:109], v[130:133], v[192:195], v[106:109]
	v_mfma_f32_16x16x32_bf16 v[102:105], v[122:125], v[200:203], v[102:105]
	v_mfma_f32_16x16x32_bf16 v[90:93], v[130:133], v[200:203], v[90:93]
	v_mfma_f32_16x16x32_bf16 v[86:89], v[122:125], v[208:211], v[86:89]
	v_mfma_f32_16x16x32_bf16 v[74:77], v[130:133], v[208:211], v[74:77]
	v_mfma_f32_16x16x32_bf16 v[142:145], v[126:129], v[188:191], v[142:145]
	v_mfma_f32_16x16x32_bf16 v[138:141], v[134:137], v[188:191], v[138:141]
	v_mfma_f32_16x16x32_bf16 v[118:121], v[126:129], v[196:199], v[118:121]
	v_mfma_f32_16x16x32_bf16 v[106:109], v[134:137], v[196:199], v[106:109]
	v_mfma_f32_16x16x32_bf16 v[102:105], v[126:129], v[204:207], v[102:105]
	v_mfma_f32_16x16x32_bf16 v[90:93], v[134:137], v[204:207], v[90:93]
	v_mfma_f32_16x16x32_bf16 v[86:89], v[126:129], v[212:215], v[86:89]
	v_mfma_f32_16x16x32_bf16 v[74:77], v[134:137], v[212:215], v[74:77]
	s_setprio 2
	s_setprio 0
	v_mfma_f32_16x16x32_bf16 v[114:117], v[162:165], v[184:187], v[114:117]
	v_mfma_f32_16x16x32_bf16 v[110:113], v[176:179], v[184:187], v[110:113]
	v_mfma_f32_16x16x32_bf16 v[98:101], v[162:165], v[192:195], v[98:101]
	v_mfma_f32_16x16x32_bf16 v[94:97], v[176:179], v[192:195], v[94:97]
	v_mfma_f32_16x16x32_bf16 v[82:85], v[162:165], v[200:203], v[82:85]
	v_mfma_f32_16x16x32_bf16 v[78:81], v[176:179], v[200:203], v[78:81]
	v_mfma_f32_16x16x32_bf16 v[70:73], v[162:165], v[208:211], v[70:73]
	v_mfma_f32_16x16x32_bf16 v[66:69], v[176:179], v[208:211], v[66:69]
	v_mfma_f32_16x16x32_bf16 v[114:117], v[172:175], v[188:191], v[114:117]
	v_mfma_f32_16x16x32_bf16 v[110:113], v[180:183], v[188:191], v[110:113]
	v_mfma_f32_16x16x32_bf16 v[98:101], v[172:175], v[196:199], v[98:101]
	v_mfma_f32_16x16x32_bf16 v[94:97], v[180:183], v[196:199], v[94:97]
	v_mfma_f32_16x16x32_bf16 v[82:85], v[172:175], v[204:207], v[82:85]
	v_mfma_f32_16x16x32_bf16 v[78:81], v[180:183], v[204:207], v[78:81]
	v_mfma_f32_16x16x32_bf16 v[70:73], v[172:175], v[212:215], v[70:73]
	v_mfma_f32_16x16x32_bf16 v[66:69], v[180:183], v[212:215], v[66:69]
	s_setprio 2
	s_barrier
	s_add_i32 s33, s56, s42
	v_lshl_add_u64 v[216:217], s[36:37], 0, v[150:151]
	s_mov_b32 m0, s33
	s_nop 0
	global_load_lds_dwordx4 v[216:217], off
	s_add_i32 m0, s33, 0x2000
	s_add_u32 s64, s36, 0x40000
	v_lshl_add_u64 v[218:219], s[36:37], 0, v[146:147]
	s_addc_u32 s65, s37, 0
	s_add_i32 s33, s57, s42
	global_load_lds_dwordx4 v[218:219], off
	v_lshl_add_u64 v[220:221], s[64:65], 0, v[150:151]
	s_mov_b32 m0, s33
	v_lshl_add_u64 v[222:223], s[38:39], 0, v[148:149]
	global_load_lds_dwordx4 v[220:221], off
	v_lshl_add_u64 v[220:221], s[64:65], 0, v[146:147]
	s_add_i32 m0, s33, 0x2000
	s_nop 0
	global_load_lds_dwordx4 v[220:221], off
	v_lshl_add_u64 v[220:221], s[38:39], 0, v[152:153]
	s_mov_b32 m0, s23
	s_nop 0
	global_load_lds_dwordx4 v[220:221], off
	s_mov_b32 m0, s25
	s_nop 0
	global_load_lds_dwordx4 v[222:223], off
	ds_read_b128 v[184:187], v170 offset:16384
	ds_read_b128 v[188:191], v170 offset:17408
	ds_read_b128 v[192:195], v170 offset:18432
	ds_read_b128 v[196:199], v170 offset:19456
	ds_read_b128 v[200:203], v170 offset:20480
	ds_read_b128 v[204:207], v170 offset:21504
	ds_read_b128 v[208:211], v170 offset:22528
	ds_read_b128 v[212:215], v170 offset:23552
	s_waitcnt vmcnt(8)
	s_waitcnt lgkmcnt(0)
	s_barrier
; #define PG8_STAGE(bufoff, gbase, voff) do { _Pragma("unroll") for (int _i = 0; _i < 2; ++_i) \
;         __builtin_amdgcn_global_load_lds((const unsigned*)((const char*)(gbase) + (voff)[_i]), (LAS unsigned*)(lds + (bufoff) + ldsw + _i * 8192), 16, 0, 0); } while (0)
; #define PG8_LDA(dst, b, h) do { _Pragma("unroll") for (int m = 0; m < 4; ++m) _Pragma("unroll") for (int k = 0; k < 2; ++k) dst[m][k] = *(const LAS bf16x8*)(lds + PG8_SA(b, h) + aoff + m * 2048 + k * 1024); } while (0)
; #define PG8_LDB(dst, b, h) do { _Pragma("unroll") for (int n = 0; n < 2; ++n) _Pragma("unroll") for (int k = 0; k < 2; ++k) dst[n][k] = *(const LAS bf16x8*)(lds + PG8_SB(b, h) + boff + n * 2048 + k * 1024); } while (0)
; #define PG8_MMA(ai, bj, At, Bt) do { __builtin_amdgcn_s_setprio(1); _Pragma("unroll") for (int m = 0; m < 4; ++m) _Pragma("unroll") for (int n = 0; n < 2; ++n) _Pragma("unroll") for (int k = 0; k < 2; ++k) \
;         acc[ai][bj][m][n] = __builtin_amdgcn_mfma_f32_16x16x32_bf16(Bt[n][k], At[m][k], acc[ai][bj][m][n], 0, 0, 0); __builtin_amdgcn_s_setprio(0); } while (0)
; #define PG8_WAIT_V(n) asm volatile("s_waitcnt vmcnt(" #n ")" ::: "memory")
; #define PG8_WAIT_L(n) asm volatile("s_waitcnt lgkmcnt(" #n ")" ::: "memory")
; #define PG8_BAR __builtin_amdgcn_s_barrier()
; #define PG8_SCHED __builtin_amdgcn_sched_barrier(0)
; template <class Epi>
; __device__ __forceinline__ void gemm_phase(LAS unsigned char* lds, const Gemm g, int G, int c, const Epi& E) {
;     ...
;             PG8_WAIT_V(8); PG8_WAIT_L(0); PG8_BAR; PG8_MMA(1, 0, At, B0); PG8_MMA(1, 1, At, B1); PG8_BAR; PG8_SCHED;
;             PG8_LDB(B0, 1, 0); PG8_LDB(B1, 1, 1); PG8_SCHED; PG8_LDA(At, 1, 0); PG8_STAGE(PG8_SA(0, 1), a2 + hstepA, voffA);
;             PG8_WAIT_V(8); PG8_WAIT_L(0); PG8_BAR; PG8_MMA(0, 0, At, B0); PG8_MMA(0, 1, At, B1); PG8_BAR; PG8_SCHED;
	s_setprio 0
	s_waitcnt lgkmcnt(0)
	v_mfma_f32_16x16x32_bf16 v[62:65], v[122:125], v[184:187], v[62:65]
	v_mfma_f32_16x16x32_bf16 v[58:61], v[130:133], v[184:187], v[58:61]
	v_mfma_f32_16x16x32_bf16 v[54:57], v[122:125], v[192:195], v[54:57]
	v_mfma_f32_16x16x32_bf16 v[42:45], v[130:133], v[192:195], v[42:45]
	v_mfma_f32_16x16x32_bf16 v[38:41], v[122:125], v[200:203], v[38:41]
	v_mfma_f32_16x16x32_bf16 v[26:29], v[130:133], v[200:203], v[26:29]
	v_mfma_f32_16x16x32_bf16 v[22:25], v[122:125], v[208:211], v[22:25]
	v_mfma_f32_16x16x32_bf16 v[10:13], v[130:133], v[208:211], v[10:13]
	v_mfma_f32_16x16x32_bf16 v[62:65], v[126:129], v[188:191], v[62:65]
	v_mfma_f32_16x16x32_bf16 v[58:61], v[134:137], v[188:191], v[58:61]
	v_mfma_f32_16x16x32_bf16 v[54:57], v[126:129], v[196:199], v[54:57]
	v_mfma_f32_16x16x32_bf16 v[42:45], v[134:137], v[196:199], v[42:45]
	v_mfma_f32_16x16x32_bf16 v[38:41], v[126:129], v[204:207], v[38:41]
	v_mfma_f32_16x16x32_bf16 v[26:29], v[134:137], v[204:207], v[26:29]
	v_mfma_f32_16x16x32_bf16 v[22:25], v[126:129], v[212:215], v[22:25]
	v_mfma_f32_16x16x32_bf16 v[10:13], v[134:137], v[212:215], v[10:13]
	s_setprio 2
	s_setprio 0
	v_mfma_f32_16x16x32_bf16 v[50:53], v[162:165], v[184:187], v[50:53]
	v_mfma_f32_16x16x32_bf16 v[46:49], v[176:179], v[184:187], v[46:49]
	v_mfma_f32_16x16x32_bf16 v[34:37], v[162:165], v[192:195], v[34:37]
	v_mfma_f32_16x16x32_bf16 v[30:33], v[176:179], v[192:195], v[30:33]
	v_mfma_f32_16x16x32_bf16 v[18:21], v[162:165], v[200:203], v[18:21]
	v_mfma_f32_16x16x32_bf16 v[14:17], v[176:179], v[200:203], v[14:17]
	v_mfma_f32_16x16x32_bf16 v[6:9], v[162:165], v[208:211], v[6:9]
	v_mfma_f32_16x16x32_bf16 v[2:5], v[176:179], v[208:211], v[2:5]
	v_mfma_f32_16x16x32_bf16 v[50:53], v[172:175], v[188:191], v[50:53]
	v_mfma_f32_16x16x32_bf16 v[46:49], v[180:183], v[188:191], v[46:49]
	v_mfma_f32_16x16x32_bf16 v[34:37], v[172:175], v[196:199], v[34:37]
	v_mfma_f32_16x16x32_bf16 v[30:33], v[180:183], v[196:199], v[30:33]
	v_mfma_f32_16x16x32_bf16 v[18:21], v[172:175], v[204:207], v[18:21]
	v_mfma_f32_16x16x32_bf16 v[14:17], v[180:183], v[204:207], v[14:17]
	v_mfma_f32_16x16x32_bf16 v[6:9], v[172:175], v[212:215], v[6:9]
	v_mfma_f32_16x16x32_bf16 v[2:5], v[180:183], v[212:215], v[2:5]
	s_setprio 2
	s_barrier
	s_add_i32 s33, 0, 0x18000
	s_add_i32 s63, 0, 0x1c000
	s_add_u32 s38, s38, 0x40000
	s_addc_u32 s39, s39, 0
	s_mov_b32 m0, s44
	v_lshl_add_u64 v[224:225], s[38:39], 0, v[152:153]
	global_load_lds_dwordx4 v[224:225], off
	v_lshl_add_u64 v[224:225], s[38:39], 0, v[148:149]
	s_mov_b32 m0, s45
	s_nop 0
	global_load_lds_dwordx4 v[224:225], off
	v_add_u32_e32 v134, s33, v167
	v_add_u32_e32 v171, s63, v167
	ds_read_b128 v[122:125], v134
	ds_read_b128 v[126:129], v134 offset:1024
	ds_read_b128 v[130:133], v134 offset:2048
	ds_read_b128 v[134:137], v134 offset:3072
	ds_read_b128 v[162:165], v171
	ds_read_b128 v[172:175], v171 offset:1024
	ds_read_b128 v[176:179], v171 offset:2048
	ds_read_b128 v[180:183], v171 offset:3072
	ds_read_b128 v[184:187], v170 offset:32768
	ds_read_b128 v[188:191], v170 offset:33792
	ds_read_b128 v[192:195], v170 offset:34816
	ds_read_b128 v[196:199], v170 offset:35840
	ds_read_b128 v[200:203], v170 offset:36864
	ds_read_b128 v[204:207], v170 offset:37888
	ds_read_b128 v[208:211], v170 offset:38912
	ds_read_b128 v[212:215], v170 offset:39936
	s_waitcnt vmcnt(8)
	s_waitcnt lgkmcnt(0)
	s_barrier
	s_setprio 0
	s_waitcnt lgkmcnt(0)
	v_mfma_f32_16x16x32_bf16 v[142:145], v[122:125], v[184:187], v[142:145]
	v_mfma_f32_16x16x32_bf16 v[138:141], v[130:133], v[184:187], v[138:141]
	v_mfma_f32_16x16x32_bf16 v[118:121], v[122:125], v[192:195], v[118:121]
	v_mfma_f32_16x16x32_bf16 v[106:109], v[130:133], v[192:195], v[106:109]
	v_mfma_f32_16x16x32_bf16 v[102:105], v[122:125], v[200:203], v[102:105]
	v_mfma_f32_16x16x32_bf16 v[90:93], v[130:133], v[200:203], v[90:93]
	v_mfma_f32_16x16x32_bf16 v[86:89], v[122:125], v[208:211], v[86:89]
	v_mfma_f32_16x16x32_bf16 v[74:77], v[130:133], v[208:211], v[74:77]
	v_mfma_f32_16x16x32_bf16 v[142:145], v[126:129], v[188:191], v[142:145]
	v_mfma_f32_16x16x32_bf16 v[138:141], v[134:137], v[188:191], v[138:141]
	v_mfma_f32_16x16x32_bf16 v[118:121], v[126:129], v[196:199], v[118:121]
	v_mfma_f32_16x16x32_bf16 v[106:109], v[134:137], v[196:199], v[106:109]
	v_mfma_f32_16x16x32_bf16 v[102:105], v[126:129], v[204:207], v[102:105]
	v_mfma_f32_16x16x32_bf16 v[90:93], v[134:137], v[204:207], v[90:93]
	v_mfma_f32_16x16x32_bf16 v[86:89], v[126:129], v[212:215], v[86:89]
	v_mfma_f32_16x16x32_bf16 v[74:77], v[134:137], v[212:215], v[74:77]
	s_setprio 2
	s_setprio 0
	v_mfma_f32_16x16x32_bf16 v[114:117], v[162:165], v[184:187], v[114:117]
	v_mfma_f32_16x16x32_bf16 v[110:113], v[176:179], v[184:187], v[110:113]
	v_mfma_f32_16x16x32_bf16 v[98:101], v[162:165], v[192:195], v[98:101]
	v_mfma_f32_16x16x32_bf16 v[94:97], v[176:179], v[192:195], v[94:97]
	v_mfma_f32_16x16x32_bf16 v[82:85], v[162:165], v[200:203], v[82:85]
	v_mfma_f32_16x16x32_bf16 v[78:81], v[176:179], v[200:203], v[78:81]
	v_mfma_f32_16x16x32_bf16 v[70:73], v[162:165], v[208:211], v[70:73]
	v_mfma_f32_16x16x32_bf16 v[66:69], v[176:179], v[208:211], v[66:69]
	v_mfma_f32_16x16x32_bf16 v[114:117], v[172:175], v[188:191], v[114:117]
	v_mfma_f32_16x16x32_bf16 v[110:113], v[180:183], v[188:191], v[110:113]
	v_mfma_f32_16x16x32_bf16 v[98:101], v[172:175], v[196:199], v[98:101]
	v_mfma_f32_16x16x32_bf16 v[94:97], v[180:183], v[196:199], v[94:97]
	v_mfma_f32_16x16x32_bf16 v[82:85], v[172:175], v[204:207], v[82:85]
	v_mfma_f32_16x16x32_bf16 v[78:81], v[180:183], v[204:207], v[78:81]
	v_mfma_f32_16x16x32_bf16 v[70:73], v[172:175], v[212:215], v[70:73]
	v_mfma_f32_16x16x32_bf16 v[66:69], v[180:183], v[212:215], v[66:69]
	s_setprio 2
	s_barrier
; #define PG8_STAGE(bufoff, gbase, voff) do { _Pragma("unroll") for (int _i = 0; _i < 2; ++_i) \
;         __builtin_amdgcn_global_load_lds((const unsigned*)((const char*)(gbase) + (voff)[_i]), (LAS unsigned*)(lds + (bufoff) + ldsw + _i * 8192), 16, 0, 0); } while (0)
; #define PG8_LDA(dst, b, h) do { _Pragma("unroll") for (int m = 0; m < 4; ++m) _Pragma("unroll") for (int k = 0; k < 2; ++k) dst[m][k] = *(const LAS bf16x8*)(lds + PG8_SA(b, h) + aoff + m * 2048 + k * 1024); } while (0)
; #define PG8_MMA(ai, bj, At, Bt) do { __builtin_amdgcn_s_setprio(1); _Pragma("unroll") for (int m = 0; m < 4; ++m) _Pragma("unroll") for (int n = 0; n < 2; ++n) _Pragma("unroll") for (int k = 0; k < 2; ++k) \
;         acc[ai][bj][m][n] = __builtin_amdgcn_mfma_f32_16x16x32_bf16(Bt[n][k], At[m][k], acc[ai][bj][m][n], 0, 0, 0); __builtin_amdgcn_s_setprio(0); } while (0)
; #define PG8_WAIT_V(n) asm volatile("s_waitcnt vmcnt(" #n ")" ::: "memory")
; #define PG8_WAIT_L(n) asm volatile("s_waitcnt lgkmcnt(" #n ")" ::: "memory")
; #define PG8_BAR __builtin_amdgcn_s_barrier()
; #define PG8_SCHED __builtin_amdgcn_sched_barrier(0)
; template <class Epi>
; __device__ __forceinline__ void gemm_phase(LAS unsigned char* lds, const Gemm g, int G, int c, const Epi& E) {
;     ...
;             PG8_LDA(At, 1, 1); PG8_STAGE(PG8_SB(1, 0), b3, voffB); PG8_STAGE(PG8_SB(1, 1), b3 + hstepB, voffB); PG8_STAGE(PG8_SA(1, 0), a3, voffA);
;             PG8_WAIT_V(8); PG8_WAIT_L(0); PG8_BAR; PG8_MMA(1, 0, At, B0); PG8_MMA(1, 1, At, B1); PG8_BAR; PG8_SCHED;
;         }
;         if (wr == 0) PG8_BAR;
	s_add_i32 s33, s33, s42
	v_lshl_add_u64 v[216:217], v[216:217], 0, s[10:11]
	s_mov_b32 m0, s33
	s_nop 0
	global_load_lds_dwordx4 v[216:217], off
	s_add_i32 m0, s33, 0x2000
	s_add_u32 s36, s36, 0x40080
	v_lshl_add_u64 v[216:217], v[218:219], 0, s[10:11]
	s_addc_u32 s37, s37, 0
	s_add_i32 s33, s63, s42
	global_load_lds_dwordx4 v[216:217], off
	v_lshl_add_u64 v[216:217], s[36:37], 0, v[150:151]
	s_mov_b32 m0, s33
	s_nop 0
	global_load_lds_dwordx4 v[216:217], off
	v_lshl_add_u64 v[216:217], s[36:37], 0, v[146:147]
	s_add_i32 m0, s33, 0x2000
	s_nop 0
	global_load_lds_dwordx4 v[216:217], off
	v_lshl_add_u64 v[216:217], v[220:221], 0, s[10:11]
	s_mov_b32 m0, s53
	s_nop 0
	global_load_lds_dwordx4 v[216:217], off
	v_lshl_add_u64 v[216:217], v[222:223], 0, s[10:11]
	s_mov_b32 m0, s54
	s_nop 0
	global_load_lds_dwordx4 v[216:217], off
	ds_read_b128 v[184:187], v170 offset:49152
	ds_read_b128 v[188:191], v170 offset:50176
	ds_read_b128 v[192:195], v170 offset:51200
	ds_read_b128 v[196:199], v170 offset:52224
	ds_read_b128 v[200:203], v170 offset:53248
	ds_read_b128 v[204:207], v170 offset:54272
	ds_read_b128 v[208:211], v170 offset:55296
	ds_read_b128 v[212:215], v170 offset:56320
	s_waitcnt vmcnt(8)
	s_waitcnt lgkmcnt(0)
	s_barrier
	s_setprio 0
	s_waitcnt lgkmcnt(0)
	v_mfma_f32_16x16x32_bf16 v[62:65], v[122:125], v[184:187], v[62:65]
	v_mfma_f32_16x16x32_bf16 v[58:61], v[130:133], v[184:187], v[58:61]
	v_mfma_f32_16x16x32_bf16 v[54:57], v[122:125], v[192:195], v[54:57]
	v_mfma_f32_16x16x32_bf16 v[42:45], v[130:133], v[192:195], v[42:45]
	v_mfma_f32_16x16x32_bf16 v[38:41], v[122:125], v[200:203], v[38:41]
	v_mfma_f32_16x16x32_bf16 v[26:29], v[130:133], v[200:203], v[26:29]
	v_mfma_f32_16x16x32_bf16 v[22:25], v[122:125], v[208:211], v[22:25]
	v_mfma_f32_16x16x32_bf16 v[10:13], v[130:133], v[208:211], v[10:13]
	v_mfma_f32_16x16x32_bf16 v[62:65], v[126:129], v[188:191], v[62:65]
	v_mfma_f32_16x16x32_bf16 v[58:61], v[134:137], v[188:191], v[58:61]
	v_mfma_f32_16x16x32_bf16 v[54:57], v[126:129], v[196:199], v[54:57]
	v_mfma_f32_16x16x32_bf16 v[42:45], v[134:137], v[196:199], v[42:45]
	v_mfma_f32_16x16x32_bf16 v[38:41], v[126:129], v[204:207], v[38:41]
	v_mfma_f32_16x16x32_bf16 v[26:29], v[134:137], v[204:207], v[26:29]
	v_mfma_f32_16x16x32_bf16 v[22:25], v[126:129], v[212:215], v[22:25]
	v_mfma_f32_16x16x32_bf16 v[10:13], v[134:137], v[212:215], v[10:13]
	s_setprio 2
	s_setprio 0
	v_mfma_f32_16x16x32_bf16 v[50:53], v[162:165], v[184:187], v[50:53]
	v_mfma_f32_16x16x32_bf16 v[46:49], v[176:179], v[184:187], v[46:49]
	v_mfma_f32_16x16x32_bf16 v[34:37], v[162:165], v[192:195], v[34:37]
	v_mfma_f32_16x16x32_bf16 v[30:33], v[176:179], v[192:195], v[30:33]
	v_mfma_f32_16x16x32_bf16 v[18:21], v[162:165], v[200:203], v[18:21]
	v_mfma_f32_16x16x32_bf16 v[14:17], v[176:179], v[200:203], v[14:17]
	v_mfma_f32_16x16x32_bf16 v[6:9], v[162:165], v[208:211], v[6:9]
	v_mfma_f32_16x16x32_bf16 v[2:5], v[176:179], v[208:211], v[2:5]
	v_mfma_f32_16x16x32_bf16 v[50:53], v[172:175], v[188:191], v[50:53]
	v_mfma_f32_16x16x32_bf16 v[46:49], v[180:183], v[188:191], v[46:49]
	v_mfma_f32_16x16x32_bf16 v[34:37], v[172:175], v[196:199], v[34:37]
	v_mfma_f32_16x16x32_bf16 v[30:33], v[180:183], v[196:199], v[30:33]
	v_mfma_f32_16x16x32_bf16 v[18:21], v[172:175], v[204:207], v[18:21]
	v_mfma_f32_16x16x32_bf16 v[14:17], v[180:183], v[204:207], v[14:17]
	v_mfma_f32_16x16x32_bf16 v[6:9], v[172:175], v[212:215], v[6:9]
	v_mfma_f32_16x16x32_bf16 v[2:5], v[180:183], v[212:215], v[2:5]
	s_setprio 2
	s_barrier
	s_add_i32 s62, s62, 2
	s_add_u32 s4, s4, 0x100
	s_addc_u32 s5, s5, 0
	s_add_u32 s60, s60, 0x100
	s_addc_u32 s61, s61, 0
	s_cmp_gt_u32 s62, 13
	s_cbranch_scc0 .LBB0_1931
	s_and_b64 vcc, exec, s[12:13]
	s_cbranch_vccz .LBB0_1934
	s_barrier

; #define PG8_STAGE(bufoff, gbase, voff) do { _Pragma("unroll") for (int _i = 0; _i < 2; ++_i) \
;         __builtin_amdgcn_global_load_lds((const unsigned*)((const char*)(gbase) + (voff)[_i]), (LAS unsigned*)(lds + (bufoff) + ldsw + _i * 8192), 16, 0, 0); } while (0)
; #define PG8_LDA(dst, b, h) do { _Pragma("unroll") for (int m = 0; m < 4; ++m) _Pragma("unroll") for (int k = 0; k < 2; ++k) dst[m][k] = *(const LAS bf16x8*)(lds + PG8_SA(b, h) + aoff + m * 2048 + k * 1024); } while (0)
; #define PG8_LDB(dst, b, h) do { _Pragma("unroll") for (int n = 0; n < 2; ++n) _Pragma("unroll") for (int k = 0; k < 2; ++k) dst[n][k] = *(const LAS bf16x8*)(lds + PG8_SB(b, h) + boff + n * 2048 + k * 1024); } while (0)
; #define PG8_MMA(ai, bj, At, Bt) do { __builtin_amdgcn_s_setprio(1); _Pragma("unroll") for (int m = 0; m < 4; ++m) _Pragma("unroll") for (int n = 0; n < 2; ++n) _Pragma("unroll") for (int k = 0; k < 2; ++k) \
;         acc[ai][bj][m][n] = __builtin_amdgcn_mfma_f32_16x16x32_bf16(Bt[n][k], At[m][k], acc[ai][bj][m][n], 0, 0, 0); __builtin_amdgcn_s_setprio(0); } while (0)
; #define PG8_WAIT_V(n) asm volatile("s_waitcnt vmcnt(" #n ")" ::: "memory")
; #define PG8_WAIT_L(n) asm volatile("s_waitcnt lgkmcnt(" #n ")" ::: "memory")
; #define PG8_BAR __builtin_amdgcn_s_barrier()
; #define PG8_SCHED __builtin_amdgcn_sched_barrier(0)
; template <class Epi>
; __device__ __forceinline__ void gemm_phase(LAS unsigned char* lds, const Gemm g, int G, int c, const Epi& E) {
;     ...
;             const char* a1 = cA + (size_t)(t + 1) * kstep;
;             const char* a2 = last ? nA : cA + (size_t)(t + 2) * kstep; const char* b2 = last ? nB : cB + (size_t)(t + 2) * kstep;
;             const char* a3 = a2 + kstep; const char* b3 = b2 + kstep;
;             PG8_LDB(B0, 0, 0); PG8_LDB(B1, 0, 1); PG8_SCHED; PG8_LDA(At, 0, 0); PG8_STAGE(PG8_SA(1, 1), a1 + hstepA, voffA);
;             PG8_WAIT_V(8); PG8_WAIT_L(0); PG8_BAR; PG8_MMA(0, 0, At, B0); PG8_MMA(0, 1, At, B1); PG8_BAR; PG8_SCHED;
;             PG8_LDA(At, 0, 1); PG8_STAGE(PG8_SB(0, 0), b2, voffB); PG8_STAGE(PG8_SB(0, 1), b2 + hstepB, voffB); PG8_STAGE(PG8_SA(0, 0), a2, voffA);
;             PG8_WAIT_V(8); PG8_WAIT_L(0); PG8_BAR; PG8_MMA(1, 0, At, B0); PG8_MMA(1, 1, At, B1); PG8_BAR; PG8_SCHED;
.LBB0_2084:
	s_add_u32 s33, s4, 0xfffc0080
	s_addc_u32 s38, s5, -1
	s_cmp_eq_u32 s68, 12
	s_cselect_b32 s41, s21, s38
	s_cselect_b32 s40, s20, s33
	s_cselect_b32 s39, s17, s67
	s_cselect_b32 s38, s19, s66
	v_lshl_add_u64 v[216:217], s[4:5], 0, v[138:139]
	s_add_i32 m0, s25, 0xc000
	s_nop 0
	global_load_lds_dwordx4 v[216:217], off
	v_lshl_add_u64 v[216:217], s[4:5], 0, v[140:141]
	s_add_i32 m0, s25, 0xe000
	s_nop 0
	global_load_lds_dwordx4 v[216:217], off
	ds_read_b128 v[152:155], v148
	ds_read_b128 v[156:159], v148 offset:1024
	ds_read_b128 v[160:163], v148 offset:2048
	ds_read_b128 v[164:167], v148 offset:3072
	ds_read_b128 v[168:171], v149
	ds_read_b128 v[172:175], v149 offset:1024
	ds_read_b128 v[176:179], v149 offset:2048
	ds_read_b128 v[180:183], v149 offset:3072
	ds_read_b128 v[184:187], v150
	ds_read_b128 v[188:191], v150 offset:1024
	ds_read_b128 v[192:195], v150 offset:2048
	ds_read_b128 v[196:199], v150 offset:3072
	ds_read_b128 v[200:203], v150 offset:4096
	ds_read_b128 v[204:207], v150 offset:5120
	ds_read_b128 v[208:211], v150 offset:6144
	ds_read_b128 v[212:215], v150 offset:7168
	s_waitcnt vmcnt(8)
	s_waitcnt lgkmcnt(0)
	s_barrier
	s_setprio 0
	s_waitcnt lgkmcnt(0)
	v_mfma_f32_16x16x32_bf16 v[126:129], v[152:155], v[184:187], v[126:129]
	v_mfma_f32_16x16x32_bf16 v[122:125], v[160:163], v[184:187], v[122:125]
	v_mfma_f32_16x16x32_bf16 v[110:113], v[152:155], v[192:195], v[110:113]
	v_mfma_f32_16x16x32_bf16 v[106:109], v[160:163], v[192:195], v[106:109]
	v_mfma_f32_16x16x32_bf16 v[94:97], v[152:155], v[200:203], v[94:97]
	v_mfma_f32_16x16x32_bf16 v[90:93], v[160:163], v[200:203], v[90:93]
	v_mfma_f32_16x16x32_bf16 v[78:81], v[152:155], v[208:211], v[78:81]
	v_mfma_f32_16x16x32_bf16 v[74:77], v[160:163], v[208:211], v[74:77]
	v_mfma_f32_16x16x32_bf16 v[126:129], v[156:159], v[188:191], v[126:129]
	v_mfma_f32_16x16x32_bf16 v[122:125], v[164:167], v[188:191], v[122:125]
	v_mfma_f32_16x16x32_bf16 v[110:113], v[156:159], v[196:199], v[110:113]
	v_mfma_f32_16x16x32_bf16 v[106:109], v[164:167], v[196:199], v[106:109]
	v_mfma_f32_16x16x32_bf16 v[94:97], v[156:159], v[204:207], v[94:97]
	v_mfma_f32_16x16x32_bf16 v[90:93], v[164:167], v[204:207], v[90:93]
	v_mfma_f32_16x16x32_bf16 v[78:81], v[156:159], v[212:215], v[78:81]
	v_mfma_f32_16x16x32_bf16 v[74:77], v[164:167], v[212:215], v[74:77]
	s_setprio 2
	s_setprio 0
	v_mfma_f32_16x16x32_bf16 v[118:121], v[168:171], v[184:187], v[118:121]
	v_mfma_f32_16x16x32_bf16 v[114:117], v[176:179], v[184:187], v[114:117]
	v_mfma_f32_16x16x32_bf16 v[102:105], v[168:171], v[192:195], v[102:105]
	v_mfma_f32_16x16x32_bf16 v[98:101], v[176:179], v[192:195], v[98:101]
	v_mfma_f32_16x16x32_bf16 v[86:89], v[168:171], v[200:203], v[86:89]
	v_mfma_f32_16x16x32_bf16 v[82:85], v[176:179], v[200:203], v[82:85]
	v_mfma_f32_16x16x32_bf16 v[70:73], v[168:171], v[208:211], v[70:73]
	v_mfma_f32_16x16x32_bf16 v[66:69], v[176:179], v[208:211], v[66:69]
	v_mfma_f32_16x16x32_bf16 v[118:121], v[172:175], v[188:191], v[118:121]
	v_mfma_f32_16x16x32_bf16 v[114:117], v[180:183], v[188:191], v[114:117]
	v_mfma_f32_16x16x32_bf16 v[102:105], v[172:175], v[196:199], v[102:105]
	v_mfma_f32_16x16x32_bf16 v[98:101], v[180:183], v[196:199], v[98:101]
	v_mfma_f32_16x16x32_bf16 v[86:89], v[172:175], v[204:207], v[86:89]
	v_mfma_f32_16x16x32_bf16 v[82:85], v[180:183], v[204:207], v[82:85]
	v_mfma_f32_16x16x32_bf16 v[70:73], v[172:175], v[212:215], v[70:73]
	v_mfma_f32_16x16x32_bf16 v[66:69], v[180:183], v[212:215], v[66:69]
	s_setprio 2
	s_barrier
	s_add_i32 s33, s56, s46
	v_lshl_add_u64 v[216:217], s[38:39], 0, v[134:135]
	s_mov_b32 m0, s33
	s_nop 0
	global_load_lds_dwordx4 v[216:217], off
	s_add_i32 m0, s33, 0x2000
	s_add_u32 s70, s38, 0x40000
	v_lshl_add_u64 v[218:219], s[38:39], 0, v[130:131]
	s_addc_u32 s71, s39, 0
	s_add_i32 s33, s57, s46
	global_load_lds_dwordx4 v[218:219], off
	v_lshl_add_u64 v[220:221], s[70:71], 0, v[134:135]
	s_mov_b32 m0, s33
	v_lshl_add_u64 v[222:223], s[40:41], 0, v[132:133]
	global_load_lds_dwordx4 v[220:221], off
	v_lshl_add_u64 v[220:221], s[70:71], 0, v[130:131]
	s_add_i32 m0, s33, 0x2000
	s_nop 0
	global_load_lds_dwordx4 v[220:221], off
	v_lshl_add_u64 v[220:221], s[40:41], 0, v[136:137]
	s_mov_b32 m0, s25
	s_nop 0
	global_load_lds_dwordx4 v[220:221], off
	s_mov_b32 m0, s37
	s_nop 0
	global_load_lds_dwordx4 v[222:223], off
	ds_read_b128 v[184:187], v150 offset:16384
	ds_read_b128 v[188:191], v150 offset:17408
	ds_read_b128 v[192:195], v150 offset:18432
	ds_read_b128 v[196:199], v150 offset:19456
	ds_read_b128 v[200:203], v150 offset:20480
	ds_read_b128 v[204:207], v150 offset:21504
	ds_read_b128 v[208:211], v150 offset:22528
	ds_read_b128 v[212:215], v150 offset:23552
	s_waitcnt vmcnt(8)
	s_waitcnt lgkmcnt(0)
	s_barrier
; #define PG8_STAGE(bufoff, gbase, voff) do { _Pragma("unroll") for (int _i = 0; _i < 2; ++_i) \
;         __builtin_amdgcn_global_load_lds((const unsigned*)((const char*)(gbase) + (voff)[_i]), (LAS unsigned*)(lds + (bufoff) + ldsw + _i * 8192), 16, 0, 0); } while (0)
; #define PG8_LDA(dst, b, h) do { _Pragma("unroll") for (int m = 0; m < 4; ++m) _Pragma("unroll") for (int k = 0; k < 2; ++k) dst[m][k] = *(const LAS bf16x8*)(lds + PG8_SA(b, h) + aoff + m * 2048 + k * 1024); } while (0)
; #define PG8_LDB(dst, b, h) do { _Pragma("unroll") for (int n = 0; n < 2; ++n) _Pragma("unroll") for (int k = 0; k < 2; ++k) dst[n][k] = *(const LAS bf16x8*)(lds + PG8_SB(b, h) + boff + n * 2048 + k * 1024); } while (0)
; #define PG8_MMA(ai, bj, At, Bt) do { __builtin_amdgcn_s_setprio(1); _Pragma("unroll") for (int m = 0; m < 4; ++m) _Pragma("unroll") for (int n = 0; n < 2; ++n) _Pragma("unroll") for (int k = 0; k < 2; ++k) \
;         acc[ai][bj][m][n] = __builtin_amdgcn_mfma_f32_16x16x32_bf16(Bt[n][k], At[m][k], acc[ai][bj][m][n], 0, 0, 0); __builtin_amdgcn_s_setprio(0); } while (0)
; #define PG8_WAIT_V(n) asm volatile("s_waitcnt vmcnt(" #n ")" ::: "memory")
; #define PG8_WAIT_L(n) asm volatile("s_waitcnt lgkmcnt(" #n ")" ::: "memory")
; #define PG8_BAR __builtin_amdgcn_s_barrier()
; #define PG8_SCHED __builtin_amdgcn_sched_barrier(0)
; template <class Epi>
; __device__ __forceinline__ void gemm_phase(LAS unsigned char* lds, const Gemm g, int G, int c, const Epi& E) {
;     ...
;             PG8_WAIT_V(8); PG8_WAIT_L(0); PG8_BAR; PG8_MMA(1, 0, At, B0); PG8_MMA(1, 1, At, B1); PG8_BAR; PG8_SCHED;
;             PG8_LDB(B0, 1, 0); PG8_LDB(B1, 1, 1); PG8_SCHED; PG8_LDA(At, 1, 0); PG8_STAGE(PG8_SA(0, 1), a2 + hstepA, voffA);
;             PG8_WAIT_V(8); PG8_WAIT_L(0); PG8_BAR; PG8_MMA(0, 0, At, B0); PG8_MMA(0, 1, At, B1); PG8_BAR; PG8_SCHED;
	s_setprio 0
	s_waitcnt lgkmcnt(0)
	v_mfma_f32_16x16x32_bf16 v[62:65], v[152:155], v[184:187], v[62:65]
	v_mfma_f32_16x16x32_bf16 v[58:61], v[160:163], v[184:187], v[58:61]
	v_mfma_f32_16x16x32_bf16 v[46:49], v[152:155], v[192:195], v[46:49]
	v_mfma_f32_16x16x32_bf16 v[42:45], v[160:163], v[192:195], v[42:45]
	v_mfma_f32_16x16x32_bf16 v[30:33], v[152:155], v[200:203], v[30:33]
	v_mfma_f32_16x16x32_bf16 v[26:29], v[160:163], v[200:203], v[26:29]
	v_mfma_f32_16x16x32_bf16 v[14:17], v[152:155], v[208:211], v[14:17]
	v_mfma_f32_16x16x32_bf16 v[10:13], v[160:163], v[208:211], v[10:13]
	v_mfma_f32_16x16x32_bf16 v[62:65], v[156:159], v[188:191], v[62:65]
	v_mfma_f32_16x16x32_bf16 v[58:61], v[164:167], v[188:191], v[58:61]
	v_mfma_f32_16x16x32_bf16 v[46:49], v[156:159], v[196:199], v[46:49]
	v_mfma_f32_16x16x32_bf16 v[42:45], v[164:167], v[196:199], v[42:45]
	v_mfma_f32_16x16x32_bf16 v[30:33], v[156:159], v[204:207], v[30:33]
	v_mfma_f32_16x16x32_bf16 v[26:29], v[164:167], v[204:207], v[26:29]
	v_mfma_f32_16x16x32_bf16 v[14:17], v[156:159], v[212:215], v[14:17]
	v_mfma_f32_16x16x32_bf16 v[10:13], v[164:167], v[212:215], v[10:13]
	s_setprio 2
	s_setprio 0
	v_mfma_f32_16x16x32_bf16 v[54:57], v[168:171], v[184:187], v[54:57]
	v_mfma_f32_16x16x32_bf16 v[50:53], v[176:179], v[184:187], v[50:53]
	v_mfma_f32_16x16x32_bf16 v[38:41], v[168:171], v[192:195], v[38:41]
	v_mfma_f32_16x16x32_bf16 v[34:37], v[176:179], v[192:195], v[34:37]
	v_mfma_f32_16x16x32_bf16 v[22:25], v[168:171], v[200:203], v[22:25]
	v_mfma_f32_16x16x32_bf16 v[18:21], v[176:179], v[200:203], v[18:21]
	v_mfma_f32_16x16x32_bf16 v[6:9], v[168:171], v[208:211], v[6:9]
	v_mfma_f32_16x16x32_bf16 v[2:5], v[176:179], v[208:211], v[2:5]
	v_mfma_f32_16x16x32_bf16 v[54:57], v[172:175], v[188:191], v[54:57]
	v_mfma_f32_16x16x32_bf16 v[50:53], v[180:183], v[188:191], v[50:53]
	v_mfma_f32_16x16x32_bf16 v[38:41], v[172:175], v[196:199], v[38:41]
	v_mfma_f32_16x16x32_bf16 v[34:37], v[180:183], v[196:199], v[34:37]
	v_mfma_f32_16x16x32_bf16 v[22:25], v[172:175], v[204:207], v[22:25]
	v_mfma_f32_16x16x32_bf16 v[18:21], v[180:183], v[204:207], v[18:21]
	v_mfma_f32_16x16x32_bf16 v[6:9], v[172:175], v[212:215], v[6:9]
	v_mfma_f32_16x16x32_bf16 v[2:5], v[180:183], v[212:215], v[2:5]
	s_setprio 2
	s_barrier
	s_add_i32 s33, 0, 0x18000
	s_add_i32 s69, 0, 0x1c000
	s_add_u32 s40, s40, 0x40000
	s_addc_u32 s41, s41, 0
	s_mov_b32 m0, s47
	v_lshl_add_u64 v[224:225], s[40:41], 0, v[136:137]
	global_load_lds_dwordx4 v[224:225], off
	v_lshl_add_u64 v[224:225], s[40:41], 0, v[132:133]
	s_mov_b32 m0, s48
	s_nop 0
	global_load_lds_dwordx4 v[224:225], off
	v_add_u32_e32 v164, s33, v147
	v_add_u32_e32 v180, s69, v147
	ds_read_b128 v[152:155], v164
	ds_read_b128 v[156:159], v164 offset:1024
	ds_read_b128 v[160:163], v164 offset:2048
	ds_read_b128 v[164:167], v164 offset:3072
	ds_read_b128 v[168:171], v180
	ds_read_b128 v[172:175], v180 offset:1024
	ds_read_b128 v[176:179], v180 offset:2048
	ds_read_b128 v[180:183], v180 offset:3072
	ds_read_b128 v[184:187], v150 offset:32768
	ds_read_b128 v[188:191], v150 offset:33792
	ds_read_b128 v[192:195], v150 offset:34816
	ds_read_b128 v[196:199], v150 offset:35840
	ds_read_b128 v[200:203], v150 offset:36864
	ds_read_b128 v[204:207], v150 offset:37888
	ds_read_b128 v[208:211], v150 offset:38912
	ds_read_b128 v[212:215], v150 offset:39936
	s_waitcnt vmcnt(8)
	s_waitcnt lgkmcnt(0)
	s_barrier
	s_setprio 0
	s_waitcnt lgkmcnt(0)
	v_mfma_f32_16x16x32_bf16 v[126:129], v[152:155], v[184:187], v[126:129]
	v_mfma_f32_16x16x32_bf16 v[122:125], v[160:163], v[184:187], v[122:125]
	v_mfma_f32_16x16x32_bf16 v[110:113], v[152:155], v[192:195], v[110:113]
	v_mfma_f32_16x16x32_bf16 v[106:109], v[160:163], v[192:195], v[106:109]
	v_mfma_f32_16x16x32_bf16 v[94:97], v[152:155], v[200:203], v[94:97]
	v_mfma_f32_16x16x32_bf16 v[90:93], v[160:163], v[200:203], v[90:93]
	v_mfma_f32_16x16x32_bf16 v[78:81], v[152:155], v[208:211], v[78:81]
	v_mfma_f32_16x16x32_bf16 v[74:77], v[160:163], v[208:211], v[74:77]
	v_mfma_f32_16x16x32_bf16 v[126:129], v[156:159], v[188:191], v[126:129]
	v_mfma_f32_16x16x32_bf16 v[122:125], v[164:167], v[188:191], v[122:125]
	v_mfma_f32_16x16x32_bf16 v[110:113], v[156:159], v[196:199], v[110:113]
	v_mfma_f32_16x16x32_bf16 v[106:109], v[164:167], v[196:199], v[106:109]
	v_mfma_f32_16x16x32_bf16 v[94:97], v[156:159], v[204:207], v[94:97]
	v_mfma_f32_16x16x32_bf16 v[90:93], v[164:167], v[204:207], v[90:93]
	v_mfma_f32_16x16x32_bf16 v[78:81], v[156:159], v[212:215], v[78:81]
	v_mfma_f32_16x16x32_bf16 v[74:77], v[164:167], v[212:215], v[74:77]
	s_setprio 2
	s_setprio 0
	v_mfma_f32_16x16x32_bf16 v[118:121], v[168:171], v[184:187], v[118:121]
	v_mfma_f32_16x16x32_bf16 v[114:117], v[176:179], v[184:187], v[114:117]
	v_mfma_f32_16x16x32_bf16 v[102:105], v[168:171], v[192:195], v[102:105]
	v_mfma_f32_16x16x32_bf16 v[98:101], v[176:179], v[192:195], v[98:101]
	v_mfma_f32_16x16x32_bf16 v[86:89], v[168:171], v[200:203], v[86:89]
	v_mfma_f32_16x16x32_bf16 v[82:85], v[176:179], v[200:203], v[82:85]
	v_mfma_f32_16x16x32_bf16 v[70:73], v[168:171], v[208:211], v[70:73]
	v_mfma_f32_16x16x32_bf16 v[66:69], v[176:179], v[208:211], v[66:69]
	v_mfma_f32_16x16x32_bf16 v[118:121], v[172:175], v[188:191], v[118:121]
	v_mfma_f32_16x16x32_bf16 v[114:117], v[180:183], v[188:191], v[114:117]
	v_mfma_f32_16x16x32_bf16 v[102:105], v[172:175], v[196:199], v[102:105]
	v_mfma_f32_16x16x32_bf16 v[98:101], v[180:183], v[196:199], v[98:101]
	v_mfma_f32_16x16x32_bf16 v[86:89], v[172:175], v[204:207], v[86:89]
	v_mfma_f32_16x16x32_bf16 v[82:85], v[180:183], v[204:207], v[82:85]
	v_mfma_f32_16x16x32_bf16 v[70:73], v[172:175], v[212:215], v[70:73]
	v_mfma_f32_16x16x32_bf16 v[66:69], v[180:183], v[212:215], v[66:69]
	s_setprio 2
	s_barrier
; #define PG8_STAGE(bufoff, gbase, voff) do { _Pragma("unroll") for (int _i = 0; _i < 2; ++_i) \
;         __builtin_amdgcn_global_load_lds((const unsigned*)((const char*)(gbase) + (voff)[_i]), (LAS unsigned*)(lds + (bufoff) + ldsw + _i * 8192), 16, 0, 0); } while (0)
; #define PG8_LDA(dst, b, h) do { _Pragma("unroll") for (int m = 0; m < 4; ++m) _Pragma("unroll") for (int k = 0; k < 2; ++k) dst[m][k] = *(const LAS bf16x8*)(lds + PG8_SA(b, h) + aoff + m * 2048 + k * 1024); } while (0)
; #define PG8_MMA(ai, bj, At, Bt) do { __builtin_amdgcn_s_setprio(1); _Pragma("unroll") for (int m = 0; m < 4; ++m) _Pragma("unroll") for (int n = 0; n < 2; ++n) _Pragma("unroll") for (int k = 0; k < 2; ++k) \
;         acc[ai][bj][m][n] = __builtin_amdgcn_mfma_f32_16x16x32_bf16(Bt[n][k], At[m][k], acc[ai][bj][m][n], 0, 0, 0); __builtin_amdgcn_s_setprio(0); } while (0)
; #define PG8_WAIT_V(n) asm volatile("s_waitcnt vmcnt(" #n ")" ::: "memory")
; #define PG8_WAIT_L(n) asm volatile("s_waitcnt lgkmcnt(" #n ")" ::: "memory")
; #define PG8_BAR __builtin_amdgcn_s_barrier()
; #define PG8_SCHED __builtin_amdgcn_sched_barrier(0)
; template <class Epi>
; __device__ __forceinline__ void gemm_phase(LAS unsigned char* lds, const Gemm g, int G, int c, const Epi& E) {
;     ...
;             PG8_LDA(At, 1, 1); PG8_STAGE(PG8_SB(1, 0), b3, voffB); PG8_STAGE(PG8_SB(1, 1), b3 + hstepB, voffB); PG8_STAGE(PG8_SA(1, 0), a3, voffA);
;             PG8_WAIT_V(8); PG8_WAIT_L(0); PG8_BAR; PG8_MMA(1, 0, At, B0); PG8_MMA(1, 1, At, B1); PG8_BAR; PG8_SCHED;
;         }
;         if (wr == 0) PG8_BAR;
	s_add_i32 s33, s33, s46
	v_lshl_add_u64 v[216:217], v[216:217], 0, s[12:13]
	s_mov_b32 m0, s33
	s_nop 0
	global_load_lds_dwordx4 v[216:217], off
	s_add_i32 m0, s33, 0x2000
	s_add_u32 s38, s38, 0x40080
	v_lshl_add_u64 v[216:217], v[218:219], 0, s[12:13]
	s_addc_u32 s39, s39, 0
	s_add_i32 s33, s69, s46
	global_load_lds_dwordx4 v[216:217], off
	v_lshl_add_u64 v[216:217], s[38:39], 0, v[134:135]
	s_mov_b32 m0, s33
	s_nop 0
	global_load_lds_dwordx4 v[216:217], off
	v_lshl_add_u64 v[216:217], s[38:39], 0, v[130:131]
	s_add_i32 m0, s33, 0x2000
	s_nop 0
	global_load_lds_dwordx4 v[216:217], off
	v_lshl_add_u64 v[216:217], v[220:221], 0, s[12:13]
	s_mov_b32 m0, s53
	s_nop 0
	global_load_lds_dwordx4 v[216:217], off
	v_lshl_add_u64 v[216:217], v[222:223], 0, s[12:13]
	s_mov_b32 m0, s54
	s_nop 0
	global_load_lds_dwordx4 v[216:217], off
	ds_read_b128 v[184:187], v150 offset:49152
	ds_read_b128 v[188:191], v150 offset:50176
	ds_read_b128 v[192:195], v150 offset:51200
	ds_read_b128 v[196:199], v150 offset:52224
	ds_read_b128 v[200:203], v150 offset:53248
	ds_read_b128 v[204:207], v150 offset:54272
	ds_read_b128 v[208:211], v150 offset:55296
	ds_read_b128 v[212:215], v150 offset:56320
	s_waitcnt vmcnt(8)
	s_waitcnt lgkmcnt(0)
	s_barrier
	s_setprio 0
	s_waitcnt lgkmcnt(0)
	v_mfma_f32_16x16x32_bf16 v[62:65], v[152:155], v[184:187], v[62:65]
	v_mfma_f32_16x16x32_bf16 v[58:61], v[160:163], v[184:187], v[58:61]
	v_mfma_f32_16x16x32_bf16 v[46:49], v[152:155], v[192:195], v[46:49]
	v_mfma_f32_16x16x32_bf16 v[42:45], v[160:163], v[192:195], v[42:45]
	v_mfma_f32_16x16x32_bf16 v[30:33], v[152:155], v[200:203], v[30:33]
	v_mfma_f32_16x16x32_bf16 v[26:29], v[160:163], v[200:203], v[26:29]
	v_mfma_f32_16x16x32_bf16 v[14:17], v[152:155], v[208:211], v[14:17]
	v_mfma_f32_16x16x32_bf16 v[10:13], v[160:163], v[208:211], v[10:13]
	v_mfma_f32_16x16x32_bf16 v[62:65], v[156:159], v[188:191], v[62:65]
	v_mfma_f32_16x16x32_bf16 v[58:61], v[164:167], v[188:191], v[58:61]
	v_mfma_f32_16x16x32_bf16 v[46:49], v[156:159], v[196:199], v[46:49]
	v_mfma_f32_16x16x32_bf16 v[42:45], v[164:167], v[196:199], v[42:45]
	v_mfma_f32_16x16x32_bf16 v[30:33], v[156:159], v[204:207], v[30:33]
	v_mfma_f32_16x16x32_bf16 v[26:29], v[164:167], v[204:207], v[26:29]
	v_mfma_f32_16x16x32_bf16 v[14:17], v[156:159], v[212:215], v[14:17]
	v_mfma_f32_16x16x32_bf16 v[10:13], v[164:167], v[212:215], v[10:13]
	s_setprio 2
	s_setprio 0
	v_mfma_f32_16x16x32_bf16 v[54:57], v[168:171], v[184:187], v[54:57]
	v_mfma_f32_16x16x32_bf16 v[50:53], v[176:179], v[184:187], v[50:53]
	v_mfma_f32_16x16x32_bf16 v[38:41], v[168:171], v[192:195], v[38:41]
	v_mfma_f32_16x16x32_bf16 v[34:37], v[176:179], v[192:195], v[34:37]
	v_mfma_f32_16x16x32_bf16 v[22:25], v[168:171], v[200:203], v[22:25]
	v_mfma_f32_16x16x32_bf16 v[18:21], v[176:179], v[200:203], v[18:21]
	v_mfma_f32_16x16x32_bf16 v[6:9], v[168:171], v[208:211], v[6:9]
	v_mfma_f32_16x16x32_bf16 v[2:5], v[176:179], v[208:211], v[2:5]
	v_mfma_f32_16x16x32_bf16 v[54:57], v[172:175], v[188:191], v[54:57]
	v_mfma_f32_16x16x32_bf16 v[50:53], v[180:183], v[188:191], v[50:53]
	v_mfma_f32_16x16x32_bf16 v[38:41], v[172:175], v[196:199], v[38:41]
	v_mfma_f32_16x16x32_bf16 v[34:37], v[180:183], v[196:199], v[34:37]
	v_mfma_f32_16x16x32_bf16 v[22:25], v[172:175], v[204:207], v[22:25]
	v_mfma_f32_16x16x32_bf16 v[18:21], v[180:183], v[204:207], v[18:21]
	v_mfma_f32_16x16x32_bf16 v[6:9], v[172:175], v[212:215], v[6:9]
	v_mfma_f32_16x16x32_bf16 v[2:5], v[180:183], v[212:215], v[2:5]
	s_setprio 2
	s_barrier
	s_add_i32 s68, s68, 2
	s_add_u32 s4, s4, 0x100
	s_addc_u32 s5, s5, 0
	s_add_u32 s66, s66, 0x100
	s_addc_u32 s67, s67, 0
	s_cmp_gt_u32 s68, 13
	s_cbranch_scc0 .LBB0_2084
	s_and_b64 vcc, exec, s[14:15]
	s_cbranch_vccz .LBB0_2087
	s_barrier

; #define PG8_STAGE(bufoff, gbase, voff) do { _Pragma("unroll") for (int _i = 0; _i < 2; ++_i) \
;         __builtin_amdgcn_global_load_lds((const unsigned*)((const char*)(gbase) + (voff)[_i]), (LAS unsigned*)(lds + (bufoff) + ldsw + _i * 8192), 16, 0, 0); } while (0)
; #define PG8_LDA(dst, b, h) do { _Pragma("unroll") for (int m = 0; m < 4; ++m) _Pragma("unroll") for (int k = 0; k < 2; ++k) dst[m][k] = *(const LAS bf16x8*)(lds + PG8_SA(b, h) + aoff + m * 2048 + k * 1024); } while (0)
; #define PG8_LDB(dst, b, h) do { _Pragma("unroll") for (int n = 0; n < 2; ++n) _Pragma("unroll") for (int k = 0; k < 2; ++k) dst[n][k] = *(const LAS bf16x8*)(lds + PG8_SB(b, h) + boff + n * 2048 + k * 1024); } while (0)
; #define PG8_MMA(ai, bj, At, Bt) do { __builtin_amdgcn_s_setprio(1); _Pragma("unroll") for (int m = 0; m < 4; ++m) _Pragma("unroll") for (int n = 0; n < 2; ++n) _Pragma("unroll") for (int k = 0; k < 2; ++k) \
;         acc[ai][bj][m][n] = __builtin_amdgcn_mfma_f32_16x16x32_bf16(Bt[n][k], At[m][k], acc[ai][bj][m][n], 0, 0, 0); __builtin_amdgcn_s_setprio(0); } while (0)
; #define PG8_WAIT_V(n) asm volatile("s_waitcnt vmcnt(" #n ")" ::: "memory")
; #define PG8_WAIT_L(n) asm volatile("s_waitcnt lgkmcnt(" #n ")" ::: "memory")
; #define PG8_BAR __builtin_amdgcn_s_barrier()
; #define PG8_SCHED __builtin_amdgcn_sched_barrier(0)
; template <class Epi>
; __device__ __forceinline__ void gemm_phase(LAS unsigned char* lds, const Gemm g, int G, int c, const Epi& E) {
;     ...
;             const char* a1 = cA + (size_t)(t + 1) * kstep;
;             const char* a2 = last ? nA : cA + (size_t)(t + 2) * kstep; const char* b2 = last ? nB : cB + (size_t)(t + 2) * kstep;
;             const char* a3 = a2 + kstep; const char* b3 = b2 + kstep;
;             PG8_LDB(B0, 0, 0); PG8_LDB(B1, 0, 1); PG8_SCHED; PG8_LDA(At, 0, 0); PG8_STAGE(PG8_SA(1, 1), a1 + hstepA, voffA);
;             PG8_WAIT_V(8); PG8_WAIT_L(0); PG8_BAR; PG8_MMA(0, 0, At, B0); PG8_MMA(0, 1, At, B1); PG8_BAR; PG8_SCHED;
;             PG8_LDA(At, 0, 1); PG8_STAGE(PG8_SB(0, 0), b2, voffB); PG8_STAGE(PG8_SB(0, 1), b2 + hstepB, voffB); PG8_STAGE(PG8_SA(0, 0), a2, voffA);
;             PG8_WAIT_V(8); PG8_WAIT_L(0); PG8_BAR; PG8_MMA(1, 0, At, B0); PG8_MMA(1, 1, At, B1); PG8_BAR; PG8_SCHED;
.LBB0_2169:
	s_add_u32 s20, s18, 0x100
	s_addc_u32 s21, s19, 0
	s_cmp_eq_u32 s62, 40
	s_cselect_b32 s25, s5, s21
	s_cselect_b32 s24, s4, s20
	s_cselect_b32 s23, s17, s61
	s_cselect_b32 s22, s16, s60
	v_lshl_add_u64 v[216:217], s[18:19], 0, v[154:155]
	s_add_i32 m0, s40, 0xc000
	s_nop 0
	global_load_lds_dwordx4 v[216:217], off
	v_lshl_add_u64 v[216:217], s[18:19], 0, v[156:157]
	s_add_i32 m0, s40, 0xe000
	s_nop 0
	global_load_lds_dwordx4 v[216:217], off
	ds_read_b128 v[106:109], v168
	ds_read_b128 v[110:113], v168 offset:1024
	ds_read_b128 v[114:117], v168 offset:2048
	ds_read_b128 v[118:121], v168 offset:3072
	ds_read_b128 v[162:165], v169
	ds_read_b128 v[172:175], v169 offset:1024
	ds_read_b128 v[176:179], v169 offset:2048
	ds_read_b128 v[180:183], v169 offset:3072
	ds_read_b128 v[184:187], v170
	ds_read_b128 v[188:191], v170 offset:1024
	ds_read_b128 v[192:195], v170 offset:2048
	ds_read_b128 v[196:199], v170 offset:3072
	ds_read_b128 v[200:203], v170 offset:4096
	ds_read_b128 v[204:207], v170 offset:5120
	ds_read_b128 v[208:211], v170 offset:6144
	ds_read_b128 v[212:215], v170 offset:7168
	s_waitcnt vmcnt(8)
	s_waitcnt lgkmcnt(0)
	s_barrier
	s_setprio 0
	s_waitcnt lgkmcnt(0)
	v_mfma_f32_16x16x32_bf16 v[142:145], v[106:109], v[184:187], v[142:145]
	v_mfma_f32_16x16x32_bf16 v[138:141], v[114:117], v[184:187], v[138:141]
	v_mfma_f32_16x16x32_bf16 v[126:129], v[106:109], v[192:195], v[126:129]
	v_mfma_f32_16x16x32_bf16 v[122:125], v[114:117], v[192:195], v[122:125]
	v_mfma_f32_16x16x32_bf16 v[94:97], v[106:109], v[200:203], v[94:97]
	v_mfma_f32_16x16x32_bf16 v[90:93], v[114:117], v[200:203], v[90:93]
	v_mfma_f32_16x16x32_bf16 v[78:81], v[106:109], v[208:211], v[78:81]
	v_mfma_f32_16x16x32_bf16 v[74:77], v[114:117], v[208:211], v[74:77]
	v_mfma_f32_16x16x32_bf16 v[142:145], v[110:113], v[188:191], v[142:145]
	v_mfma_f32_16x16x32_bf16 v[138:141], v[118:121], v[188:191], v[138:141]
	v_mfma_f32_16x16x32_bf16 v[126:129], v[110:113], v[196:199], v[126:129]
	v_mfma_f32_16x16x32_bf16 v[122:125], v[118:121], v[196:199], v[122:125]
	v_mfma_f32_16x16x32_bf16 v[94:97], v[110:113], v[204:207], v[94:97]
	v_mfma_f32_16x16x32_bf16 v[90:93], v[118:121], v[204:207], v[90:93]
	v_mfma_f32_16x16x32_bf16 v[78:81], v[110:113], v[212:215], v[78:81]
	v_mfma_f32_16x16x32_bf16 v[74:77], v[118:121], v[212:215], v[74:77]
	s_setprio 2
	s_setprio 0
	v_mfma_f32_16x16x32_bf16 v[134:137], v[162:165], v[184:187], v[134:137]
	v_mfma_f32_16x16x32_bf16 v[130:133], v[176:179], v[184:187], v[130:133]
	v_mfma_f32_16x16x32_bf16 v[102:105], v[162:165], v[192:195], v[102:105]
	v_mfma_f32_16x16x32_bf16 v[98:101], v[176:179], v[192:195], v[98:101]
	v_mfma_f32_16x16x32_bf16 v[86:89], v[162:165], v[200:203], v[86:89]
	v_mfma_f32_16x16x32_bf16 v[82:85], v[176:179], v[200:203], v[82:85]
	v_mfma_f32_16x16x32_bf16 v[70:73], v[162:165], v[208:211], v[70:73]
	v_mfma_f32_16x16x32_bf16 v[66:69], v[176:179], v[208:211], v[66:69]
	v_mfma_f32_16x16x32_bf16 v[134:137], v[172:175], v[188:191], v[134:137]
	v_mfma_f32_16x16x32_bf16 v[130:133], v[180:183], v[188:191], v[130:133]
	v_mfma_f32_16x16x32_bf16 v[102:105], v[172:175], v[196:199], v[102:105]
	v_mfma_f32_16x16x32_bf16 v[98:101], v[180:183], v[196:199], v[98:101]
	v_mfma_f32_16x16x32_bf16 v[86:89], v[172:175], v[204:207], v[86:89]
	v_mfma_f32_16x16x32_bf16 v[82:85], v[180:183], v[204:207], v[82:85]
	v_mfma_f32_16x16x32_bf16 v[70:73], v[172:175], v[212:215], v[70:73]
	v_mfma_f32_16x16x32_bf16 v[66:69], v[180:183], v[212:215], v[66:69]
	s_setprio 2
	s_barrier
	s_add_i32 s18, s52, s38
	v_lshl_add_u64 v[216:217], s[22:23], 0, v[150:151]
	s_mov_b32 m0, s18
	s_nop 0
	global_load_lds_dwordx4 v[216:217], off
	s_add_i32 m0, s18, 0x2000
	s_add_u32 s18, s22, 0xb0000
	v_lshl_add_u64 v[218:219], s[22:23], 0, v[146:147]
	s_addc_u32 s19, s23, 0
	s_add_i32 s33, s53, s38
	global_load_lds_dwordx4 v[218:219], off
	v_lshl_add_u64 v[220:221], s[18:19], 0, v[150:151]
	s_mov_b32 m0, s33
	v_lshl_add_u64 v[222:223], s[24:25], 0, v[148:149]
	global_load_lds_dwordx4 v[220:221], off
	v_lshl_add_u64 v[220:221], s[18:19], 0, v[146:147]
	s_add_i32 m0, s33, 0x2000
	s_nop 0
	global_load_lds_dwordx4 v[220:221], off
	v_lshl_add_u64 v[220:221], s[24:25], 0, v[152:153]
	s_mov_b32 m0, s40
	s_nop 0
	global_load_lds_dwordx4 v[220:221], off
	s_mov_b32 m0, s41
	s_nop 0
	global_load_lds_dwordx4 v[222:223], off
	ds_read_b128 v[184:187], v170 offset:16384
	ds_read_b128 v[188:191], v170 offset:17408
	ds_read_b128 v[192:195], v170 offset:18432
	ds_read_b128 v[196:199], v170 offset:19456
	ds_read_b128 v[200:203], v170 offset:20480
	ds_read_b128 v[204:207], v170 offset:21504
	ds_read_b128 v[208:211], v170 offset:22528
	ds_read_b128 v[212:215], v170 offset:23552
	s_waitcnt vmcnt(8)
	s_waitcnt lgkmcnt(0)
	s_barrier
; #define PG8_STAGE(bufoff, gbase, voff) do { _Pragma("unroll") for (int _i = 0; _i < 2; ++_i) \
;         __builtin_amdgcn_global_load_lds((const unsigned*)((const char*)(gbase) + (voff)[_i]), (LAS unsigned*)(lds + (bufoff) + ldsw + _i * 8192), 16, 0, 0); } while (0)
; #define PG8_LDA(dst, b, h) do { _Pragma("unroll") for (int m = 0; m < 4; ++m) _Pragma("unroll") for (int k = 0; k < 2; ++k) dst[m][k] = *(const LAS bf16x8*)(lds + PG8_SA(b, h) + aoff + m * 2048 + k * 1024); } while (0)
; #define PG8_LDB(dst, b, h) do { _Pragma("unroll") for (int n = 0; n < 2; ++n) _Pragma("unroll") for (int k = 0; k < 2; ++k) dst[n][k] = *(const LAS bf16x8*)(lds + PG8_SB(b, h) + boff + n * 2048 + k * 1024); } while (0)
; #define PG8_MMA(ai, bj, At, Bt) do { __builtin_amdgcn_s_setprio(1); _Pragma("unroll") for (int m = 0; m < 4; ++m) _Pragma("unroll") for (int n = 0; n < 2; ++n) _Pragma("unroll") for (int k = 0; k < 2; ++k) \
;         acc[ai][bj][m][n] = __builtin_amdgcn_mfma_f32_16x16x32_bf16(Bt[n][k], At[m][k], acc[ai][bj][m][n], 0, 0, 0); __builtin_amdgcn_s_setprio(0); } while (0)
; #define PG8_WAIT_V(n) asm volatile("s_waitcnt vmcnt(" #n ")" ::: "memory")
; #define PG8_WAIT_L(n) asm volatile("s_waitcnt lgkmcnt(" #n ")" ::: "memory")
; #define PG8_BAR __builtin_amdgcn_s_barrier()
; #define PG8_SCHED __builtin_amdgcn_sched_barrier(0)
; template <class Epi>
; __device__ __forceinline__ void gemm_phase(LAS unsigned char* lds, const Gemm g, int G, int c, const Epi& E) {
;     ...
;             PG8_WAIT_V(8); PG8_WAIT_L(0); PG8_BAR; PG8_MMA(1, 0, At, B0); PG8_MMA(1, 1, At, B1); PG8_BAR; PG8_SCHED;
;             PG8_LDB(B0, 1, 0); PG8_LDB(B1, 1, 1); PG8_SCHED; PG8_LDA(At, 1, 0); PG8_STAGE(PG8_SA(0, 1), a2 + hstepA, voffA);
;             PG8_WAIT_V(8); PG8_WAIT_L(0); PG8_BAR; PG8_MMA(0, 0, At, B0); PG8_MMA(0, 1, At, B1); PG8_BAR; PG8_SCHED;
	s_setprio 0
	s_waitcnt lgkmcnt(0)
	v_mfma_f32_16x16x32_bf16 v[62:65], v[106:109], v[184:187], v[62:65]
	v_mfma_f32_16x16x32_bf16 v[58:61], v[114:117], v[184:187], v[58:61]
	v_mfma_f32_16x16x32_bf16 v[46:49], v[106:109], v[192:195], v[46:49]
	v_mfma_f32_16x16x32_bf16 v[42:45], v[114:117], v[192:195], v[42:45]
	v_mfma_f32_16x16x32_bf16 v[30:33], v[106:109], v[200:203], v[30:33]
	v_mfma_f32_16x16x32_bf16 v[26:29], v[114:117], v[200:203], v[26:29]
	v_mfma_f32_16x16x32_bf16 v[14:17], v[106:109], v[208:211], v[14:17]
	v_mfma_f32_16x16x32_bf16 v[10:13], v[114:117], v[208:211], v[10:13]
	v_mfma_f32_16x16x32_bf16 v[62:65], v[110:113], v[188:191], v[62:65]
	v_mfma_f32_16x16x32_bf16 v[58:61], v[118:121], v[188:191], v[58:61]
	v_mfma_f32_16x16x32_bf16 v[46:49], v[110:113], v[196:199], v[46:49]
	v_mfma_f32_16x16x32_bf16 v[42:45], v[118:121], v[196:199], v[42:45]
	v_mfma_f32_16x16x32_bf16 v[30:33], v[110:113], v[204:207], v[30:33]
	v_mfma_f32_16x16x32_bf16 v[26:29], v[118:121], v[204:207], v[26:29]
	v_mfma_f32_16x16x32_bf16 v[14:17], v[110:113], v[212:215], v[14:17]
	v_mfma_f32_16x16x32_bf16 v[10:13], v[118:121], v[212:215], v[10:13]
	s_setprio 2
	s_setprio 0
	v_mfma_f32_16x16x32_bf16 v[54:57], v[162:165], v[184:187], v[54:57]
	v_mfma_f32_16x16x32_bf16 v[50:53], v[176:179], v[184:187], v[50:53]
	v_mfma_f32_16x16x32_bf16 v[38:41], v[162:165], v[192:195], v[38:41]
	v_mfma_f32_16x16x32_bf16 v[34:37], v[176:179], v[192:195], v[34:37]
	v_mfma_f32_16x16x32_bf16 v[22:25], v[162:165], v[200:203], v[22:25]
	v_mfma_f32_16x16x32_bf16 v[18:21], v[176:179], v[200:203], v[18:21]
	v_mfma_f32_16x16x32_bf16 v[6:9], v[162:165], v[208:211], v[6:9]
	v_mfma_f32_16x16x32_bf16 v[2:5], v[176:179], v[208:211], v[2:5]
	v_mfma_f32_16x16x32_bf16 v[54:57], v[172:175], v[188:191], v[54:57]
	v_mfma_f32_16x16x32_bf16 v[50:53], v[180:183], v[188:191], v[50:53]
	v_mfma_f32_16x16x32_bf16 v[38:41], v[172:175], v[196:199], v[38:41]
	v_mfma_f32_16x16x32_bf16 v[34:37], v[180:183], v[196:199], v[34:37]
	v_mfma_f32_16x16x32_bf16 v[22:25], v[172:175], v[204:207], v[22:25]
	v_mfma_f32_16x16x32_bf16 v[18:21], v[180:183], v[204:207], v[18:21]
	v_mfma_f32_16x16x32_bf16 v[6:9], v[172:175], v[212:215], v[6:9]
	v_mfma_f32_16x16x32_bf16 v[2:5], v[180:183], v[212:215], v[2:5]
	s_setprio 2
	s_barrier
	s_add_i32 s33, 0, 0x18000
	s_add_i32 s63, 0, 0x1c000
	s_add_u32 s18, s24, 0xb0000
	s_addc_u32 s19, s25, 0
	s_mov_b32 m0, s42
	v_lshl_add_u64 v[224:225], s[18:19], 0, v[152:153]
	global_load_lds_dwordx4 v[224:225], off
	v_lshl_add_u64 v[224:225], s[18:19], 0, v[148:149]
	s_mov_b32 m0, s43
	s_nop 0
	global_load_lds_dwordx4 v[224:225], off
	v_add_u32_e32 v118, s33, v167
	v_add_u32_e32 v171, s63, v167
	ds_read_b128 v[106:109], v118
	ds_read_b128 v[110:113], v118 offset:1024
	ds_read_b128 v[114:117], v118 offset:2048
	ds_read_b128 v[118:121], v118 offset:3072
	ds_read_b128 v[162:165], v171
	ds_read_b128 v[172:175], v171 offset:1024
	ds_read_b128 v[176:179], v171 offset:2048
	ds_read_b128 v[180:183], v171 offset:3072
	ds_read_b128 v[184:187], v170 offset:32768
	ds_read_b128 v[188:191], v170 offset:33792
	ds_read_b128 v[192:195], v170 offset:34816
	ds_read_b128 v[196:199], v170 offset:35840
	ds_read_b128 v[200:203], v170 offset:36864
	ds_read_b128 v[204:207], v170 offset:37888
	ds_read_b128 v[208:211], v170 offset:38912
	ds_read_b128 v[212:215], v170 offset:39936
	s_waitcnt vmcnt(8)
	s_waitcnt lgkmcnt(0)
	s_barrier
	s_setprio 0
	s_waitcnt lgkmcnt(0)
	v_mfma_f32_16x16x32_bf16 v[142:145], v[106:109], v[184:187], v[142:145]
	v_mfma_f32_16x16x32_bf16 v[138:141], v[114:117], v[184:187], v[138:141]
	v_mfma_f32_16x16x32_bf16 v[126:129], v[106:109], v[192:195], v[126:129]
	v_mfma_f32_16x16x32_bf16 v[122:125], v[114:117], v[192:195], v[122:125]
	v_mfma_f32_16x16x32_bf16 v[94:97], v[106:109], v[200:203], v[94:97]
	v_mfma_f32_16x16x32_bf16 v[90:93], v[114:117], v[200:203], v[90:93]
	v_mfma_f32_16x16x32_bf16 v[78:81], v[106:109], v[208:211], v[78:81]
	v_mfma_f32_16x16x32_bf16 v[74:77], v[114:117], v[208:211], v[74:77]
	v_mfma_f32_16x16x32_bf16 v[142:145], v[110:113], v[188:191], v[142:145]
	v_mfma_f32_16x16x32_bf16 v[138:141], v[118:121], v[188:191], v[138:141]
	v_mfma_f32_16x16x32_bf16 v[126:129], v[110:113], v[196:199], v[126:129]
	v_mfma_f32_16x16x32_bf16 v[122:125], v[118:121], v[196:199], v[122:125]
	v_mfma_f32_16x16x32_bf16 v[94:97], v[110:113], v[204:207], v[94:97]
	v_mfma_f32_16x16x32_bf16 v[90:93], v[118:121], v[204:207], v[90:93]
	v_mfma_f32_16x16x32_bf16 v[78:81], v[110:113], v[212:215], v[78:81]
	v_mfma_f32_16x16x32_bf16 v[74:77], v[118:121], v[212:215], v[74:77]
	s_setprio 2
	s_setprio 0
	v_mfma_f32_16x16x32_bf16 v[134:137], v[162:165], v[184:187], v[134:137]
	v_mfma_f32_16x16x32_bf16 v[130:133], v[176:179], v[184:187], v[130:133]
	v_mfma_f32_16x16x32_bf16 v[102:105], v[162:165], v[192:195], v[102:105]
	v_mfma_f32_16x16x32_bf16 v[98:101], v[176:179], v[192:195], v[98:101]
	v_mfma_f32_16x16x32_bf16 v[86:89], v[162:165], v[200:203], v[86:89]
	v_mfma_f32_16x16x32_bf16 v[82:85], v[176:179], v[200:203], v[82:85]
	v_mfma_f32_16x16x32_bf16 v[70:73], v[162:165], v[208:211], v[70:73]
	v_mfma_f32_16x16x32_bf16 v[66:69], v[176:179], v[208:211], v[66:69]
	v_mfma_f32_16x16x32_bf16 v[134:137], v[172:175], v[188:191], v[134:137]
	v_mfma_f32_16x16x32_bf16 v[130:133], v[180:183], v[188:191], v[130:133]
	v_mfma_f32_16x16x32_bf16 v[102:105], v[172:175], v[196:199], v[102:105]
	v_mfma_f32_16x16x32_bf16 v[98:101], v[180:183], v[196:199], v[98:101]
	v_mfma_f32_16x16x32_bf16 v[86:89], v[172:175], v[204:207], v[86:89]
	v_mfma_f32_16x16x32_bf16 v[82:85], v[180:183], v[204:207], v[82:85]
	v_mfma_f32_16x16x32_bf16 v[70:73], v[172:175], v[212:215], v[70:73]
	v_mfma_f32_16x16x32_bf16 v[66:69], v[180:183], v[212:215], v[66:69]
	s_setprio 2
	s_barrier
; #define PG8_STAGE(bufoff, gbase, voff) do { _Pragma("unroll") for (int _i = 0; _i < 2; ++_i) \
;         __builtin_amdgcn_global_load_lds((const unsigned*)((const char*)(gbase) + (voff)[_i]), (LAS unsigned*)(lds + (bufoff) + ldsw + _i * 8192), 16, 0, 0); } while (0)
; #define PG8_LDA(dst, b, h) do { _Pragma("unroll") for (int m = 0; m < 4; ++m) _Pragma("unroll") for (int k = 0; k < 2; ++k) dst[m][k] = *(const LAS bf16x8*)(lds + PG8_SA(b, h) + aoff + m * 2048 + k * 1024); } while (0)
; #define PG8_MMA(ai, bj, At, Bt) do { __builtin_amdgcn_s_setprio(1); _Pragma("unroll") for (int m = 0; m < 4; ++m) _Pragma("unroll") for (int n = 0; n < 2; ++n) _Pragma("unroll") for (int k = 0; k < 2; ++k) \
;         acc[ai][bj][m][n] = __builtin_amdgcn_mfma_f32_16x16x32_bf16(Bt[n][k], At[m][k], acc[ai][bj][m][n], 0, 0, 0); __builtin_amdgcn_s_setprio(0); } while (0)
; #define PG8_WAIT_V(n) asm volatile("s_waitcnt vmcnt(" #n ")" ::: "memory")
; #define PG8_WAIT_L(n) asm volatile("s_waitcnt lgkmcnt(" #n ")" ::: "memory")
; #define PG8_BAR __builtin_amdgcn_s_barrier()
; #define PG8_SCHED __builtin_amdgcn_sched_barrier(0)
; template <class Epi>
; __device__ __forceinline__ void gemm_phase(LAS unsigned char* lds, const Gemm g, int G, int c, const Epi& E) {
;     ...
;             PG8_LDA(At, 1, 1); PG8_STAGE(PG8_SB(1, 0), b3, voffB); PG8_STAGE(PG8_SB(1, 1), b3 + hstepB, voffB); PG8_STAGE(PG8_SA(1, 0), a3, voffA);
;             PG8_WAIT_V(8); PG8_WAIT_L(0); PG8_BAR; PG8_MMA(1, 0, At, B0); PG8_MMA(1, 1, At, B1); PG8_BAR; PG8_SCHED;
;         }
;         if (wr == 0) PG8_BAR;
	s_add_i32 s18, s33, s38
	v_lshl_add_u64 v[216:217], v[216:217], 0, s[12:13]
	s_mov_b32 m0, s18
	s_nop 0
	global_load_lds_dwordx4 v[216:217], off
	s_add_i32 m0, s18, 0x2000
	s_add_u32 s18, s22, 0xb0080
	v_lshl_add_u64 v[216:217], v[218:219], 0, s[12:13]
	s_addc_u32 s19, s23, 0
	s_add_i32 s22, s63, s38
	global_load_lds_dwordx4 v[216:217], off
	v_lshl_add_u64 v[216:217], s[18:19], 0, v[150:151]
	s_mov_b32 m0, s22
	s_nop 0
	global_load_lds_dwordx4 v[216:217], off
	v_lshl_add_u64 v[216:217], s[18:19], 0, v[146:147]
	s_add_i32 m0, s22, 0x2000
	s_nop 0
	global_load_lds_dwordx4 v[216:217], off
	v_lshl_add_u64 v[216:217], v[220:221], 0, s[12:13]
	s_mov_b32 m0, s49
	s_nop 0
	global_load_lds_dwordx4 v[216:217], off
	v_lshl_add_u64 v[216:217], v[222:223], 0, s[12:13]
	s_mov_b32 m0, s50
	s_nop 0
	global_load_lds_dwordx4 v[216:217], off
	ds_read_b128 v[184:187], v170 offset:49152
	ds_read_b128 v[188:191], v170 offset:50176
	ds_read_b128 v[192:195], v170 offset:51200
	ds_read_b128 v[196:199], v170 offset:52224
	ds_read_b128 v[200:203], v170 offset:53248
	ds_read_b128 v[204:207], v170 offset:54272
	ds_read_b128 v[208:211], v170 offset:55296
	ds_read_b128 v[212:215], v170 offset:56320
	s_waitcnt vmcnt(8)
	s_waitcnt lgkmcnt(0)
	s_barrier
	s_setprio 0
	s_waitcnt lgkmcnt(0)
	v_mfma_f32_16x16x32_bf16 v[62:65], v[106:109], v[184:187], v[62:65]
	v_mfma_f32_16x16x32_bf16 v[58:61], v[114:117], v[184:187], v[58:61]
	v_mfma_f32_16x16x32_bf16 v[46:49], v[106:109], v[192:195], v[46:49]
	v_mfma_f32_16x16x32_bf16 v[42:45], v[114:117], v[192:195], v[42:45]
	v_mfma_f32_16x16x32_bf16 v[30:33], v[106:109], v[200:203], v[30:33]
	v_mfma_f32_16x16x32_bf16 v[26:29], v[114:117], v[200:203], v[26:29]
	v_mfma_f32_16x16x32_bf16 v[14:17], v[106:109], v[208:211], v[14:17]
	v_mfma_f32_16x16x32_bf16 v[10:13], v[114:117], v[208:211], v[10:13]
	v_mfma_f32_16x16x32_bf16 v[62:65], v[110:113], v[188:191], v[62:65]
	v_mfma_f32_16x16x32_bf16 v[58:61], v[118:121], v[188:191], v[58:61]
	v_mfma_f32_16x16x32_bf16 v[46:49], v[110:113], v[196:199], v[46:49]
	v_mfma_f32_16x16x32_bf16 v[42:45], v[118:121], v[196:199], v[42:45]
	v_mfma_f32_16x16x32_bf16 v[30:33], v[110:113], v[204:207], v[30:33]
	v_mfma_f32_16x16x32_bf16 v[26:29], v[118:121], v[204:207], v[26:29]
	v_mfma_f32_16x16x32_bf16 v[14:17], v[110:113], v[212:215], v[14:17]
	v_mfma_f32_16x16x32_bf16 v[10:13], v[118:121], v[212:215], v[10:13]
	s_setprio 2
	s_setprio 0
	v_mfma_f32_16x16x32_bf16 v[54:57], v[162:165], v[184:187], v[54:57]
	v_mfma_f32_16x16x32_bf16 v[50:53], v[176:179], v[184:187], v[50:53]
	v_mfma_f32_16x16x32_bf16 v[38:41], v[162:165], v[192:195], v[38:41]
	v_mfma_f32_16x16x32_bf16 v[34:37], v[176:179], v[192:195], v[34:37]
	v_mfma_f32_16x16x32_bf16 v[22:25], v[162:165], v[200:203], v[22:25]
	v_mfma_f32_16x16x32_bf16 v[18:21], v[176:179], v[200:203], v[18:21]
	v_mfma_f32_16x16x32_bf16 v[6:9], v[162:165], v[208:211], v[6:9]
	v_mfma_f32_16x16x32_bf16 v[2:5], v[176:179], v[208:211], v[2:5]
	v_mfma_f32_16x16x32_bf16 v[54:57], v[172:175], v[188:191], v[54:57]
	v_mfma_f32_16x16x32_bf16 v[50:53], v[180:183], v[188:191], v[50:53]
	v_mfma_f32_16x16x32_bf16 v[38:41], v[172:175], v[196:199], v[38:41]
	v_mfma_f32_16x16x32_bf16 v[34:37], v[180:183], v[196:199], v[34:37]
	v_mfma_f32_16x16x32_bf16 v[22:25], v[172:175], v[204:207], v[22:25]
	v_mfma_f32_16x16x32_bf16 v[18:21], v[180:183], v[204:207], v[18:21]
	v_mfma_f32_16x16x32_bf16 v[6:9], v[172:175], v[212:215], v[6:9]
	v_mfma_f32_16x16x32_bf16 v[2:5], v[180:183], v[212:215], v[2:5]
	s_setprio 2
	s_barrier
	s_add_i32 s62, s62, 2
	s_add_u32 s60, s60, 0x100
	s_addc_u32 s61, s61, 0
	s_cmp_gt_u32 s62, 41
	s_mov_b64 s[18:19], s[20:21]
	s_cbranch_scc0 .LBB0_2169
	s_and_b64 vcc, exec, s[14:15]
	s_cbranch_vccz .LBB0_2172
	s_barrier
